# speedup vs baseline: 1.0785x; 1.0177x over previous
; DEV f32x4 mfma16(bf16x8 a, bf16x8 b, f32x4 c) { return __builtin_amdgcn_mfma_f32_16x16x32_bf16(a, b, c, 0, 0, 0); }
; template <int EPI, bool AF32>
; DEV void gemm_tile(const void* Ap, int lda, const u16* Bt, int ldb, int K, int m0, int n0, const Epi& ea, char* smem) {
;     ...
;   for (int kt = 0; kt < nk; kt++) {
;     const int buf = kt & 1;
;     if (kt + 1 < nk) swrite(buf ^ 1);
;     if (kt + 2 < nk) gload(kt + 2);
; #pragma unroll
;     for (int ks = 0; ks < 2; ks++) {
;       bf16x8 a[4], b[4];
; #pragma unroll
;       for (int m = 0; m < 4; m++) a[m] = *(const bf16x8*)(sA + buf * 9216 + (wr * 64 + m * 16 + fr) * 72 + ks * 32 + fq * 8);
; #pragma unroll
;       for (int n = 0; n < 4; n++) b[n] = *(const bf16x8*)(sB + buf * 9216 + (wc * 64 + n * 16 + fr) * 72 + ks * 32 + fq * 8);
;       __builtin_amdgcn_s_setprio(1);
; #pragma unroll
;       for (int m = 0; m < 4; m++)
; #pragma unroll
;         for (int n = 0; n < 4; n++) acc[m][n] = mfma16(a[m], b[n], acc[m][n]);
;       __builtin_amdgcn_s_setprio(0);
;     }
;     __syncthreads();
;   }
.Lgk0_loop:
	s_waitcnt lgkmcnt(0)
	ds_read_b128 v[222:225], v161 offset:64
	ds_read_b128 v[226:229], v161 offset:2368
	ds_read_b128 v[230:233], v161 offset:4672
	ds_read_b128 v[234:237], v161 offset:6976
	ds_read_b128 v[238:241], v129 offset:36928
	ds_read_b128 v[242:245], v129 offset:39232
	ds_read_b128 v[246:249], v129 offset:41536
	ds_read_b128 v[250:253], v129 offset:43840
	v_mfma_f32_16x16x32_bf16 v[94:97], v[130:133], v[146:149], v[94:97]
	v_mfma_f32_16x16x32_bf16 v[90:93], v[130:133], v[150:153], v[90:93]
	v_mfma_f32_16x16x32_bf16 v[86:89], v[130:133], v[162:165], v[86:89]
	v_mfma_f32_16x16x32_bf16 v[82:85], v[130:133], v[166:169], v[82:85]
	s_waitcnt vmcnt(0)
	ds_write_b128 v122, v[22:25] offset:18432
	ds_write_b128 v122, v[6:9] offset:55296
	v_mfma_f32_16x16x32_bf16 v[78:81], v[134:137], v[146:149], v[78:81]
	ds_write_b128 v121, v[18:21] offset:18432
	ds_write_b128 v121, v[10:13] offset:55296
	v_mfma_f32_16x16x32_bf16 v[74:77], v[134:137], v[150:153], v[74:77]
	ds_write_b128 v120, v[14:17] offset:18432
	ds_write_b128 v120, v[2:5] offset:55296
	v_mfma_f32_16x16x32_bf16 v[70:73], v[134:137], v[162:165], v[70:73]
	ds_write_b128 v124, v[26:29] offset:18432
	ds_write_b128 v124, v[30:33] offset:55296
	v_mfma_f32_16x16x32_bf16 v[66:69], v[134:137], v[166:169], v[66:69]
	global_load_dwordx4 v[22:25], v[112:113], off
	v_mfma_f32_16x16x32_bf16 v[62:65], v[138:141], v[146:149], v[62:65]
	global_load_dwordx4 v[6:9], v[110:111], off
	v_mfma_f32_16x16x32_bf16 v[58:61], v[138:141], v[150:153], v[58:61]
	global_load_dwordx4 v[18:21], v[108:109], off
	v_mfma_f32_16x16x32_bf16 v[54:57], v[138:141], v[162:165], v[54:57]
	global_load_dwordx4 v[10:13], v[106:107], off
	v_mfma_f32_16x16x32_bf16 v[50:53], v[138:141], v[166:169], v[50:53]
	global_load_dwordx4 v[14:17], v[104:105], off
	v_mfma_f32_16x16x32_bf16 v[46:49], v[142:145], v[146:149], v[46:49]
	global_load_dwordx4 v[2:5], v[102:103], off
	v_mfma_f32_16x16x32_bf16 v[42:45], v[142:145], v[150:153], v[42:45]
	global_load_dwordx4 v[26:29], v[100:101], off
	v_mfma_f32_16x16x32_bf16 v[38:41], v[142:145], v[162:165], v[38:41]
	global_load_dwordx4 v[30:33], v[98:99], off
	v_mfma_f32_16x16x32_bf16 v[34:37], v[142:145], v[166:169], v[34:37]
	s_waitcnt lgkmcnt(0)
	s_barrier
	ds_read_b128 v[130:133], v161 offset:18432
	v_mfma_f32_16x16x32_bf16 v[94:97], v[222:225], v[238:241], v[94:97]
	ds_read_b128 v[134:137], v161 offset:20736
	v_mfma_f32_16x16x32_bf16 v[90:93], v[222:225], v[242:245], v[90:93]
	ds_read_b128 v[138:141], v161 offset:23040
	v_mfma_f32_16x16x32_bf16 v[86:89], v[222:225], v[246:249], v[86:89]
	ds_read_b128 v[142:145], v161 offset:25344
	v_mfma_f32_16x16x32_bf16 v[82:85], v[222:225], v[250:253], v[82:85]
	ds_read_b128 v[146:149], v129 offset:55296
	v_mfma_f32_16x16x32_bf16 v[78:81], v[226:229], v[238:241], v[78:81]
	ds_read_b128 v[150:153], v129 offset:57600
	v_mfma_f32_16x16x32_bf16 v[74:77], v[226:229], v[242:245], v[74:77]
	ds_read_b128 v[162:165], v129 offset:59904
	v_mfma_f32_16x16x32_bf16 v[70:73], v[226:229], v[246:249], v[70:73]
	ds_read_b128 v[166:169], v129 offset:62208
	v_mfma_f32_16x16x32_bf16 v[66:69], v[226:229], v[250:253], v[66:69]
	v_mfma_f32_16x16x32_bf16 v[62:65], v[230:233], v[238:241], v[62:65]
	v_mfma_f32_16x16x32_bf16 v[58:61], v[230:233], v[242:245], v[58:61]
	v_mfma_f32_16x16x32_bf16 v[54:57], v[230:233], v[246:249], v[54:57]
	v_mfma_f32_16x16x32_bf16 v[50:53], v[230:233], v[250:253], v[50:53]
	v_mfma_f32_16x16x32_bf16 v[46:49], v[234:237], v[238:241], v[46:49]
	v_mfma_f32_16x16x32_bf16 v[42:45], v[234:237], v[242:245], v[42:45]
	v_mfma_f32_16x16x32_bf16 v[38:41], v[234:237], v[246:249], v[38:41]
	v_mfma_f32_16x16x32_bf16 v[34:37], v[234:237], v[250:253], v[34:37]
	s_waitcnt lgkmcnt(0)
	ds_read_b128 v[222:225], v161 offset:18496
	ds_read_b128 v[226:229], v161 offset:20800
	ds_read_b128 v[230:233], v161 offset:23104
	ds_read_b128 v[234:237], v161 offset:25408
	ds_read_b128 v[238:241], v129 offset:55360
	ds_read_b128 v[242:245], v129 offset:57664
	ds_read_b128 v[246:249], v129 offset:59968
	ds_read_b128 v[250:253], v129 offset:62272
	v_mfma_f32_16x16x32_bf16 v[94:97], v[130:133], v[146:149], v[94:97]
	v_mfma_f32_16x16x32_bf16 v[90:93], v[130:133], v[150:153], v[90:93]
	v_mfma_f32_16x16x32_bf16 v[86:89], v[130:133], v[162:165], v[86:89]
	v_mfma_f32_16x16x32_bf16 v[82:85], v[130:133], v[166:169], v[82:85]
	s_waitcnt vmcnt(0)
	ds_write_b128 v122, v[22:25]
	ds_write_b128 v122, v[6:9] offset:36864
	v_mfma_f32_16x16x32_bf16 v[78:81], v[134:137], v[146:149], v[78:81]
	ds_write_b128 v121, v[18:21]
	ds_write_b128 v121, v[10:13] offset:36864
	v_mfma_f32_16x16x32_bf16 v[74:77], v[134:137], v[150:153], v[74:77]
	ds_write_b128 v120, v[14:17]
	ds_write_b128 v120, v[2:5] offset:36864
	v_mfma_f32_16x16x32_bf16 v[70:73], v[134:137], v[162:165], v[70:73]
	ds_write_b128 v124, v[26:29]
	ds_write_b128 v124, v[30:33] offset:36864
	v_mfma_f32_16x16x32_bf16 v[66:69], v[134:137], v[166:169], v[66:69]
	global_load_dwordx4 v[22:25], v[112:113], off offset:128
	v_mfma_f32_16x16x32_bf16 v[62:65], v[138:141], v[146:149], v[62:65]
	global_load_dwordx4 v[6:9], v[110:111], off offset:128
	v_mfma_f32_16x16x32_bf16 v[58:61], v[138:141], v[150:153], v[58:61]
	global_load_dwordx4 v[18:21], v[108:109], off offset:128
	v_mfma_f32_16x16x32_bf16 v[54:57], v[138:141], v[162:165], v[54:57]
	global_load_dwordx4 v[10:13], v[106:107], off offset:128
	v_mfma_f32_16x16x32_bf16 v[50:53], v[138:141], v[166:169], v[50:53]
	global_load_dwordx4 v[14:17], v[104:105], off offset:128
	v_mfma_f32_16x16x32_bf16 v[46:49], v[142:145], v[146:149], v[46:49]
	global_load_dwordx4 v[2:5], v[102:103], off offset:128
	v_mfma_f32_16x16x32_bf16 v[42:45], v[142:145], v[150:153], v[42:45]
	global_load_dwordx4 v[26:29], v[100:101], off offset:128
	v_mfma_f32_16x16x32_bf16 v[38:41], v[142:145], v[162:165], v[38:41]
	global_load_dwordx4 v[30:33], v[98:99], off offset:128
	v_mfma_f32_16x16x32_bf16 v[34:37], v[142:145], v[166:169], v[34:37]
	s_waitcnt lgkmcnt(0)
	s_barrier
; DEV f32x4 mfma16(bf16x8 a, bf16x8 b, f32x4 c) { return __builtin_amdgcn_mfma_f32_16x16x32_bf16(a, b, c, 0, 0, 0); }
; template <int EPI, bool AF32>
; DEV void gemm_tile(const void* Ap, int lda, const u16* Bt, int ldb, int K, int m0, int n0, const Epi& ea, char* smem) {
;     ...
;   for (int kt = 0; kt < nk; kt++) {
;     const int buf = kt & 1;
;     if (kt + 1 < nk) swrite(buf ^ 1);
;     if (kt + 2 < nk) gload(kt + 2);
; #pragma unroll
;     for (int ks = 0; ks < 2; ks++) {
;       bf16x8 a[4], b[4];
; #pragma unroll
;       for (int m = 0; m < 4; m++) a[m] = *(const bf16x8*)(sA + buf * 9216 + (wr * 64 + m * 16 + fr) * 72 + ks * 32 + fq * 8);
; #pragma unroll
;       for (int n = 0; n < 4; n++) b[n] = *(const bf16x8*)(sB + buf * 9216 + (wc * 64 + n * 16 + fr) * 72 + ks * 32 + fq * 8);
;       __builtin_amdgcn_s_setprio(1);
; #pragma unroll
;       for (int m = 0; m < 4; m++)
; #pragma unroll
;         for (int n = 0; n < 4; n++) acc[m][n] = mfma16(a[m], b[n], acc[m][n]);
;       __builtin_amdgcn_s_setprio(0);
;     }
;     __syncthreads();
;   }
	ds_read_b128 v[130:133], v161
	v_mfma_f32_16x16x32_bf16 v[94:97], v[222:225], v[238:241], v[94:97]
	ds_read_b128 v[134:137], v161 offset:2304
	v_mfma_f32_16x16x32_bf16 v[90:93], v[222:225], v[242:245], v[90:93]
	ds_read_b128 v[138:141], v161 offset:4608
	v_mfma_f32_16x16x32_bf16 v[86:89], v[222:225], v[246:249], v[86:89]
	ds_read_b128 v[142:145], v161 offset:6912
	v_mfma_f32_16x16x32_bf16 v[82:85], v[222:225], v[250:253], v[82:85]
	ds_read_b128 v[146:149], v129 offset:36864
	v_mfma_f32_16x16x32_bf16 v[78:81], v[226:229], v[238:241], v[78:81]
	ds_read_b128 v[150:153], v129 offset:39168
	v_mfma_f32_16x16x32_bf16 v[74:77], v[226:229], v[242:245], v[74:77]
	ds_read_b128 v[162:165], v129 offset:41472
	v_mfma_f32_16x16x32_bf16 v[70:73], v[226:229], v[246:249], v[70:73]
	ds_read_b128 v[166:169], v129 offset:43776
	v_mfma_f32_16x16x32_bf16 v[66:69], v[226:229], v[250:253], v[66:69]
	v_mfma_f32_16x16x32_bf16 v[62:65], v[230:233], v[238:241], v[62:65]
	v_lshl_add_u64 v[112:113], v[112:113], 0, s[6:7]
	v_mfma_f32_16x16x32_bf16 v[58:61], v[230:233], v[242:245], v[58:61]
	v_lshl_add_u64 v[110:111], v[110:111], 0, s[6:7]
	v_mfma_f32_16x16x32_bf16 v[54:57], v[230:233], v[246:249], v[54:57]
	v_lshl_add_u64 v[108:109], v[108:109], 0, s[6:7]
	v_mfma_f32_16x16x32_bf16 v[50:53], v[230:233], v[250:253], v[50:53]
	v_lshl_add_u64 v[106:107], v[106:107], 0, s[6:7]
	v_mfma_f32_16x16x32_bf16 v[46:49], v[234:237], v[238:241], v[46:49]
	v_lshl_add_u64 v[104:105], v[104:105], 0, s[6:7]
	v_mfma_f32_16x16x32_bf16 v[42:45], v[234:237], v[242:245], v[42:45]
	v_lshl_add_u64 v[102:103], v[102:103], 0, s[6:7]
	v_mfma_f32_16x16x32_bf16 v[38:41], v[234:237], v[246:249], v[38:41]
	v_lshl_add_u64 v[100:101], v[100:101], 0, s[6:7]
	v_mfma_f32_16x16x32_bf16 v[34:37], v[234:237], v[250:253], v[34:37]
	v_lshl_add_u64 v[98:99], v[98:99], 0, s[6:7]
	s_add_i32 s11, s11, 1
	s_cmp_lg_u32 s11, 7
	s_cbranch_scc1 .Lgk0_loop
	s_waitcnt lgkmcnt(0)
	ds_read_b128 v[222:225], v161 offset:64
	ds_read_b128 v[226:229], v161 offset:2368
	ds_read_b128 v[230:233], v161 offset:4672
	ds_read_b128 v[234:237], v161 offset:6976
	ds_read_b128 v[238:241], v129 offset:36928
	ds_read_b128 v[242:245], v129 offset:39232
	ds_read_b128 v[246:249], v129 offset:41536
	ds_read_b128 v[250:253], v129 offset:43840
	v_mfma_f32_16x16x32_bf16 v[94:97], v[130:133], v[146:149], v[94:97]
	v_mfma_f32_16x16x32_bf16 v[90:93], v[130:133], v[150:153], v[90:93]
	v_mfma_f32_16x16x32_bf16 v[86:89], v[130:133], v[162:165], v[86:89]
	v_mfma_f32_16x16x32_bf16 v[82:85], v[130:133], v[166:169], v[82:85]
	s_waitcnt vmcnt(0)
	ds_write_b128 v122, v[22:25] offset:18432
	ds_write_b128 v122, v[6:9] offset:55296
	v_mfma_f32_16x16x32_bf16 v[78:81], v[134:137], v[146:149], v[78:81]
	ds_write_b128 v121, v[18:21] offset:18432
	ds_write_b128 v121, v[10:13] offset:55296
	v_mfma_f32_16x16x32_bf16 v[74:77], v[134:137], v[150:153], v[74:77]
	ds_write_b128 v120, v[14:17] offset:18432
	ds_write_b128 v120, v[2:5] offset:55296
	v_mfma_f32_16x16x32_bf16 v[70:73], v[134:137], v[162:165], v[70:73]
	ds_write_b128 v124, v[26:29] offset:18432
	ds_write_b128 v124, v[30:33] offset:55296
	v_mfma_f32_16x16x32_bf16 v[66:69], v[134:137], v[166:169], v[66:69]
	v_mfma_f32_16x16x32_bf16 v[62:65], v[138:141], v[146:149], v[62:65]
	v_mfma_f32_16x16x32_bf16 v[58:61], v[138:141], v[150:153], v[58:61]
	v_mfma_f32_16x16x32_bf16 v[54:57], v[138:141], v[162:165], v[54:57]
	v_mfma_f32_16x16x32_bf16 v[50:53], v[138:141], v[166:169], v[50:53]
	v_mfma_f32_16x16x32_bf16 v[46:49], v[142:145], v[146:149], v[46:49]
	v_mfma_f32_16x16x32_bf16 v[42:45], v[142:145], v[150:153], v[42:45]
	v_mfma_f32_16x16x32_bf16 v[38:41], v[142:145], v[162:165], v[38:41]
	v_mfma_f32_16x16x32_bf16 v[34:37], v[142:145], v[166:169], v[34:37]
	s_waitcnt lgkmcnt(0)
	s_barrier
	ds_read_b128 v[130:133], v161 offset:18432
	v_mfma_f32_16x16x32_bf16 v[94:97], v[222:225], v[238:241], v[94:97]
	ds_read_b128 v[134:137], v161 offset:20736
	v_mfma_f32_16x16x32_bf16 v[90:93], v[222:225], v[242:245], v[90:93]
	ds_read_b128 v[138:141], v161 offset:23040
	v_mfma_f32_16x16x32_bf16 v[86:89], v[222:225], v[246:249], v[86:89]
	ds_read_b128 v[142:145], v161 offset:25344
	v_mfma_f32_16x16x32_bf16 v[82:85], v[222:225], v[250:253], v[82:85]
	ds_read_b128 v[146:149], v129 offset:55296
	v_mfma_f32_16x16x32_bf16 v[78:81], v[226:229], v[238:241], v[78:81]
	ds_read_b128 v[150:153], v129 offset:57600
	v_mfma_f32_16x16x32_bf16 v[74:77], v[226:229], v[242:245], v[74:77]
	ds_read_b128 v[162:165], v129 offset:59904
	v_mfma_f32_16x16x32_bf16 v[70:73], v[226:229], v[246:249], v[70:73]
	ds_read_b128 v[166:169], v129 offset:62208
	v_mfma_f32_16x16x32_bf16 v[66:69], v[226:229], v[250:253], v[66:69]
	v_mfma_f32_16x16x32_bf16 v[62:65], v[230:233], v[238:241], v[62:65]
	v_mfma_f32_16x16x32_bf16 v[58:61], v[230:233], v[242:245], v[58:61]
	v_mfma_f32_16x16x32_bf16 v[54:57], v[230:233], v[246:249], v[54:57]
	v_mfma_f32_16x16x32_bf16 v[50:53], v[230:233], v[250:253], v[50:53]
	v_mfma_f32_16x16x32_bf16 v[46:49], v[234:237], v[238:241], v[46:49]
	v_mfma_f32_16x16x32_bf16 v[42:45], v[234:237], v[242:245], v[42:45]
	v_mfma_f32_16x16x32_bf16 v[38:41], v[234:237], v[246:249], v[38:41]
	v_mfma_f32_16x16x32_bf16 v[34:37], v[234:237], v[250:253], v[34:37]
	s_waitcnt lgkmcnt(0)
; DEV f32x4 mfma16(bf16x8 a, bf16x8 b, f32x4 c) { return __builtin_amdgcn_mfma_f32_16x16x32_bf16(a, b, c, 0, 0, 0); }
; template <int EPI, bool AF32>
; DEV void gemm_tile(const void* Ap, int lda, const u16* Bt, int ldb, int K, int m0, int n0, const Epi& ea, char* smem) {
;     ...
;   for (int kt = 0; kt < nk; kt++) {
;     const int buf = kt & 1;
;     if (kt + 1 < nk) swrite(buf ^ 1);
;     if (kt + 2 < nk) gload(kt + 2);
; #pragma unroll
;     for (int ks = 0; ks < 2; ks++) {
;       bf16x8 a[4], b[4];
; #pragma unroll
;       for (int m = 0; m < 4; m++) a[m] = *(const bf16x8*)(sA + buf * 9216 + (wr * 64 + m * 16 + fr) * 72 + ks * 32 + fq * 8);
; #pragma unroll
;       for (int n = 0; n < 4; n++) b[n] = *(const bf16x8*)(sB + buf * 9216 + (wc * 64 + n * 16 + fr) * 72 + ks * 32 + fq * 8);
;       __builtin_amdgcn_s_setprio(1);
; #pragma unroll
;       for (int m = 0; m < 4; m++)
; #pragma unroll
;         for (int n = 0; n < 4; n++) acc[m][n] = mfma16(a[m], b[n], acc[m][n]);
;       __builtin_amdgcn_s_setprio(0);
;     }
;     __syncthreads();
;   }
;     ...
; #pragma unroll
;   for (int m = 0; m < 4; m++) {
; #pragma unroll
;     for (int j = 0; j < 4; j++) {
;       const int row = m0 + wr * 64 + m * 16 + fq * 4 + j;
;       if (EPI == EP_F32) {
;         float* C = (float*)ea.p0;
; #pragma unroll
;         for (int n = 0; n < 4; n++) C[(size_t)row * ea.ld + cb + n * 16 + fr] = acc[m][n][j];
	ds_read_b128 v[222:225], v161 offset:18496
	ds_read_b128 v[226:229], v161 offset:20800
	ds_read_b128 v[230:233], v161 offset:23104
	ds_read_b128 v[234:237], v161 offset:25408
	ds_read_b128 v[238:241], v129 offset:55360
	ds_read_b128 v[242:245], v129 offset:57664
	ds_read_b128 v[246:249], v129 offset:59968
	ds_read_b128 v[250:253], v129 offset:62272
	v_mfma_f32_16x16x32_bf16 v[94:97], v[130:133], v[146:149], v[94:97]
	v_mfma_f32_16x16x32_bf16 v[90:93], v[130:133], v[150:153], v[90:93]
	v_mfma_f32_16x16x32_bf16 v[86:89], v[130:133], v[162:165], v[86:89]
	v_mfma_f32_16x16x32_bf16 v[82:85], v[130:133], v[166:169], v[82:85]
	v_mfma_f32_16x16x32_bf16 v[78:81], v[134:137], v[146:149], v[78:81]
	v_mfma_f32_16x16x32_bf16 v[74:77], v[134:137], v[150:153], v[74:77]
	v_mfma_f32_16x16x32_bf16 v[70:73], v[134:137], v[162:165], v[70:73]
	v_mfma_f32_16x16x32_bf16 v[66:69], v[134:137], v[166:169], v[66:69]
	v_mfma_f32_16x16x32_bf16 v[62:65], v[138:141], v[146:149], v[62:65]
	v_mfma_f32_16x16x32_bf16 v[58:61], v[138:141], v[150:153], v[58:61]
	v_mfma_f32_16x16x32_bf16 v[54:57], v[138:141], v[162:165], v[54:57]
	v_mfma_f32_16x16x32_bf16 v[50:53], v[138:141], v[166:169], v[50:53]
	v_mfma_f32_16x16x32_bf16 v[46:49], v[142:145], v[146:149], v[46:49]
	v_mfma_f32_16x16x32_bf16 v[42:45], v[142:145], v[150:153], v[42:45]
	v_mfma_f32_16x16x32_bf16 v[38:41], v[142:145], v[162:165], v[38:41]
	v_mfma_f32_16x16x32_bf16 v[34:37], v[142:145], v[166:169], v[34:37]
	s_waitcnt lgkmcnt(0)
	v_mfma_f32_16x16x32_bf16 v[94:97], v[222:225], v[238:241], v[94:97]
	v_mfma_f32_16x16x32_bf16 v[90:93], v[222:225], v[242:245], v[90:93]
	v_mfma_f32_16x16x32_bf16 v[86:89], v[222:225], v[246:249], v[86:89]
	v_mfma_f32_16x16x32_bf16 v[2:5], v[222:225], v[250:253], v[82:85]
	v_mfma_f32_16x16x32_bf16 v[30:33], v[226:229], v[238:241], v[78:81]
	v_mfma_f32_16x16x32_bf16 v[6:9], v[226:229], v[250:253], v[66:69]
	v_mfma_f32_16x16x32_bf16 v[10:13], v[230:233], v[250:253], v[50:53]
	v_mfma_f32_16x16x32_bf16 v[18:21], v[234:237], v[238:241], v[46:49]
	v_mfma_f32_16x16x32_bf16 v[22:25], v[234:237], v[242:245], v[42:45]
	v_mfma_f32_16x16x32_bf16 v[26:29], v[234:237], v[246:249], v[38:41]
	v_mfma_f32_16x16x32_bf16 v[14:17], v[234:237], v[250:253], v[34:37]
	v_mfma_f32_16x16x32_bf16 v[38:41], v[226:229], v[242:245], v[74:77]
	v_mfma_f32_16x16x32_bf16 v[46:49], v[226:229], v[246:249], v[70:73]
	v_mfma_f32_16x16x32_bf16 v[34:37], v[230:233], v[238:241], v[62:65]
	v_mfma_f32_16x16x32_bf16 v[42:45], v[230:233], v[242:245], v[58:61]
	v_mfma_f32_16x16x32_bf16 v[50:53], v[230:233], v[246:249], v[54:57]
	s_nop 7
	v_and_or_b32 v54, v114, 64, s10
	v_add_u32_e32 v0, s9, v117
	v_ashrrev_i32_e32 v55, 31, v54
	v_lshl_or_b32 v58, v116, 2, v0
	v_lshl_add_u64 v[54:55], v[54:55], 2, s[0:1]
	v_lshlrev_b32_e32 v0, 2, v115
	v_lshl_add_u64 v[54:55], v[54:55], 0, v[0:1]
	v_mad_i64_i32 v[56:57], s[6:7], v58, s68, v[54:55]
	v_or_b32_e32 v0, 1, v58
	s_barrier
	global_store_dword v[56:57], v94, off
	global_store_dword v[56:57], v90, off offset:64
	global_store_dword v[56:57], v86, off offset:128
	global_store_dword v[56:57], v2, off offset:192
	v_mad_i64_i32 v[56:57], s[6:7], v0, s68, v[54:55]
	v_or_b32_e32 v0, 2, v58
	global_store_dword v[56:57], v95, off
	global_store_dword v[56:57], v91, off offset:64
	global_store_dword v[56:57], v87, off offset:128
	global_store_dword v[56:57], v3, off offset:192
	v_mad_i64_i32 v[2:3], s[6:7], v0, s68, v[54:55]
	v_or_b32_e32 v0, 3, v58
	global_store_dword v[2:3], v96, off
	global_store_dword v[2:3], v92, off offset:64
	global_store_dword v[2:3], v88, off offset:128
	global_store_dword v[2:3], v4, off offset:192
	v_mad_i64_i32 v[2:3], s[6:7], v0, s68, v[54:55]
	v_or_b32_e32 v0, 16, v58
	global_store_dword v[2:3], v97, off
	global_store_dword v[2:3], v93, off offset:64
	global_store_dword v[2:3], v89, off offset:128
	global_store_dword v[2:3], v5, off offset:192
	v_mad_i64_i32 v[2:3], s[6:7], v0, s68, v[54:55]
	v_or_b32_e32 v0, 17, v58
	global_store_dword v[2:3], v30, off
	global_store_dword v[2:3], v38, off offset:64
	global_store_dword v[2:3], v46, off offset:128
	global_store_dword v[2:3], v6, off offset:192
	v_mad_i64_i32 v[2:3], s[6:7], v0, s68, v[54:55]
	v_or_b32_e32 v0, 18, v58
	global_store_dword v[2:3], v31, off
	global_store_dword v[2:3], v39, off offset:64
	global_store_dword v[2:3], v47, off offset:128
	global_store_dword v[2:3], v7, off offset:192
	v_mad_i64_i32 v[2:3], s[6:7], v0, s68, v[54:55]
	v_or_b32_e32 v0, 19, v58
	global_store_dword v[2:3], v32, off
	global_store_dword v[2:3], v40, off offset:64
	global_store_dword v[2:3], v48, off offset:128
	global_store_dword v[2:3], v8, off offset:192
	v_mad_i64_i32 v[2:3], s[6:7], v0, s68, v[54:55]
	v_or_b32_e32 v0, 32, v58
	global_store_dword v[2:3], v33, off
	global_store_dword v[2:3], v41, off offset:64
	global_store_dword v[2:3], v49, off offset:128
	global_store_dword v[2:3], v9, off offset:192
	v_mad_i64_i32 v[2:3], s[6:7], v0, s68, v[54:55]
	v_or_b32_e32 v0, 33, v58
	global_store_dword v[2:3], v34, off
	global_store_dword v[2:3], v42, off offset:64
	global_store_dword v[2:3], v50, off offset:128
	global_store_dword v[2:3], v10, off offset:192
	v_mad_i64_i32 v[2:3], s[6:7], v0, s68, v[54:55]
	v_or_b32_e32 v0, 34, v58
	global_store_dword v[2:3], v35, off
	global_store_dword v[2:3], v43, off offset:64
	global_store_dword v[2:3], v51, off offset:128
	global_store_dword v[2:3], v11, off offset:192
	v_mad_i64_i32 v[2:3], s[6:7], v0, s68, v[54:55]
	v_or_b32_e32 v0, 35, v58
	global_store_dword v[2:3], v36, off
	global_store_dword v[2:3], v44, off offset:64
	global_store_dword v[2:3], v52, off offset:128
	global_store_dword v[2:3], v12, off offset:192
	v_mad_i64_i32 v[2:3], s[6:7], v0, s68, v[54:55]
	v_or_b32_e32 v0, 48, v58
	global_store_dword v[2:3], v37, off
	global_store_dword v[2:3], v45, off offset:64
	global_store_dword v[2:3], v53, off offset:128
	global_store_dword v[2:3], v13, off offset:192
	v_mad_i64_i32 v[2:3], s[6:7], v0, s68, v[54:55]
	v_or_b32_e32 v0, 49, v58
	global_store_dword v[2:3], v18, off
	global_store_dword v[2:3], v22, off offset:64
	global_store_dword v[2:3], v26, off offset:128
	global_store_dword v[2:3], v14, off offset:192
	v_mad_i64_i32 v[2:3], s[6:7], v0, s68, v[54:55]
	v_or_b32_e32 v0, 50, v58
	global_store_dword v[2:3], v19, off
	global_store_dword v[2:3], v23, off offset:64
	global_store_dword v[2:3], v27, off offset:128
	global_store_dword v[2:3], v15, off offset:192
	v_mad_i64_i32 v[2:3], s[6:7], v0, s68, v[54:55]
	v_or_b32_e32 v0, 51, v58
	global_store_dword v[2:3], v20, off
	global_store_dword v[2:3], v24, off offset:64
	global_store_dword v[2:3], v28, off offset:128
	global_store_dword v[2:3], v16, off offset:192
	v_mad_i64_i32 v[2:3], s[6:7], v0, s68, v[54:55]
	v_readfirstlane_b32 s6, v198
	global_store_dword v[2:3], v21, off
	global_store_dword v[2:3], v25, off offset:64
	global_store_dword v[2:3], v29, off offset:128
	global_store_dword v[2:3], v17, off offset:192
	s_add_i32 s8, s6, s8
	s_cmpk_lt_i32 s8, 0x618
	s_cbranch_scc1 .LBB0_164

; template <int DQ, int DV, int NQT, bool SAMPLE>
; DEV void attn_item(const Params& p, int item, char* smem) {
;     ...
;   if (!SAMPLE) {
;     const int qb = 63 - (item >> 5), bh = item & 31, b = bh >> 3, h = bh & 7;
;     K1 = (const u16*)(ws + A_KN) + (size_t)(b * 8 + h) * 8192 * 128;
;     ld1 = 128;
;     K2 = (const u16*)(ws + E_KRP) + (size_t)b * 8192 * 64;
;     Vt = (const u16*)(ws + OFF_B) + (size_t)(b * 8 + h) * 8192 * 128;
;     ldv = 0;
;     nkt = 4 * qb + 4;
;     wlim = 4 * qb + 2 * (w >> 1) + 1;
; #pragma unroll
;     for (int qt = 0; qt < NQT; qt++) {
;       const int t = b * 8192 + qb * 128 + w * 16 * NQT + qt * 16 + fr;
;       qrow[qt] = (const u16*)(ws + A_Q) + (size_t)t * 1536 + h * 192;
;       orow[qt] = (u16*)(ws + OFF_C) + (size_t)t * 1024 + h * 128;
;     }
;   } else {
;     const int b = item >> 2, grp = item & 3;
;     K1 = (const u16*)(ws + D_CKC) + (size_t)b * 4128 * 256;
;     ld1 = 256;
;     K2 = (const u16*)(ws + D_KRC) + (size_t)b * 4128 * 64;
;     Vt = (const u16*)(ws + A_VTC) + (size_t)b * 130 * 256 * 32;
;     ldv = 0;
;     nkt = 129;
;     wlim = 129;
; #pragma unroll
;     for (int qt = 0; qt < NQT; qt++) {
;       const int r = w * 16 * NQT + qt * 16 + fr;
;       const int h = grp * 2 + (r >> 5), q = r & 31;
;       qrow[qt] = (const u16*)(ws + D_QL) + (size_t)(b * 32 + q) * 2560 + h * 320;
;       orow[qt] = (u16*)(ws + D_OL) + (size_t)(b * 32 + q) * 2048 + h * 256;
;     }
;   }
;   bf16x8 qf[NQT][NKS];
; #pragma unroll
;   for (int qt = 0; qt < NQT; qt++)
; #pragma unroll
;     for (int ks = 0; ks < NKS; ks++) qf[qt][ks] = *(const bf16x8*)(qrow[qt] + ks * 32 + fq * 8);
;   f32x4 o[DV / 16][NQT];
;   float mrun[NQT], lrun[NQT];
; #pragma unroll
;   for (int qt = 0; qt < NQT; qt++) {
;     mrun[qt] = -INFINITY;
;     lrun[qt] = 0.f;
; #pragma unroll
;     for (int d = 0; d < DV / 16; d++) o[d][qt] = (f32x4){0.f, 0.f, 0.f, 0.f};
;   }
;   u32x4 rk[NKC], rv[NVC];
;   auto gload = [&](int kt) {
; #pragma unroll
; DEV void phase_attn(const Params& p, int* ctr, char* smem) {
;     ...
;   for (;;) {
;     __syncthreads();
;     if (tidx() == 0) *sitem = atomicAdd(ctr, 1);
;     __syncthreads();
;     const int item = __builtin_amdgcn_readfirstlane(*sitem);
;     if (item >= 64 + 2048) break;
;     if (item < 64) attn_item<320, 256, 1, true>(p, item, smem);
;     else attn_item<192, 128, 2, false>(p, item - 64, smem);
.LBB0_447:
	s_or_b64 exec, exec, s[0:1]
	s_waitcnt lgkmcnt(0)
	s_barrier
	ds_read_b32 v0, v202
	s_mov_b64 s[0:1], -1
	s_waitcnt lgkmcnt(0)
	v_readfirstlane_b32 s16, v0
	s_cmpk_gt_i32 s16, 0x83f
	s_cbranch_scc1 .LBB0_442
	s_cmp_gt_i32 s16, 63
	s_cbranch_scc0 .LBB0_476
	s_sub_i32 s0, s16, 64
	s_lshr_b32 s1, s0, 5
	s_xor_b32 s19, s1, 63
	s_bfe_u32 s2, s16, 0x20003
	v_mov_b32_e32 v29, v157
	s_lshl_b32 s18, s0, 20
	s_lshl_b32 s0, s2, 13
	s_lshl_b32 s1, s19, 7
	s_mov_b64 s[8:9], s[62:63]
	v_and_b32_e32 v28, 15, v29
	s_and_b32 s17, s16, 7
	s_and_b32 s3, s18, 0x1f00000
	s_add_i32 s1, s1, s0
	v_ashrrev_i32_e32 v0, 1, v29
	v_and_b32_e32 v0, 0xffffffe0, v0
	v_or_b32_e32 v2, s1, v28
	s_add_u32 s0, s8, 0x2800000
	v_add_u32_e32 v152, v2, v0
	s_addc_u32 s1, s9, 0
	v_mov_b64_e32 v[2:3], s[0:1]
	v_or_b32_e32 v162, 16, v152
	v_mad_i64_i32 v[4:5], s[0:1], v152, s68, v[2:3]
	s_mov_b32 s5, s41
	s_mul_i32 s4, s17, 0x180
	v_mad_i64_i32 v[2:3], s[0:1], v162, s68, v[2:3]
	v_bfe_u32 v30, v29, 4, 2
	v_lshl_add_u64 v[4:5], v[4:5], 0, s[4:5]
	v_lshl_add_u64 v[2:3], v[2:3], 0, s[4:5]
	v_lshlrev_b32_e32 v0, 4, v30
	v_lshl_add_u64 v[4:5], v[4:5], 0, v[0:1]
	v_lshl_add_u64 v[2:3], v[2:3], 0, v[0:1]
	global_load_dwordx4 v[108:111], v[4:5], off
	global_load_dwordx4 v[96:99], v[4:5], off offset:64
	global_load_dwordx4 v[92:95], v[4:5], off offset:128
	global_load_dwordx4 v[80:83], v[4:5], off offset:192
	global_load_dwordx4 v[76:79], v[4:5], off offset:256
	global_load_dwordx4 v[68:71], v[4:5], off offset:320
	global_load_dwordx4 v[112:115], v[2:3], off
	global_load_dwordx4 v[104:107], v[2:3], off offset:64
	global_load_dwordx4 v[100:103], v[2:3], off offset:128
	global_load_dwordx4 v[88:91], v[2:3], off offset:192
	global_load_dwordx4 v[84:87], v[2:3], off offset:256
	global_load_dwordx4 v[72:75], v[2:3], off offset:320
	s_lshl_b32 s0, s2, 20
	s_add_u32 s0, s8, s0
	s_addc_u32 s1, s9, 0
	s_add_u32 s10, s0, 0x1d868000
	v_mul_hi_i32 v0, v29, s28
	s_addc_u32 s11, s1, 0
	s_lshl_b32 s20, s3, 1
	v_lshrrev_b32_e32 v2, 31, v0
	v_ashrrev_i32_e32 v0, 2, v0
	s_add_u32 s0, s8, s20
	v_add_u32_e32 v8, v0, v2
	s_addc_u32 s1, s9, 0
	v_mul_lo_u32 v0, v8, 24
	s_add_u32 s0, s0, 0x8980000
	v_sub_u32_e32 v0, v29, v0
	v_ashrrev_i32_e32 v9, 31, v8
	s_mov_b32 s21, s41
	s_addc_u32 s1, s1, 0
	v_lshlrev_b32_e32 v2, 3, v0
	v_cmp_gt_i32_e64 s[2:3], 16, v0
	v_cmp_lt_i32_e32 vcc, 15, v0
	v_lshlrev_b64 v[4:5], 7, v[8:9]
	s_and_saveexec_b64 s[4:5], vcc
	s_xor_b64 s[4:5], exec, s[4:5]
	v_lshl_add_u64 v[6:7], s[10:11], 0, v[4:5]
	v_mov_b32_e32 v3, v1
	v_lshl_add_u64 v[6:7], v[2:3], 1, v[6:7]
	v_lshl_add_u64 v[10:11], v[6:7], 0, s[50:51]
	s_or_saveexec_b64 s[4:5], s[4:5]
	v_lshlrev_b64 v[6:7], 8, v[8:9]
	v_ashrrev_i32_e32 v3, 31, v2
	s_xor_b64 exec, exec, s[4:5]
	v_lshl_add_u64 v[10:11], s[0:1], 0, v[6:7]
	v_lshl_add_u64 v[10:11], v[2:3], 1, v[10:11]
	s_or_b64 exec, exec, s[4:5]
	global_load_dwordx4 v[116:119], v[10:11], off
	v_add_u32_e32 v9, 0x100, v29
	v_mul_hi_i32 v0, v9, s28
	v_lshrrev_b32_e32 v10, 31, v0
	v_ashrrev_i32_e32 v0, 2, v0
	v_add_u32_e32 v16, v0, v10
	v_mul_lo_u32 v0, v16, 24
	v_sub_u32_e32 v0, v9, v0
	v_ashrrev_i32_e32 v17, 31, v16
	v_lshlrev_b32_e32 v10, 3, v0
	v_cmp_gt_i32_e64 s[4:5], 16, v0
	v_cmp_lt_i32_e32 vcc, 15, v0
	v_lshlrev_b64 v[12:13], 7, v[16:17]
	s_and_saveexec_b64 s[6:7], vcc
	s_xor_b64 s[6:7], exec, s[6:7]
	v_lshl_add_u64 v[14:15], s[10:11], 0, v[12:13]
	v_mov_b32_e32 v11, v1
	v_lshl_add_u64 v[14:15], v[10:11], 1, v[14:15]
	v_lshl_add_u64 v[18:19], v[14:15], 0, s[50:51]
	s_or_saveexec_b64 s[6:7], s[6:7]
	v_lshlrev_b64 v[14:15], 8, v[16:17]
	v_ashrrev_i32_e32 v11, 31, v10
	s_xor_b64 exec, exec, s[6:7]
	v_lshl_add_u64 v[18:19], s[0:1], 0, v[14:15]
	v_lshl_add_u64 v[18:19], v[10:11], 1, v[18:19]
	s_or_b64 exec, exec, s[6:7]
	global_load_dwordx4 v[120:123], v[18:19], off
	v_add_u32_e32 v0, 0x200, v29
	v_mul_hi_i32 v17, v0, s28
	v_lshrrev_b32_e32 v18, 31, v17
	v_ashrrev_i32_e32 v17, 2, v17
	v_add_u32_e32 v22, v17, v18
	v_mul_lo_u32 v17, v22, 24
	v_sub_u32_e32 v17, v0, v17
	v_ashrrev_i32_e32 v23, 31, v22
	v_lshlrev_b32_e32 v0, 3, v17
	v_cmp_gt_i32_e64 s[6:7], 16, v17
	v_cmp_lt_i32_e32 vcc, 15, v17
	v_lshlrev_b64 v[20:21], 7, v[22:23]
	v_lshlrev_b64 v[18:19], 8, v[22:23]
	s_and_saveexec_b64 s[14:15], vcc
	s_xor_b64 s[14:15], exec, s[14:15]
	v_lshlrev_b64 v[20:21], 7, v[22:23]
	v_lshl_add_u64 v[18:19], s[10:11], 0, v[20:21]
	v_lshl_add_u64 v[18:19], v[0:1], 1, v[18:19]
	v_lshl_add_u64 v[26:27], v[18:19], 0, s[50:51]
	v_lshlrev_b64 v[18:19], 8, v[22:23]
	s_or_saveexec_b64 s[10:11], s[14:15]
	v_mov_b64_e32 v[24:25], v[0:1]
	s_xor_b64 exec, exec, s[10:11]
	v_lshl_add_u64 v[26:27], s[0:1], 0, v[18:19]
	v_ashrrev_i32_e32 v25, 31, v0
	v_mov_b32_e32 v24, v0
	v_lshl_add_u64 v[26:27], v[24:25], 1, v[26:27]
	s_or_b64 exec, exec, s[10:11]
	s_lshl_b32 s14, s19, 2
	s_add_u32 s0, s8, s20
	global_load_dwordx4 v[124:127], v[26:27], off
	v_lshlrev_b32_e32 v26, 3, v29
	s_addc_u32 s1, s9, 0
	v_ashrrev_i32_e32 v27, 31, v26
	s_add_u32 s0, s0, 0xeb00000
	v_lshlrev_b64 v[32:33], 1, v[26:27]
	v_add_u32_e32 v26, 0x800, v26
	s_addc_u32 s1, s1, 0
	v_ashrrev_i32_e32 v27, 31, v26
	v_lshl_add_u64 v[34:35], s[0:1], 0, v[32:33]
	v_lshlrev_b64 v[26:27], 1, v[26:27]
	v_lshl_add_u64 v[36:37], s[0:1], 0, v[26:27]
	global_load_dwordx4 v[132:135], v[34:35], off
	global_load_dwordx4 v[128:131], v[36:37], off
	v_mul_lo_u32 v8, v8, s31
	v_lshl_add_u32 v189, v2, 1, v8
	v_mul_lo_u32 v8, v16, s31
	v_lshl_add_u32 v190, v10, 1, v8
	v_mul_lo_u32 v8, v22, s31
	v_lshl_add_u32 v191, v24, 1, v8
	v_lshlrev_b32_e32 v8, 4, v29
	v_lshrrev_b32_e32 v16, 2, v29
	v_and_b32_e32 v8, 48, v8
	v_mad_u64_u32 v[164:165], s[0:1], v16, s36, v[8:9]
	v_lshrrev_b32_e32 v9, 2, v9
	v_mad_u64_u32 v[166:167], s[0:1], v9, s36, v[8:9]
	s_lshl_b32 s0, s18, 1
	s_or_b32 s15, s14, 3
	s_and_b32 s10, s0, 0x3e00000
	s_add_u32 s0, s10, 0xeb02000
	s_addc_u32 s1, 0, 0
	v_lshl_add_u64 v[168:169], s[0:1], 0, v[26:27]
	v_lshl_add_u64 v[170:171], s[0:1], 0, v[32:33]
	s_lshl_b32 s0, s16, 17
	s_and_b32 s0, s0, 0x300000
	s_or_b32 s0, s0, 0x1d868f00
	v_ashrrev_i32_e32 v17, 6, v29
	s_mov_b32 s1, 0
	s_add_u32 s10, s10, 0x8982000
	v_add_u32_e32 v17, s14, v17
	v_mov_b32_e32 v8, v2
	v_mov_b32_e32 v9, v1
	s_addc_u32 s11, 0, 0
	v_lshl_add_u64 v[4:5], s[0:1], 0, v[4:5]
	v_or_b32_e32 v188, 1, v17
	v_mov_b32_e32 v16, v10
	v_mov_b32_e32 v17, v1
	v_lshl_add_u64 v[12:13], s[0:1], 0, v[12:13]
	s_waitcnt vmcnt(24)
; DEV f32x4 mfma16(bf16x8 a, bf16x8 b, f32x4 c) { return __builtin_amdgcn_mfma_f32_16x16x32_bf16(a, b, c, 0, 0, 0); }
; template <int DQ, int DV, int NQT, bool SAMPLE>
; DEV void attn_item(const Params& p, int item, char* smem) {
;     ...
;     for (int i = 0; i < NKC; i++) {
;       const int c = tid + i * 256, row = c / CPR, col = (c % CPR) * 8;
;       const size_t key = (size_t)kt * 32 + row;
;       const u16* srcp = (col < D1) ? (K1 + key * ld1 + col) : (K2 + key * 64 + (col - D1));
;       rk[i] = *(const u32x4*)srcp;
;     }
; #pragma unroll
;     for (int i = 0; i < NVC; i++) {
;       const int c = tid + i * 256, row = c >> 2, kc = c & 3;
;       rv[i] = *(const u32x4*)(Vt + (size_t)kt * (DV * 32) + (row * 4 + kc) * 8);
;     ...
;         float ps = 0.f;
; #pragma unroll
;         for (int a = 0; a < 2; a++)
; #pragma unroll
;           for (int j = 0; j < 4; j++) {
;             const float pv = __builtin_amdgcn_exp2f(s[a][qt][j] * sc - mnew);
;             s[a][qt][j] = pv;
;             ps += pv;
;           }
;         lrun[qt] += ps;
;         pb[qt] = mk8(pack2(s[0][qt][0], s[0][qt][1]), pack2(s[0][qt][2], s[0][qt][3]),
;                      pack2(s[1][qt][0], s[1][qt][1]), pack2(s[1][qt][2], s[1][qt][3]));
;       }
;       __builtin_amdgcn_s_setprio(1);
; #pragma unroll
;       for (int d = 0; d < DV / 16; d++) {
;         const uint2 vlo = *(const uint2*)(sV + (d * 16 + fr) * VS + fq * 4);
;         const uint2 vhi = *(const uint2*)(sV + (d * 16 + fr) * VS + 16 + fq * 4);
;         const bf16x8 vf = mk8(vlo.x, vlo.y, vhi.x, vhi.y);
; #pragma unroll
;         for (int qt = 0; qt < NQT; qt++) o[d][qt] = mfma16(vf, pb[qt], o[d][qt]);
;       }
	v_lshl_add_u64 v[180:181], v[8:9], 1, v[4:5]
	v_lshl_add_u64 v[4:5], s[10:11], 0, v[6:7]
	v_lshlrev_b32_e32 v23, 3, v30
	v_lshl_add_u64 v[20:21], s[0:1], 0, v[20:21]
	v_lshl_add_u64 v[18:19], s[10:11], 0, v[18:19]
	v_lshl_add_u64 v[176:177], v[16:17], 1, v[12:13]
	v_lshl_add_u64 v[12:13], s[10:11], 0, v[14:15]
	v_lshl_add_u64 v[182:183], v[2:3], 1, v[4:5]
	v_mov_b32_e32 v2, v1
	v_mov_b32_e32 v3, v1
	v_lshlrev_b32_e32 v186, 1, v23
	v_lshlrev_b32_e32 v165, 2, v30
	v_mul_u32_u24_e32 v187, 0x190, v28
	v_mad_u32_u24 v167, v28, s36, v23
	v_lshl_add_u64 v[172:173], v[0:1], 1, v[20:21]
	v_lshl_add_u64 v[174:175], v[24:25], 1, v[18:19]
	v_lshl_add_u64 v[178:179], v[10:11], 1, v[12:13]
	v_mov_b32_e32 v0, v1
	v_mov_b64_e32 v[6:7], v[2:3]
	v_mov_b64_e32 v[38:39], v[2:3]
	v_mov_b64_e32 v[10:11], v[2:3]
	v_mov_b64_e32 v[42:43], v[2:3]
	v_mov_b64_e32 v[14:15], v[2:3]
	v_mov_b64_e32 v[46:47], v[2:3]
	v_mov_b64_e32 v[18:19], v[2:3]
	v_mov_b64_e32 v[50:51], v[2:3]
	v_mov_b64_e32 v[22:23], v[2:3]
	v_mov_b64_e32 v[54:55], v[2:3]
	v_mov_b64_e32 v[26:27], v[2:3]
	v_mov_b64_e32 v[58:59], v[2:3]
	v_mov_b64_e32 v[30:31], v[2:3]
	v_mov_b64_e32 v[62:63], v[2:3]
	v_mov_b64_e32 v[34:35], v[2:3]
	v_mov_b64_e32 v[66:67], v[2:3]
	v_ashrrev_i32_e32 v153, 31, v152
	v_ashrrev_i32_e32 v163, 31, v162
	v_add_u32_e32 v184, 0x500, v167
	v_mov_b32_e32 v161, 0
	s_waitcnt vmcnt(23)
	v_mov_b32_e32 v185, 0xff800000
	v_mov_b64_e32 v[4:5], v[0:1]
	v_mov_b64_e32 v[36:37], v[0:1]
	v_mov_b64_e32 v[8:9], v[0:1]
	v_mov_b64_e32 v[40:41], v[0:1]
	v_mov_b64_e32 v[12:13], v[0:1]
	v_mov_b64_e32 v[44:45], v[0:1]
	v_mov_b64_e32 v[16:17], v[0:1]
	v_mov_b64_e32 v[48:49], v[0:1]
	v_mov_b64_e32 v[20:21], v[0:1]
	v_mov_b64_e32 v[52:53], v[0:1]
	v_mov_b64_e32 v[24:25], v[0:1]
	v_mov_b64_e32 v[56:57], v[0:1]
	v_mov_b64_e32 v[28:29], v[0:1]
	v_mov_b64_e32 v[60:61], v[0:1]
	v_mov_b64_e32 v[32:33], v[0:1]
	v_mov_b64_e32 v[64:65], v[0:1]
	v_mov_b32_e32 v2, 0xff800000
	v_mov_b32_e32 v0, 0
	v_mov_b32_e32 v3, 0x2000
	v_mov_b32_e32 v192, 0x1000
	v_cndmask_b32_e64 v183, v181, v183, s[2:3]
	v_cndmask_b32_e64 v182, v180, v182, s[2:3]
	v_lshl_add_u64 v[182:183], s[8:9], 0, v[182:183]
	v_cndmask_b32_e64 v180, v192, v3, s[2:3]
	v_mov_b32_e32 v181, 0
	v_cndmask_b32_e64 v179, v177, v179, s[4:5]
	v_cndmask_b32_e64 v178, v176, v178, s[4:5]
	v_lshl_add_u64 v[178:179], s[8:9], 0, v[178:179]
	v_cndmask_b32_e64 v176, v192, v3, s[4:5]
	v_mov_b32_e32 v177, 0
	v_cndmask_b32_e64 v175, v173, v175, s[6:7]
	v_cndmask_b32_e64 v174, v172, v174, s[6:7]
	v_lshl_add_u64 v[174:175], s[8:9], 0, v[174:175]
	v_cndmask_b32_e64 v172, v192, v3, s[6:7]
	v_mov_b32_e32 v173, 0
	v_lshl_add_u64 v[170:171], s[8:9], 0, v[170:171]
	v_lshl_add_u64 v[168:169], s[8:9], 0, v[168:169]
	s_branch .LBB0_464
.LBB0_462:
	v_fma_f32 v140, v140, s33, -v3
	v_exp_f32_e32 v140, v140
	v_fma_f32 v141, v141, s33, -v3
	v_exp_f32_e32 v141, v141
	v_fma_f32 v142, v142, s33, -v3
	v_exp_f32_e32 v142, v142
	v_fma_f32 v143, v143, s33, -v3
	v_exp_f32_e32 v143, v143
	v_fma_f32 v148, v148, s33, -v3
	v_exp_f32_e32 v148, v148
	v_fma_f32 v149, v149, s33, -v3
	v_add_f32_e32 v193, v141, v140
	v_exp_f32_e32 v149, v149
	v_fma_f32 v150, v150, s33, -v3
	v_add_f32_e32 v193, v142, v193
	v_exp_f32_e32 v150, v150
	v_fma_f32 v3, v151, s33, -v3
	v_add_f32_e32 v193, v143, v193
	v_exp_f32_e32 v3, v3
	v_add_f32_e32 v151, v148, v193
	v_add_f32_e32 v151, v149, v151
	v_add_f32_e32 v151, v150, v151
	v_add_f32_e32 v151, v3, v151
	v_cvt_pk_bf16_f32 v140, v140, v141
	v_cvt_pk_bf16_f32 v141, v142, v143
	v_cvt_pk_bf16_f32 v143, v150, v3
	v_fma_f32 v3, v136, s33, -v192
	v_exp_f32_e32 v3, v3
	v_fma_f32 v136, v137, s33, -v192
	v_exp_f32_e32 v136, v136
	v_fma_f32 v137, v138, s33, -v192
	v_exp_f32_e32 v137, v137
	v_fma_f32 v138, v139, s33, -v192
	v_exp_f32_e32 v138, v138
	v_fma_f32 v144, v144, s33, -v192
	v_exp_f32_e32 v144, v144
	v_fma_f32 v145, v145, s33, -v192
	v_add_f32_e32 v139, v136, v3
	v_exp_f32_e32 v145, v145
	v_fma_f32 v146, v146, s33, -v192
	v_add_f32_e32 v139, v137, v139
	v_exp_f32_e32 v146, v146
	v_fma_f32 v147, v147, s33, -v192
	v_add_f32_e32 v139, v138, v139
	v_exp_f32_e32 v147, v147
	v_add_f32_e32 v139, v144, v139
	v_add_f32_e32 v139, v145, v139
	v_add_f32_e32 v139, v146, v139
	v_add_f32_e32 v139, v147, v139
	v_add_f32_e32 v0, v151, v0
	v_add_f32_e32 v161, v139, v161
	v_cvt_pk_bf16_f32 v142, v148, v149
	v_cvt_pk_bf16_f32 v136, v3, v136
	v_cvt_pk_bf16_f32 v137, v137, v138
	v_cvt_pk_bf16_f32 v138, v144, v145
	v_cvt_pk_bf16_f32 v139, v146, v147
	s_setprio 1
	s_waitcnt lgkmcnt(0)
	s_nop 1
	v_mfma_f32_16x16x32_bf16 v[64:67], v[222:225], v[140:143], v[64:67]
	v_mfma_f32_16x16x32_bf16 v[32:35], v[222:225], v[136:139], v[32:35]
	v_mfma_f32_16x16x32_bf16 v[60:63], v[226:229], v[140:143], v[60:63]
	v_mfma_f32_16x16x32_bf16 v[28:31], v[226:229], v[136:139], v[28:31]
	v_mfma_f32_16x16x32_bf16 v[56:59], v[230:233], v[140:143], v[56:59]
	v_mfma_f32_16x16x32_bf16 v[24:27], v[230:233], v[136:139], v[24:27]
	v_mfma_f32_16x16x32_bf16 v[52:55], v[234:237], v[140:143], v[52:55]
	v_mfma_f32_16x16x32_bf16 v[20:23], v[234:237], v[136:139], v[20:23]
	v_mfma_f32_16x16x32_bf16 v[48:51], v[238:241], v[140:143], v[48:51]
	v_mfma_f32_16x16x32_bf16 v[16:19], v[238:241], v[136:139], v[16:19]
	v_mfma_f32_16x16x32_bf16 v[44:47], v[242:245], v[140:143], v[44:47]
	v_mfma_f32_16x16x32_bf16 v[12:15], v[242:245], v[136:139], v[12:15]
	v_mfma_f32_16x16x32_bf16 v[40:43], v[246:249], v[140:143], v[40:43]
	v_mfma_f32_16x16x32_bf16 v[8:11], v[246:249], v[136:139], v[8:11]
	v_mfma_f32_16x16x32_bf16 v[36:39], v[250:253], v[140:143], v[36:39]
	v_mfma_f32_16x16x32_bf16 v[4:7], v[250:253], v[136:139], v[4:7]
	s_setprio 0
; DEV f32x4 mfma16(bf16x8 a, bf16x8 b, f32x4 c) { return __builtin_amdgcn_mfma_f32_16x16x32_bf16(a, b, c, 0, 0, 0); }
; template <int DQ, int DV, int NQT, bool SAMPLE>
; DEV void attn_item(const Params& p, int item, char* smem) {
;     ...
;   for (int kt = 0; kt < nkt; kt++) {
;     swrite();
;     __syncthreads();
;     if (kt + 1 < nkt) gload(kt + 1);
;     if (kt <= wlim) {
;       f32x4 s[2][NQT];
; #pragma unroll
;       for (int a = 0; a < 2; a++)
; #pragma unroll
;         for (int qt = 0; qt < NQT; qt++) s[a][qt] = (f32x4){0.f, 0.f, 0.f, 0.f};
;       __builtin_amdgcn_s_setprio(1);
; #pragma unroll
;       for (int a = 0; a < 2; a++)
; #pragma unroll
;         for (int ks = 0; ks < NKS; ks++) {
;           const bf16x8 kf = *(const bf16x8*)(sK + (a * 16 + fr) * KS + ks * 32 + fq * 8);
; #pragma unroll
;           for (int qt = 0; qt < NQT; qt++) s[a][qt] = mfma16(kf, qf[qt][ks], s[a][qt]);
;         }
;       __builtin_amdgcn_s_setprio(0);
;       bf16x8 pb[NQT];
; #pragma unroll
;       for (int qt = 0; qt < NQT; qt++) {
;         float mx = -INFINITY;
; #pragma unroll
;         for (int a = 0; a < 2; a++)
; #pragma unroll
;           for (int j = 0; j < 4; j++) mx = fmaxf(mx, s[a][qt][j]);
;         mx = xor16_max(mx);
;         mx = xor32_max(mx);
;         const float mnew = fmaxf(mrun[qt], mx * sc);
;         if (__builtin_amdgcn_ballot_w64(mnew > mrun[qt]) != 0ull) {
;           const float alpha = __builtin_amdgcn_exp2f(mrun[qt] - mnew);
;           lrun[qt] *= alpha;
; #pragma unroll
;           for (int d = 0; d < DV / 16; d++) o[d][qt] *= alpha;
;           mrun[qt] = mnew;
;         }
.LBB0_463:
	s_or_b64 exec, exec, s[10:11]
	s_add_i32 s1, s1, 1
	s_mov_b64 s[10:11], 0x2000
	v_lshl_add_u64 v[168:169], v[168:169], 0, s[10:11]
	v_lshl_add_u64 v[170:171], v[170:171], 0, s[10:11]
	v_lshl_add_u64 v[174:175], v[174:175], 0, v[172:173]
	v_lshl_add_u64 v[178:179], v[178:179], 0, v[176:177]
	v_lshl_add_u64 v[182:183], v[182:183], 0, v[180:181]
	s_cmp_eq_u32 s15, s1
	v_xor_b32_e32 v189, 0x8000, v189
	v_xor_b32_e32 v190, 0x8000, v190
	v_xor_b32_e32 v191, 0x8000, v191
	v_xor_b32_e32 v164, 0x8000, v164
	v_xor_b32_e32 v166, 0x8000, v166
	v_xor_b32_e32 v187, 0x8000, v187
	v_xor_b32_e32 v167, 0x8000, v167
	v_xor_b32_e32 v184, 0x8000, v184
	s_cbranch_scc1 .LBB0_469
.LBB0_464:
	s_waitcnt vmcnt(0)
	ds_write_b128 v189, v[116:119]
	ds_write_b128 v190, v[120:123]
	ds_write_b128 v191, v[124:127]
	ds_write_b128 v164, v[132:135] offset:12800
	ds_write_b128 v166, v[128:131] offset:12800
	v_cmp_le_i32_e32 vcc, s1, v188
	s_waitcnt lgkmcnt(0)
	s_barrier
	global_load_dwordx4 v[116:119], v[182:183], off
	global_load_dwordx4 v[120:123], v[178:179], off
	global_load_dwordx4 v[124:127], v[174:175], off
	global_load_dwordx4 v[132:135], v[170:171], off
	global_load_dwordx4 v[128:131], v[168:169], off
	s_and_saveexec_b64 s[10:11], vcc
	s_cbranch_execz .LBB0_463
	s_setprio 1
	v_add_u32_e32 v3, v186, v187
	ds_read_b128 v[222:225], v3
	ds_read_b128 v[226:229], v3 offset:6400
	ds_read_b128 v[230:233], v3 offset:64
	ds_read_b128 v[234:237], v3 offset:6464
	ds_read_b128 v[238:241], v3 offset:128
	ds_read_b128 v[242:245], v3 offset:6528
	ds_read_b128 v[246:249], v3 offset:192
	ds_read_b128 v[250:253], v3 offset:6592
	ds_read_b128 v[192:195], v3 offset:256
	s_waitcnt lgkmcnt(8)
	v_mfma_f32_16x16x32_bf16 v[140:143], v[222:225], v[108:111], 0
	v_mfma_f32_16x16x32_bf16 v[136:139], v[222:225], v[112:115], 0
	s_waitcnt lgkmcnt(7)
	v_mfma_f32_16x16x32_bf16 v[148:151], v[226:229], v[108:111], 0
	v_mfma_f32_16x16x32_bf16 v[144:147], v[226:229], v[112:115], 0
	ds_read_b128 v[222:225], v3 offset:6656
	s_waitcnt lgkmcnt(7)
	v_mfma_f32_16x16x32_bf16 v[140:143], v[230:233], v[96:99], v[140:143]
	v_mfma_f32_16x16x32_bf16 v[136:139], v[230:233], v[104:107], v[136:139]
	ds_read_b128 v[226:229], v3 offset:320
	s_waitcnt lgkmcnt(7)
	v_mfma_f32_16x16x32_bf16 v[148:151], v[234:237], v[96:99], v[148:151]
	v_mfma_f32_16x16x32_bf16 v[144:147], v[234:237], v[104:107], v[144:147]
	ds_read_b128 v[230:233], v3 offset:6720
	s_waitcnt lgkmcnt(7)
	v_mfma_f32_16x16x32_bf16 v[140:143], v[238:241], v[92:95], v[140:143]
	v_mfma_f32_16x16x32_bf16 v[136:139], v[238:241], v[100:103], v[136:139]
	s_waitcnt lgkmcnt(6)
	v_mfma_f32_16x16x32_bf16 v[148:151], v[242:245], v[92:95], v[148:151]
	v_mfma_f32_16x16x32_bf16 v[144:147], v[242:245], v[100:103], v[144:147]
	s_waitcnt lgkmcnt(5)
	v_mfma_f32_16x16x32_bf16 v[140:143], v[246:249], v[80:83], v[140:143]
	v_mfma_f32_16x16x32_bf16 v[136:139], v[246:249], v[88:91], v[136:139]
	s_waitcnt lgkmcnt(4)
	v_mfma_f32_16x16x32_bf16 v[148:151], v[250:253], v[80:83], v[148:151]
	v_mfma_f32_16x16x32_bf16 v[144:147], v[250:253], v[88:91], v[144:147]
	s_waitcnt lgkmcnt(3)
	v_mfma_f32_16x16x32_bf16 v[140:143], v[192:195], v[76:79], v[140:143]
	v_mfma_f32_16x16x32_bf16 v[136:139], v[192:195], v[84:87], v[136:139]
	s_waitcnt lgkmcnt(2)
	v_mfma_f32_16x16x32_bf16 v[148:151], v[222:225], v[76:79], v[148:151]
	v_mfma_f32_16x16x32_bf16 v[144:147], v[222:225], v[84:87], v[144:147]
	s_waitcnt lgkmcnt(1)
	v_mfma_f32_16x16x32_bf16 v[140:143], v[226:229], v[68:71], v[140:143]
	v_mfma_f32_16x16x32_bf16 v[136:139], v[226:229], v[72:75], v[136:139]
	s_waitcnt lgkmcnt(0)
	v_mfma_f32_16x16x32_bf16 v[148:151], v[230:233], v[68:71], v[148:151]
	v_mfma_f32_16x16x32_bf16 v[144:147], v[230:233], v[72:75], v[144:147]
	v_add_u32_e32 v3, 0x3000, v167
	ds_read2_b64 v[222:225], v3 offset0:64 offset1:68
	v_add_u32_e32 v3, 0x3000, v184
	ds_read2_b64 v[226:229], v3 offset0:64 offset1:68
	v_add_u32_e32 v3, 0x3800, v167
	ds_read2_b64 v[230:233], v3 offset0:128 offset1:132
	v_add_u32_e32 v3, 0x4000, v167
	ds_read2_b64 v[234:237], v3 offset0:32 offset1:36
	ds_read2_b64 v[238:241], v3 offset0:192 offset1:196
	v_add_u32_e32 v3, 0x4800, v167
	ds_read2_b64 v[242:245], v3 offset0:96 offset1:100
	v_add_u32_e32 v3, 0x5000, v167
	ds_read2_b64 v[246:249], v3 offset1:4
	ds_read2_b64 v[250:253], v3 offset0:160 offset1:164
	s_setprio 0
	v_max3_f32 v3, v140, s29, v141
	v_max3_f32 v3, v3, v142, v143
	v_max3_f32 v3, v3, v148, v149
	v_max3_f32 v3, v3, v150, v151
	v_mov_b32_e32 v192, v3
	s_nop 1
	v_permlane16_swap_b32_e32 v3, v192
	v_max_f32_e32 v3, v3, v192
	v_mov_b32_e32 v192, v3
	s_nop 1
	v_permlane32_swap_b32_e32 v3, v192
	v_max_f32_e32 v3, v3, v192
	v_mul_f32_e32 v3, 0x3dd53b94, v3
	v_max_f32_e32 v3, v2, v3
	v_cmp_gt_f32_e32 vcc, v3, v2
	s_cbranch_vccz .LBB0_467
	v_sub_f32_e32 v2, v2, v3
	v_exp_f32_e32 v2, v2
	s_nop 0
	v_mul_f32_e32 v0, v0, v2
	v_pk_mul_f32 v[66:67], v[66:67], v[2:3] op_sel_hi:[1,0]
	v_pk_mul_f32 v[64:65], v[64:65], v[2:3] op_sel_hi:[1,0]
	v_pk_mul_f32 v[62:63], v[62:63], v[2:3] op_sel_hi:[1,0]
	v_pk_mul_f32 v[60:61], v[60:61], v[2:3] op_sel_hi:[1,0]
	v_pk_mul_f32 v[58:59], v[58:59], v[2:3] op_sel_hi:[1,0]
	v_pk_mul_f32 v[56:57], v[56:57], v[2:3] op_sel_hi:[1,0]
	v_pk_mul_f32 v[54:55], v[54:55], v[2:3] op_sel_hi:[1,0]
	v_pk_mul_f32 v[52:53], v[52:53], v[2:3] op_sel_hi:[1,0]
	v_pk_mul_f32 v[50:51], v[50:51], v[2:3] op_sel_hi:[1,0]
	v_pk_mul_f32 v[48:49], v[48:49], v[2:3] op_sel_hi:[1,0]
	v_pk_mul_f32 v[46:47], v[46:47], v[2:3] op_sel_hi:[1,0]
	v_pk_mul_f32 v[44:45], v[44:45], v[2:3] op_sel_hi:[1,0]
	v_pk_mul_f32 v[42:43], v[42:43], v[2:3] op_sel_hi:[1,0]
	v_pk_mul_f32 v[40:41], v[40:41], v[2:3] op_sel_hi:[1,0]
	v_pk_mul_f32 v[38:39], v[38:39], v[2:3] op_sel_hi:[1,0]
	v_pk_mul_f32 v[36:37], v[36:37], v[2:3] op_sel_hi:[1,0]
	v_mov_b32_e32 v2, v3
; template <int DQ, int DV, int NQT, bool SAMPLE>
; DEV void attn_item(const Params& p, int item, char* smem) {
;     ...
;       for (int qt = 0; qt < NQT; qt++) {
;         float mx = -INFINITY;
; #pragma unroll
;         for (int a = 0; a < 2; a++)
; #pragma unroll
;           for (int j = 0; j < 4; j++) mx = fmaxf(mx, s[a][qt][j]);
;         mx = xor16_max(mx);
;         mx = xor32_max(mx);
;         const float mnew = fmaxf(mrun[qt], mx * sc);
;         if (__builtin_amdgcn_ballot_w64(mnew > mrun[qt]) != 0ull) {
;           const float alpha = __builtin_amdgcn_exp2f(mrun[qt] - mnew);
;           lrun[qt] *= alpha;
; #pragma unroll
;           for (int d = 0; d < DV / 16; d++) o[d][qt] *= alpha;
;           mrun[qt] = mnew;
;         }
.LBB0_467:
	v_max3_f32 v192, v136, s29, v137
	v_max3_f32 v192, v192, v138, v139
	v_max3_f32 v192, v192, v144, v145
	v_max3_f32 v192, v192, v146, v147
	v_mov_b32_e32 v193, v192
	s_nop 1
	v_permlane16_swap_b32_e32 v192, v193
	v_max_f32_e32 v192, v192, v193
	v_mov_b32_e32 v193, v192
	s_nop 1
	v_permlane32_swap_b32_e32 v192, v193
	v_max_f32_e32 v192, v192, v193
	v_mul_f32_e32 v192, 0x3dd53b94, v192
	v_max_f32_e32 v192, v185, v192
	v_cmp_gt_f32_e32 vcc, v192, v185
	s_cbranch_vccz .LBB0_462
	v_sub_f32_e32 v185, v185, v192
	v_exp_f32_e32 v194, v185
	v_mov_b32_e32 v185, v192
	v_mul_f32_e32 v161, v161, v194
	v_pk_mul_f32 v[34:35], v[34:35], v[194:195] op_sel_hi:[1,0]
	v_pk_mul_f32 v[32:33], v[32:33], v[194:195] op_sel_hi:[1,0]
	v_pk_mul_f32 v[30:31], v[30:31], v[194:195] op_sel_hi:[1,0]
	v_pk_mul_f32 v[28:29], v[28:29], v[194:195] op_sel_hi:[1,0]
	v_pk_mul_f32 v[26:27], v[26:27], v[194:195] op_sel_hi:[1,0]
	v_pk_mul_f32 v[24:25], v[24:25], v[194:195] op_sel_hi:[1,0]
	v_pk_mul_f32 v[22:23], v[22:23], v[194:195] op_sel_hi:[1,0]
	v_pk_mul_f32 v[20:21], v[20:21], v[194:195] op_sel_hi:[1,0]
	v_pk_mul_f32 v[18:19], v[18:19], v[194:195] op_sel_hi:[1,0]
	v_pk_mul_f32 v[16:17], v[16:17], v[194:195] op_sel_hi:[1,0]
	v_pk_mul_f32 v[14:15], v[14:15], v[194:195] op_sel_hi:[1,0]
	v_pk_mul_f32 v[12:13], v[12:13], v[194:195] op_sel_hi:[1,0]
	v_pk_mul_f32 v[10:11], v[10:11], v[194:195] op_sel_hi:[1,0]
	v_pk_mul_f32 v[8:9], v[8:9], v[194:195] op_sel_hi:[1,0]
	v_pk_mul_f32 v[6:7], v[6:7], v[194:195] op_sel_hi:[1,0]
	v_pk_mul_f32 v[4:5], v[4:5], v[194:195] op_sel_hi:[1,0]
	s_branch .LBB0_462

; DEV f32x4 mfma16(bf16x8 a, bf16x8 b, f32x4 c) { return __builtin_amdgcn_mfma_f32_16x16x32_bf16(a, b, c, 0, 0, 0); }
; template <int EPI, bool AF32>
; DEV void gemm_tile(const void* Ap, int lda, const u16* Bt, int ldb, int K, int m0, int n0, const Epi& ea, char* smem) {
;     ...
;   for (int kt = 0; kt < nk; kt++) {
;     const int buf = kt & 1;
;     if (kt + 1 < nk) swrite(buf ^ 1);
;     if (kt + 2 < nk) gload(kt + 2);
; #pragma unroll
;     for (int ks = 0; ks < 2; ks++) {
;       bf16x8 a[4], b[4];
; #pragma unroll
;       for (int m = 0; m < 4; m++) a[m] = *(const bf16x8*)(sA + buf * 9216 + (wr * 64 + m * 16 + fr) * 72 + ks * 32 + fq * 8);
; #pragma unroll
;       for (int n = 0; n < 4; n++) b[n] = *(const bf16x8*)(sB + buf * 9216 + (wc * 64 + n * 16 + fr) * 72 + ks * 32 + fq * 8);
;       __builtin_amdgcn_s_setprio(1);
; #pragma unroll
;       for (int m = 0; m < 4; m++)
; #pragma unroll
;         for (int n = 0; n < 4; n++) acc[m][n] = mfma16(a[m], b[n], acc[m][n]);
;       __builtin_amdgcn_s_setprio(0);
;     }
;     __syncthreads();
;   }
.Lgk1_loop:
	s_waitcnt lgkmcnt(0)
	ds_read_b128 v[222:225], v161 offset:64
	ds_read_b128 v[226:229], v161 offset:2368
	ds_read_b128 v[230:233], v161 offset:4672
	ds_read_b128 v[234:237], v161 offset:6976
	ds_read_b128 v[238:241], v129 offset:36928
	ds_read_b128 v[242:245], v129 offset:39232
	ds_read_b128 v[246:249], v129 offset:41536
	ds_read_b128 v[250:253], v129 offset:43840
	v_mfma_f32_16x16x32_bf16 v[94:97], v[130:133], v[146:149], v[94:97]
	v_mfma_f32_16x16x32_bf16 v[90:93], v[130:133], v[150:153], v[90:93]
	v_mfma_f32_16x16x32_bf16 v[86:89], v[130:133], v[162:165], v[86:89]
	v_mfma_f32_16x16x32_bf16 v[82:85], v[130:133], v[166:169], v[82:85]
	s_waitcnt vmcnt(0)
	ds_write_b128 v122, v[22:25] offset:18432
	ds_write_b128 v122, v[6:9] offset:55296
	v_mfma_f32_16x16x32_bf16 v[78:81], v[134:137], v[146:149], v[78:81]
	ds_write_b128 v121, v[18:21] offset:18432
	ds_write_b128 v121, v[10:13] offset:55296
	v_mfma_f32_16x16x32_bf16 v[74:77], v[134:137], v[150:153], v[74:77]
	ds_write_b128 v120, v[14:17] offset:18432
	ds_write_b128 v120, v[2:5] offset:55296
	v_mfma_f32_16x16x32_bf16 v[70:73], v[134:137], v[162:165], v[70:73]
	ds_write_b128 v124, v[26:29] offset:18432
	ds_write_b128 v124, v[30:33] offset:55296
	v_mfma_f32_16x16x32_bf16 v[66:69], v[134:137], v[166:169], v[66:69]
	global_load_dwordx4 v[22:25], v[112:113], off
	v_mfma_f32_16x16x32_bf16 v[62:65], v[138:141], v[146:149], v[62:65]
	global_load_dwordx4 v[6:9], v[110:111], off
	v_mfma_f32_16x16x32_bf16 v[58:61], v[138:141], v[150:153], v[58:61]
	global_load_dwordx4 v[18:21], v[108:109], off
	v_mfma_f32_16x16x32_bf16 v[54:57], v[138:141], v[162:165], v[54:57]
	global_load_dwordx4 v[10:13], v[106:107], off
	v_mfma_f32_16x16x32_bf16 v[50:53], v[138:141], v[166:169], v[50:53]
	global_load_dwordx4 v[14:17], v[104:105], off
	v_mfma_f32_16x16x32_bf16 v[46:49], v[142:145], v[146:149], v[46:49]
	global_load_dwordx4 v[2:5], v[102:103], off
	v_mfma_f32_16x16x32_bf16 v[42:45], v[142:145], v[150:153], v[42:45]
	global_load_dwordx4 v[26:29], v[100:101], off
	v_mfma_f32_16x16x32_bf16 v[38:41], v[142:145], v[162:165], v[38:41]
	global_load_dwordx4 v[30:33], v[98:99], off
	v_mfma_f32_16x16x32_bf16 v[34:37], v[142:145], v[166:169], v[34:37]
	s_waitcnt lgkmcnt(0)
	s_barrier
	ds_read_b128 v[130:133], v161 offset:18432
	v_mfma_f32_16x16x32_bf16 v[94:97], v[222:225], v[238:241], v[94:97]
	ds_read_b128 v[134:137], v161 offset:20736
	v_mfma_f32_16x16x32_bf16 v[90:93], v[222:225], v[242:245], v[90:93]
	ds_read_b128 v[138:141], v161 offset:23040
	v_mfma_f32_16x16x32_bf16 v[86:89], v[222:225], v[246:249], v[86:89]
	ds_read_b128 v[142:145], v161 offset:25344
	v_mfma_f32_16x16x32_bf16 v[82:85], v[222:225], v[250:253], v[82:85]
	ds_read_b128 v[146:149], v129 offset:55296
	v_mfma_f32_16x16x32_bf16 v[78:81], v[226:229], v[238:241], v[78:81]
	ds_read_b128 v[150:153], v129 offset:57600
	v_mfma_f32_16x16x32_bf16 v[74:77], v[226:229], v[242:245], v[74:77]
	ds_read_b128 v[162:165], v129 offset:59904
	v_mfma_f32_16x16x32_bf16 v[70:73], v[226:229], v[246:249], v[70:73]
	ds_read_b128 v[166:169], v129 offset:62208
	v_mfma_f32_16x16x32_bf16 v[66:69], v[226:229], v[250:253], v[66:69]
	v_mfma_f32_16x16x32_bf16 v[62:65], v[230:233], v[238:241], v[62:65]
	v_mfma_f32_16x16x32_bf16 v[58:61], v[230:233], v[242:245], v[58:61]
	v_mfma_f32_16x16x32_bf16 v[54:57], v[230:233], v[246:249], v[54:57]
	v_mfma_f32_16x16x32_bf16 v[50:53], v[230:233], v[250:253], v[50:53]
	v_mfma_f32_16x16x32_bf16 v[46:49], v[234:237], v[238:241], v[46:49]
	v_mfma_f32_16x16x32_bf16 v[42:45], v[234:237], v[242:245], v[42:45]
	v_mfma_f32_16x16x32_bf16 v[38:41], v[234:237], v[246:249], v[38:41]
	v_mfma_f32_16x16x32_bf16 v[34:37], v[234:237], v[250:253], v[34:37]
	s_waitcnt lgkmcnt(0)
	ds_read_b128 v[222:225], v161 offset:18496
	ds_read_b128 v[226:229], v161 offset:20800
	ds_read_b128 v[230:233], v161 offset:23104
	ds_read_b128 v[234:237], v161 offset:25408
	ds_read_b128 v[238:241], v129 offset:55360
	ds_read_b128 v[242:245], v129 offset:57664
	ds_read_b128 v[246:249], v129 offset:59968
	ds_read_b128 v[250:253], v129 offset:62272
	v_mfma_f32_16x16x32_bf16 v[94:97], v[130:133], v[146:149], v[94:97]
	v_mfma_f32_16x16x32_bf16 v[90:93], v[130:133], v[150:153], v[90:93]
	v_mfma_f32_16x16x32_bf16 v[86:89], v[130:133], v[162:165], v[86:89]
	v_mfma_f32_16x16x32_bf16 v[82:85], v[130:133], v[166:169], v[82:85]
	s_waitcnt vmcnt(0)
	ds_write_b128 v122, v[22:25]
	ds_write_b128 v122, v[6:9] offset:36864
	v_mfma_f32_16x16x32_bf16 v[78:81], v[134:137], v[146:149], v[78:81]
	ds_write_b128 v121, v[18:21]
	ds_write_b128 v121, v[10:13] offset:36864
	v_mfma_f32_16x16x32_bf16 v[74:77], v[134:137], v[150:153], v[74:77]
	ds_write_b128 v120, v[14:17]
	ds_write_b128 v120, v[2:5] offset:36864
	v_mfma_f32_16x16x32_bf16 v[70:73], v[134:137], v[162:165], v[70:73]
	ds_write_b128 v124, v[26:29]
	ds_write_b128 v124, v[30:33] offset:36864
	v_mfma_f32_16x16x32_bf16 v[66:69], v[134:137], v[166:169], v[66:69]
	global_load_dwordx4 v[22:25], v[112:113], off offset:128
	v_mfma_f32_16x16x32_bf16 v[62:65], v[138:141], v[146:149], v[62:65]
	global_load_dwordx4 v[6:9], v[110:111], off offset:128
	v_mfma_f32_16x16x32_bf16 v[58:61], v[138:141], v[150:153], v[58:61]
	global_load_dwordx4 v[18:21], v[108:109], off offset:128
	v_mfma_f32_16x16x32_bf16 v[54:57], v[138:141], v[162:165], v[54:57]
	global_load_dwordx4 v[10:13], v[106:107], off offset:128
	v_mfma_f32_16x16x32_bf16 v[50:53], v[138:141], v[166:169], v[50:53]
	global_load_dwordx4 v[14:17], v[104:105], off offset:128
	v_mfma_f32_16x16x32_bf16 v[46:49], v[142:145], v[146:149], v[46:49]
	global_load_dwordx4 v[2:5], v[102:103], off offset:128
	v_mfma_f32_16x16x32_bf16 v[42:45], v[142:145], v[150:153], v[42:45]
	global_load_dwordx4 v[26:29], v[100:101], off offset:128
	v_mfma_f32_16x16x32_bf16 v[38:41], v[142:145], v[162:165], v[38:41]
	global_load_dwordx4 v[30:33], v[98:99], off offset:128
	v_mfma_f32_16x16x32_bf16 v[34:37], v[142:145], v[166:169], v[34:37]
	s_waitcnt lgkmcnt(0)
	s_barrier
; DEV f32x4 mfma16(bf16x8 a, bf16x8 b, f32x4 c) { return __builtin_amdgcn_mfma_f32_16x16x32_bf16(a, b, c, 0, 0, 0); }
; template <int EPI, bool AF32>
; DEV void gemm_tile(const void* Ap, int lda, const u16* Bt, int ldb, int K, int m0, int n0, const Epi& ea, char* smem) {
;     ...
;   for (int kt = 0; kt < nk; kt++) {
;     const int buf = kt & 1;
;     if (kt + 1 < nk) swrite(buf ^ 1);
;     if (kt + 2 < nk) gload(kt + 2);
; #pragma unroll
;     for (int ks = 0; ks < 2; ks++) {
;       bf16x8 a[4], b[4];
; #pragma unroll
;       for (int m = 0; m < 4; m++) a[m] = *(const bf16x8*)(sA + buf * 9216 + (wr * 64 + m * 16 + fr) * 72 + ks * 32 + fq * 8);
; #pragma unroll
;       for (int n = 0; n < 4; n++) b[n] = *(const bf16x8*)(sB + buf * 9216 + (wc * 64 + n * 16 + fr) * 72 + ks * 32 + fq * 8);
;       __builtin_amdgcn_s_setprio(1);
; #pragma unroll
;       for (int m = 0; m < 4; m++)
; #pragma unroll
;         for (int n = 0; n < 4; n++) acc[m][n] = mfma16(a[m], b[n], acc[m][n]);
;       __builtin_amdgcn_s_setprio(0);
;     }
;     __syncthreads();
;   }
	ds_read_b128 v[130:133], v161
	v_mfma_f32_16x16x32_bf16 v[94:97], v[222:225], v[238:241], v[94:97]
	ds_read_b128 v[134:137], v161 offset:2304
	v_mfma_f32_16x16x32_bf16 v[90:93], v[222:225], v[242:245], v[90:93]
	ds_read_b128 v[138:141], v161 offset:4608
	v_mfma_f32_16x16x32_bf16 v[86:89], v[222:225], v[246:249], v[86:89]
	ds_read_b128 v[142:145], v161 offset:6912
	v_mfma_f32_16x16x32_bf16 v[82:85], v[222:225], v[250:253], v[82:85]
	ds_read_b128 v[146:149], v129 offset:36864
	v_mfma_f32_16x16x32_bf16 v[78:81], v[226:229], v[238:241], v[78:81]
	ds_read_b128 v[150:153], v129 offset:39168
	v_mfma_f32_16x16x32_bf16 v[74:77], v[226:229], v[242:245], v[74:77]
	ds_read_b128 v[162:165], v129 offset:41472
	v_mfma_f32_16x16x32_bf16 v[70:73], v[226:229], v[246:249], v[70:73]
	ds_read_b128 v[166:169], v129 offset:43776
	v_mfma_f32_16x16x32_bf16 v[66:69], v[226:229], v[250:253], v[66:69]
	v_mfma_f32_16x16x32_bf16 v[62:65], v[230:233], v[238:241], v[62:65]
	v_lshl_add_u64 v[112:113], v[112:113], 0, s[0:1]
	v_mfma_f32_16x16x32_bf16 v[58:61], v[230:233], v[242:245], v[58:61]
	v_lshl_add_u64 v[110:111], v[110:111], 0, s[0:1]
	v_mfma_f32_16x16x32_bf16 v[54:57], v[230:233], v[246:249], v[54:57]
	v_lshl_add_u64 v[108:109], v[108:109], 0, s[0:1]
	v_mfma_f32_16x16x32_bf16 v[50:53], v[230:233], v[250:253], v[50:53]
	v_lshl_add_u64 v[106:107], v[106:107], 0, s[0:1]
	v_mfma_f32_16x16x32_bf16 v[46:49], v[234:237], v[238:241], v[46:49]
	v_lshl_add_u64 v[104:105], v[104:105], 0, s[0:1]
	v_mfma_f32_16x16x32_bf16 v[42:45], v[234:237], v[242:245], v[42:45]
	v_lshl_add_u64 v[102:103], v[102:103], 0, s[0:1]
	v_mfma_f32_16x16x32_bf16 v[38:41], v[234:237], v[246:249], v[38:41]
	v_lshl_add_u64 v[100:101], v[100:101], 0, s[0:1]
	v_mfma_f32_16x16x32_bf16 v[34:37], v[234:237], v[250:253], v[34:37]
	v_lshl_add_u64 v[98:99], v[98:99], 0, s[0:1]
	s_add_i32 s4, s4, 1
	s_cmp_lg_u32 s4, 7
	s_cbranch_scc1 .Lgk1_loop
	s_waitcnt lgkmcnt(0)
	ds_read_b128 v[222:225], v161 offset:64
	ds_read_b128 v[226:229], v161 offset:2368
	ds_read_b128 v[230:233], v161 offset:4672
	ds_read_b128 v[234:237], v161 offset:6976
	ds_read_b128 v[238:241], v129 offset:36928
	ds_read_b128 v[242:245], v129 offset:39232
	ds_read_b128 v[246:249], v129 offset:41536
	ds_read_b128 v[250:253], v129 offset:43840
	v_mfma_f32_16x16x32_bf16 v[94:97], v[130:133], v[146:149], v[94:97]
	v_mfma_f32_16x16x32_bf16 v[90:93], v[130:133], v[150:153], v[90:93]
	v_mfma_f32_16x16x32_bf16 v[86:89], v[130:133], v[162:165], v[86:89]
	v_mfma_f32_16x16x32_bf16 v[82:85], v[130:133], v[166:169], v[82:85]
	s_waitcnt vmcnt(0)
	ds_write_b128 v122, v[22:25] offset:18432
	ds_write_b128 v122, v[6:9] offset:55296
	v_mfma_f32_16x16x32_bf16 v[78:81], v[134:137], v[146:149], v[78:81]
	ds_write_b128 v121, v[18:21] offset:18432
	ds_write_b128 v121, v[10:13] offset:55296
	v_mfma_f32_16x16x32_bf16 v[74:77], v[134:137], v[150:153], v[74:77]
	ds_write_b128 v120, v[14:17] offset:18432
	ds_write_b128 v120, v[2:5] offset:55296
	v_mfma_f32_16x16x32_bf16 v[70:73], v[134:137], v[162:165], v[70:73]
	ds_write_b128 v124, v[26:29] offset:18432
	ds_write_b128 v124, v[30:33] offset:55296
	v_mfma_f32_16x16x32_bf16 v[66:69], v[134:137], v[166:169], v[66:69]
	v_mfma_f32_16x16x32_bf16 v[62:65], v[138:141], v[146:149], v[62:65]
	v_mfma_f32_16x16x32_bf16 v[58:61], v[138:141], v[150:153], v[58:61]
	v_mfma_f32_16x16x32_bf16 v[54:57], v[138:141], v[162:165], v[54:57]
	v_mfma_f32_16x16x32_bf16 v[50:53], v[138:141], v[166:169], v[50:53]
	v_mfma_f32_16x16x32_bf16 v[46:49], v[142:145], v[146:149], v[46:49]
	v_mfma_f32_16x16x32_bf16 v[42:45], v[142:145], v[150:153], v[42:45]
	v_mfma_f32_16x16x32_bf16 v[38:41], v[142:145], v[162:165], v[38:41]
	v_mfma_f32_16x16x32_bf16 v[34:37], v[142:145], v[166:169], v[34:37]
	s_waitcnt lgkmcnt(0)
	s_barrier
; template <int EPI, bool AF32>
; DEV void gemm_tile(const void* Ap, int lda, const u16* Bt, int ldb, int K, int m0, int n0, const Epi& ea, char* smem) {
;     ...
;   for (int kt = 0; kt < nk; kt++) {
;     const int buf = kt & 1;
;     if (kt + 1 < nk) swrite(buf ^ 1);
;     if (kt + 2 < nk) gload(kt + 2);
; #pragma unroll
;     for (int ks = 0; ks < 2; ks++) {
;       bf16x8 a[4], b[4];
; #pragma unroll
;       for (int m = 0; m < 4; m++) a[m] = *(const bf16x8*)(sA + buf * 9216 + (wr * 64 + m * 16 + fr) * 72 + ks * 32 + fq * 8);
; #pragma unroll
;       for (int n = 0; n < 4; n++) b[n] = *(const bf16x8*)(sB + buf * 9216 + (wc * 64 + n * 16 + fr) * 72 + ks * 32 + fq * 8);
;       __builtin_amdgcn_s_setprio(1);
; #pragma unroll
;       for (int m = 0; m < 4; m++)
; #pragma unroll
;         for (int n = 0; n < 4; n++) acc[m][n] = mfma16(a[m], b[n], acc[m][n]);
;       __builtin_amdgcn_s_setprio(0);
;     }
;     __syncthreads();
;   }
;     ...
;         if (cb < 3072) {
;           u16* C = (u16*)ea.p0;
;           u16* H = (u16*)ea.p2;
;           float* O = (float*)ea.p3;
;           const int l = ea.layer;
; #pragma unroll
;           for (int n = 0; n < 4; n++) {
;             const int col = cb + n * 16 + fr;
;             const float v = acc[m][n][j];
;             const u16 hv = f2bf(v);
;             if (row < T_P) {
;               __builtin_nontemporal_store(hv, &C[((size_t)((row >> 6) * 8 + ((col >> 7) & 7)) * 3 + (col >> 10)) * 8192 + (row & 63) * 128 + (col & 127)]);
;               const int r = row & 63, ci = row >> 6;
;               if (r >= 61 && ((ci + 1) & 127) != 0) H[((size_t)(ci + 1) * 3 + (r - 61)) * 3072 + col] = hv;
;               const int pos = row & 8191;
;               if (pos >= 8189) O[O_PCONV + ((size_t)(l * 4 + (row >> 13)) * 3 + (pos - 8189)) * 3072 + col] = v;
;             } else {
;               const int ts = row - T_P, i = ts & 31;
;               ((u16*)ea.p2)[(size_t)(56590336 / 2) + (size_t)ts * 3072 + col] = hv;
;               if (i >= 29) O[O_SCONV + ((size_t)(l * 16 + (ts >> 5)) * 3 + (i - 29)) * 3072 + col] = v;
;             }
;           }
;         } else {
;           u16* Z = (u16*)ea.p1;
; #pragma unroll
;           for (int n = 0; n < 4; n++) Z[(size_t)row * 1024 + cb - 3072 + n * 16 + fr] = f2bf(acc[m][n][j]);
	ds_read_b128 v[130:133], v161 offset:18432
	v_mfma_f32_16x16x32_bf16 v[94:97], v[222:225], v[238:241], v[94:97]
	ds_read_b128 v[134:137], v161 offset:20736
	v_mfma_f32_16x16x32_bf16 v[90:93], v[222:225], v[242:245], v[90:93]
	ds_read_b128 v[138:141], v161 offset:23040
	v_mfma_f32_16x16x32_bf16 v[86:89], v[222:225], v[246:249], v[86:89]
	ds_read_b128 v[142:145], v161 offset:25344
	v_mfma_f32_16x16x32_bf16 v[82:85], v[222:225], v[250:253], v[82:85]
	ds_read_b128 v[146:149], v129 offset:55296
	v_mfma_f32_16x16x32_bf16 v[78:81], v[226:229], v[238:241], v[78:81]
	ds_read_b128 v[150:153], v129 offset:57600
	v_mfma_f32_16x16x32_bf16 v[74:77], v[226:229], v[242:245], v[74:77]
	ds_read_b128 v[162:165], v129 offset:59904
	v_mfma_f32_16x16x32_bf16 v[70:73], v[226:229], v[246:249], v[70:73]
	ds_read_b128 v[166:169], v129 offset:62208
	v_mfma_f32_16x16x32_bf16 v[66:69], v[226:229], v[250:253], v[66:69]
	v_mfma_f32_16x16x32_bf16 v[62:65], v[230:233], v[238:241], v[62:65]
	v_mfma_f32_16x16x32_bf16 v[58:61], v[230:233], v[242:245], v[58:61]
	v_mfma_f32_16x16x32_bf16 v[54:57], v[230:233], v[246:249], v[54:57]
	v_mfma_f32_16x16x32_bf16 v[50:53], v[230:233], v[250:253], v[50:53]
	v_mfma_f32_16x16x32_bf16 v[46:49], v[234:237], v[238:241], v[46:49]
	v_mfma_f32_16x16x32_bf16 v[42:45], v[234:237], v[242:245], v[42:45]
	v_mfma_f32_16x16x32_bf16 v[38:41], v[234:237], v[246:249], v[38:41]
	v_mfma_f32_16x16x32_bf16 v[34:37], v[234:237], v[250:253], v[34:37]
	s_waitcnt lgkmcnt(0)
	ds_read_b128 v[222:225], v161 offset:18496
	ds_read_b128 v[226:229], v161 offset:20800
	ds_read_b128 v[230:233], v161 offset:23104
	ds_read_b128 v[234:237], v161 offset:25408
	ds_read_b128 v[238:241], v129 offset:55360
	ds_read_b128 v[242:245], v129 offset:57664
	ds_read_b128 v[246:249], v129 offset:59968
	ds_read_b128 v[250:253], v129 offset:62272
	v_mfma_f32_16x16x32_bf16 v[94:97], v[130:133], v[146:149], v[94:97]
	v_mfma_f32_16x16x32_bf16 v[90:93], v[130:133], v[150:153], v[90:93]
	v_mfma_f32_16x16x32_bf16 v[86:89], v[130:133], v[162:165], v[86:89]
	v_mfma_f32_16x16x32_bf16 v[82:85], v[130:133], v[166:169], v[82:85]
	v_mfma_f32_16x16x32_bf16 v[78:81], v[134:137], v[146:149], v[78:81]
	v_mfma_f32_16x16x32_bf16 v[74:77], v[134:137], v[150:153], v[74:77]
	v_mfma_f32_16x16x32_bf16 v[70:73], v[134:137], v[162:165], v[70:73]
	v_mfma_f32_16x16x32_bf16 v[66:69], v[134:137], v[166:169], v[66:69]
	v_mfma_f32_16x16x32_bf16 v[62:65], v[138:141], v[146:149], v[62:65]
	v_mfma_f32_16x16x32_bf16 v[58:61], v[138:141], v[150:153], v[58:61]
	v_mfma_f32_16x16x32_bf16 v[54:57], v[138:141], v[162:165], v[54:57]
	v_mfma_f32_16x16x32_bf16 v[50:53], v[138:141], v[166:169], v[50:53]
	v_mfma_f32_16x16x32_bf16 v[46:49], v[142:145], v[146:149], v[46:49]
	v_mfma_f32_16x16x32_bf16 v[42:45], v[142:145], v[150:153], v[42:45]
	v_mfma_f32_16x16x32_bf16 v[38:41], v[142:145], v[162:165], v[38:41]
	v_mfma_f32_16x16x32_bf16 v[34:37], v[142:145], v[166:169], v[34:37]
	s_waitcnt lgkmcnt(0)
	v_mfma_f32_16x16x32_bf16 v[30:33], v[230:233], v[238:241], v[62:65]
	v_mfma_f32_16x16x32_bf16 v[26:29], v[230:233], v[242:245], v[58:61]
	v_mfma_f32_16x16x32_bf16 v[22:25], v[230:233], v[246:249], v[54:57]
	v_mfma_f32_16x16x32_bf16 v[18:21], v[230:233], v[250:253], v[50:53]
	v_mfma_f32_16x16x32_bf16 v[14:17], v[234:237], v[238:241], v[46:49]
	v_mfma_f32_16x16x32_bf16 v[10:13], v[234:237], v[242:245], v[42:45]
	v_mfma_f32_16x16x32_bf16 v[6:9], v[234:237], v[246:249], v[38:41]
	v_mfma_f32_16x16x32_bf16 v[2:5], v[234:237], v[250:253], v[34:37]
	v_mfma_f32_16x16x32_bf16 v[62:65], v[222:225], v[238:241], v[94:97]
	v_mfma_f32_16x16x32_bf16 v[58:61], v[222:225], v[242:245], v[90:93]
	v_mfma_f32_16x16x32_bf16 v[54:57], v[222:225], v[246:249], v[86:89]
	v_mfma_f32_16x16x32_bf16 v[50:53], v[222:225], v[250:253], v[82:85]
	v_mfma_f32_16x16x32_bf16 v[46:49], v[226:229], v[238:241], v[78:81]
	v_mfma_f32_16x16x32_bf16 v[42:45], v[226:229], v[242:245], v[74:77]
	v_mfma_f32_16x16x32_bf16 v[38:41], v[226:229], v[246:249], v[70:73]
	v_mfma_f32_16x16x32_bf16 v[34:37], v[226:229], v[250:253], v[66:69]
	s_nop 7
	v_and_or_b32 v0, v114, 64, s3
	v_add_u32_e32 v80, s2, v117
	s_movk_i32 s0, 0xbff
	v_lshl_or_b32 v68, v115, 2, v80
	v_cmp_lt_i32_e64 s[2:3], s0, v0
	v_lshl_add_u64 v[72:73], v[0:1], 1, s[16:17]
	v_lshlrev_b32_e32 v70, 1, v116
	s_barrier
	s_and_saveexec_b64 s[0:1], s[2:3]
	s_xor_b64 s[0:1], exec, s[0:1]
	s_cbranch_execz .LBB0_551
	v_ashrrev_i32_e32 v69, 31, v68
	v_lshlrev_b64 v[66:67], 11, v[68:69]
	v_lshl_add_u64 v[66:67], v[72:73], 0, v[66:67]
	v_mov_b32_e32 v71, v1
	v_lshl_add_u64 v[66:67], v[66:67], 0, v[70:71]
	v_lshl_add_u64 v[74:75], v[66:67], 0, s[36:37]
	v_add_co_u32_e32 v66, vcc, 0xfffff000, v66
	v_cvt_pk_bf16_f32 v69, v62, s0
	s_nop 0
	v_addc_co_u32_e32 v67, vcc, -1, v67, vcc
	global_store_short v[66:67], v69, off offset:-2048
	v_cvt_pk_bf16_f32 v66, v58, s0
	global_store_short v[74:75], v66, off offset:32
	v_cvt_pk_bf16_f32 v66, v54, s0
	global_store_short v[74:75], v66, off offset:64
	v_cvt_pk_bf16_f32 v66, v50, s0
	global_store_short v[74:75], v66, off offset:96

; DEV f32x4 mfma16(bf16x8 a, bf16x8 b, f32x4 c) { return __builtin_amdgcn_mfma_f32_16x16x32_bf16(a, b, c, 0, 0, 0); }
; template <int EPI, bool AF32>
; DEV void gemm_tile(const void* Ap, int lda, const u16* Bt, int ldb, int K, int m0, int n0, const Epi& ea, char* smem) {
;     ...
;   for (int kt = 0; kt < nk; kt++) {
;     const int buf = kt & 1;
;     if (kt + 1 < nk) swrite(buf ^ 1);
;     if (kt + 2 < nk) gload(kt + 2);
; #pragma unroll
;     for (int ks = 0; ks < 2; ks++) {
;       bf16x8 a[4], b[4];
; #pragma unroll
;       for (int m = 0; m < 4; m++) a[m] = *(const bf16x8*)(sA + buf * 9216 + (wr * 64 + m * 16 + fr) * 72 + ks * 32 + fq * 8);
; #pragma unroll
;       for (int n = 0; n < 4; n++) b[n] = *(const bf16x8*)(sB + buf * 9216 + (wc * 64 + n * 16 + fr) * 72 + ks * 32 + fq * 8);
;       __builtin_amdgcn_s_setprio(1);
; #pragma unroll
;       for (int m = 0; m < 4; m++)
; #pragma unroll
;         for (int n = 0; n < 4; n++) acc[m][n] = mfma16(a[m], b[n], acc[m][n]);
;       __builtin_amdgcn_s_setprio(0);
;     }
;     __syncthreads();
;   }
.Lgk2_loop:
	s_waitcnt lgkmcnt(0)
	ds_read_b128 v[222:225], v161 offset:64
	ds_read_b128 v[226:229], v161 offset:2368
	ds_read_b128 v[230:233], v161 offset:4672
	ds_read_b128 v[234:237], v161 offset:6976
	ds_read_b128 v[238:241], v129 offset:36928
	ds_read_b128 v[242:245], v129 offset:39232
	ds_read_b128 v[246:249], v129 offset:41536
	ds_read_b128 v[250:253], v129 offset:43840
	v_mfma_f32_16x16x32_bf16 v[94:97], v[130:133], v[146:149], v[94:97]
	v_mfma_f32_16x16x32_bf16 v[90:93], v[130:133], v[150:153], v[90:93]
	v_mfma_f32_16x16x32_bf16 v[86:89], v[130:133], v[162:165], v[86:89]
	v_mfma_f32_16x16x32_bf16 v[82:85], v[130:133], v[166:169], v[82:85]
	s_waitcnt vmcnt(0)
	ds_write_b128 v122, v[22:25] offset:18432
	ds_write_b128 v122, v[6:9] offset:55296
	v_mfma_f32_16x16x32_bf16 v[78:81], v[134:137], v[146:149], v[78:81]
	ds_write_b128 v121, v[18:21] offset:18432
	ds_write_b128 v121, v[10:13] offset:55296
	v_mfma_f32_16x16x32_bf16 v[74:77], v[134:137], v[150:153], v[74:77]
	ds_write_b128 v120, v[14:17] offset:18432
	ds_write_b128 v120, v[2:5] offset:55296
	v_mfma_f32_16x16x32_bf16 v[70:73], v[134:137], v[162:165], v[70:73]
	ds_write_b128 v124, v[26:29] offset:18432
	ds_write_b128 v124, v[30:33] offset:55296
	v_mfma_f32_16x16x32_bf16 v[66:69], v[134:137], v[166:169], v[66:69]
	global_load_dwordx4 v[22:25], v[112:113], off
	v_mfma_f32_16x16x32_bf16 v[62:65], v[138:141], v[146:149], v[62:65]
	global_load_dwordx4 v[6:9], v[110:111], off
	v_mfma_f32_16x16x32_bf16 v[58:61], v[138:141], v[150:153], v[58:61]
	global_load_dwordx4 v[18:21], v[108:109], off
	v_mfma_f32_16x16x32_bf16 v[54:57], v[138:141], v[162:165], v[54:57]
	global_load_dwordx4 v[10:13], v[106:107], off
	v_mfma_f32_16x16x32_bf16 v[50:53], v[138:141], v[166:169], v[50:53]
	global_load_dwordx4 v[14:17], v[104:105], off
	v_mfma_f32_16x16x32_bf16 v[46:49], v[142:145], v[146:149], v[46:49]
	global_load_dwordx4 v[2:5], v[102:103], off
	v_mfma_f32_16x16x32_bf16 v[42:45], v[142:145], v[150:153], v[42:45]
	global_load_dwordx4 v[26:29], v[100:101], off
	v_mfma_f32_16x16x32_bf16 v[38:41], v[142:145], v[162:165], v[38:41]
	global_load_dwordx4 v[30:33], v[98:99], off
	v_mfma_f32_16x16x32_bf16 v[34:37], v[142:145], v[166:169], v[34:37]
	s_waitcnt lgkmcnt(0)
	s_barrier
	ds_read_b128 v[130:133], v161 offset:18432
	v_mfma_f32_16x16x32_bf16 v[94:97], v[222:225], v[238:241], v[94:97]
	ds_read_b128 v[134:137], v161 offset:20736
	v_mfma_f32_16x16x32_bf16 v[90:93], v[222:225], v[242:245], v[90:93]
	ds_read_b128 v[138:141], v161 offset:23040
	v_mfma_f32_16x16x32_bf16 v[86:89], v[222:225], v[246:249], v[86:89]
	ds_read_b128 v[142:145], v161 offset:25344
	v_mfma_f32_16x16x32_bf16 v[82:85], v[222:225], v[250:253], v[82:85]
	ds_read_b128 v[146:149], v129 offset:55296
	v_mfma_f32_16x16x32_bf16 v[78:81], v[226:229], v[238:241], v[78:81]
	ds_read_b128 v[150:153], v129 offset:57600
	v_mfma_f32_16x16x32_bf16 v[74:77], v[226:229], v[242:245], v[74:77]
	ds_read_b128 v[162:165], v129 offset:59904
	v_mfma_f32_16x16x32_bf16 v[70:73], v[226:229], v[246:249], v[70:73]
	ds_read_b128 v[166:169], v129 offset:62208
	v_mfma_f32_16x16x32_bf16 v[66:69], v[226:229], v[250:253], v[66:69]
	v_mfma_f32_16x16x32_bf16 v[62:65], v[230:233], v[238:241], v[62:65]
	v_mfma_f32_16x16x32_bf16 v[58:61], v[230:233], v[242:245], v[58:61]
	v_mfma_f32_16x16x32_bf16 v[54:57], v[230:233], v[246:249], v[54:57]
	v_mfma_f32_16x16x32_bf16 v[50:53], v[230:233], v[250:253], v[50:53]
	v_mfma_f32_16x16x32_bf16 v[46:49], v[234:237], v[238:241], v[46:49]
	v_mfma_f32_16x16x32_bf16 v[42:45], v[234:237], v[242:245], v[42:45]
	v_mfma_f32_16x16x32_bf16 v[38:41], v[234:237], v[246:249], v[38:41]
	v_mfma_f32_16x16x32_bf16 v[34:37], v[234:237], v[250:253], v[34:37]
	s_waitcnt lgkmcnt(0)
	ds_read_b128 v[222:225], v161 offset:18496
	ds_read_b128 v[226:229], v161 offset:20800
	ds_read_b128 v[230:233], v161 offset:23104
	ds_read_b128 v[234:237], v161 offset:25408
	ds_read_b128 v[238:241], v129 offset:55360
	ds_read_b128 v[242:245], v129 offset:57664
	ds_read_b128 v[246:249], v129 offset:59968
	ds_read_b128 v[250:253], v129 offset:62272
	v_mfma_f32_16x16x32_bf16 v[94:97], v[130:133], v[146:149], v[94:97]
	v_mfma_f32_16x16x32_bf16 v[90:93], v[130:133], v[150:153], v[90:93]
	v_mfma_f32_16x16x32_bf16 v[86:89], v[130:133], v[162:165], v[86:89]
	v_mfma_f32_16x16x32_bf16 v[82:85], v[130:133], v[166:169], v[82:85]
	s_waitcnt vmcnt(0)
	ds_write_b128 v122, v[22:25]
	ds_write_b128 v122, v[6:9] offset:36864
	v_mfma_f32_16x16x32_bf16 v[78:81], v[134:137], v[146:149], v[78:81]
	ds_write_b128 v121, v[18:21]
	ds_write_b128 v121, v[10:13] offset:36864
	v_mfma_f32_16x16x32_bf16 v[74:77], v[134:137], v[150:153], v[74:77]
	ds_write_b128 v120, v[14:17]
	ds_write_b128 v120, v[2:5] offset:36864
	v_mfma_f32_16x16x32_bf16 v[70:73], v[134:137], v[162:165], v[70:73]
	ds_write_b128 v124, v[26:29]
	ds_write_b128 v124, v[30:33] offset:36864
	v_mfma_f32_16x16x32_bf16 v[66:69], v[134:137], v[166:169], v[66:69]
	global_load_dwordx4 v[22:25], v[112:113], off offset:128
	v_mfma_f32_16x16x32_bf16 v[62:65], v[138:141], v[146:149], v[62:65]
	global_load_dwordx4 v[6:9], v[110:111], off offset:128
	v_mfma_f32_16x16x32_bf16 v[58:61], v[138:141], v[150:153], v[58:61]
	global_load_dwordx4 v[18:21], v[108:109], off offset:128
	v_mfma_f32_16x16x32_bf16 v[54:57], v[138:141], v[162:165], v[54:57]
	global_load_dwordx4 v[10:13], v[106:107], off offset:128
	v_mfma_f32_16x16x32_bf16 v[50:53], v[138:141], v[166:169], v[50:53]
	global_load_dwordx4 v[14:17], v[104:105], off offset:128
	v_mfma_f32_16x16x32_bf16 v[46:49], v[142:145], v[146:149], v[46:49]
	global_load_dwordx4 v[2:5], v[102:103], off offset:128
	v_mfma_f32_16x16x32_bf16 v[42:45], v[142:145], v[150:153], v[42:45]
	global_load_dwordx4 v[26:29], v[100:101], off offset:128
	v_mfma_f32_16x16x32_bf16 v[38:41], v[142:145], v[162:165], v[38:41]
	global_load_dwordx4 v[30:33], v[98:99], off offset:128
	v_mfma_f32_16x16x32_bf16 v[34:37], v[142:145], v[166:169], v[34:37]
	s_waitcnt lgkmcnt(0)
	s_barrier
; DEV f32x4 mfma16(bf16x8 a, bf16x8 b, f32x4 c) { return __builtin_amdgcn_mfma_f32_16x16x32_bf16(a, b, c, 0, 0, 0); }
; template <int EPI, bool AF32>
; DEV void gemm_tile(const void* Ap, int lda, const u16* Bt, int ldb, int K, int m0, int n0, const Epi& ea, char* smem) {
;     ...
;   for (int kt = 0; kt < nk; kt++) {
;     const int buf = kt & 1;
;     if (kt + 1 < nk) swrite(buf ^ 1);
;     if (kt + 2 < nk) gload(kt + 2);
; #pragma unroll
;     for (int ks = 0; ks < 2; ks++) {
;       bf16x8 a[4], b[4];
; #pragma unroll
;       for (int m = 0; m < 4; m++) a[m] = *(const bf16x8*)(sA + buf * 9216 + (wr * 64 + m * 16 + fr) * 72 + ks * 32 + fq * 8);
; #pragma unroll
;       for (int n = 0; n < 4; n++) b[n] = *(const bf16x8*)(sB + buf * 9216 + (wc * 64 + n * 16 + fr) * 72 + ks * 32 + fq * 8);
;       __builtin_amdgcn_s_setprio(1);
; #pragma unroll
;       for (int m = 0; m < 4; m++)
; #pragma unroll
;         for (int n = 0; n < 4; n++) acc[m][n] = mfma16(a[m], b[n], acc[m][n]);
;       __builtin_amdgcn_s_setprio(0);
;     }
;     __syncthreads();
;   }
	ds_read_b128 v[130:133], v161
	v_mfma_f32_16x16x32_bf16 v[94:97], v[222:225], v[238:241], v[94:97]
	ds_read_b128 v[134:137], v161 offset:2304
	v_mfma_f32_16x16x32_bf16 v[90:93], v[222:225], v[242:245], v[90:93]
	ds_read_b128 v[138:141], v161 offset:4608
	v_mfma_f32_16x16x32_bf16 v[86:89], v[222:225], v[246:249], v[86:89]
	ds_read_b128 v[142:145], v161 offset:6912
	v_mfma_f32_16x16x32_bf16 v[82:85], v[222:225], v[250:253], v[82:85]
	ds_read_b128 v[146:149], v129 offset:36864
	v_mfma_f32_16x16x32_bf16 v[78:81], v[226:229], v[238:241], v[78:81]
	ds_read_b128 v[150:153], v129 offset:39168
	v_mfma_f32_16x16x32_bf16 v[74:77], v[226:229], v[242:245], v[74:77]
	ds_read_b128 v[162:165], v129 offset:41472
	v_mfma_f32_16x16x32_bf16 v[70:73], v[226:229], v[246:249], v[70:73]
	ds_read_b128 v[166:169], v129 offset:43776
	v_mfma_f32_16x16x32_bf16 v[66:69], v[226:229], v[250:253], v[66:69]
	v_mfma_f32_16x16x32_bf16 v[62:65], v[230:233], v[238:241], v[62:65]
	v_lshl_add_u64 v[112:113], v[112:113], 0, s[0:1]
	v_mfma_f32_16x16x32_bf16 v[58:61], v[230:233], v[242:245], v[58:61]
	v_lshl_add_u64 v[110:111], v[110:111], 0, s[0:1]
	v_mfma_f32_16x16x32_bf16 v[54:57], v[230:233], v[246:249], v[54:57]
	v_lshl_add_u64 v[108:109], v[108:109], 0, s[0:1]
	v_mfma_f32_16x16x32_bf16 v[50:53], v[230:233], v[250:253], v[50:53]
	v_lshl_add_u64 v[106:107], v[106:107], 0, s[0:1]
	v_mfma_f32_16x16x32_bf16 v[46:49], v[234:237], v[238:241], v[46:49]
	v_lshl_add_u64 v[104:105], v[104:105], 0, s[0:1]
	v_mfma_f32_16x16x32_bf16 v[42:45], v[234:237], v[242:245], v[42:45]
	v_lshl_add_u64 v[102:103], v[102:103], 0, s[0:1]
	v_mfma_f32_16x16x32_bf16 v[38:41], v[234:237], v[246:249], v[38:41]
	v_lshl_add_u64 v[100:101], v[100:101], 0, s[0:1]
	v_mfma_f32_16x16x32_bf16 v[34:37], v[234:237], v[250:253], v[34:37]
	v_lshl_add_u64 v[98:99], v[98:99], 0, s[0:1]
	s_add_i32 s11, s11, 1
	s_cmp_lg_u32 s11, 7
	s_cbranch_scc1 .Lgk2_loop
	s_waitcnt lgkmcnt(0)
	ds_read_b128 v[222:225], v161 offset:64
	ds_read_b128 v[226:229], v161 offset:2368
	ds_read_b128 v[230:233], v161 offset:4672
	ds_read_b128 v[234:237], v161 offset:6976
	ds_read_b128 v[238:241], v129 offset:36928
	ds_read_b128 v[242:245], v129 offset:39232
	ds_read_b128 v[246:249], v129 offset:41536
	ds_read_b128 v[250:253], v129 offset:43840
	v_mfma_f32_16x16x32_bf16 v[94:97], v[130:133], v[146:149], v[94:97]
	v_mfma_f32_16x16x32_bf16 v[90:93], v[130:133], v[150:153], v[90:93]
	v_mfma_f32_16x16x32_bf16 v[86:89], v[130:133], v[162:165], v[86:89]
	v_mfma_f32_16x16x32_bf16 v[82:85], v[130:133], v[166:169], v[82:85]
	s_waitcnt vmcnt(0)
	ds_write_b128 v122, v[22:25] offset:18432
	ds_write_b128 v122, v[6:9] offset:55296
	v_mfma_f32_16x16x32_bf16 v[78:81], v[134:137], v[146:149], v[78:81]
	ds_write_b128 v121, v[18:21] offset:18432
	ds_write_b128 v121, v[10:13] offset:55296
	v_mfma_f32_16x16x32_bf16 v[74:77], v[134:137], v[150:153], v[74:77]
	ds_write_b128 v120, v[14:17] offset:18432
	ds_write_b128 v120, v[2:5] offset:55296
	v_mfma_f32_16x16x32_bf16 v[70:73], v[134:137], v[162:165], v[70:73]
	ds_write_b128 v124, v[26:29] offset:18432
	ds_write_b128 v124, v[30:33] offset:55296
	v_mfma_f32_16x16x32_bf16 v[66:69], v[134:137], v[166:169], v[66:69]
	v_mfma_f32_16x16x32_bf16 v[62:65], v[138:141], v[146:149], v[62:65]
	v_mfma_f32_16x16x32_bf16 v[58:61], v[138:141], v[150:153], v[58:61]
	v_mfma_f32_16x16x32_bf16 v[54:57], v[138:141], v[162:165], v[54:57]
	v_mfma_f32_16x16x32_bf16 v[50:53], v[138:141], v[166:169], v[50:53]
	v_mfma_f32_16x16x32_bf16 v[46:49], v[142:145], v[146:149], v[46:49]
	v_mfma_f32_16x16x32_bf16 v[42:45], v[142:145], v[150:153], v[42:45]
	v_mfma_f32_16x16x32_bf16 v[38:41], v[142:145], v[162:165], v[38:41]
	v_mfma_f32_16x16x32_bf16 v[34:37], v[142:145], v[166:169], v[34:37]
	s_waitcnt lgkmcnt(0)
	s_barrier
	ds_read_b128 v[130:133], v161 offset:18432
	v_mfma_f32_16x16x32_bf16 v[94:97], v[222:225], v[238:241], v[94:97]
	ds_read_b128 v[134:137], v161 offset:20736
	v_mfma_f32_16x16x32_bf16 v[90:93], v[222:225], v[242:245], v[90:93]
	ds_read_b128 v[138:141], v161 offset:23040
	v_mfma_f32_16x16x32_bf16 v[86:89], v[222:225], v[246:249], v[86:89]
	ds_read_b128 v[142:145], v161 offset:25344
	v_mfma_f32_16x16x32_bf16 v[82:85], v[222:225], v[250:253], v[82:85]
	ds_read_b128 v[146:149], v129 offset:55296
	v_mfma_f32_16x16x32_bf16 v[78:81], v[226:229], v[238:241], v[78:81]
	ds_read_b128 v[150:153], v129 offset:57600
	v_mfma_f32_16x16x32_bf16 v[74:77], v[226:229], v[242:245], v[74:77]
	ds_read_b128 v[162:165], v129 offset:59904
	v_mfma_f32_16x16x32_bf16 v[70:73], v[226:229], v[246:249], v[70:73]
	ds_read_b128 v[166:169], v129 offset:62208
	v_mfma_f32_16x16x32_bf16 v[66:69], v[226:229], v[250:253], v[66:69]
	v_mfma_f32_16x16x32_bf16 v[62:65], v[230:233], v[238:241], v[62:65]
	v_mfma_f32_16x16x32_bf16 v[58:61], v[230:233], v[242:245], v[58:61]
	v_mfma_f32_16x16x32_bf16 v[54:57], v[230:233], v[246:249], v[54:57]
	v_mfma_f32_16x16x32_bf16 v[50:53], v[230:233], v[250:253], v[50:53]
	v_mfma_f32_16x16x32_bf16 v[46:49], v[234:237], v[238:241], v[46:49]
	v_mfma_f32_16x16x32_bf16 v[42:45], v[234:237], v[242:245], v[42:45]
	v_mfma_f32_16x16x32_bf16 v[38:41], v[234:237], v[246:249], v[38:41]
	v_mfma_f32_16x16x32_bf16 v[34:37], v[234:237], v[250:253], v[34:37]
	s_waitcnt lgkmcnt(0)
; DEV float sigmf(float x) { return __builtin_amdgcn_rcpf(1.f + __expf(-x)); }
; DEV f32x4 mfma16(bf16x8 a, bf16x8 b, f32x4 c) { return __builtin_amdgcn_mfma_f32_16x16x32_bf16(a, b, c, 0, 0, 0); }
; template <int EPI, bool AF32>
; DEV void gemm_tile(const void* Ap, int lda, const u16* Bt, int ldb, int K, int m0, int n0, const Epi& ea, char* smem) {
;     ...
;   for (int kt = 0; kt < nk; kt++) {
;     const int buf = kt & 1;
;     if (kt + 1 < nk) swrite(buf ^ 1);
;     if (kt + 2 < nk) gload(kt + 2);
; #pragma unroll
;     for (int ks = 0; ks < 2; ks++) {
;       bf16x8 a[4], b[4];
; #pragma unroll
;       for (int m = 0; m < 4; m++) a[m] = *(const bf16x8*)(sA + buf * 9216 + (wr * 64 + m * 16 + fr) * 72 + ks * 32 + fq * 8);
; #pragma unroll
;       for (int n = 0; n < 4; n++) b[n] = *(const bf16x8*)(sB + buf * 9216 + (wc * 64 + n * 16 + fr) * 72 + ks * 32 + fq * 8);
;       __builtin_amdgcn_s_setprio(1);
; #pragma unroll
;       for (int m = 0; m < 4; m++)
; #pragma unroll
;         for (int n = 0; n < 4; n++) acc[m][n] = mfma16(a[m], b[n], acc[m][n]);
;       __builtin_amdgcn_s_setprio(0);
;     }
;     __syncthreads();
;   }
;     ...
; #pragma unroll
;   for (int m = 0; m < 4; m++) {
; #pragma unroll
;     for (int j = 0; j < 4; j++) {
;       const int row = m0 + wr * 64 + m * 16 + fq * 4 + j;
;       if (EPI == EP_F32) {
;         float* C = (float*)ea.p0;
; #pragma unroll
;         for (int n = 0; n < 4; n++) C[(size_t)row * ea.ld + cb + n * 16 + fr] = acc[m][n][j];
;       } else if (EPI == EP_BF16) {
;         u16* C = (u16*)ea.p0;
; #pragma unroll
;         for (int n = 0; n < 4; n++) C[(size_t)row * ea.ld + cb + n * 16 + fr] = f2bf(acc[m][n][j]);
;       } else if (EPI == EP_SIG) {
;         u16* C = (u16*)ea.p0;
; #pragma unroll
;         for (int n = 0; n < 4; n++) C[(size_t)row * ea.ld + cb + n * 16 + fr] = f2bf(sigmf(acc[m][n][j]));
	ds_read_b128 v[222:225], v161 offset:18496
	ds_read_b128 v[226:229], v161 offset:20800
	ds_read_b128 v[230:233], v161 offset:23104
	ds_read_b128 v[234:237], v161 offset:25408
	ds_read_b128 v[238:241], v129 offset:55360
	ds_read_b128 v[242:245], v129 offset:57664
	ds_read_b128 v[246:249], v129 offset:59968
	ds_read_b128 v[250:253], v129 offset:62272
	v_mfma_f32_16x16x32_bf16 v[94:97], v[130:133], v[146:149], v[94:97]
	v_mfma_f32_16x16x32_bf16 v[90:93], v[130:133], v[150:153], v[90:93]
	v_mfma_f32_16x16x32_bf16 v[86:89], v[130:133], v[162:165], v[86:89]
	v_mfma_f32_16x16x32_bf16 v[82:85], v[130:133], v[166:169], v[82:85]
	v_mfma_f32_16x16x32_bf16 v[78:81], v[134:137], v[146:149], v[78:81]
	v_mfma_f32_16x16x32_bf16 v[74:77], v[134:137], v[150:153], v[74:77]
	v_mfma_f32_16x16x32_bf16 v[70:73], v[134:137], v[162:165], v[70:73]
	v_mfma_f32_16x16x32_bf16 v[66:69], v[134:137], v[166:169], v[66:69]
	v_mfma_f32_16x16x32_bf16 v[62:65], v[138:141], v[146:149], v[62:65]
	v_mfma_f32_16x16x32_bf16 v[58:61], v[138:141], v[150:153], v[58:61]
	v_mfma_f32_16x16x32_bf16 v[54:57], v[138:141], v[162:165], v[54:57]
	v_mfma_f32_16x16x32_bf16 v[50:53], v[138:141], v[166:169], v[50:53]
	v_mfma_f32_16x16x32_bf16 v[46:49], v[142:145], v[146:149], v[46:49]
	v_mfma_f32_16x16x32_bf16 v[42:45], v[142:145], v[150:153], v[42:45]
	v_mfma_f32_16x16x32_bf16 v[38:41], v[142:145], v[162:165], v[38:41]
	v_mfma_f32_16x16x32_bf16 v[34:37], v[142:145], v[166:169], v[34:37]
	s_waitcnt lgkmcnt(0)
	v_mfma_f32_16x16x32_bf16 v[94:97], v[222:225], v[238:241], v[94:97]
	v_mfma_f32_16x16x32_bf16 v[90:93], v[222:225], v[242:245], v[90:93]
	v_mfma_f32_16x16x32_bf16 v[86:89], v[222:225], v[246:249], v[86:89]
	v_mfma_f32_16x16x32_bf16 v[122:125], v[222:225], v[250:253], v[82:85]
	v_mfma_f32_16x16x32_bf16 v[30:33], v[230:233], v[238:241], v[62:65]
	v_mfma_f32_16x16x32_bf16 v[26:29], v[230:233], v[242:245], v[58:61]
	v_mfma_f32_16x16x32_bf16 v[22:25], v[230:233], v[246:249], v[54:57]
	v_mfma_f32_16x16x32_bf16 v[18:21], v[230:233], v[250:253], v[50:53]
	v_mfma_f32_16x16x32_bf16 v[14:17], v[234:237], v[238:241], v[46:49]
	v_mfma_f32_16x16x32_bf16 v[10:13], v[234:237], v[242:245], v[42:45]
	v_mfma_f32_16x16x32_bf16 v[6:9], v[234:237], v[246:249], v[38:41]
	v_mfma_f32_16x16x32_bf16 v[2:5], v[234:237], v[250:253], v[34:37]
	v_mfma_f32_16x16x32_bf16 v[46:49], v[226:229], v[238:241], v[78:81]
	v_mfma_f32_16x16x32_bf16 v[42:45], v[226:229], v[242:245], v[74:77]
	v_mfma_f32_16x16x32_bf16 v[38:41], v[226:229], v[246:249], v[70:73]
	v_mfma_f32_16x16x32_bf16 v[34:37], v[226:229], v[250:253], v[66:69]
	s_nop 7
	s_nop 1
	v_mul_f32_e32 v51, 0xbfb8aa3b, v94
	v_exp_f32_e32 v56, v51
	v_and_or_b32 v52, v114, 64, s10
	v_add_u32_e32 v0, s9, v117
	v_ashrrev_i32_e32 v53, 31, v52
	v_lshl_or_b32 v50, v116, 2, v0
	v_lshl_add_u64 v[52:53], v[52:53], 1, s[2:3]
	v_lshlrev_b32_e32 v0, 1, v115
	v_lshl_add_u64 v[52:53], v[52:53], 0, v[0:1]
	v_ashrrev_i32_e32 v51, 31, v50
	v_add_f32_e32 v0, 1.0, v56
	v_lshlrev_b64 v[54:55], 12, v[50:51]
	v_rcp_f32_e32 v0, v0
	v_mul_f32_e32 v51, 0xbfb8aa3b, v90
	v_exp_f32_e32 v51, v51
	v_lshl_add_u64 v[54:55], v[52:53], 0, v[54:55]
	v_cvt_pk_bf16_f32 v0, v0, s0
	s_barrier
	global_store_short v[54:55], v0, off
	v_add_f32_e32 v0, 1.0, v51
	v_mul_f32_e32 v51, 0xbfb8aa3b, v86
	v_exp_f32_e32 v51, v51
	v_mul_f32_e32 v56, 0xbfb8aa3b, v122
	v_exp_f32_e32 v56, v56
	v_rcp_f32_e32 v0, v0
	v_add_f32_e32 v51, 1.0, v51
	v_rcp_f32_e32 v51, v51
	v_add_f32_e32 v56, 1.0, v56
	v_rcp_f32_e32 v56, v56
	v_cvt_pk_bf16_f32 v0, v0, s0
	global_store_short v[54:55], v0, off offset:32
	v_cvt_pk_bf16_f32 v0, v51, s0
	global_store_short v[54:55], v0, off offset:64
	v_cvt_pk_bf16_f32 v0, v56, s0
	global_store_short v[54:55], v0, off offset:96
	v_mul_f32_e32 v0, 0xbfb8aa3b, v95
	v_exp_f32_e32 v0, v0
	v_mul_f32_e32 v51, 0xbfb8aa3b, v91
	v_or_b32_e32 v54, 1, v50
	v_exp_f32_e32 v51, v51
	v_add_f32_e32 v0, 1.0, v0
	v_rcp_f32_e32 v0, v0
	v_ashrrev_i32_e32 v55, 31, v54
	v_lshlrev_b64 v[54:55], 12, v[54:55]
	v_lshl_add_u64 v[54:55], v[52:53], 0, v[54:55]
	v_cvt_pk_bf16_f32 v0, v0, s0
	global_store_short v[54:55], v0, off
	v_add_f32_e32 v0, 1.0, v51
	v_mul_f32_e32 v51, 0xbfb8aa3b, v87
	v_exp_f32_e32 v51, v51
	v_mul_f32_e32 v56, 0xbfb8aa3b, v123
	v_exp_f32_e32 v56, v56
	v_rcp_f32_e32 v0, v0
	v_add_f32_e32 v51, 1.0, v51
	v_rcp_f32_e32 v51, v51
	v_add_f32_e32 v56, 1.0, v56
	v_rcp_f32_e32 v56, v56
	v_cvt_pk_bf16_f32 v0, v0, s0
	global_store_short v[54:55], v0, off offset:32
	v_cvt_pk_bf16_f32 v0, v51, s0
	global_store_short v[54:55], v0, off offset:64
	v_cvt_pk_bf16_f32 v0, v56, s0
	global_store_short v[54:55], v0, off offset:96
	v_mul_f32_e32 v0, 0xbfb8aa3b, v96
	v_exp_f32_e32 v0, v0
	v_mul_f32_e32 v51, 0xbfb8aa3b, v92
	v_or_b32_e32 v54, 2, v50
	v_exp_f32_e32 v51, v51
	v_add_f32_e32 v0, 1.0, v0
	v_rcp_f32_e32 v0, v0
	v_ashrrev_i32_e32 v55, 31, v54
	v_lshlrev_b64 v[54:55], 12, v[54:55]
	v_lshl_add_u64 v[54:55], v[52:53], 0, v[54:55]
	v_cvt_pk_bf16_f32 v0, v0, s0
	global_store_short v[54:55], v0, off
	v_add_f32_e32 v0, 1.0, v51
	v_mul_f32_e32 v51, 0xbfb8aa3b, v88
	v_exp_f32_e32 v51, v51
	v_mul_f32_e32 v56, 0xbfb8aa3b, v124
	v_exp_f32_e32 v56, v56
	v_rcp_f32_e32 v0, v0
	v_add_f32_e32 v51, 1.0, v51
	v_rcp_f32_e32 v51, v51
	v_add_f32_e32 v56, 1.0, v56
	v_rcp_f32_e32 v56, v56
	v_cvt_pk_bf16_f32 v0, v0, s0
	global_store_short v[54:55], v0, off offset:32
	v_cvt_pk_bf16_f32 v0, v51, s0
	global_store_short v[54:55], v0, off offset:64
	v_cvt_pk_bf16_f32 v0, v56, s0
	global_store_short v[54:55], v0, off offset:96
	v_mul_f32_e32 v0, 0xbfb8aa3b, v97
	v_exp_f32_e32 v0, v0
	v_mul_f32_e32 v51, 0xbfb8aa3b, v93
	v_or_b32_e32 v54, 3, v50
	v_exp_f32_e32 v51, v51
; DEV float sigmf(float x) { return __builtin_amdgcn_rcpf(1.f + __expf(-x)); }
; template <int EPI, bool AF32>
; DEV void gemm_tile(const void* Ap, int lda, const u16* Bt, int ldb, int K, int m0, int n0, const Epi& ea, char* smem) {
;     ...
; #pragma unroll
;   for (int m = 0; m < 4; m++) {
; #pragma unroll
;     for (int j = 0; j < 4; j++) {
;       const int row = m0 + wr * 64 + m * 16 + fq * 4 + j;
;       if (EPI == EP_F32) {
;         float* C = (float*)ea.p0;
; #pragma unroll
;         for (int n = 0; n < 4; n++) C[(size_t)row * ea.ld + cb + n * 16 + fr] = acc[m][n][j];
;       } else if (EPI == EP_BF16) {
;         u16* C = (u16*)ea.p0;
; #pragma unroll
;         for (int n = 0; n < 4; n++) C[(size_t)row * ea.ld + cb + n * 16 + fr] = f2bf(acc[m][n][j]);
;       } else if (EPI == EP_SIG) {
;         u16* C = (u16*)ea.p0;
; #pragma unroll
;         for (int n = 0; n < 4; n++) C[(size_t)row * ea.ld + cb + n * 16 + fr] = f2bf(sigmf(acc[m][n][j]));
	v_add_f32_e32 v0, 1.0, v0
	v_rcp_f32_e32 v0, v0
	v_ashrrev_i32_e32 v55, 31, v54
	v_lshlrev_b64 v[54:55], 12, v[54:55]
	v_lshl_add_u64 v[54:55], v[52:53], 0, v[54:55]
	v_cvt_pk_bf16_f32 v0, v0, s0
	global_store_short v[54:55], v0, off
	v_add_f32_e32 v0, 1.0, v51
	v_mul_f32_e32 v51, 0xbfb8aa3b, v89
	v_exp_f32_e32 v51, v51
	v_mul_f32_e32 v56, 0xbfb8aa3b, v125
	v_exp_f32_e32 v56, v56
	v_rcp_f32_e32 v0, v0
	v_add_f32_e32 v51, 1.0, v51
	v_rcp_f32_e32 v51, v51
	v_add_f32_e32 v56, 1.0, v56
	v_rcp_f32_e32 v56, v56
	v_cvt_pk_bf16_f32 v0, v0, s0
	global_store_short v[54:55], v0, off offset:32
	v_cvt_pk_bf16_f32 v0, v51, s0
	global_store_short v[54:55], v0, off offset:64
	v_cvt_pk_bf16_f32 v0, v56, s0
	global_store_short v[54:55], v0, off offset:96
	v_mul_f32_e32 v0, 0xbfb8aa3b, v46
	v_exp_f32_e32 v0, v0
	v_mul_f32_e32 v42, 0xbfb8aa3b, v42
	v_or_b32_e32 v54, 16, v50
	v_exp_f32_e32 v42, v42
	v_add_f32_e32 v0, 1.0, v0
	v_rcp_f32_e32 v0, v0
	v_mul_f32_e32 v38, 0xbfb8aa3b, v38
	v_ashrrev_i32_e32 v55, 31, v54
	v_exp_f32_e32 v38, v38
	v_mul_f32_e32 v34, 0xbfb8aa3b, v34
	v_lshlrev_b64 v[54:55], 12, v[54:55]
	v_exp_f32_e32 v34, v34
	v_lshl_add_u64 v[54:55], v[52:53], 0, v[54:55]
	v_cvt_pk_bf16_f32 v0, v0, s0
	global_store_short v[54:55], v0, off
	v_add_f32_e32 v0, 1.0, v42
	v_rcp_f32_e32 v0, v0
	v_add_f32_e32 v38, 1.0, v38
	v_rcp_f32_e32 v38, v38
	v_add_f32_e32 v34, 1.0, v34
	v_rcp_f32_e32 v34, v34
	v_cvt_pk_bf16_f32 v0, v0, s0
	global_store_short v[54:55], v0, off offset:32
	v_cvt_pk_bf16_f32 v0, v38, s0
	global_store_short v[54:55], v0, off offset:64
	v_cvt_pk_bf16_f32 v0, v34, s0
	global_store_short v[54:55], v0, off offset:96
	v_mul_f32_e32 v0, 0xbfb8aa3b, v47
	v_exp_f32_e32 v0, v0
	v_mul_f32_e32 v34, 0xbfb8aa3b, v43
	v_or_b32_e32 v46, 17, v50
	v_exp_f32_e32 v34, v34
	v_add_f32_e32 v0, 1.0, v0
	v_rcp_f32_e32 v0, v0
	v_ashrrev_i32_e32 v47, 31, v46
	v_lshlrev_b64 v[46:47], 12, v[46:47]
	v_lshl_add_u64 v[42:43], v[52:53], 0, v[46:47]
	v_cvt_pk_bf16_f32 v0, v0, s0
	global_store_short v[42:43], v0, off
	v_add_f32_e32 v0, 1.0, v34
	v_mul_f32_e32 v34, 0xbfb8aa3b, v39
	v_exp_f32_e32 v34, v34
	v_mul_f32_e32 v35, 0xbfb8aa3b, v35
	v_exp_f32_e32 v35, v35
	v_rcp_f32_e32 v0, v0
	v_add_f32_e32 v34, 1.0, v34
	v_rcp_f32_e32 v34, v34
	v_add_f32_e32 v35, 1.0, v35
	v_rcp_f32_e32 v35, v35
	v_cvt_pk_bf16_f32 v0, v0, s0
	global_store_short v[42:43], v0, off offset:32
	v_cvt_pk_bf16_f32 v0, v34, s0
	global_store_short v[42:43], v0, off offset:64
	v_cvt_pk_bf16_f32 v0, v35, s0
	global_store_short v[42:43], v0, off offset:96
	v_mul_f32_e32 v0, 0xbfb8aa3b, v48
	v_exp_f32_e32 v0, v0
	v_mul_f32_e32 v38, 0xbfb8aa3b, v44
	v_or_b32_e32 v34, 18, v50
	v_exp_f32_e32 v38, v38
	v_add_f32_e32 v0, 1.0, v0
	v_rcp_f32_e32 v0, v0
	v_ashrrev_i32_e32 v35, 31, v34
	v_lshlrev_b64 v[34:35], 12, v[34:35]
	v_lshl_add_u64 v[34:35], v[52:53], 0, v[34:35]
	v_cvt_pk_bf16_f32 v0, v0, s0
	global_store_short v[34:35], v0, off
	v_add_f32_e32 v0, 1.0, v38
	v_mul_f32_e32 v38, 0xbfb8aa3b, v40
	v_exp_f32_e32 v38, v38
	v_mul_f32_e32 v36, 0xbfb8aa3b, v36
	v_exp_f32_e32 v36, v36
	v_rcp_f32_e32 v0, v0
	v_add_f32_e32 v38, 1.0, v38
	v_rcp_f32_e32 v38, v38
	v_add_f32_e32 v36, 1.0, v36
	v_rcp_f32_e32 v36, v36
	v_cvt_pk_bf16_f32 v0, v0, s0
	global_store_short v[34:35], v0, off offset:32
	v_cvt_pk_bf16_f32 v0, v38, s0
	global_store_short v[34:35], v0, off offset:64
	v_cvt_pk_bf16_f32 v0, v36, s0
	global_store_short v[34:35], v0, off offset:96
	v_mul_f32_e32 v0, 0xbfb8aa3b, v49
	v_exp_f32_e32 v0, v0
	v_mul_f32_e32 v36, 0xbfb8aa3b, v45
	v_or_b32_e32 v34, 19, v50
	v_exp_f32_e32 v36, v36
	v_add_f32_e32 v0, 1.0, v0
	v_rcp_f32_e32 v0, v0
	v_ashrrev_i32_e32 v35, 31, v34
	v_lshlrev_b64 v[34:35], 12, v[34:35]
	v_lshl_add_u64 v[34:35], v[52:53], 0, v[34:35]
	v_cvt_pk_bf16_f32 v0, v0, s0
	global_store_short v[34:35], v0, off
	v_add_f32_e32 v0, 1.0, v36
	v_mul_f32_e32 v36, 0xbfb8aa3b, v41
	v_exp_f32_e32 v36, v36
	v_mul_f32_e32 v37, 0xbfb8aa3b, v37
	v_exp_f32_e32 v37, v37
	v_rcp_f32_e32 v0, v0
	v_add_f32_e32 v36, 1.0, v36
	v_rcp_f32_e32 v36, v36
	v_add_f32_e32 v37, 1.0, v37
	v_rcp_f32_e32 v37, v37
	v_cvt_pk_bf16_f32 v0, v0, s0
	global_store_short v[34:35], v0, off offset:32
	v_cvt_pk_bf16_f32 v0, v36, s0
	global_store_short v[34:35], v0, off offset:64
	v_cvt_pk_bf16_f32 v0, v37, s0
	global_store_short v[34:35], v0, off offset:96
	v_mul_f32_e32 v0, 0xbfb8aa3b, v30
	v_exp_f32_e32 v0, v0
	v_mul_f32_e32 v26, 0xbfb8aa3b, v26
	v_or_b32_e32 v34, 32, v50
	v_exp_f32_e32 v26, v26
	v_add_f32_e32 v0, 1.0, v0
	v_rcp_f32_e32 v0, v0
	v_mul_f32_e32 v22, 0xbfb8aa3b, v22
	v_ashrrev_i32_e32 v35, 31, v34
	v_exp_f32_e32 v22, v22
	v_mul_f32_e32 v18, 0xbfb8aa3b, v18
	v_lshlrev_b64 v[34:35], 12, v[34:35]
	v_exp_f32_e32 v18, v18
	v_lshl_add_u64 v[34:35], v[52:53], 0, v[34:35]
	v_cvt_pk_bf16_f32 v0, v0, s0
	global_store_short v[34:35], v0, off
	v_add_f32_e32 v0, 1.0, v26
	v_rcp_f32_e32 v0, v0
	v_add_f32_e32 v22, 1.0, v22
	v_rcp_f32_e32 v22, v22
	v_add_f32_e32 v18, 1.0, v18
	v_rcp_f32_e32 v18, v18
	v_cvt_pk_bf16_f32 v0, v0, s0
	global_store_short v[34:35], v0, off offset:32
	v_cvt_pk_bf16_f32 v0, v22, s0
	global_store_short v[34:35], v0, off offset:64
	v_cvt_pk_bf16_f32 v0, v18, s0
	global_store_short v[34:35], v0, off offset:96
	v_mul_f32_e32 v0, 0xbfb8aa3b, v31
	v_exp_f32_e32 v0, v0
	v_mul_f32_e32 v18, 0xbfb8aa3b, v27
	v_or_b32_e32 v30, 33, v50
	v_exp_f32_e32 v18, v18
	v_add_f32_e32 v0, 1.0, v0
	v_rcp_f32_e32 v0, v0
	v_ashrrev_i32_e32 v31, 31, v30
	v_lshlrev_b64 v[30:31], 12, v[30:31]
	v_lshl_add_u64 v[26:27], v[52:53], 0, v[30:31]
	v_cvt_pk_bf16_f32 v0, v0, s0
	global_store_short v[26:27], v0, off
	v_add_f32_e32 v0, 1.0, v18
	v_mul_f32_e32 v18, 0xbfb8aa3b, v23
; DEV int bidx() { int b = __builtin_amdgcn_readfirstlane(blockIdx.x); asm volatile("" : "+s"(b)); return b; }
; DEV int gdim() { int g = __builtin_amdgcn_readfirstlane(gridDim.x); asm volatile("" : "+s"(g)); return g; }
; DEV float sigmf(float x) { return __builtin_amdgcn_rcpf(1.f + __expf(-x)); }
; template <int EPI, bool AF32>
; DEV void gemm_tile(const void* Ap, int lda, const u16* Bt, int ldb, int K, int m0, int n0, const Epi& ea, char* smem) {
;     ...
; #pragma unroll
;   for (int m = 0; m < 4; m++) {
; #pragma unroll
;     for (int j = 0; j < 4; j++) {
;       const int row = m0 + wr * 64 + m * 16 + fq * 4 + j;
;       if (EPI == EP_F32) {
;         float* C = (float*)ea.p0;
; #pragma unroll
;         for (int n = 0; n < 4; n++) C[(size_t)row * ea.ld + cb + n * 16 + fr] = acc[m][n][j];
;       } else if (EPI == EP_BF16) {
;         u16* C = (u16*)ea.p0;
; #pragma unroll
;         for (int n = 0; n < 4; n++) C[(size_t)row * ea.ld + cb + n * 16 + fr] = f2bf(acc[m][n][j]);
;       } else if (EPI == EP_SIG) {
;         u16* C = (u16*)ea.p0;
; #pragma unroll
;         for (int n = 0; n < 4; n++) C[(size_t)row * ea.ld + cb + n * 16 + fr] = f2bf(sigmf(acc[m][n][j]));
; template <int EPI, bool AF32>
; DEV void gemm_phase(const void* A, int lda, const u16* Bt, int ldb, int M, int N, int K, const Epi& ea, char* smem) {
;     ...
;   for (int tile = bidx(); tile < ntm * ntn; tile += gdim()) {
;     int m, n;
;     tile_mn(tile, ntm, ntn, m, n);
;     gemm_tile<EPI, AF32>(A, lda, Bt, ldb, K, m << 7, n << 7, ea, smem);
;   }
	v_exp_f32_e32 v18, v18
	v_mul_f32_e32 v19, 0xbfb8aa3b, v19
	v_exp_f32_e32 v19, v19
	v_rcp_f32_e32 v0, v0
	v_add_f32_e32 v18, 1.0, v18
	v_rcp_f32_e32 v18, v18
	v_add_f32_e32 v19, 1.0, v19
	v_rcp_f32_e32 v19, v19
	v_cvt_pk_bf16_f32 v0, v0, s0
	global_store_short v[26:27], v0, off offset:32
	v_cvt_pk_bf16_f32 v0, v18, s0
	global_store_short v[26:27], v0, off offset:64
	v_cvt_pk_bf16_f32 v0, v19, s0
	global_store_short v[26:27], v0, off offset:96
	v_mul_f32_e32 v0, 0xbfb8aa3b, v32
	v_exp_f32_e32 v0, v0
	v_mul_f32_e32 v22, 0xbfb8aa3b, v28
	v_or_b32_e32 v18, 34, v50
	v_exp_f32_e32 v22, v22
	v_add_f32_e32 v0, 1.0, v0
	v_rcp_f32_e32 v0, v0
	v_ashrrev_i32_e32 v19, 31, v18
	v_lshlrev_b64 v[18:19], 12, v[18:19]
	v_lshl_add_u64 v[18:19], v[52:53], 0, v[18:19]
	v_cvt_pk_bf16_f32 v0, v0, s0
	global_store_short v[18:19], v0, off
	v_add_f32_e32 v0, 1.0, v22
	v_mul_f32_e32 v22, 0xbfb8aa3b, v24
	v_exp_f32_e32 v22, v22
	v_mul_f32_e32 v20, 0xbfb8aa3b, v20
	v_exp_f32_e32 v20, v20
	v_rcp_f32_e32 v0, v0
	v_add_f32_e32 v22, 1.0, v22
	v_rcp_f32_e32 v22, v22
	v_add_f32_e32 v20, 1.0, v20
	v_rcp_f32_e32 v20, v20
	v_cvt_pk_bf16_f32 v0, v0, s0
	global_store_short v[18:19], v0, off offset:32
	v_cvt_pk_bf16_f32 v0, v22, s0
	global_store_short v[18:19], v0, off offset:64
	v_cvt_pk_bf16_f32 v0, v20, s0
	global_store_short v[18:19], v0, off offset:96
	v_mul_f32_e32 v0, 0xbfb8aa3b, v33
	v_exp_f32_e32 v0, v0
	v_mul_f32_e32 v20, 0xbfb8aa3b, v29
	v_or_b32_e32 v18, 35, v50
	v_exp_f32_e32 v20, v20
	v_add_f32_e32 v0, 1.0, v0
	v_rcp_f32_e32 v0, v0
	v_ashrrev_i32_e32 v19, 31, v18
	v_lshlrev_b64 v[18:19], 12, v[18:19]
	v_lshl_add_u64 v[18:19], v[52:53], 0, v[18:19]
	v_cvt_pk_bf16_f32 v0, v0, s0
	global_store_short v[18:19], v0, off
	v_add_f32_e32 v0, 1.0, v20
	v_mul_f32_e32 v20, 0xbfb8aa3b, v25
	v_exp_f32_e32 v20, v20
	v_mul_f32_e32 v21, 0xbfb8aa3b, v21
	v_exp_f32_e32 v21, v21
	v_rcp_f32_e32 v0, v0
	v_add_f32_e32 v20, 1.0, v20
	v_rcp_f32_e32 v20, v20
	v_add_f32_e32 v21, 1.0, v21
	v_rcp_f32_e32 v21, v21
	v_cvt_pk_bf16_f32 v0, v0, s0
	global_store_short v[18:19], v0, off offset:32
	v_cvt_pk_bf16_f32 v0, v20, s0
	global_store_short v[18:19], v0, off offset:64
	v_cvt_pk_bf16_f32 v0, v21, s0
	global_store_short v[18:19], v0, off offset:96
	v_mul_f32_e32 v0, 0xbfb8aa3b, v14
	v_exp_f32_e32 v0, v0
	v_mul_f32_e32 v10, 0xbfb8aa3b, v10
	v_or_b32_e32 v18, 48, v50
	v_exp_f32_e32 v10, v10
	v_add_f32_e32 v0, 1.0, v0
	v_rcp_f32_e32 v0, v0
	v_mul_f32_e32 v6, 0xbfb8aa3b, v6
	v_ashrrev_i32_e32 v19, 31, v18
	v_exp_f32_e32 v6, v6
	v_mul_f32_e32 v2, 0xbfb8aa3b, v2
	v_lshlrev_b64 v[18:19], 12, v[18:19]
	v_exp_f32_e32 v2, v2
	v_lshl_add_u64 v[18:19], v[52:53], 0, v[18:19]
	v_cvt_pk_bf16_f32 v0, v0, s0
	global_store_short v[18:19], v0, off
	v_add_f32_e32 v0, 1.0, v10
	v_rcp_f32_e32 v0, v0
	v_add_f32_e32 v6, 1.0, v6
	v_rcp_f32_e32 v6, v6
	v_add_f32_e32 v2, 1.0, v2
	v_rcp_f32_e32 v2, v2
	v_cvt_pk_bf16_f32 v0, v0, s0
	global_store_short v[18:19], v0, off offset:32
	v_cvt_pk_bf16_f32 v0, v6, s0
	global_store_short v[18:19], v0, off offset:64
	v_cvt_pk_bf16_f32 v0, v2, s0
	global_store_short v[18:19], v0, off offset:96
	v_mul_f32_e32 v0, 0xbfb8aa3b, v15
	v_exp_f32_e32 v0, v0
	v_mul_f32_e32 v2, 0xbfb8aa3b, v11
	v_or_b32_e32 v14, 49, v50
	v_exp_f32_e32 v2, v2
	v_add_f32_e32 v0, 1.0, v0
	v_rcp_f32_e32 v0, v0
	v_ashrrev_i32_e32 v15, 31, v14
	v_lshlrev_b64 v[14:15], 12, v[14:15]
	v_lshl_add_u64 v[10:11], v[52:53], 0, v[14:15]
	v_cvt_pk_bf16_f32 v0, v0, s0
	global_store_short v[10:11], v0, off
	v_add_f32_e32 v0, 1.0, v2
	v_mul_f32_e32 v2, 0xbfb8aa3b, v7
	v_exp_f32_e32 v2, v2
	v_mul_f32_e32 v3, 0xbfb8aa3b, v3
	v_exp_f32_e32 v3, v3
	v_rcp_f32_e32 v0, v0
	v_add_f32_e32 v2, 1.0, v2
	v_rcp_f32_e32 v2, v2
	v_add_f32_e32 v3, 1.0, v3
	v_rcp_f32_e32 v3, v3
	v_cvt_pk_bf16_f32 v0, v0, s0
	global_store_short v[10:11], v0, off offset:32
	v_cvt_pk_bf16_f32 v0, v2, s0
	global_store_short v[10:11], v0, off offset:64
	v_cvt_pk_bf16_f32 v0, v3, s0
	global_store_short v[10:11], v0, off offset:96
	v_mul_f32_e32 v0, 0xbfb8aa3b, v16
	v_exp_f32_e32 v0, v0
	v_mul_f32_e32 v6, 0xbfb8aa3b, v12
	v_or_b32_e32 v2, 50, v50
	v_exp_f32_e32 v6, v6
	v_add_f32_e32 v0, 1.0, v0
	v_rcp_f32_e32 v0, v0
	v_ashrrev_i32_e32 v3, 31, v2
	v_lshlrev_b64 v[2:3], 12, v[2:3]
	v_lshl_add_u64 v[2:3], v[52:53], 0, v[2:3]
	v_cvt_pk_bf16_f32 v0, v0, s0
	global_store_short v[2:3], v0, off
	v_add_f32_e32 v0, 1.0, v6
	v_mul_f32_e32 v6, 0xbfb8aa3b, v8
	v_exp_f32_e32 v6, v6
	v_mul_f32_e32 v4, 0xbfb8aa3b, v4
	v_exp_f32_e32 v4, v4
	v_rcp_f32_e32 v0, v0
	v_add_f32_e32 v6, 1.0, v6
	v_rcp_f32_e32 v6, v6
	v_add_f32_e32 v4, 1.0, v4
	v_rcp_f32_e32 v4, v4
	v_cvt_pk_bf16_f32 v0, v0, s0
	global_store_short v[2:3], v0, off offset:32
	v_cvt_pk_bf16_f32 v0, v6, s0
	global_store_short v[2:3], v0, off offset:64
	v_cvt_pk_bf16_f32 v0, v4, s0
	global_store_short v[2:3], v0, off offset:96
	v_mul_f32_e32 v0, 0xbfb8aa3b, v17
	v_exp_f32_e32 v0, v0
	v_mul_f32_e32 v4, 0xbfb8aa3b, v13
	v_or_b32_e32 v2, 51, v50
	v_exp_f32_e32 v4, v4
	v_add_f32_e32 v0, 1.0, v0
	v_rcp_f32_e32 v0, v0
	v_ashrrev_i32_e32 v3, 31, v2
	v_lshlrev_b64 v[2:3], 12, v[2:3]
	v_lshl_add_u64 v[2:3], v[52:53], 0, v[2:3]
	v_cvt_pk_bf16_f32 v0, v0, s0
	global_store_short v[2:3], v0, off
	v_add_f32_e32 v0, 1.0, v4
	v_mul_f32_e32 v4, 0xbfb8aa3b, v9
	v_exp_f32_e32 v4, v4
	v_mul_f32_e32 v5, 0xbfb8aa3b, v5
	v_exp_f32_e32 v5, v5
	v_rcp_f32_e32 v0, v0
	v_add_f32_e32 v4, 1.0, v4
	v_rcp_f32_e32 v4, v4
	v_add_f32_e32 v5, 1.0, v5
	v_rcp_f32_e32 v5, v5
	v_cvt_pk_bf16_f32 v0, v0, s0
	global_store_short v[2:3], v0, off offset:32
	v_cvt_pk_bf16_f32 v0, v4, s0
	global_store_short v[2:3], v0, off offset:64
	v_cvt_pk_bf16_f32 v0, v5, s0
	v_readfirstlane_b32 s0, v198
	global_store_short v[2:3], v0, off offset:96
	s_add_i32 s8, s0, s8
	s_cmpk_lt_i32 s8, 0x1040
	s_cbranch_scc1 .LBB0_1262

; DEV f32x4 mfma16(bf16x8 a, bf16x8 b, f32x4 c) { return __builtin_amdgcn_mfma_f32_16x16x32_bf16(a, b, c, 0, 0, 0); }
; template <int EPI, bool AF32>
; DEV void gemm_tile(const void* Ap, int lda, const u16* Bt, int ldb, int K, int m0, int n0, const Epi& ea, char* smem) {
;     ...
;   for (int kt = 0; kt < nk; kt++) {
;     const int buf = kt & 1;
;     if (kt + 1 < nk) swrite(buf ^ 1);
;     if (kt + 2 < nk) gload(kt + 2);
; #pragma unroll
;     for (int ks = 0; ks < 2; ks++) {
;       bf16x8 a[4], b[4];
; #pragma unroll
;       for (int m = 0; m < 4; m++) a[m] = *(const bf16x8*)(sA + buf * 9216 + (wr * 64 + m * 16 + fr) * 72 + ks * 32 + fq * 8);
; #pragma unroll
;       for (int n = 0; n < 4; n++) b[n] = *(const bf16x8*)(sB + buf * 9216 + (wc * 64 + n * 16 + fr) * 72 + ks * 32 + fq * 8);
;       __builtin_amdgcn_s_setprio(1);
; #pragma unroll
;       for (int m = 0; m < 4; m++)
; #pragma unroll
;         for (int n = 0; n < 4; n++) acc[m][n] = mfma16(a[m], b[n], acc[m][n]);
;       __builtin_amdgcn_s_setprio(0);
;     }
;     __syncthreads();
;   }
.Lgk3_loop:
	s_waitcnt lgkmcnt(0)
	ds_read_b128 v[222:225], v161 offset:64
	ds_read_b128 v[226:229], v161 offset:2368
	ds_read_b128 v[230:233], v161 offset:4672
	ds_read_b128 v[234:237], v161 offset:6976
	ds_read_b128 v[238:241], v129 offset:36928
	ds_read_b128 v[242:245], v129 offset:39232
	ds_read_b128 v[246:249], v129 offset:41536
	ds_read_b128 v[250:253], v129 offset:43840
	v_mfma_f32_16x16x32_bf16 v[34:37], v[130:133], v[146:149], v[34:37]
	v_mfma_f32_16x16x32_bf16 v[38:41], v[130:133], v[150:153], v[38:41]
	v_mfma_f32_16x16x32_bf16 v[42:45], v[130:133], v[162:165], v[42:45]
	v_mfma_f32_16x16x32_bf16 v[46:49], v[130:133], v[166:169], v[46:49]
	s_waitcnt vmcnt(0)
	ds_write_b128 v122, v[22:25] offset:18432
	ds_write_b128 v122, v[6:9] offset:55296
	v_mfma_f32_16x16x32_bf16 v[50:53], v[134:137], v[146:149], v[50:53]
	ds_write_b128 v121, v[18:21] offset:18432
	ds_write_b128 v121, v[10:13] offset:55296
	v_mfma_f32_16x16x32_bf16 v[54:57], v[134:137], v[150:153], v[54:57]
	ds_write_b128 v120, v[14:17] offset:18432
	ds_write_b128 v120, v[2:5] offset:55296
	v_mfma_f32_16x16x32_bf16 v[58:61], v[134:137], v[162:165], v[58:61]
	ds_write_b128 v124, v[26:29] offset:18432
	ds_write_b128 v124, v[30:33] offset:55296
	v_mfma_f32_16x16x32_bf16 v[62:65], v[134:137], v[166:169], v[62:65]
	global_load_dwordx4 v[22:25], v[112:113], off
	v_mfma_f32_16x16x32_bf16 v[66:69], v[138:141], v[146:149], v[66:69]
	global_load_dwordx4 v[6:9], v[110:111], off
	v_mfma_f32_16x16x32_bf16 v[70:73], v[138:141], v[150:153], v[70:73]
	global_load_dwordx4 v[18:21], v[108:109], off
	v_mfma_f32_16x16x32_bf16 v[74:77], v[138:141], v[162:165], v[74:77]
	global_load_dwordx4 v[10:13], v[106:107], off
	v_mfma_f32_16x16x32_bf16 v[78:81], v[138:141], v[166:169], v[78:81]
	global_load_dwordx4 v[14:17], v[104:105], off
	v_mfma_f32_16x16x32_bf16 v[82:85], v[142:145], v[146:149], v[82:85]
	global_load_dwordx4 v[2:5], v[102:103], off
	v_mfma_f32_16x16x32_bf16 v[86:89], v[142:145], v[150:153], v[86:89]
	global_load_dwordx4 v[26:29], v[100:101], off
	v_mfma_f32_16x16x32_bf16 v[90:93], v[142:145], v[162:165], v[90:93]
	global_load_dwordx4 v[30:33], v[98:99], off
	v_mfma_f32_16x16x32_bf16 v[94:97], v[142:145], v[166:169], v[94:97]
	s_waitcnt lgkmcnt(0)
	s_barrier
	ds_read_b128 v[130:133], v161 offset:18432
	v_mfma_f32_16x16x32_bf16 v[34:37], v[222:225], v[238:241], v[34:37]
	ds_read_b128 v[134:137], v161 offset:20736
	v_mfma_f32_16x16x32_bf16 v[38:41], v[222:225], v[242:245], v[38:41]
	ds_read_b128 v[138:141], v161 offset:23040
	v_mfma_f32_16x16x32_bf16 v[42:45], v[222:225], v[246:249], v[42:45]
	ds_read_b128 v[142:145], v161 offset:25344
	v_mfma_f32_16x16x32_bf16 v[46:49], v[222:225], v[250:253], v[46:49]
	ds_read_b128 v[146:149], v129 offset:55296
	v_mfma_f32_16x16x32_bf16 v[50:53], v[226:229], v[238:241], v[50:53]
	ds_read_b128 v[150:153], v129 offset:57600
	v_mfma_f32_16x16x32_bf16 v[54:57], v[226:229], v[242:245], v[54:57]
	ds_read_b128 v[162:165], v129 offset:59904
	v_mfma_f32_16x16x32_bf16 v[58:61], v[226:229], v[246:249], v[58:61]
	ds_read_b128 v[166:169], v129 offset:62208
	v_mfma_f32_16x16x32_bf16 v[62:65], v[226:229], v[250:253], v[62:65]
	v_mfma_f32_16x16x32_bf16 v[66:69], v[230:233], v[238:241], v[66:69]
	v_mfma_f32_16x16x32_bf16 v[70:73], v[230:233], v[242:245], v[70:73]
	v_mfma_f32_16x16x32_bf16 v[74:77], v[230:233], v[246:249], v[74:77]
	v_mfma_f32_16x16x32_bf16 v[78:81], v[230:233], v[250:253], v[78:81]
	v_mfma_f32_16x16x32_bf16 v[82:85], v[234:237], v[238:241], v[82:85]
	v_mfma_f32_16x16x32_bf16 v[86:89], v[234:237], v[242:245], v[86:89]
	v_mfma_f32_16x16x32_bf16 v[90:93], v[234:237], v[246:249], v[90:93]
	v_mfma_f32_16x16x32_bf16 v[94:97], v[234:237], v[250:253], v[94:97]
	s_waitcnt lgkmcnt(0)
	ds_read_b128 v[222:225], v161 offset:18496
	ds_read_b128 v[226:229], v161 offset:20800
	ds_read_b128 v[230:233], v161 offset:23104
	ds_read_b128 v[234:237], v161 offset:25408
	ds_read_b128 v[238:241], v129 offset:55360
	ds_read_b128 v[242:245], v129 offset:57664
	ds_read_b128 v[246:249], v129 offset:59968
	ds_read_b128 v[250:253], v129 offset:62272
	v_mfma_f32_16x16x32_bf16 v[34:37], v[130:133], v[146:149], v[34:37]
	v_mfma_f32_16x16x32_bf16 v[38:41], v[130:133], v[150:153], v[38:41]
	v_mfma_f32_16x16x32_bf16 v[42:45], v[130:133], v[162:165], v[42:45]
	v_mfma_f32_16x16x32_bf16 v[46:49], v[130:133], v[166:169], v[46:49]
	s_waitcnt vmcnt(0)
	ds_write_b128 v122, v[22:25]
	ds_write_b128 v122, v[6:9] offset:36864
	v_mfma_f32_16x16x32_bf16 v[50:53], v[134:137], v[146:149], v[50:53]
	ds_write_b128 v121, v[18:21]
	ds_write_b128 v121, v[10:13] offset:36864
	v_mfma_f32_16x16x32_bf16 v[54:57], v[134:137], v[150:153], v[54:57]
	ds_write_b128 v120, v[14:17]
	ds_write_b128 v120, v[2:5] offset:36864
	v_mfma_f32_16x16x32_bf16 v[58:61], v[134:137], v[162:165], v[58:61]
	ds_write_b128 v124, v[26:29]
	ds_write_b128 v124, v[30:33] offset:36864
	v_mfma_f32_16x16x32_bf16 v[62:65], v[134:137], v[166:169], v[62:65]
	global_load_dwordx4 v[22:25], v[112:113], off offset:128
	v_mfma_f32_16x16x32_bf16 v[66:69], v[138:141], v[146:149], v[66:69]
	global_load_dwordx4 v[6:9], v[110:111], off offset:128
	v_mfma_f32_16x16x32_bf16 v[70:73], v[138:141], v[150:153], v[70:73]
	global_load_dwordx4 v[18:21], v[108:109], off offset:128
	v_mfma_f32_16x16x32_bf16 v[74:77], v[138:141], v[162:165], v[74:77]
	global_load_dwordx4 v[10:13], v[106:107], off offset:128
	v_mfma_f32_16x16x32_bf16 v[78:81], v[138:141], v[166:169], v[78:81]
	global_load_dwordx4 v[14:17], v[104:105], off offset:128
	v_mfma_f32_16x16x32_bf16 v[82:85], v[142:145], v[146:149], v[82:85]
	global_load_dwordx4 v[2:5], v[102:103], off offset:128
	v_mfma_f32_16x16x32_bf16 v[86:89], v[142:145], v[150:153], v[86:89]
	global_load_dwordx4 v[26:29], v[100:101], off offset:128
	v_mfma_f32_16x16x32_bf16 v[90:93], v[142:145], v[162:165], v[90:93]
	global_load_dwordx4 v[30:33], v[98:99], off offset:128
	v_mfma_f32_16x16x32_bf16 v[94:97], v[142:145], v[166:169], v[94:97]
	s_waitcnt lgkmcnt(0)
	s_barrier
; DEV f32x4 mfma16(bf16x8 a, bf16x8 b, f32x4 c) { return __builtin_amdgcn_mfma_f32_16x16x32_bf16(a, b, c, 0, 0, 0); }
; template <int EPI, bool AF32>
; DEV void gemm_tile(const void* Ap, int lda, const u16* Bt, int ldb, int K, int m0, int n0, const Epi& ea, char* smem) {
;     ...
;   for (int kt = 0; kt < nk; kt++) {
;     const int buf = kt & 1;
;     if (kt + 1 < nk) swrite(buf ^ 1);
;     if (kt + 2 < nk) gload(kt + 2);
; #pragma unroll
;     for (int ks = 0; ks < 2; ks++) {
;       bf16x8 a[4], b[4];
; #pragma unroll
;       for (int m = 0; m < 4; m++) a[m] = *(const bf16x8*)(sA + buf * 9216 + (wr * 64 + m * 16 + fr) * 72 + ks * 32 + fq * 8);
; #pragma unroll
;       for (int n = 0; n < 4; n++) b[n] = *(const bf16x8*)(sB + buf * 9216 + (wc * 64 + n * 16 + fr) * 72 + ks * 32 + fq * 8);
;       __builtin_amdgcn_s_setprio(1);
; #pragma unroll
;       for (int m = 0; m < 4; m++)
; #pragma unroll
;         for (int n = 0; n < 4; n++) acc[m][n] = mfma16(a[m], b[n], acc[m][n]);
;       __builtin_amdgcn_s_setprio(0);
;     }
;     __syncthreads();
;   }
	ds_read_b128 v[130:133], v161
	v_mfma_f32_16x16x32_bf16 v[34:37], v[222:225], v[238:241], v[34:37]
	ds_read_b128 v[134:137], v161 offset:2304
	v_mfma_f32_16x16x32_bf16 v[38:41], v[222:225], v[242:245], v[38:41]
	ds_read_b128 v[138:141], v161 offset:4608
	v_mfma_f32_16x16x32_bf16 v[42:45], v[222:225], v[246:249], v[42:45]
	ds_read_b128 v[142:145], v161 offset:6912
	v_mfma_f32_16x16x32_bf16 v[46:49], v[222:225], v[250:253], v[46:49]
	ds_read_b128 v[146:149], v129 offset:36864
	v_mfma_f32_16x16x32_bf16 v[50:53], v[226:229], v[238:241], v[50:53]
	ds_read_b128 v[150:153], v129 offset:39168
	v_mfma_f32_16x16x32_bf16 v[54:57], v[226:229], v[242:245], v[54:57]
	ds_read_b128 v[162:165], v129 offset:41472
	v_mfma_f32_16x16x32_bf16 v[58:61], v[226:229], v[246:249], v[58:61]
	ds_read_b128 v[166:169], v129 offset:43776
	v_mfma_f32_16x16x32_bf16 v[62:65], v[226:229], v[250:253], v[62:65]
	v_mfma_f32_16x16x32_bf16 v[66:69], v[230:233], v[238:241], v[66:69]
	v_lshl_add_u64 v[112:113], v[112:113], 0, s[0:1]
	v_mfma_f32_16x16x32_bf16 v[70:73], v[230:233], v[242:245], v[70:73]
	v_lshl_add_u64 v[110:111], v[110:111], 0, s[0:1]
	v_mfma_f32_16x16x32_bf16 v[74:77], v[230:233], v[246:249], v[74:77]
	v_lshl_add_u64 v[108:109], v[108:109], 0, s[0:1]
	v_mfma_f32_16x16x32_bf16 v[78:81], v[230:233], v[250:253], v[78:81]
	v_lshl_add_u64 v[106:107], v[106:107], 0, s[0:1]
	v_mfma_f32_16x16x32_bf16 v[82:85], v[234:237], v[238:241], v[82:85]
	v_lshl_add_u64 v[104:105], v[104:105], 0, s[0:1]
	v_mfma_f32_16x16x32_bf16 v[86:89], v[234:237], v[242:245], v[86:89]
	v_lshl_add_u64 v[102:103], v[102:103], 0, s[0:1]
	v_mfma_f32_16x16x32_bf16 v[90:93], v[234:237], v[246:249], v[90:93]
	v_lshl_add_u64 v[100:101], v[100:101], 0, s[0:1]
	v_mfma_f32_16x16x32_bf16 v[94:97], v[234:237], v[250:253], v[94:97]
	v_lshl_add_u64 v[98:99], v[98:99], 0, s[0:1]
	s_add_i32 s19, s19, 1
	s_cmp_lg_u32 s19, 7
	s_cbranch_scc1 .Lgk3_loop
	s_waitcnt lgkmcnt(0)
	ds_read_b128 v[222:225], v161 offset:64
	ds_read_b128 v[226:229], v161 offset:2368
	ds_read_b128 v[230:233], v161 offset:4672
	ds_read_b128 v[234:237], v161 offset:6976
	ds_read_b128 v[238:241], v129 offset:36928
	ds_read_b128 v[242:245], v129 offset:39232
	ds_read_b128 v[246:249], v129 offset:41536
	ds_read_b128 v[250:253], v129 offset:43840
	v_mfma_f32_16x16x32_bf16 v[34:37], v[130:133], v[146:149], v[34:37]
	v_mfma_f32_16x16x32_bf16 v[38:41], v[130:133], v[150:153], v[38:41]
	v_mfma_f32_16x16x32_bf16 v[42:45], v[130:133], v[162:165], v[42:45]
	v_mfma_f32_16x16x32_bf16 v[46:49], v[130:133], v[166:169], v[46:49]
	s_waitcnt vmcnt(0)
	ds_write_b128 v122, v[22:25] offset:18432
	ds_write_b128 v122, v[6:9] offset:55296
	v_mfma_f32_16x16x32_bf16 v[50:53], v[134:137], v[146:149], v[50:53]
	ds_write_b128 v121, v[18:21] offset:18432
	ds_write_b128 v121, v[10:13] offset:55296
	v_mfma_f32_16x16x32_bf16 v[54:57], v[134:137], v[150:153], v[54:57]
	ds_write_b128 v120, v[14:17] offset:18432
	ds_write_b128 v120, v[2:5] offset:55296
	v_mfma_f32_16x16x32_bf16 v[58:61], v[134:137], v[162:165], v[58:61]
	ds_write_b128 v124, v[26:29] offset:18432
	ds_write_b128 v124, v[30:33] offset:55296
	v_mfma_f32_16x16x32_bf16 v[62:65], v[134:137], v[166:169], v[62:65]
	v_mfma_f32_16x16x32_bf16 v[66:69], v[138:141], v[146:149], v[66:69]
	v_mfma_f32_16x16x32_bf16 v[70:73], v[138:141], v[150:153], v[70:73]
	v_mfma_f32_16x16x32_bf16 v[74:77], v[138:141], v[162:165], v[74:77]
	v_mfma_f32_16x16x32_bf16 v[78:81], v[138:141], v[166:169], v[78:81]
	v_mfma_f32_16x16x32_bf16 v[82:85], v[142:145], v[146:149], v[82:85]
	v_mfma_f32_16x16x32_bf16 v[86:89], v[142:145], v[150:153], v[86:89]
	v_mfma_f32_16x16x32_bf16 v[90:93], v[142:145], v[162:165], v[90:93]
	v_mfma_f32_16x16x32_bf16 v[94:97], v[142:145], v[166:169], v[94:97]
	s_waitcnt lgkmcnt(0)
	s_barrier
	ds_read_b128 v[130:133], v161 offset:18432
	v_mfma_f32_16x16x32_bf16 v[34:37], v[222:225], v[238:241], v[34:37]
	ds_read_b128 v[134:137], v161 offset:20736
	v_mfma_f32_16x16x32_bf16 v[38:41], v[222:225], v[242:245], v[38:41]
	ds_read_b128 v[138:141], v161 offset:23040
	v_mfma_f32_16x16x32_bf16 v[42:45], v[222:225], v[246:249], v[42:45]
	ds_read_b128 v[142:145], v161 offset:25344
	v_mfma_f32_16x16x32_bf16 v[46:49], v[222:225], v[250:253], v[46:49]
	ds_read_b128 v[146:149], v129 offset:55296
	v_mfma_f32_16x16x32_bf16 v[50:53], v[226:229], v[238:241], v[50:53]
	ds_read_b128 v[150:153], v129 offset:57600
	v_mfma_f32_16x16x32_bf16 v[54:57], v[226:229], v[242:245], v[54:57]
	ds_read_b128 v[162:165], v129 offset:59904
	v_mfma_f32_16x16x32_bf16 v[58:61], v[226:229], v[246:249], v[58:61]
	ds_read_b128 v[166:169], v129 offset:62208
	v_mfma_f32_16x16x32_bf16 v[62:65], v[226:229], v[250:253], v[62:65]
	v_mfma_f32_16x16x32_bf16 v[66:69], v[230:233], v[238:241], v[66:69]
	v_mfma_f32_16x16x32_bf16 v[70:73], v[230:233], v[242:245], v[70:73]
	v_mfma_f32_16x16x32_bf16 v[74:77], v[230:233], v[246:249], v[74:77]
	v_mfma_f32_16x16x32_bf16 v[78:81], v[230:233], v[250:253], v[78:81]
	v_mfma_f32_16x16x32_bf16 v[82:85], v[234:237], v[238:241], v[82:85]
	v_mfma_f32_16x16x32_bf16 v[86:89], v[234:237], v[242:245], v[86:89]
	v_mfma_f32_16x16x32_bf16 v[90:93], v[234:237], v[246:249], v[90:93]
	v_mfma_f32_16x16x32_bf16 v[94:97], v[234:237], v[250:253], v[94:97]
	s_waitcnt lgkmcnt(0)
; DEV f32x4 mfma16(bf16x8 a, bf16x8 b, f32x4 c) { return __builtin_amdgcn_mfma_f32_16x16x32_bf16(a, b, c, 0, 0, 0); }
; template <int EPI, bool AF32>
; DEV void gemm_tile(const void* Ap, int lda, const u16* Bt, int ldb, int K, int m0, int n0, const Epi& ea, char* smem) {
;     ...
;     for (int ks = 0; ks < 2; ks++) {
;       bf16x8 a[4], b[4];
; #pragma unroll
;       for (int m = 0; m < 4; m++) a[m] = *(const bf16x8*)(sA + buf * 9216 + (wr * 64 + m * 16 + fr) * 72 + ks * 32 + fq * 8);
; #pragma unroll
;       for (int n = 0; n < 4; n++) b[n] = *(const bf16x8*)(sB + buf * 9216 + (wc * 64 + n * 16 + fr) * 72 + ks * 32 + fq * 8);
;       __builtin_amdgcn_s_setprio(1);
; #pragma unroll
;       for (int m = 0; m < 4; m++)
; #pragma unroll
;         for (int n = 0; n < 4; n++) acc[m][n] = mfma16(a[m], b[n], acc[m][n]);
;       __builtin_amdgcn_s_setprio(0);
;     }
;     __syncthreads();
;     ...
;       const u16* G = (const u16*)ea.p1 + (EPI == EP_MERGE2 ? 1024 : 0);
;       u16 gv[4][4][4], cv[4][4][4];
; #pragma unroll
;       for (int m = 0; m < 4; m++)
; #pragma unroll
;         for (int j = 0; j < 4; j++)
; #pragma unroll
;           for (int n = 0; n < 4; n++) {
;             gv[m][j][n] = G[(size_t)(rbase + m * 16 + j) * 2048 + cbase + n * 16];
;             if (EPI == EP_MERGE2) cv[m][j][n] = C[(size_t)(rbase + m * 16 + j) * 1024 + cbase + n * 16];
;           }
	ds_read_b128 v[222:225], v161 offset:18496
	ds_read_b128 v[226:229], v161 offset:20800
	ds_read_b128 v[230:233], v161 offset:23104
	ds_read_b128 v[234:237], v161 offset:25408
	ds_read_b128 v[238:241], v129 offset:55360
	ds_read_b128 v[242:245], v129 offset:57664
	ds_read_b128 v[246:249], v129 offset:59968
	ds_read_b128 v[250:253], v129 offset:62272
	v_mfma_f32_16x16x32_bf16 v[34:37], v[130:133], v[146:149], v[34:37]
	v_mfma_f32_16x16x32_bf16 v[38:41], v[130:133], v[150:153], v[38:41]
	v_mfma_f32_16x16x32_bf16 v[42:45], v[130:133], v[162:165], v[42:45]
	v_mfma_f32_16x16x32_bf16 v[98:101], v[130:133], v[166:169], v[46:49]
	v_mfma_f32_16x16x32_bf16 v[50:53], v[134:137], v[146:149], v[50:53]
	v_mfma_f32_16x16x32_bf16 v[54:57], v[134:137], v[150:153], v[54:57]
	v_mfma_f32_16x16x32_bf16 v[58:61], v[134:137], v[162:165], v[58:61]
	v_mfma_f32_16x16x32_bf16 v[62:65], v[134:137], v[166:169], v[62:65]
	v_mfma_f32_16x16x32_bf16 v[66:69], v[138:141], v[146:149], v[66:69]
	v_mfma_f32_16x16x32_bf16 v[70:73], v[138:141], v[150:153], v[70:73]
	v_mfma_f32_16x16x32_bf16 v[74:77], v[138:141], v[162:165], v[74:77]
	v_mfma_f32_16x16x32_bf16 v[78:81], v[138:141], v[166:169], v[78:81]
	v_mfma_f32_16x16x32_bf16 v[82:85], v[142:145], v[146:149], v[82:85]
	v_mfma_f32_16x16x32_bf16 v[86:89], v[142:145], v[150:153], v[86:89]
	v_mfma_f32_16x16x32_bf16 v[90:93], v[142:145], v[162:165], v[90:93]
	v_mfma_f32_16x16x32_bf16 v[94:97], v[142:145], v[166:169], v[94:97]
	s_waitcnt lgkmcnt(0)
	v_mfma_f32_16x16x32_bf16 v[118:121], v[222:225], v[238:241], v[34:37]
	v_mfma_f32_16x16x32_bf16 v[122:125], v[222:225], v[242:245], v[38:41]
	v_mfma_f32_16x16x32_bf16 v[126:129], v[222:225], v[246:249], v[42:45]
	v_mfma_f32_16x16x32_bf16 v[42:45], v[226:229], v[242:245], v[54:57]
	v_mfma_f32_16x16x32_bf16 v[38:41], v[226:229], v[246:249], v[58:61]
	v_mfma_f32_16x16x32_bf16 v[34:37], v[226:229], v[250:253], v[62:65]
	v_mfma_f32_16x16x32_bf16 v[30:33], v[230:233], v[238:241], v[66:69]
	v_mfma_f32_16x16x32_bf16 v[26:29], v[230:233], v[242:245], v[70:73]
	v_mfma_f32_16x16x32_bf16 v[22:25], v[230:233], v[246:249], v[74:77]
	v_mfma_f32_16x16x32_bf16 v[18:21], v[230:233], v[250:253], v[78:81]
	v_mfma_f32_16x16x32_bf16 v[14:17], v[234:237], v[238:241], v[82:85]
	v_mfma_f32_16x16x32_bf16 v[10:13], v[234:237], v[242:245], v[86:89]
	v_mfma_f32_16x16x32_bf16 v[6:9], v[234:237], v[246:249], v[90:93]
	v_mfma_f32_16x16x32_bf16 v[2:5], v[234:237], v[250:253], v[94:97]
	v_mfma_f32_16x16x32_bf16 v[46:49], v[226:229], v[238:241], v[50:53]
	v_mfma_f32_16x16x32_bf16 v[50:53], v[222:225], v[250:253], v[98:101]
	s_nop 7
	v_and_b32_e32 v114, 64, v114
	v_add_u32_e32 v0, s18, v117
	v_or3_b32 v54, v114, s17, v115
	v_lshl_or_b32 v72, v116, 2, v0
	v_ashrrev_i32_e32 v55, 31, v54
	v_lshlrev_b64 v[66:67], 1, v[54:55]
	v_ashrrev_i32_e32 v73, 31, v72
	v_or_b32_e32 v78, 1, v72
	v_lshl_add_u64 v[74:75], s[4:5], 0, v[66:67]
	v_lshlrev_b64 v[54:55], 12, v[72:73]
	v_ashrrev_i32_e32 v79, 31, v78
	v_or_b32_e32 v82, 2, v72
	v_lshl_add_u64 v[76:77], v[74:75], 0, v[54:55]
	v_lshlrev_b64 v[54:55], 12, v[78:79]
	v_ashrrev_i32_e32 v83, 31, v82
	v_or_b32_e32 v86, 3, v72
	v_lshl_add_u64 v[80:81], v[74:75], 0, v[54:55]
	v_lshlrev_b64 v[54:55], 12, v[82:83]
	v_ashrrev_i32_e32 v87, 31, v86
	v_or_b32_e32 v90, 16, v72
	v_lshl_add_u64 v[84:85], v[74:75], 0, v[54:55]
	v_lshlrev_b64 v[54:55], 12, v[86:87]
	v_ashrrev_i32_e32 v91, 31, v90
	v_or_b32_e32 v94, 17, v72
	v_lshl_add_u64 v[88:89], v[74:75], 0, v[54:55]
	v_lshlrev_b64 v[54:55], 12, v[90:91]
	v_ashrrev_i32_e32 v95, 31, v94
	v_or_b32_e32 v98, 18, v72
	v_lshl_add_u64 v[92:93], v[74:75], 0, v[54:55]
	v_lshlrev_b64 v[54:55], 12, v[94:95]
	v_ashrrev_i32_e32 v99, 31, v98
	v_or_b32_e32 v102, 19, v72
	v_lshl_add_u64 v[96:97], v[74:75], 0, v[54:55]
	v_lshlrev_b64 v[54:55], 12, v[98:99]
	v_ashrrev_i32_e32 v103, 31, v102
	v_or_b32_e32 v70, 32, v72
	v_lshl_add_u64 v[100:101], v[74:75], 0, v[54:55]
	v_lshlrev_b64 v[54:55], 12, v[102:103]
	v_ashrrev_i32_e32 v71, 31, v70
	v_or_b32_e32 v68, 33, v72
	v_lshl_add_u64 v[104:105], v[74:75], 0, v[54:55]
	v_lshlrev_b64 v[54:55], 12, v[70:71]
	v_ashrrev_i32_e32 v69, 31, v68
	v_or_b32_e32 v64, 34, v72
	v_lshl_add_u64 v[106:107], v[74:75], 0, v[54:55]
	v_lshlrev_b64 v[54:55], 12, v[68:69]
	v_ashrrev_i32_e32 v65, 31, v64
	v_or_b32_e32 v62, 35, v72
	v_lshl_add_u64 v[108:109], v[74:75], 0, v[54:55]
	v_lshlrev_b64 v[54:55], 12, v[64:65]
	v_ashrrev_i32_e32 v63, 31, v62
	v_or_b32_e32 v60, 48, v72
	v_lshl_add_u64 v[110:111], v[74:75], 0, v[54:55]
	v_lshlrev_b64 v[54:55], 12, v[62:63]
	v_ashrrev_i32_e32 v61, 31, v60
	v_or_b32_e32 v58, 49, v72
	v_lshl_add_u64 v[112:113], v[74:75], 0, v[54:55]
	v_lshlrev_b64 v[54:55], 12, v[60:61]
	v_ashrrev_i32_e32 v59, 31, v58
	v_or_b32_e32 v56, 50, v72
	v_lshl_add_u64 v[114:115], v[74:75], 0, v[54:55]
	v_lshlrev_b64 v[54:55], 12, v[58:59]
	v_ashrrev_i32_e32 v57, 31, v56
	v_lshl_add_u64 v[116:117], v[74:75], 0, v[54:55]
	v_lshlrev_b64 v[54:55], 12, v[56:57]
	v_lshl_add_u64 v[130:131], v[74:75], 0, v[54:55]
	v_or_b32_e32 v54, 51, v72
	v_ashrrev_i32_e32 v55, 31, v54
	v_lshlrev_b64 v[132:133], 12, v[54:55]
	v_lshl_add_u64 v[74:75], v[74:75], 0, v[132:133]
	s_barrier
; DEV float bf2f(u16 h) { return __uint_as_float(((unsigned)h) << 16); }
; template <int EPI, bool AF32>
; DEV void gemm_tile(const void* Ap, int lda, const u16* Bt, int ldb, int K, int m0, int n0, const Epi& ea, char* smem) {
;     ...
;       const u16* G = (const u16*)ea.p1 + (EPI == EP_MERGE2 ? 1024 : 0);
;       u16 gv[4][4][4], cv[4][4][4];
; #pragma unroll
;       for (int m = 0; m < 4; m++)
; #pragma unroll
;         for (int j = 0; j < 4; j++)
; #pragma unroll
;           for (int n = 0; n < 4; n++) {
;             gv[m][j][n] = G[(size_t)(rbase + m * 16 + j) * 2048 + cbase + n * 16];
;             if (EPI == EP_MERGE2) cv[m][j][n] = C[(size_t)(rbase + m * 16 + j) * 1024 + cbase + n * 16];
;           }
;       __builtin_amdgcn_sched_barrier(0);
; #pragma unroll
;       for (int m = 0; m < 4; m++)
; #pragma unroll
;         for (int j = 0; j < 4; j++)
; #pragma unroll
;           for (int n = 0; n < 4; n++) {
;             float v = bf2f(gv[m][j][n]) * acc[m][n][j];
;             if (EPI == EP_MERGE2) v += bf2f(cv[m][j][n]);
;             C[(size_t)(rbase + m * 16 + j) * 1024 + cbase + n * 16] = f2bf(v);
	global_load_ushort v0, v[76:77], off
	global_load_ushort v132, v[76:77], off offset:32
	global_load_ushort v133, v[76:77], off offset:64
	s_nop 0
	global_load_ushort v76, v[76:77], off offset:96
	s_nop 0
	global_load_ushort v77, v[80:81], off
	global_load_ushort v134, v[80:81], off offset:32
	global_load_ushort v135, v[80:81], off offset:64
	s_nop 0
	global_load_ushort v80, v[80:81], off offset:96
	s_nop 0
	global_load_ushort v81, v[84:85], off
	global_load_ushort v136, v[84:85], off offset:32
	global_load_ushort v137, v[84:85], off offset:64
	s_nop 0
	global_load_ushort v84, v[84:85], off offset:96
	s_nop 0
	global_load_ushort v85, v[88:89], off
	global_load_ushort v138, v[88:89], off offset:32
	global_load_ushort v139, v[88:89], off offset:64
	s_nop 0
	global_load_ushort v88, v[88:89], off offset:96
	s_nop 0
	global_load_ushort v89, v[92:93], off
	global_load_ushort v140, v[92:93], off offset:32
	global_load_ushort v141, v[92:93], off offset:64
	s_nop 0
	global_load_ushort v92, v[92:93], off offset:96
	s_nop 0
	global_load_ushort v93, v[96:97], off
	global_load_ushort v142, v[96:97], off offset:32
	global_load_ushort v143, v[96:97], off offset:64
	s_nop 0
	global_load_ushort v96, v[96:97], off offset:96
	s_nop 0
	global_load_ushort v97, v[100:101], off
	global_load_ushort v144, v[100:101], off offset:32
	global_load_ushort v145, v[100:101], off offset:64
	s_nop 0
	global_load_ushort v100, v[100:101], off offset:96
	s_nop 0
	global_load_ushort v101, v[104:105], off
	global_load_ushort v146, v[104:105], off offset:32
	global_load_ushort v147, v[104:105], off offset:64
	s_nop 0
	global_load_ushort v104, v[104:105], off offset:96
	s_nop 0
	global_load_ushort v105, v[106:107], off
	global_load_ushort v148, v[106:107], off offset:32
	global_load_ushort v149, v[106:107], off offset:64
	s_nop 0
	global_load_ushort v106, v[106:107], off offset:96
	s_nop 0
	global_load_ushort v107, v[108:109], off
	global_load_ushort v150, v[108:109], off offset:32
	global_load_ushort v151, v[108:109], off offset:64
	s_nop 0
	global_load_ushort v108, v[108:109], off offset:96
	s_nop 0
	global_load_ushort v109, v[110:111], off
	global_load_ushort v152, v[110:111], off offset:32
	global_load_ushort v153, v[110:111], off offset:64
	s_nop 0
	global_load_ushort v110, v[110:111], off offset:96
	s_nop 0
	global_load_ushort v111, v[112:113], off
	global_load_ushort v161, v[112:113], off offset:32
	global_load_ushort v162, v[112:113], off offset:64
	s_nop 0
	global_load_ushort v112, v[112:113], off offset:96
	s_nop 0
	global_load_ushort v113, v[114:115], off
	global_load_ushort v163, v[114:115], off offset:32
	global_load_ushort v164, v[114:115], off offset:64
	s_nop 0
	global_load_ushort v114, v[114:115], off offset:96
	s_nop 0
	global_load_ushort v115, v[116:117], off
	global_load_ushort v165, v[116:117], off offset:32
	global_load_ushort v166, v[116:117], off offset:64
	s_nop 0
	global_load_ushort v116, v[116:117], off offset:96
	s_nop 0
	global_load_ushort v117, v[130:131], off
	global_load_ushort v167, v[130:131], off offset:32
	global_load_ushort v168, v[130:131], off offset:64
	s_nop 0
	global_load_ushort v130, v[130:131], off offset:96
	s_nop 0
	global_load_ushort v131, v[74:75], off
	global_load_ushort v169, v[74:75], off offset:32
	global_load_ushort v170, v[74:75], off offset:64
	s_nop 0
	global_load_ushort v74, v[74:75], off offset:96
	s_waitcnt vmcnt(62)
	v_lshlrev_b32_e32 v0, 16, v0
	v_lshl_add_u64 v[66:67], s[2:3], 0, v[66:67]
	v_lshlrev_b64 v[72:73], 11, v[72:73]
	v_mul_f32_e32 v0, v118, v0
	v_lshl_add_u64 v[72:73], v[66:67], 0, v[72:73]
	v_cvt_pk_bf16_f32 v0, v0, s0
	global_store_short v[72:73], v0, off
	v_lshlrev_b32_e32 v0, 16, v132
	v_mul_f32_e32 v0, v122, v0
	v_cvt_pk_bf16_f32 v0, v0, s0
	global_store_short v[72:73], v0, off offset:32
	s_waitcnt vmcnt(62)
	v_lshlrev_b32_e32 v0, 16, v133
	v_mul_f32_e32 v0, v126, v0
	v_cvt_pk_bf16_f32 v0, v0, s0
	global_store_short v[72:73], v0, off offset:64
	v_lshlrev_b32_e32 v0, 16, v76
	v_mul_f32_e32 v0, v50, v0
	v_cvt_pk_bf16_f32 v0, v0, s0
	global_store_short v[72:73], v0, off offset:96
	s_waitcnt vmcnt(62)
	v_lshlrev_b32_e32 v0, 16, v77
	v_lshlrev_b64 v[72:73], 11, v[78:79]
	v_mul_f32_e32 v0, v119, v0
	v_lshl_add_u64 v[72:73], v[66:67], 0, v[72:73]
	v_cvt_pk_bf16_f32 v0, v0, s0
	global_store_short v[72:73], v0, off
	v_lshlrev_b32_e32 v0, 16, v134
	v_mul_f32_e32 v0, v123, v0
	v_cvt_pk_bf16_f32 v0, v0, s0
	global_store_short v[72:73], v0, off offset:32
	s_waitcnt vmcnt(62)
	v_lshlrev_b32_e32 v0, 16, v135
	v_mul_f32_e32 v0, v127, v0
	v_cvt_pk_bf16_f32 v0, v0, s0
	global_store_short v[72:73], v0, off offset:64
	v_lshlrev_b32_e32 v0, 16, v80
	v_mul_f32_e32 v0, v51, v0
	v_cvt_pk_bf16_f32 v0, v0, s0
	global_store_short v[72:73], v0, off offset:96
	s_waitcnt vmcnt(62)
	v_lshlrev_b32_e32 v0, 16, v81
	v_lshlrev_b64 v[50:51], 11, v[82:83]
	v_mul_f32_e32 v0, v120, v0
	v_lshl_add_u64 v[50:51], v[66:67], 0, v[50:51]
	v_cvt_pk_bf16_f32 v0, v0, s0
	global_store_short v[50:51], v0, off
	v_lshlrev_b32_e32 v0, 16, v136
	v_mul_f32_e32 v0, v124, v0
	v_cvt_pk_bf16_f32 v0, v0, s0
	global_store_short v[50:51], v0, off offset:32
	s_waitcnt vmcnt(62)
	v_lshlrev_b32_e32 v0, 16, v137
	v_mul_f32_e32 v0, v128, v0
	v_cvt_pk_bf16_f32 v0, v0, s0
	global_store_short v[50:51], v0, off offset:64
	v_lshlrev_b32_e32 v0, 16, v84
	v_mul_f32_e32 v0, v52, v0
	v_cvt_pk_bf16_f32 v0, v0, s0
	global_store_short v[50:51], v0, off offset:96
	s_waitcnt vmcnt(62)
	v_lshlrev_b32_e32 v0, 16, v85
	v_lshlrev_b64 v[50:51], 11, v[86:87]
	v_mul_f32_e32 v0, v121, v0
	v_lshl_add_u64 v[50:51], v[66:67], 0, v[50:51]
	v_cvt_pk_bf16_f32 v0, v0, s0
	global_store_short v[50:51], v0, off
	v_lshlrev_b32_e32 v0, 16, v138
	v_mul_f32_e32 v0, v125, v0
	v_cvt_pk_bf16_f32 v0, v0, s0
	global_store_short v[50:51], v0, off offset:32
	s_waitcnt vmcnt(62)
; DEV float bf2f(u16 h) { return __uint_as_float(((unsigned)h) << 16); }
; template <int EPI, bool AF32>
; DEV void gemm_tile(const void* Ap, int lda, const u16* Bt, int ldb, int K, int m0, int n0, const Epi& ea, char* smem) {
;     ...
; #pragma unroll
;       for (int m = 0; m < 4; m++)
; #pragma unroll
;         for (int j = 0; j < 4; j++)
; #pragma unroll
;           for (int n = 0; n < 4; n++) {
;             float v = bf2f(gv[m][j][n]) * acc[m][n][j];
;             if (EPI == EP_MERGE2) v += bf2f(cv[m][j][n]);
;             C[(size_t)(rbase + m * 16 + j) * 1024 + cbase + n * 16] = f2bf(v);
	v_lshlrev_b32_e32 v0, 16, v139
	v_mul_f32_e32 v0, v129, v0
	v_cvt_pk_bf16_f32 v0, v0, s0
	global_store_short v[50:51], v0, off offset:64
	v_lshlrev_b32_e32 v0, 16, v88
	v_mul_f32_e32 v0, v53, v0
	v_cvt_pk_bf16_f32 v0, v0, s0
	global_store_short v[50:51], v0, off offset:96
	s_waitcnt vmcnt(62)
	v_lshlrev_b32_e32 v0, 16, v89
	v_lshlrev_b64 v[50:51], 11, v[90:91]
	v_mul_f32_e32 v0, v46, v0
	v_lshl_add_u64 v[50:51], v[66:67], 0, v[50:51]
	v_cvt_pk_bf16_f32 v0, v0, s0
	global_store_short v[50:51], v0, off
	v_lshlrev_b32_e32 v0, 16, v140
	v_mul_f32_e32 v0, v42, v0
	v_cvt_pk_bf16_f32 v0, v0, s0
	global_store_short v[50:51], v0, off offset:32
	s_waitcnt vmcnt(62)
	v_lshlrev_b32_e32 v0, 16, v141
	v_mul_f32_e32 v0, v38, v0
	v_cvt_pk_bf16_f32 v0, v0, s0
	global_store_short v[50:51], v0, off offset:64
	v_lshlrev_b32_e32 v0, 16, v92
	v_mul_f32_e32 v0, v34, v0
	v_cvt_pk_bf16_f32 v0, v0, s0
	global_store_short v[50:51], v0, off offset:96
	s_waitcnt vmcnt(62)
	v_lshlrev_b32_e32 v0, 16, v93
	v_lshlrev_b64 v[50:51], 11, v[94:95]
	v_mul_f32_e32 v0, v47, v0
	v_lshl_add_u64 v[50:51], v[66:67], 0, v[50:51]
	v_cvt_pk_bf16_f32 v0, v0, s0
	global_store_short v[50:51], v0, off
	v_lshlrev_b32_e32 v0, 16, v142
	v_mul_f32_e32 v0, v43, v0
	v_cvt_pk_bf16_f32 v0, v0, s0
	global_store_short v[50:51], v0, off offset:32
	s_waitcnt vmcnt(62)
	v_lshlrev_b32_e32 v0, 16, v143
	v_mul_f32_e32 v0, v39, v0
	v_cvt_pk_bf16_f32 v0, v0, s0
	global_store_short v[50:51], v0, off offset:64
	v_lshlrev_b32_e32 v0, 16, v96
	v_mul_f32_e32 v0, v35, v0
	v_cvt_pk_bf16_f32 v0, v0, s0
	global_store_short v[50:51], v0, off offset:96
	s_waitcnt vmcnt(62)
	v_lshlrev_b32_e32 v0, 16, v97
	v_lshlrev_b64 v[34:35], 11, v[98:99]
	v_mul_f32_e32 v0, v48, v0
	v_lshl_add_u64 v[34:35], v[66:67], 0, v[34:35]
	v_cvt_pk_bf16_f32 v0, v0, s0
	global_store_short v[34:35], v0, off
	v_lshlrev_b32_e32 v0, 16, v144
	v_mul_f32_e32 v0, v44, v0
	v_cvt_pk_bf16_f32 v0, v0, s0
	global_store_short v[34:35], v0, off offset:32
	s_waitcnt vmcnt(62)
	v_lshlrev_b32_e32 v0, 16, v145
	v_mul_f32_e32 v0, v40, v0
	v_cvt_pk_bf16_f32 v0, v0, s0
	global_store_short v[34:35], v0, off offset:64
	v_lshlrev_b32_e32 v0, 16, v100
	v_mul_f32_e32 v0, v36, v0
	v_cvt_pk_bf16_f32 v0, v0, s0
	global_store_short v[34:35], v0, off offset:96
	s_waitcnt vmcnt(62)
	v_lshlrev_b32_e32 v0, 16, v101
	v_lshlrev_b64 v[34:35], 11, v[102:103]
	v_mul_f32_e32 v0, v49, v0
	v_lshl_add_u64 v[34:35], v[66:67], 0, v[34:35]
	v_cvt_pk_bf16_f32 v0, v0, s0
	global_store_short v[34:35], v0, off
	v_lshlrev_b32_e32 v0, 16, v146
	v_mul_f32_e32 v0, v45, v0
	v_cvt_pk_bf16_f32 v0, v0, s0
	global_store_short v[34:35], v0, off offset:32
	s_waitcnt vmcnt(62)
	v_lshlrev_b32_e32 v0, 16, v147
	v_mul_f32_e32 v0, v41, v0
	v_cvt_pk_bf16_f32 v0, v0, s0
	global_store_short v[34:35], v0, off offset:64
	v_lshlrev_b32_e32 v0, 16, v104
	v_mul_f32_e32 v0, v37, v0
	v_cvt_pk_bf16_f32 v0, v0, s0
	global_store_short v[34:35], v0, off offset:96
	s_waitcnt vmcnt(62)
	v_lshlrev_b32_e32 v0, 16, v105
	v_lshlrev_b64 v[34:35], 11, v[70:71]
	v_mul_f32_e32 v0, v30, v0
	v_lshl_add_u64 v[34:35], v[66:67], 0, v[34:35]
	v_cvt_pk_bf16_f32 v0, v0, s0
	global_store_short v[34:35], v0, off
	v_lshlrev_b32_e32 v0, 16, v148
	v_mul_f32_e32 v0, v26, v0
	v_cvt_pk_bf16_f32 v0, v0, s0
	global_store_short v[34:35], v0, off offset:32
	s_waitcnt vmcnt(62)
	v_lshlrev_b32_e32 v0, 16, v149
	v_mul_f32_e32 v0, v22, v0
	v_cvt_pk_bf16_f32 v0, v0, s0
	global_store_short v[34:35], v0, off offset:64
	v_lshlrev_b32_e32 v0, 16, v106
	v_mul_f32_e32 v0, v18, v0
	v_cvt_pk_bf16_f32 v0, v0, s0
	global_store_short v[34:35], v0, off offset:96
	s_waitcnt vmcnt(62)
	v_lshlrev_b32_e32 v0, 16, v107
	v_lshlrev_b64 v[34:35], 11, v[68:69]
	v_mul_f32_e32 v0, v31, v0
	v_lshl_add_u64 v[34:35], v[66:67], 0, v[34:35]
	v_cvt_pk_bf16_f32 v0, v0, s0
	global_store_short v[34:35], v0, off
	v_lshlrev_b32_e32 v0, 16, v150
	v_mul_f32_e32 v0, v27, v0
	v_cvt_pk_bf16_f32 v0, v0, s0
	global_store_short v[34:35], v0, off offset:32
	s_waitcnt vmcnt(62)
	v_lshlrev_b32_e32 v0, 16, v151
	v_mul_f32_e32 v0, v23, v0
	v_cvt_pk_bf16_f32 v0, v0, s0
	global_store_short v[34:35], v0, off offset:64
	v_lshlrev_b32_e32 v0, 16, v108
	v_mul_f32_e32 v0, v19, v0
	v_cvt_pk_bf16_f32 v0, v0, s0
	global_store_short v[34:35], v0, off offset:96
	s_waitcnt vmcnt(62)
; DEV int bidx() { int b = __builtin_amdgcn_readfirstlane(blockIdx.x); asm volatile("" : "+s"(b)); return b; }
; DEV int gdim() { int g = __builtin_amdgcn_readfirstlane(gridDim.x); asm volatile("" : "+s"(g)); return g; }
; DEV float bf2f(u16 h) { return __uint_as_float(((unsigned)h) << 16); }
; template <int EPI, bool AF32>
; DEV void gemm_tile(const void* Ap, int lda, const u16* Bt, int ldb, int K, int m0, int n0, const Epi& ea, char* smem) {
;     ...
; #pragma unroll
;       for (int m = 0; m < 4; m++)
; #pragma unroll
;         for (int j = 0; j < 4; j++)
; #pragma unroll
;           for (int n = 0; n < 4; n++) {
;             float v = bf2f(gv[m][j][n]) * acc[m][n][j];
;             if (EPI == EP_MERGE2) v += bf2f(cv[m][j][n]);
;             C[(size_t)(rbase + m * 16 + j) * 1024 + cbase + n * 16] = f2bf(v);
; template <int EPI, bool AF32>
; DEV void gemm_phase(const void* A, int lda, const u16* Bt, int ldb, int M, int N, int K, const Epi& ea, char* smem) {
;     ...
;   for (int tile = bidx(); tile < ntm * ntn; tile += gdim()) {
;     int m, n;
;     tile_mn(tile, ntm, ntn, m, n);
	v_lshlrev_b32_e32 v0, 16, v109
	v_lshlrev_b64 v[18:19], 11, v[64:65]
	v_mul_f32_e32 v0, v32, v0
	v_lshl_add_u64 v[18:19], v[66:67], 0, v[18:19]
	v_cvt_pk_bf16_f32 v0, v0, s0
	global_store_short v[18:19], v0, off
	v_lshlrev_b32_e32 v0, 16, v152
	v_mul_f32_e32 v0, v28, v0
	v_cvt_pk_bf16_f32 v0, v0, s0
	global_store_short v[18:19], v0, off offset:32
	s_waitcnt vmcnt(62)
	v_lshlrev_b32_e32 v0, 16, v153
	v_mul_f32_e32 v0, v24, v0
	v_cvt_pk_bf16_f32 v0, v0, s0
	global_store_short v[18:19], v0, off offset:64
	v_lshlrev_b32_e32 v0, 16, v110
	v_mul_f32_e32 v0, v20, v0
	v_cvt_pk_bf16_f32 v0, v0, s0
	global_store_short v[18:19], v0, off offset:96
	s_waitcnt vmcnt(62)
	v_lshlrev_b32_e32 v0, 16, v111
	v_lshlrev_b64 v[18:19], 11, v[62:63]
	v_mul_f32_e32 v0, v33, v0
	v_lshl_add_u64 v[18:19], v[66:67], 0, v[18:19]
	v_cvt_pk_bf16_f32 v0, v0, s0
	global_store_short v[18:19], v0, off
	v_lshlrev_b32_e32 v0, 16, v161
	v_mul_f32_e32 v0, v29, v0
	v_cvt_pk_bf16_f32 v0, v0, s0
	global_store_short v[18:19], v0, off offset:32
	s_waitcnt vmcnt(62)
	v_lshlrev_b32_e32 v0, 16, v162
	v_mul_f32_e32 v0, v25, v0
	v_cvt_pk_bf16_f32 v0, v0, s0
	global_store_short v[18:19], v0, off offset:64
	v_lshlrev_b32_e32 v0, 16, v112
	v_mul_f32_e32 v0, v21, v0
	v_cvt_pk_bf16_f32 v0, v0, s0
	global_store_short v[18:19], v0, off offset:96
	s_waitcnt vmcnt(62)
	v_lshlrev_b32_e32 v0, 16, v113
	v_lshlrev_b64 v[18:19], 11, v[60:61]
	v_mul_f32_e32 v0, v14, v0
	v_lshl_add_u64 v[18:19], v[66:67], 0, v[18:19]
	v_cvt_pk_bf16_f32 v0, v0, s0
	global_store_short v[18:19], v0, off
	v_lshlrev_b32_e32 v0, 16, v163
	v_mul_f32_e32 v0, v10, v0
	v_cvt_pk_bf16_f32 v0, v0, s0
	global_store_short v[18:19], v0, off offset:32
	s_waitcnt vmcnt(62)
	v_lshlrev_b32_e32 v0, 16, v164
	v_mul_f32_e32 v0, v6, v0
	v_cvt_pk_bf16_f32 v0, v0, s0
	global_store_short v[18:19], v0, off offset:64
	v_lshlrev_b32_e32 v0, 16, v114
	v_mul_f32_e32 v0, v2, v0
	v_cvt_pk_bf16_f32 v0, v0, s0
	global_store_short v[18:19], v0, off offset:96
	s_waitcnt vmcnt(62)
	v_lshlrev_b32_e32 v0, 16, v115
	v_lshlrev_b64 v[18:19], 11, v[58:59]
	v_mul_f32_e32 v0, v15, v0
	v_lshl_add_u64 v[18:19], v[66:67], 0, v[18:19]
	v_cvt_pk_bf16_f32 v0, v0, s0
	global_store_short v[18:19], v0, off
	v_lshlrev_b32_e32 v0, 16, v165
	v_mul_f32_e32 v0, v11, v0
	v_cvt_pk_bf16_f32 v0, v0, s0
	global_store_short v[18:19], v0, off offset:32
	s_waitcnt vmcnt(62)
	v_lshlrev_b32_e32 v0, 16, v166
	v_mul_f32_e32 v0, v7, v0
	v_cvt_pk_bf16_f32 v0, v0, s0
	global_store_short v[18:19], v0, off offset:64
	v_lshlrev_b32_e32 v0, 16, v116
	v_mul_f32_e32 v0, v3, v0
	v_cvt_pk_bf16_f32 v0, v0, s0
	global_store_short v[18:19], v0, off offset:96
	s_waitcnt vmcnt(62)
	v_lshlrev_b32_e32 v0, 16, v117
	v_lshlrev_b64 v[2:3], 11, v[56:57]
	v_mul_f32_e32 v0, v16, v0
	v_lshl_add_u64 v[2:3], v[66:67], 0, v[2:3]
	v_cvt_pk_bf16_f32 v0, v0, s0
	global_store_short v[2:3], v0, off
	v_lshlrev_b32_e32 v0, 16, v167
	v_mul_f32_e32 v0, v12, v0
	v_cvt_pk_bf16_f32 v0, v0, s0
	global_store_short v[2:3], v0, off offset:32
	s_waitcnt vmcnt(62)
	v_lshlrev_b32_e32 v0, 16, v168
	v_mul_f32_e32 v0, v8, v0
	v_cvt_pk_bf16_f32 v0, v0, s0
	global_store_short v[2:3], v0, off offset:64
	v_lshlrev_b32_e32 v0, 16, v130
	v_mul_f32_e32 v0, v4, v0
	v_cvt_pk_bf16_f32 v0, v0, s0
	global_store_short v[2:3], v0, off offset:96
	s_waitcnt vmcnt(62)
	v_lshlrev_b32_e32 v0, 16, v131
	v_lshlrev_b64 v[2:3], 11, v[54:55]
	v_mul_f32_e32 v0, v17, v0
	v_lshl_add_u64 v[2:3], v[66:67], 0, v[2:3]
	v_cvt_pk_bf16_f32 v0, v0, s0
	global_store_short v[2:3], v0, off
	v_lshlrev_b32_e32 v0, 16, v169
	v_mul_f32_e32 v0, v13, v0
	v_cvt_pk_bf16_f32 v0, v0, s0
	global_store_short v[2:3], v0, off offset:32
	s_waitcnt vmcnt(62)
	v_lshlrev_b32_e32 v0, 16, v170
	v_mul_f32_e32 v0, v9, v0
	v_cvt_pk_bf16_f32 v0, v0, s0
	global_store_short v[2:3], v0, off offset:64
	v_lshlrev_b32_e32 v0, 16, v74
	v_mul_f32_e32 v0, v5, v0
	v_cvt_pk_bf16_f32 v0, v0, s0
	v_readfirstlane_b32 s0, v198
	global_store_short v[2:3], v0, off offset:96
	s_add_i32 s16, s0, s16
	s_cmpk_lt_i32 s16, 0x820
	s_cbranch_scc1 .LBB0_1304

; DEV f32x4 mfma16(bf16x8 a, bf16x8 b, f32x4 c) { return __builtin_amdgcn_mfma_f32_16x16x32_bf16(a, b, c, 0, 0, 0); }
; template <int EPI, bool AF32>
; DEV void gemm_tile(const void* Ap, int lda, const u16* Bt, int ldb, int K, int m0, int n0, const Epi& ea, char* smem) {
;     ...
;   gload(0);
;   swrite(0);
;   if (nk > 1) gload(1);
;   __syncthreads();
;   for (int kt = 0; kt < nk; kt++) {
;     const int buf = kt & 1;
;     if (kt + 1 < nk) swrite(buf ^ 1);
;     if (kt + 2 < nk) gload(kt + 2);
; #pragma unroll
;     for (int ks = 0; ks < 2; ks++) {
;       bf16x8 a[4], b[4];
; #pragma unroll
;       for (int m = 0; m < 4; m++) a[m] = *(const bf16x8*)(sA + buf * 9216 + (wr * 64 + m * 16 + fr) * 72 + ks * 32 + fq * 8);
; #pragma unroll
;       for (int n = 0; n < 4; n++) b[n] = *(const bf16x8*)(sB + buf * 9216 + (wc * 64 + n * 16 + fr) * 72 + ks * 32 + fq * 8);
;       __builtin_amdgcn_s_setprio(1);
; #pragma unroll
;       for (int m = 0; m < 4; m++)
; #pragma unroll
;         for (int n = 0; n < 4; n++) acc[m][n] = mfma16(a[m], b[n], acc[m][n]);
;       __builtin_amdgcn_s_setprio(0);
;     }
;     __syncthreads();
;   }
.Lgk4_loop:
	s_waitcnt lgkmcnt(0)
	ds_read_b128 v[222:225], v161 offset:64
	ds_read_b128 v[226:229], v161 offset:2368
	ds_read_b128 v[230:233], v161 offset:4672
	ds_read_b128 v[234:237], v161 offset:6976
	ds_read_b128 v[238:241], v129 offset:36928
	ds_read_b128 v[242:245], v129 offset:39232
	ds_read_b128 v[246:249], v129 offset:41536
	ds_read_b128 v[250:253], v129 offset:43840
	v_mfma_f32_16x16x32_bf16 v[34:37], v[130:133], v[146:149], v[34:37]
	v_mfma_f32_16x16x32_bf16 v[38:41], v[130:133], v[150:153], v[38:41]
	v_mfma_f32_16x16x32_bf16 v[42:45], v[130:133], v[162:165], v[42:45]
	v_mfma_f32_16x16x32_bf16 v[46:49], v[130:133], v[166:169], v[46:49]
	s_waitcnt vmcnt(0)
	ds_write_b128 v122, v[22:25] offset:18432
	ds_write_b128 v122, v[6:9] offset:55296
	v_mfma_f32_16x16x32_bf16 v[50:53], v[134:137], v[146:149], v[50:53]
	ds_write_b128 v121, v[18:21] offset:18432
	ds_write_b128 v121, v[10:13] offset:55296
	v_mfma_f32_16x16x32_bf16 v[54:57], v[134:137], v[150:153], v[54:57]
	ds_write_b128 v120, v[14:17] offset:18432
	ds_write_b128 v120, v[2:5] offset:55296
	v_mfma_f32_16x16x32_bf16 v[58:61], v[134:137], v[162:165], v[58:61]
	ds_write_b128 v124, v[26:29] offset:18432
	ds_write_b128 v124, v[30:33] offset:55296
	v_mfma_f32_16x16x32_bf16 v[62:65], v[134:137], v[166:169], v[62:65]
	global_load_dwordx4 v[22:25], v[112:113], off
	v_mfma_f32_16x16x32_bf16 v[66:69], v[138:141], v[146:149], v[66:69]
	global_load_dwordx4 v[6:9], v[110:111], off
	v_mfma_f32_16x16x32_bf16 v[70:73], v[138:141], v[150:153], v[70:73]
	global_load_dwordx4 v[18:21], v[108:109], off
	v_mfma_f32_16x16x32_bf16 v[74:77], v[138:141], v[162:165], v[74:77]
	global_load_dwordx4 v[10:13], v[106:107], off
	v_mfma_f32_16x16x32_bf16 v[78:81], v[138:141], v[166:169], v[78:81]
	global_load_dwordx4 v[14:17], v[104:105], off
	v_mfma_f32_16x16x32_bf16 v[82:85], v[142:145], v[146:149], v[82:85]
	global_load_dwordx4 v[2:5], v[102:103], off
	v_mfma_f32_16x16x32_bf16 v[86:89], v[142:145], v[150:153], v[86:89]
	global_load_dwordx4 v[26:29], v[100:101], off
	v_mfma_f32_16x16x32_bf16 v[90:93], v[142:145], v[162:165], v[90:93]
	global_load_dwordx4 v[30:33], v[98:99], off
	v_mfma_f32_16x16x32_bf16 v[94:97], v[142:145], v[166:169], v[94:97]
	s_waitcnt lgkmcnt(0)
	s_barrier
	ds_read_b128 v[130:133], v161 offset:18432
	v_mfma_f32_16x16x32_bf16 v[34:37], v[222:225], v[238:241], v[34:37]
	ds_read_b128 v[134:137], v161 offset:20736
	v_mfma_f32_16x16x32_bf16 v[38:41], v[222:225], v[242:245], v[38:41]
	ds_read_b128 v[138:141], v161 offset:23040
	v_mfma_f32_16x16x32_bf16 v[42:45], v[222:225], v[246:249], v[42:45]
	ds_read_b128 v[142:145], v161 offset:25344
	v_mfma_f32_16x16x32_bf16 v[46:49], v[222:225], v[250:253], v[46:49]
	ds_read_b128 v[146:149], v129 offset:55296
	v_mfma_f32_16x16x32_bf16 v[50:53], v[226:229], v[238:241], v[50:53]
	ds_read_b128 v[150:153], v129 offset:57600
	v_mfma_f32_16x16x32_bf16 v[54:57], v[226:229], v[242:245], v[54:57]
	ds_read_b128 v[162:165], v129 offset:59904
	v_mfma_f32_16x16x32_bf16 v[58:61], v[226:229], v[246:249], v[58:61]
	ds_read_b128 v[166:169], v129 offset:62208
	v_mfma_f32_16x16x32_bf16 v[62:65], v[226:229], v[250:253], v[62:65]
	v_mfma_f32_16x16x32_bf16 v[66:69], v[230:233], v[238:241], v[66:69]
	v_mfma_f32_16x16x32_bf16 v[70:73], v[230:233], v[242:245], v[70:73]
	v_mfma_f32_16x16x32_bf16 v[74:77], v[230:233], v[246:249], v[74:77]
	v_mfma_f32_16x16x32_bf16 v[78:81], v[230:233], v[250:253], v[78:81]
	v_mfma_f32_16x16x32_bf16 v[82:85], v[234:237], v[238:241], v[82:85]
	v_mfma_f32_16x16x32_bf16 v[86:89], v[234:237], v[242:245], v[86:89]
	v_mfma_f32_16x16x32_bf16 v[90:93], v[234:237], v[246:249], v[90:93]
	v_mfma_f32_16x16x32_bf16 v[94:97], v[234:237], v[250:253], v[94:97]
	s_waitcnt lgkmcnt(0)
	ds_read_b128 v[222:225], v161 offset:18496
	ds_read_b128 v[226:229], v161 offset:20800
	ds_read_b128 v[230:233], v161 offset:23104
	ds_read_b128 v[234:237], v161 offset:25408
	ds_read_b128 v[238:241], v129 offset:55360
	ds_read_b128 v[242:245], v129 offset:57664
	ds_read_b128 v[246:249], v129 offset:59968
	ds_read_b128 v[250:253], v129 offset:62272
	v_mfma_f32_16x16x32_bf16 v[34:37], v[130:133], v[146:149], v[34:37]
	v_mfma_f32_16x16x32_bf16 v[38:41], v[130:133], v[150:153], v[38:41]
	v_mfma_f32_16x16x32_bf16 v[42:45], v[130:133], v[162:165], v[42:45]
	v_mfma_f32_16x16x32_bf16 v[46:49], v[130:133], v[166:169], v[46:49]
	s_waitcnt vmcnt(0)
	ds_write_b128 v122, v[22:25]
	ds_write_b128 v122, v[6:9] offset:36864
	v_mfma_f32_16x16x32_bf16 v[50:53], v[134:137], v[146:149], v[50:53]
	ds_write_b128 v121, v[18:21]
	ds_write_b128 v121, v[10:13] offset:36864
	v_mfma_f32_16x16x32_bf16 v[54:57], v[134:137], v[150:153], v[54:57]
	ds_write_b128 v120, v[14:17]
	ds_write_b128 v120, v[2:5] offset:36864
	v_mfma_f32_16x16x32_bf16 v[58:61], v[134:137], v[162:165], v[58:61]
	ds_write_b128 v124, v[26:29]
	ds_write_b128 v124, v[30:33] offset:36864
	v_mfma_f32_16x16x32_bf16 v[62:65], v[134:137], v[166:169], v[62:65]
	global_load_dwordx4 v[22:25], v[112:113], off offset:128
	v_mfma_f32_16x16x32_bf16 v[66:69], v[138:141], v[146:149], v[66:69]
	global_load_dwordx4 v[6:9], v[110:111], off offset:128
	v_mfma_f32_16x16x32_bf16 v[70:73], v[138:141], v[150:153], v[70:73]
	global_load_dwordx4 v[18:21], v[108:109], off offset:128
	v_mfma_f32_16x16x32_bf16 v[74:77], v[138:141], v[162:165], v[74:77]
	global_load_dwordx4 v[10:13], v[106:107], off offset:128
	v_mfma_f32_16x16x32_bf16 v[78:81], v[138:141], v[166:169], v[78:81]
	global_load_dwordx4 v[14:17], v[104:105], off offset:128
	v_mfma_f32_16x16x32_bf16 v[82:85], v[142:145], v[146:149], v[82:85]
	global_load_dwordx4 v[2:5], v[102:103], off offset:128
	v_mfma_f32_16x16x32_bf16 v[86:89], v[142:145], v[150:153], v[86:89]
	global_load_dwordx4 v[26:29], v[100:101], off offset:128
	v_mfma_f32_16x16x32_bf16 v[90:93], v[142:145], v[162:165], v[90:93]
	global_load_dwordx4 v[30:33], v[98:99], off offset:128
	v_mfma_f32_16x16x32_bf16 v[94:97], v[142:145], v[166:169], v[94:97]
	s_waitcnt lgkmcnt(0)
	s_barrier
; DEV f32x4 mfma16(bf16x8 a, bf16x8 b, f32x4 c) { return __builtin_amdgcn_mfma_f32_16x16x32_bf16(a, b, c, 0, 0, 0); }
; template <int EPI, bool AF32>
; DEV void gemm_tile(const void* Ap, int lda, const u16* Bt, int ldb, int K, int m0, int n0, const Epi& ea, char* smem) {
;     ...
;   for (int kt = 0; kt < nk; kt++) {
;     const int buf = kt & 1;
;     if (kt + 1 < nk) swrite(buf ^ 1);
;     if (kt + 2 < nk) gload(kt + 2);
; #pragma unroll
;     for (int ks = 0; ks < 2; ks++) {
;       bf16x8 a[4], b[4];
; #pragma unroll
;       for (int m = 0; m < 4; m++) a[m] = *(const bf16x8*)(sA + buf * 9216 + (wr * 64 + m * 16 + fr) * 72 + ks * 32 + fq * 8);
; #pragma unroll
;       for (int n = 0; n < 4; n++) b[n] = *(const bf16x8*)(sB + buf * 9216 + (wc * 64 + n * 16 + fr) * 72 + ks * 32 + fq * 8);
;       __builtin_amdgcn_s_setprio(1);
; #pragma unroll
;       for (int m = 0; m < 4; m++)
; #pragma unroll
;         for (int n = 0; n < 4; n++) acc[m][n] = mfma16(a[m], b[n], acc[m][n]);
;       __builtin_amdgcn_s_setprio(0);
;     }
;     __syncthreads();
	ds_read_b128 v[130:133], v161
	v_mfma_f32_16x16x32_bf16 v[34:37], v[222:225], v[238:241], v[34:37]
	ds_read_b128 v[134:137], v161 offset:2304
	v_mfma_f32_16x16x32_bf16 v[38:41], v[222:225], v[242:245], v[38:41]
	ds_read_b128 v[138:141], v161 offset:4608
	v_mfma_f32_16x16x32_bf16 v[42:45], v[222:225], v[246:249], v[42:45]
	ds_read_b128 v[142:145], v161 offset:6912
	v_mfma_f32_16x16x32_bf16 v[46:49], v[222:225], v[250:253], v[46:49]
	ds_read_b128 v[146:149], v129 offset:36864
	v_mfma_f32_16x16x32_bf16 v[50:53], v[226:229], v[238:241], v[50:53]
	ds_read_b128 v[150:153], v129 offset:39168
	v_mfma_f32_16x16x32_bf16 v[54:57], v[226:229], v[242:245], v[54:57]
	ds_read_b128 v[162:165], v129 offset:41472
	v_mfma_f32_16x16x32_bf16 v[58:61], v[226:229], v[246:249], v[58:61]
	ds_read_b128 v[166:169], v129 offset:43776
	v_mfma_f32_16x16x32_bf16 v[62:65], v[226:229], v[250:253], v[62:65]
	v_mfma_f32_16x16x32_bf16 v[66:69], v[230:233], v[238:241], v[66:69]
	v_lshl_add_u64 v[112:113], v[112:113], 0, s[0:1]
	v_mfma_f32_16x16x32_bf16 v[70:73], v[230:233], v[242:245], v[70:73]
	v_lshl_add_u64 v[110:111], v[110:111], 0, s[0:1]
	v_mfma_f32_16x16x32_bf16 v[74:77], v[230:233], v[246:249], v[74:77]
	v_lshl_add_u64 v[108:109], v[108:109], 0, s[0:1]
	v_mfma_f32_16x16x32_bf16 v[78:81], v[230:233], v[250:253], v[78:81]
	v_lshl_add_u64 v[106:107], v[106:107], 0, s[0:1]
	v_mfma_f32_16x16x32_bf16 v[82:85], v[234:237], v[238:241], v[82:85]
	v_lshl_add_u64 v[104:105], v[104:105], 0, s[0:1]
	v_mfma_f32_16x16x32_bf16 v[86:89], v[234:237], v[242:245], v[86:89]
	v_lshl_add_u64 v[102:103], v[102:103], 0, s[0:1]
	v_mfma_f32_16x16x32_bf16 v[90:93], v[234:237], v[246:249], v[90:93]
	v_lshl_add_u64 v[100:101], v[100:101], 0, s[0:1]
	v_mfma_f32_16x16x32_bf16 v[94:97], v[234:237], v[250:253], v[94:97]
	v_lshl_add_u64 v[98:99], v[98:99], 0, s[0:1]
	s_add_i32 s17, s17, 1
	s_cmp_lg_u32 s17, 7
	s_cbranch_scc1 .Lgk4_loop
	s_waitcnt lgkmcnt(0)
	ds_read_b128 v[222:225], v161 offset:64
	ds_read_b128 v[226:229], v161 offset:2368
	ds_read_b128 v[230:233], v161 offset:4672
	ds_read_b128 v[234:237], v161 offset:6976
	ds_read_b128 v[238:241], v129 offset:36928
	ds_read_b128 v[242:245], v129 offset:39232
	ds_read_b128 v[246:249], v129 offset:41536
	ds_read_b128 v[250:253], v129 offset:43840
	v_mfma_f32_16x16x32_bf16 v[34:37], v[130:133], v[146:149], v[34:37]
	v_mfma_f32_16x16x32_bf16 v[38:41], v[130:133], v[150:153], v[38:41]
	v_mfma_f32_16x16x32_bf16 v[42:45], v[130:133], v[162:165], v[42:45]
	v_mfma_f32_16x16x32_bf16 v[46:49], v[130:133], v[166:169], v[46:49]
	s_waitcnt vmcnt(0)
	ds_write_b128 v122, v[22:25] offset:18432
	ds_write_b128 v122, v[6:9] offset:55296
	v_mfma_f32_16x16x32_bf16 v[50:53], v[134:137], v[146:149], v[50:53]
	ds_write_b128 v121, v[18:21] offset:18432
	ds_write_b128 v121, v[10:13] offset:55296
	v_mfma_f32_16x16x32_bf16 v[54:57], v[134:137], v[150:153], v[54:57]
	ds_write_b128 v120, v[14:17] offset:18432
	ds_write_b128 v120, v[2:5] offset:55296
	v_mfma_f32_16x16x32_bf16 v[58:61], v[134:137], v[162:165], v[58:61]
	ds_write_b128 v124, v[26:29] offset:18432
	ds_write_b128 v124, v[30:33] offset:55296
	v_mfma_f32_16x16x32_bf16 v[62:65], v[134:137], v[166:169], v[62:65]
	v_mfma_f32_16x16x32_bf16 v[66:69], v[138:141], v[146:149], v[66:69]
	v_mfma_f32_16x16x32_bf16 v[70:73], v[138:141], v[150:153], v[70:73]
	v_mfma_f32_16x16x32_bf16 v[74:77], v[138:141], v[162:165], v[74:77]
	v_mfma_f32_16x16x32_bf16 v[78:81], v[138:141], v[166:169], v[78:81]
	v_mfma_f32_16x16x32_bf16 v[82:85], v[142:145], v[146:149], v[82:85]
	v_mfma_f32_16x16x32_bf16 v[86:89], v[142:145], v[150:153], v[86:89]
	v_mfma_f32_16x16x32_bf16 v[90:93], v[142:145], v[162:165], v[90:93]
	v_mfma_f32_16x16x32_bf16 v[94:97], v[142:145], v[166:169], v[94:97]
	s_waitcnt lgkmcnt(0)
	s_barrier
	ds_read_b128 v[130:133], v161 offset:18432
	v_mfma_f32_16x16x32_bf16 v[34:37], v[222:225], v[238:241], v[34:37]
	ds_read_b128 v[134:137], v161 offset:20736
	v_mfma_f32_16x16x32_bf16 v[38:41], v[222:225], v[242:245], v[38:41]
	ds_read_b128 v[138:141], v161 offset:23040
	v_mfma_f32_16x16x32_bf16 v[42:45], v[222:225], v[246:249], v[42:45]
	ds_read_b128 v[142:145], v161 offset:25344
	v_mfma_f32_16x16x32_bf16 v[46:49], v[222:225], v[250:253], v[46:49]
	ds_read_b128 v[146:149], v129 offset:55296
	v_mfma_f32_16x16x32_bf16 v[50:53], v[226:229], v[238:241], v[50:53]
	ds_read_b128 v[150:153], v129 offset:57600
	v_mfma_f32_16x16x32_bf16 v[54:57], v[226:229], v[242:245], v[54:57]
	ds_read_b128 v[162:165], v129 offset:59904
	v_mfma_f32_16x16x32_bf16 v[58:61], v[226:229], v[246:249], v[58:61]
	ds_read_b128 v[166:169], v129 offset:62208
	v_mfma_f32_16x16x32_bf16 v[62:65], v[226:229], v[250:253], v[62:65]
	v_mfma_f32_16x16x32_bf16 v[66:69], v[230:233], v[238:241], v[66:69]
	v_mfma_f32_16x16x32_bf16 v[70:73], v[230:233], v[242:245], v[70:73]
	v_mfma_f32_16x16x32_bf16 v[74:77], v[230:233], v[246:249], v[74:77]
	v_mfma_f32_16x16x32_bf16 v[78:81], v[230:233], v[250:253], v[78:81]
	v_mfma_f32_16x16x32_bf16 v[82:85], v[234:237], v[238:241], v[82:85]
	v_mfma_f32_16x16x32_bf16 v[86:89], v[234:237], v[242:245], v[86:89]
	v_mfma_f32_16x16x32_bf16 v[90:93], v[234:237], v[246:249], v[90:93]
	v_mfma_f32_16x16x32_bf16 v[94:97], v[234:237], v[250:253], v[94:97]
	s_waitcnt lgkmcnt(0)
; DEV f32x4 mfma16(bf16x8 a, bf16x8 b, f32x4 c) { return __builtin_amdgcn_mfma_f32_16x16x32_bf16(a, b, c, 0, 0, 0); }
; template <int EPI, bool AF32>
; DEV void gemm_tile(const void* Ap, int lda, const u16* Bt, int ldb, int K, int m0, int n0, const Epi& ea, char* smem) {
;     ...
;     for (int ks = 0; ks < 2; ks++) {
;       bf16x8 a[4], b[4];
; #pragma unroll
;       for (int m = 0; m < 4; m++) a[m] = *(const bf16x8*)(sA + buf * 9216 + (wr * 64 + m * 16 + fr) * 72 + ks * 32 + fq * 8);
; #pragma unroll
;       for (int n = 0; n < 4; n++) b[n] = *(const bf16x8*)(sB + buf * 9216 + (wc * 64 + n * 16 + fr) * 72 + ks * 32 + fq * 8);
;       __builtin_amdgcn_s_setprio(1);
; #pragma unroll
;       for (int m = 0; m < 4; m++)
; #pragma unroll
;         for (int n = 0; n < 4; n++) acc[m][n] = mfma16(a[m], b[n], acc[m][n]);
;       __builtin_amdgcn_s_setprio(0);
;     }
;     __syncthreads();
;     ...
;       const u16* G = (const u16*)ea.p1 + (EPI == EP_MERGE2 ? 1024 : 0);
;       u16 gv[4][4][4], cv[4][4][4];
; #pragma unroll
;       for (int m = 0; m < 4; m++)
; #pragma unroll
;         for (int j = 0; j < 4; j++)
; #pragma unroll
;           for (int n = 0; n < 4; n++) {
;             gv[m][j][n] = G[(size_t)(rbase + m * 16 + j) * 2048 + cbase + n * 16];
;             if (EPI == EP_MERGE2) cv[m][j][n] = C[(size_t)(rbase + m * 16 + j) * 1024 + cbase + n * 16];
;           }
	ds_read_b128 v[222:225], v161 offset:18496
	ds_read_b128 v[226:229], v161 offset:20800
	ds_read_b128 v[230:233], v161 offset:23104
	ds_read_b128 v[234:237], v161 offset:25408
	ds_read_b128 v[238:241], v129 offset:55360
	ds_read_b128 v[242:245], v129 offset:57664
	ds_read_b128 v[246:249], v129 offset:59968
	ds_read_b128 v[250:253], v129 offset:62272
	v_mfma_f32_16x16x32_bf16 v[98:101], v[130:133], v[146:149], v[34:37]
	v_mfma_f32_16x16x32_bf16 v[102:105], v[130:133], v[150:153], v[38:41]
	v_mfma_f32_16x16x32_bf16 v[106:109], v[130:133], v[162:165], v[42:45]
	v_mfma_f32_16x16x32_bf16 v[110:113], v[130:133], v[166:169], v[46:49]
	v_mfma_f32_16x16x32_bf16 v[50:53], v[134:137], v[146:149], v[50:53]
	v_mfma_f32_16x16x32_bf16 v[54:57], v[134:137], v[150:153], v[54:57]
	v_mfma_f32_16x16x32_bf16 v[58:61], v[134:137], v[162:165], v[58:61]
	v_mfma_f32_16x16x32_bf16 v[62:65], v[134:137], v[166:169], v[62:65]
	v_mfma_f32_16x16x32_bf16 v[66:69], v[138:141], v[146:149], v[66:69]
	v_mfma_f32_16x16x32_bf16 v[70:73], v[138:141], v[150:153], v[70:73]
	v_mfma_f32_16x16x32_bf16 v[74:77], v[138:141], v[162:165], v[74:77]
	v_mfma_f32_16x16x32_bf16 v[78:81], v[138:141], v[166:169], v[78:81]
	v_mfma_f32_16x16x32_bf16 v[82:85], v[142:145], v[146:149], v[82:85]
	v_mfma_f32_16x16x32_bf16 v[86:89], v[142:145], v[150:153], v[86:89]
	v_mfma_f32_16x16x32_bf16 v[90:93], v[142:145], v[162:165], v[90:93]
	v_mfma_f32_16x16x32_bf16 v[94:97], v[142:145], v[166:169], v[94:97]
	s_waitcnt lgkmcnt(0)
	v_mfma_f32_16x16x32_bf16 v[30:33], v[230:233], v[238:241], v[66:69]
	v_mfma_f32_16x16x32_bf16 v[26:29], v[230:233], v[242:245], v[70:73]
	v_mfma_f32_16x16x32_bf16 v[22:25], v[230:233], v[246:249], v[74:77]
	v_mfma_f32_16x16x32_bf16 v[18:21], v[230:233], v[250:253], v[78:81]
	v_mfma_f32_16x16x32_bf16 v[14:17], v[234:237], v[238:241], v[82:85]
	v_mfma_f32_16x16x32_bf16 v[10:13], v[234:237], v[242:245], v[86:89]
	v_mfma_f32_16x16x32_bf16 v[6:9], v[234:237], v[246:249], v[90:93]
	v_mfma_f32_16x16x32_bf16 v[2:5], v[234:237], v[250:253], v[94:97]
	v_mfma_f32_16x16x32_bf16 v[34:37], v[226:229], v[250:253], v[62:65]
	v_mfma_f32_16x16x32_bf16 v[62:65], v[222:225], v[238:241], v[98:101]
	v_mfma_f32_16x16x32_bf16 v[38:41], v[226:229], v[246:249], v[58:61]
	v_mfma_f32_16x16x32_bf16 v[58:61], v[222:225], v[242:245], v[102:105]
	v_mfma_f32_16x16x32_bf16 v[42:45], v[226:229], v[242:245], v[54:57]
	v_mfma_f32_16x16x32_bf16 v[54:57], v[222:225], v[246:249], v[106:109]
	v_mfma_f32_16x16x32_bf16 v[46:49], v[226:229], v[238:241], v[50:53]
	v_mfma_f32_16x16x32_bf16 v[50:53], v[222:225], v[250:253], v[110:113]
	s_nop 7
	v_and_b32_e32 v114, 64, v114
	v_add_u32_e32 v0, s16, v117
	v_or3_b32 v68, v114, s15, v115
	v_lshl_or_b32 v66, v116, 2, v0
	v_ashrrev_i32_e32 v69, 31, v68
	v_lshlrev_b64 v[68:69], 1, v[68:69]
	v_ashrrev_i32_e32 v67, 31, v66
	v_lshl_add_u64 v[98:99], s[8:9], 0, v[68:69]
	v_lshl_add_u64 v[100:101], s[2:3], 0, v[68:69]
	v_lshlrev_b64 v[68:69], 12, v[66:67]
	v_lshl_add_u64 v[102:103], v[98:99], 0, v[68:69]
	v_lshlrev_b64 v[68:69], 11, v[66:67]
	v_lshl_add_u64 v[96:97], v[100:101], 0, v[68:69]
	v_or_b32_e32 v68, 1, v66
	v_ashrrev_i32_e32 v69, 31, v68
	v_lshlrev_b64 v[70:71], 12, v[68:69]
	v_lshlrev_b64 v[68:69], 11, v[68:69]
	v_lshl_add_u64 v[94:95], v[100:101], 0, v[68:69]
	v_or_b32_e32 v68, 2, v66
	v_ashrrev_i32_e32 v69, 31, v68
	v_lshl_add_u64 v[104:105], v[98:99], 0, v[70:71]
	v_lshlrev_b64 v[70:71], 12, v[68:69]
	v_lshlrev_b64 v[68:69], 11, v[68:69]
	v_lshl_add_u64 v[92:93], v[100:101], 0, v[68:69]
	v_or_b32_e32 v68, 3, v66
	v_ashrrev_i32_e32 v69, 31, v68
	v_lshl_add_u64 v[106:107], v[98:99], 0, v[70:71]
	v_lshlrev_b64 v[70:71], 12, v[68:69]
	v_lshlrev_b64 v[68:69], 11, v[68:69]
	v_lshl_add_u64 v[90:91], v[100:101], 0, v[68:69]
	v_or_b32_e32 v68, 16, v66
	v_ashrrev_i32_e32 v69, 31, v68
	v_lshl_add_u64 v[108:109], v[98:99], 0, v[70:71]
	v_lshlrev_b64 v[70:71], 12, v[68:69]
	v_lshlrev_b64 v[68:69], 11, v[68:69]
	v_lshl_add_u64 v[88:89], v[100:101], 0, v[68:69]
	v_or_b32_e32 v68, 17, v66
	v_ashrrev_i32_e32 v69, 31, v68
	v_lshl_add_u64 v[110:111], v[98:99], 0, v[70:71]
	v_lshlrev_b64 v[70:71], 12, v[68:69]
	v_lshlrev_b64 v[68:69], 11, v[68:69]
	v_lshl_add_u64 v[86:87], v[100:101], 0, v[68:69]
	v_or_b32_e32 v68, 18, v66
	v_ashrrev_i32_e32 v69, 31, v68
	v_lshl_add_u64 v[112:113], v[98:99], 0, v[70:71]
	v_lshlrev_b64 v[70:71], 12, v[68:69]
	v_lshlrev_b64 v[68:69], 11, v[68:69]
	v_lshl_add_u64 v[84:85], v[100:101], 0, v[68:69]
	v_or_b32_e32 v68, 19, v66
	v_ashrrev_i32_e32 v69, 31, v68
	v_lshl_add_u64 v[114:115], v[98:99], 0, v[70:71]
	v_lshlrev_b64 v[70:71], 12, v[68:69]
	v_lshlrev_b64 v[68:69], 11, v[68:69]
	v_lshl_add_u64 v[82:83], v[100:101], 0, v[68:69]
	v_or_b32_e32 v68, 32, v66
	v_ashrrev_i32_e32 v69, 31, v68
	v_lshl_add_u64 v[116:117], v[98:99], 0, v[70:71]
	v_lshlrev_b64 v[70:71], 12, v[68:69]
	v_lshlrev_b64 v[68:69], 11, v[68:69]
	v_lshl_add_u64 v[80:81], v[100:101], 0, v[68:69]
	v_or_b32_e32 v68, 33, v66
	v_ashrrev_i32_e32 v69, 31, v68
	v_lshl_add_u64 v[118:119], v[98:99], 0, v[70:71]
	v_lshlrev_b64 v[70:71], 12, v[68:69]
	v_lshlrev_b64 v[68:69], 11, v[68:69]
	v_lshl_add_u64 v[78:79], v[100:101], 0, v[68:69]
	v_or_b32_e32 v68, 34, v66
	v_ashrrev_i32_e32 v69, 31, v68
	v_lshl_add_u64 v[120:121], v[98:99], 0, v[70:71]
	v_lshlrev_b64 v[70:71], 12, v[68:69]
	v_lshlrev_b64 v[68:69], 11, v[68:69]
	v_lshl_add_u64 v[76:77], v[100:101], 0, v[68:69]
	v_or_b32_e32 v68, 35, v66
	v_ashrrev_i32_e32 v69, 31, v68
	v_lshl_add_u64 v[122:123], v[98:99], 0, v[70:71]
	v_lshlrev_b64 v[70:71], 12, v[68:69]
	v_lshlrev_b64 v[68:69], 11, v[68:69]
	v_lshl_add_u64 v[74:75], v[100:101], 0, v[68:69]
	v_or_b32_e32 v68, 48, v66
	v_ashrrev_i32_e32 v69, 31, v68
	v_lshl_add_u64 v[124:125], v[98:99], 0, v[70:71]
	v_lshlrev_b64 v[70:71], 12, v[68:69]
	v_lshlrev_b64 v[68:69], 11, v[68:69]
	v_lshl_add_u64 v[72:73], v[100:101], 0, v[68:69]
	v_or_b32_e32 v68, 49, v66
	v_ashrrev_i32_e32 v69, 31, v68
	v_lshl_add_u64 v[126:127], v[98:99], 0, v[70:71]
	v_lshlrev_b64 v[70:71], 12, v[68:69]
	v_lshlrev_b64 v[68:69], 11, v[68:69]
	v_lshl_add_u64 v[128:129], v[98:99], 0, v[70:71]
	v_lshl_add_u64 v[70:71], v[100:101], 0, v[68:69]
	v_or_b32_e32 v68, 50, v66
	v_or_b32_e32 v66, 51, v66
	v_ashrrev_i32_e32 v69, 31, v68
	v_ashrrev_i32_e32 v67, 31, v66
	v_lshlrev_b64 v[130:131], 12, v[68:69]
	v_lshlrev_b64 v[132:133], 12, v[66:67]
	v_lshl_add_u64 v[130:131], v[98:99], 0, v[130:131]
	v_lshlrev_b64 v[68:69], 11, v[68:69]
	v_lshl_add_u64 v[98:99], v[98:99], 0, v[132:133]
	v_lshlrev_b64 v[66:67], 11, v[66:67]
	s_barrier
; template <int EPI, bool AF32>
; DEV void gemm_tile(const void* Ap, int lda, const u16* Bt, int ldb, int K, int m0, int n0, const Epi& ea, char* smem) {
;     ...
;       const u16* G = (const u16*)ea.p1 + (EPI == EP_MERGE2 ? 1024 : 0);
;       u16 gv[4][4][4], cv[4][4][4];
; #pragma unroll
;       for (int m = 0; m < 4; m++)
; #pragma unroll
;         for (int j = 0; j < 4; j++)
; #pragma unroll
;           for (int n = 0; n < 4; n++) {
;             gv[m][j][n] = G[(size_t)(rbase + m * 16 + j) * 2048 + cbase + n * 16];
;             if (EPI == EP_MERGE2) cv[m][j][n] = C[(size_t)(rbase + m * 16 + j) * 1024 + cbase + n * 16];
;           }
	v_lshl_add_u64 v[68:69], v[100:101], 0, v[68:69]
	v_lshl_add_u64 v[66:67], v[100:101], 0, v[66:67]
	global_load_ushort v0, v[102:103], off
	global_load_ushort v100, v[102:103], off offset:32
	global_load_ushort v101, v[102:103], off offset:64
	s_nop 0
	global_load_ushort v102, v[102:103], off offset:96
	s_nop 0
	global_load_ushort v103, v[96:97], off
	global_load_ushort v132, v[96:97], off offset:32
	global_load_ushort v133, v[96:97], off offset:64
	global_load_ushort v134, v[96:97], off offset:96
	global_load_ushort v135, v[104:105], off
	global_load_ushort v136, v[104:105], off offset:32
	global_load_ushort v137, v[104:105], off offset:64
	s_nop 0
	global_load_ushort v104, v[104:105], off offset:96
	s_nop 0
	global_load_ushort v105, v[94:95], off
	global_load_ushort v138, v[94:95], off offset:32
	global_load_ushort v139, v[94:95], off offset:64
	global_load_ushort v140, v[94:95], off offset:96
	global_load_ushort v141, v[106:107], off
	global_load_ushort v142, v[106:107], off offset:32
	global_load_ushort v143, v[106:107], off offset:64
	s_nop 0
	global_load_ushort v106, v[106:107], off offset:96
	s_nop 0
	global_load_ushort v107, v[92:93], off
	global_load_ushort v144, v[92:93], off offset:32
	global_load_ushort v145, v[92:93], off offset:64
	global_load_ushort v146, v[92:93], off offset:96
	global_load_ushort v147, v[108:109], off
	global_load_ushort v148, v[108:109], off offset:32
	global_load_ushort v149, v[108:109], off offset:64
	s_nop 0
	global_load_ushort v108, v[108:109], off offset:96
	s_nop 0
	global_load_ushort v109, v[90:91], off
	global_load_ushort v150, v[90:91], off offset:32
	global_load_ushort v151, v[90:91], off offset:64
	global_load_ushort v152, v[90:91], off offset:96
	global_load_ushort v153, v[110:111], off
	global_load_ushort v161, v[110:111], off offset:32
	global_load_ushort v162, v[110:111], off offset:64
	s_nop 0
	global_load_ushort v110, v[110:111], off offset:96
	s_nop 0
	global_load_ushort v111, v[88:89], off
	global_load_ushort v163, v[88:89], off offset:32
	global_load_ushort v164, v[88:89], off offset:64
	global_load_ushort v165, v[88:89], off offset:96
	global_load_ushort v166, v[112:113], off
	global_load_ushort v167, v[112:113], off offset:32
	global_load_ushort v168, v[112:113], off offset:64
	s_nop 0
	global_load_ushort v112, v[112:113], off offset:96
	s_nop 0
	global_load_ushort v113, v[86:87], off
	global_load_ushort v169, v[86:87], off offset:32
	global_load_ushort v170, v[86:87], off offset:64
	global_load_ushort v171, v[86:87], off offset:96
	global_load_ushort v172, v[114:115], off
	global_load_ushort v173, v[114:115], off offset:32
	global_load_ushort v174, v[114:115], off offset:64
	s_nop 0
	global_load_ushort v114, v[114:115], off offset:96
	s_nop 0
	global_load_ushort v115, v[84:85], off
	global_load_ushort v175, v[84:85], off offset:32
	global_load_ushort v176, v[84:85], off offset:64
	global_load_ushort v177, v[84:85], off offset:96
	global_load_ushort v178, v[116:117], off
	global_load_ushort v179, v[116:117], off offset:32
	global_load_ushort v180, v[116:117], off offset:64
	s_nop 0
	global_load_ushort v116, v[116:117], off offset:96
	s_nop 0
	global_load_ushort v117, v[82:83], off
	global_load_ushort v181, v[82:83], off offset:32
	global_load_ushort v182, v[82:83], off offset:64
	global_load_ushort v183, v[82:83], off offset:96
	global_load_ushort v184, v[118:119], off
	global_load_ushort v185, v[118:119], off offset:32
	global_load_ushort v186, v[118:119], off offset:64
	s_nop 0
	global_load_ushort v118, v[118:119], off offset:96
	s_nop 0
	global_load_ushort v119, v[80:81], off
	global_load_ushort v187, v[80:81], off offset:32
	global_load_ushort v188, v[80:81], off offset:64
	global_load_ushort v189, v[80:81], off offset:96
	global_load_ushort v190, v[120:121], off
	global_load_ushort v191, v[120:121], off offset:32
	global_load_ushort v192, v[120:121], off offset:64
	s_nop 0
	global_load_ushort v120, v[120:121], off offset:96
	s_nop 0
	global_load_ushort v121, v[78:79], off
	global_load_ushort v193, v[78:79], off offset:32
	global_load_ushort v194, v[78:79], off offset:64
	global_load_ushort v195, v[78:79], off offset:96
	global_load_ushort v196, v[122:123], off
	global_load_ushort v197, v[122:123], off offset:32
	global_load_ushort v221, v[122:123], off offset:64
	s_nop 0
	global_load_ushort v122, v[122:123], off offset:96
	s_nop 0
	global_load_ushort v123, v[76:77], off
	global_load_ushort v222, v[76:77], off offset:32
	global_load_ushort v223, v[76:77], off offset:64
	global_load_ushort v224, v[76:77], off offset:96
	global_load_ushort v225, v[124:125], off
	global_load_ushort v226, v[124:125], off offset:32
	global_load_ushort v227, v[124:125], off offset:64
	s_nop 0
	global_load_ushort v124, v[124:125], off offset:96
	s_nop 0
	global_load_ushort v125, v[74:75], off
	global_load_ushort v228, v[74:75], off offset:32
	global_load_ushort v229, v[74:75], off offset:64
	global_load_ushort v230, v[74:75], off offset:96
	global_load_ushort v231, v[126:127], off
	global_load_ushort v232, v[126:127], off offset:32
	global_load_ushort v233, v[126:127], off offset:64
	s_nop 0
	global_load_ushort v126, v[126:127], off offset:96
	s_nop 0
	global_load_ushort v127, v[72:73], off
	global_load_ushort v234, v[72:73], off offset:32
	global_load_ushort v235, v[72:73], off offset:64
	global_load_ushort v236, v[72:73], off offset:96
	global_load_ushort v237, v[128:129], off
	global_load_ushort v238, v[128:129], off offset:32
	global_load_ushort v239, v[128:129], off offset:64
	s_nop 0
	global_load_ushort v128, v[128:129], off offset:96
	s_nop 0
	global_load_ushort v129, v[70:71], off
	global_load_ushort v240, v[70:71], off offset:32
	global_load_ushort v241, v[70:71], off offset:64
	global_load_ushort v242, v[70:71], off offset:96
	global_load_ushort v243, v[130:131], off
	global_load_ushort v244, v[130:131], off offset:32
	global_load_ushort v245, v[130:131], off offset:64
	s_nop 0
	global_load_ushort v130, v[130:131], off offset:96
	s_nop 0
	global_load_ushort v131, v[68:69], off
	global_load_ushort v246, v[68:69], off offset:32
	global_load_ushort v247, v[68:69], off offset:64
	global_load_ushort v248, v[68:69], off offset:96
	global_load_ushort v249, v[98:99], off
	global_load_ushort v250, v[98:99], off offset:32
	global_load_ushort v251, v[98:99], off offset:64
	s_nop 0
	global_load_ushort v98, v[98:99], off offset:96
	s_nop 0
	global_load_ushort v99, v[66:67], off
	global_load_ushort v252, v[66:67], off offset:32
	global_load_ushort v253, v[66:67], off offset:64
	global_load_ushort v201, v[66:67], off offset:96
	s_waitcnt vmcnt(62)
; DEV float bf2f(u16 h) { return __uint_as_float(((unsigned)h) << 16); }
; template <int EPI, bool AF32>
; DEV void gemm_tile(const void* Ap, int lda, const u16* Bt, int ldb, int K, int m0, int n0, const Epi& ea, char* smem) {
;     ...
; #pragma unroll
;       for (int m = 0; m < 4; m++)
; #pragma unroll
;         for (int j = 0; j < 4; j++)
; #pragma unroll
;           for (int n = 0; n < 4; n++) {
;             float v = bf2f(gv[m][j][n]) * acc[m][n][j];
;             if (EPI == EP_MERGE2) v += bf2f(cv[m][j][n]);
;             C[(size_t)(rbase + m * 16 + j) * 1024 + cbase + n * 16] = f2bf(v);
;           }
	v_lshlrev_b32_e32 v0, 16, v0
	v_lshlrev_b32_e32 v103, 16, v103
	v_fmac_f32_e32 v103, v62, v0
	v_cvt_pk_bf16_f32 v0, v103, s0
	global_store_short v[96:97], v0, off
	v_lshlrev_b32_e32 v0, 16, v100
	v_lshlrev_b32_e32 v62, 16, v132
	v_fmac_f32_e32 v62, v58, v0
	v_cvt_pk_bf16_f32 v0, v62, s0
	global_store_short v[96:97], v0, off offset:32
	v_lshlrev_b32_e32 v0, 16, v101
	v_lshlrev_b32_e32 v58, 16, v133
	v_fmac_f32_e32 v58, v54, v0
	v_cvt_pk_bf16_f32 v0, v58, s0
	global_store_short v[96:97], v0, off offset:64
	v_lshlrev_b32_e32 v0, 16, v102
	v_lshlrev_b32_e32 v54, 16, v134
	v_fmac_f32_e32 v54, v50, v0
	v_cvt_pk_bf16_f32 v0, v54, s0
	global_store_short v[96:97], v0, off offset:96
	v_lshlrev_b32_e32 v0, 16, v135
	v_lshlrev_b32_e32 v50, 16, v105
	v_fmac_f32_e32 v50, v63, v0
	v_cvt_pk_bf16_f32 v0, v50, s0
	global_store_short v[94:95], v0, off
	v_lshlrev_b32_e32 v0, 16, v136
	v_lshlrev_b32_e32 v50, 16, v138
	v_fmac_f32_e32 v50, v59, v0
	v_cvt_pk_bf16_f32 v0, v50, s0
	global_store_short v[94:95], v0, off offset:32
	v_lshlrev_b32_e32 v0, 16, v137
	v_lshlrev_b32_e32 v50, 16, v139
	v_fmac_f32_e32 v50, v55, v0
	v_cvt_pk_bf16_f32 v0, v50, s0
	global_store_short v[94:95], v0, off offset:64
	v_lshlrev_b32_e32 v0, 16, v104
	v_lshlrev_b32_e32 v50, 16, v140
	v_fmac_f32_e32 v50, v51, v0
	v_cvt_pk_bf16_f32 v0, v50, s0
	global_store_short v[94:95], v0, off offset:96
	v_lshlrev_b32_e32 v0, 16, v141
	v_lshlrev_b32_e32 v50, 16, v107
	v_fmac_f32_e32 v50, v64, v0
	v_cvt_pk_bf16_f32 v0, v50, s0
	global_store_short v[92:93], v0, off
	v_lshlrev_b32_e32 v0, 16, v142
	v_lshlrev_b32_e32 v50, 16, v144
	v_fmac_f32_e32 v50, v60, v0
	v_cvt_pk_bf16_f32 v0, v50, s0
	global_store_short v[92:93], v0, off offset:32
	v_lshlrev_b32_e32 v0, 16, v143
	v_lshlrev_b32_e32 v50, 16, v145
	v_fmac_f32_e32 v50, v56, v0
	v_cvt_pk_bf16_f32 v0, v50, s0
	global_store_short v[92:93], v0, off offset:64
	v_lshlrev_b32_e32 v0, 16, v106
	v_lshlrev_b32_e32 v50, 16, v146
	v_fmac_f32_e32 v50, v52, v0
	v_cvt_pk_bf16_f32 v0, v50, s0
	global_store_short v[92:93], v0, off offset:96
	v_lshlrev_b32_e32 v0, 16, v147
	v_lshlrev_b32_e32 v50, 16, v109
	v_fmac_f32_e32 v50, v65, v0
	v_cvt_pk_bf16_f32 v0, v50, s0
	global_store_short v[90:91], v0, off
	v_lshlrev_b32_e32 v0, 16, v148
	v_lshlrev_b32_e32 v50, 16, v150
	v_fmac_f32_e32 v50, v61, v0
	v_cvt_pk_bf16_f32 v0, v50, s0
	global_store_short v[90:91], v0, off offset:32
	v_lshlrev_b32_e32 v0, 16, v149
	v_lshlrev_b32_e32 v50, 16, v151
	v_fmac_f32_e32 v50, v57, v0
	v_cvt_pk_bf16_f32 v0, v50, s0
	global_store_short v[90:91], v0, off offset:64
	v_lshlrev_b32_e32 v0, 16, v108
	v_lshlrev_b32_e32 v50, 16, v152
	v_fmac_f32_e32 v50, v53, v0
	v_cvt_pk_bf16_f32 v0, v50, s0
	global_store_short v[90:91], v0, off offset:96
	v_lshlrev_b32_e32 v0, 16, v153
	v_lshlrev_b32_e32 v50, 16, v111
	v_fmac_f32_e32 v50, v46, v0
	v_cvt_pk_bf16_f32 v0, v50, s0
	global_store_short v[88:89], v0, off
	v_lshlrev_b32_e32 v0, 16, v161
	v_lshlrev_b32_e32 v46, 16, v163
	v_fmac_f32_e32 v46, v42, v0
	v_cvt_pk_bf16_f32 v0, v46, s0
	global_store_short v[88:89], v0, off offset:32
	v_lshlrev_b32_e32 v0, 16, v162
	v_lshlrev_b32_e32 v42, 16, v164
	v_fmac_f32_e32 v42, v38, v0
	v_cvt_pk_bf16_f32 v0, v42, s0
	global_store_short v[88:89], v0, off offset:64
	v_lshlrev_b32_e32 v0, 16, v110
	v_lshlrev_b32_e32 v38, 16, v165
	v_fmac_f32_e32 v38, v34, v0
	v_cvt_pk_bf16_f32 v0, v38, s0
	global_store_short v[88:89], v0, off offset:96
	v_lshlrev_b32_e32 v0, 16, v166
	v_lshlrev_b32_e32 v34, 16, v113
	v_fmac_f32_e32 v34, v47, v0
	v_cvt_pk_bf16_f32 v0, v34, s0
	global_store_short v[86:87], v0, off
	v_lshlrev_b32_e32 v0, 16, v167
	v_lshlrev_b32_e32 v34, 16, v169
	v_fmac_f32_e32 v34, v43, v0
	v_cvt_pk_bf16_f32 v0, v34, s0
	global_store_short v[86:87], v0, off offset:32
	v_lshlrev_b32_e32 v0, 16, v168
	v_lshlrev_b32_e32 v34, 16, v170
	v_fmac_f32_e32 v34, v39, v0
	v_cvt_pk_bf16_f32 v0, v34, s0
	global_store_short v[86:87], v0, off offset:64
	v_lshlrev_b32_e32 v0, 16, v112
	v_lshlrev_b32_e32 v34, 16, v171
	v_fmac_f32_e32 v34, v35, v0
	v_cvt_pk_bf16_f32 v0, v34, s0
	global_store_short v[86:87], v0, off offset:96
	v_lshlrev_b32_e32 v0, 16, v172
	v_lshlrev_b32_e32 v34, 16, v115
	v_fmac_f32_e32 v34, v48, v0
	v_cvt_pk_bf16_f32 v0, v34, s0
	global_store_short v[84:85], v0, off
	v_lshlrev_b32_e32 v0, 16, v173
	v_lshlrev_b32_e32 v34, 16, v175
	v_fmac_f32_e32 v34, v44, v0
	v_cvt_pk_bf16_f32 v0, v34, s0
	global_store_short v[84:85], v0, off offset:32
	v_lshlrev_b32_e32 v0, 16, v174
	v_lshlrev_b32_e32 v34, 16, v176
	v_fmac_f32_e32 v34, v40, v0
	v_cvt_pk_bf16_f32 v0, v34, s0
	global_store_short v[84:85], v0, off offset:64
	v_lshlrev_b32_e32 v0, 16, v114
	v_lshlrev_b32_e32 v34, 16, v177
	v_fmac_f32_e32 v34, v36, v0
	v_cvt_pk_bf16_f32 v0, v34, s0
	global_store_short v[84:85], v0, off offset:96
	v_lshlrev_b32_e32 v0, 16, v178
	v_lshlrev_b32_e32 v34, 16, v117
	v_fmac_f32_e32 v34, v49, v0
	v_cvt_pk_bf16_f32 v0, v34, s0
	global_store_short v[82:83], v0, off
	v_lshlrev_b32_e32 v0, 16, v179
	v_lshlrev_b32_e32 v34, 16, v181
	v_fmac_f32_e32 v34, v45, v0
	v_cvt_pk_bf16_f32 v0, v34, s0
	global_store_short v[82:83], v0, off offset:32
	v_lshlrev_b32_e32 v0, 16, v180
	v_lshlrev_b32_e32 v34, 16, v182
	v_fmac_f32_e32 v34, v41, v0
	v_cvt_pk_bf16_f32 v0, v34, s0
	global_store_short v[82:83], v0, off offset:64
	v_lshlrev_b32_e32 v0, 16, v116
	v_lshlrev_b32_e32 v34, 16, v183
	v_fmac_f32_e32 v34, v37, v0
	v_cvt_pk_bf16_f32 v0, v34, s0
	global_store_short v[82:83], v0, off offset:96
	v_lshlrev_b32_e32 v0, 16, v184
	s_waitcnt vmcnt(62)
; DEV int bidx() { int b = __builtin_amdgcn_readfirstlane(blockIdx.x); asm volatile("" : "+s"(b)); return b; }
; DEV int gdim() { int g = __builtin_amdgcn_readfirstlane(gridDim.x); asm volatile("" : "+s"(g)); return g; }
; DEV float bf2f(u16 h) { return __uint_as_float(((unsigned)h) << 16); }
; template <int EPI, bool AF32>
; DEV void gemm_tile(const void* Ap, int lda, const u16* Bt, int ldb, int K, int m0, int n0, const Epi& ea, char* smem) {
;     ...
; #pragma unroll
;       for (int m = 0; m < 4; m++)
; #pragma unroll
;         for (int j = 0; j < 4; j++)
; #pragma unroll
;           for (int n = 0; n < 4; n++) {
;             float v = bf2f(gv[m][j][n]) * acc[m][n][j];
;             if (EPI == EP_MERGE2) v += bf2f(cv[m][j][n]);
;             C[(size_t)(rbase + m * 16 + j) * 1024 + cbase + n * 16] = f2bf(v);
;           }
; template <int EPI, bool AF32>
; DEV void gemm_phase(const void* A, int lda, const u16* Bt, int ldb, int M, int N, int K, const Epi& ea, char* smem) {
;     ...
;   for (int tile = bidx(); tile < ntm * ntn; tile += gdim()) {
;     int m, n;
;     tile_mn(tile, ntm, ntn, m, n);
	v_lshlrev_b32_e32 v34, 16, v119
	v_fmac_f32_e32 v34, v30, v0
	v_cvt_pk_bf16_f32 v0, v34, s0
	global_store_short v[80:81], v0, off
	v_lshlrev_b32_e32 v0, 16, v185
	v_lshlrev_b32_e32 v30, 16, v187
	v_fmac_f32_e32 v30, v26, v0
	v_cvt_pk_bf16_f32 v0, v30, s0
	global_store_short v[80:81], v0, off offset:32
	v_lshlrev_b32_e32 v0, 16, v186
	v_lshlrev_b32_e32 v26, 16, v188
	v_fmac_f32_e32 v26, v22, v0
	v_cvt_pk_bf16_f32 v0, v26, s0
	global_store_short v[80:81], v0, off offset:64
	v_lshlrev_b32_e32 v0, 16, v118
	v_lshlrev_b32_e32 v22, 16, v189
	v_fmac_f32_e32 v22, v18, v0
	v_cvt_pk_bf16_f32 v0, v22, s0
	global_store_short v[80:81], v0, off offset:96
	v_lshlrev_b32_e32 v0, 16, v190
	v_lshlrev_b32_e32 v18, 16, v121
	v_fmac_f32_e32 v18, v31, v0
	v_cvt_pk_bf16_f32 v0, v18, s0
	global_store_short v[78:79], v0, off
	v_lshlrev_b32_e32 v0, 16, v191
	v_lshlrev_b32_e32 v18, 16, v193
	v_fmac_f32_e32 v18, v27, v0
	v_cvt_pk_bf16_f32 v0, v18, s0
	global_store_short v[78:79], v0, off offset:32
	v_lshlrev_b32_e32 v0, 16, v192
	v_lshlrev_b32_e32 v18, 16, v194
	v_fmac_f32_e32 v18, v23, v0
	v_cvt_pk_bf16_f32 v0, v18, s0
	global_store_short v[78:79], v0, off offset:64
	v_lshlrev_b32_e32 v0, 16, v120
	v_lshlrev_b32_e32 v18, 16, v195
	v_fmac_f32_e32 v18, v19, v0
	v_cvt_pk_bf16_f32 v0, v18, s0
	global_store_short v[78:79], v0, off offset:96
	v_lshlrev_b32_e32 v0, 16, v196
	v_lshlrev_b32_e32 v18, 16, v123
	v_fmac_f32_e32 v18, v32, v0
	v_cvt_pk_bf16_f32 v0, v18, s0
	global_store_short v[76:77], v0, off
	v_lshlrev_b32_e32 v0, 16, v197
	v_lshlrev_b32_e32 v18, 16, v222
	v_fmac_f32_e32 v18, v28, v0
	v_cvt_pk_bf16_f32 v0, v18, s0
	global_store_short v[76:77], v0, off offset:32
	v_lshlrev_b32_e32 v0, 16, v221
	v_lshlrev_b32_e32 v18, 16, v223
	v_fmac_f32_e32 v18, v24, v0
	v_cvt_pk_bf16_f32 v0, v18, s0
	global_store_short v[76:77], v0, off offset:64
	v_lshlrev_b32_e32 v0, 16, v122
	v_lshlrev_b32_e32 v18, 16, v224
	v_fmac_f32_e32 v18, v20, v0
	v_cvt_pk_bf16_f32 v0, v18, s0
	global_store_short v[76:77], v0, off offset:96
	v_lshlrev_b32_e32 v0, 16, v225
	v_lshlrev_b32_e32 v18, 16, v125
	v_fmac_f32_e32 v18, v33, v0
	v_cvt_pk_bf16_f32 v0, v18, s0
	global_store_short v[74:75], v0, off
	v_lshlrev_b32_e32 v0, 16, v226
	v_lshlrev_b32_e32 v18, 16, v228
	v_fmac_f32_e32 v18, v29, v0
	v_cvt_pk_bf16_f32 v0, v18, s0
	global_store_short v[74:75], v0, off offset:32
	v_lshlrev_b32_e32 v0, 16, v227
	v_lshlrev_b32_e32 v18, 16, v229
	v_fmac_f32_e32 v18, v25, v0
	v_cvt_pk_bf16_f32 v0, v18, s0
	global_store_short v[74:75], v0, off offset:64
	v_lshlrev_b32_e32 v0, 16, v124
	v_lshlrev_b32_e32 v18, 16, v230
	v_fmac_f32_e32 v18, v21, v0
	v_cvt_pk_bf16_f32 v0, v18, s0
	global_store_short v[74:75], v0, off offset:96
	v_lshlrev_b32_e32 v0, 16, v231
	s_waitcnt vmcnt(62)
	v_lshlrev_b32_e32 v18, 16, v127
	v_fmac_f32_e32 v18, v14, v0
	v_cvt_pk_bf16_f32 v0, v18, s0
	global_store_short v[72:73], v0, off
	v_lshlrev_b32_e32 v0, 16, v232
	v_lshlrev_b32_e32 v14, 16, v234
	v_fmac_f32_e32 v14, v10, v0
	v_cvt_pk_bf16_f32 v0, v14, s0
	global_store_short v[72:73], v0, off offset:32
	v_lshlrev_b32_e32 v0, 16, v233
	v_lshlrev_b32_e32 v10, 16, v235
	v_fmac_f32_e32 v10, v6, v0
	v_cvt_pk_bf16_f32 v0, v10, s0
	global_store_short v[72:73], v0, off offset:64
	v_lshlrev_b32_e32 v0, 16, v126
	v_lshlrev_b32_e32 v6, 16, v236
	v_fmac_f32_e32 v6, v2, v0
	v_cvt_pk_bf16_f32 v0, v6, s0
	global_store_short v[72:73], v0, off offset:96
	v_lshlrev_b32_e32 v0, 16, v237
	v_lshlrev_b32_e32 v2, 16, v129
	v_fmac_f32_e32 v2, v15, v0
	v_cvt_pk_bf16_f32 v0, v2, s0
	global_store_short v[70:71], v0, off
	v_lshlrev_b32_e32 v0, 16, v238
	v_lshlrev_b32_e32 v2, 16, v240
	v_fmac_f32_e32 v2, v11, v0
	v_cvt_pk_bf16_f32 v0, v2, s0
	global_store_short v[70:71], v0, off offset:32
	v_lshlrev_b32_e32 v0, 16, v239
	v_lshlrev_b32_e32 v2, 16, v241
	v_fmac_f32_e32 v2, v7, v0
	v_cvt_pk_bf16_f32 v0, v2, s0
	global_store_short v[70:71], v0, off offset:64
	v_lshlrev_b32_e32 v0, 16, v128
	v_lshlrev_b32_e32 v2, 16, v242
	v_fmac_f32_e32 v2, v3, v0
	v_cvt_pk_bf16_f32 v0, v2, s0
	global_store_short v[70:71], v0, off offset:96
	v_lshlrev_b32_e32 v0, 16, v243
	s_waitcnt vmcnt(62)
	v_lshlrev_b32_e32 v2, 16, v131
	v_fmac_f32_e32 v2, v16, v0
	v_cvt_pk_bf16_f32 v0, v2, s0
	global_store_short v[68:69], v0, off
	v_lshlrev_b32_e32 v0, 16, v244
	v_lshlrev_b32_e32 v2, 16, v246
	v_fmac_f32_e32 v2, v12, v0
	v_cvt_pk_bf16_f32 v0, v2, s0
	global_store_short v[68:69], v0, off offset:32
	v_lshlrev_b32_e32 v0, 16, v245
	v_lshlrev_b32_e32 v2, 16, v247
	v_fmac_f32_e32 v2, v8, v0
	v_cvt_pk_bf16_f32 v0, v2, s0
	global_store_short v[68:69], v0, off offset:64
	v_lshlrev_b32_e32 v0, 16, v130
	v_lshlrev_b32_e32 v2, 16, v248
	v_fmac_f32_e32 v2, v4, v0
	v_cvt_pk_bf16_f32 v0, v2, s0
	global_store_short v[68:69], v0, off offset:96
	v_lshlrev_b32_e32 v0, 16, v249
	s_waitcnt vmcnt(62)
	v_lshlrev_b32_e32 v2, 16, v99
	v_fmac_f32_e32 v2, v17, v0
	v_cvt_pk_bf16_f32 v0, v2, s0
	global_store_short v[66:67], v0, off
	v_lshlrev_b32_e32 v0, 16, v250
	v_lshlrev_b32_e32 v2, 16, v252
	v_fmac_f32_e32 v2, v13, v0
	v_cvt_pk_bf16_f32 v0, v2, s0
	global_store_short v[66:67], v0, off offset:32
	v_lshlrev_b32_e32 v0, 16, v251
	s_waitcnt vmcnt(62)
	v_lshlrev_b32_e32 v2, 16, v253
	v_fmac_f32_e32 v2, v9, v0
	v_cvt_pk_bf16_f32 v0, v2, s0
	global_store_short v[66:67], v0, off offset:64
	v_lshlrev_b32_e32 v0, 16, v98
	v_lshlrev_b32_e32 v2, 16, v201
	v_fmac_f32_e32 v2, v5, v0
	v_cvt_pk_bf16_f32 v0, v2, s0
	v_readfirstlane_b32 s0, v198
	global_store_short v[66:67], v0, off offset:96
	s_add_i32 s14, s0, s14
	s_cmpk_lt_i32 s14, 0x820
	s_cbranch_scc1 .LBB0_1309
	v_mov_b32_e32 v201, 0x2723000

; DEV f32x4 mfma16(bf16x8 a, bf16x8 b, f32x4 c) { return __builtin_amdgcn_mfma_f32_16x16x32_bf16(a, b, c, 0, 0, 0); }
; template <int EPI, bool AF32>
; DEV void gemm_tile(const void* Ap, int lda, const u16* Bt, int ldb, int K, int m0, int n0, const Epi& ea, char* smem) {
;     ...
;   gload(0);
;   swrite(0);
;   if (nk > 1) gload(1);
;   __syncthreads();
;   for (int kt = 0; kt < nk; kt++) {
;     const int buf = kt & 1;
;     if (kt + 1 < nk) swrite(buf ^ 1);
;     if (kt + 2 < nk) gload(kt + 2);
; #pragma unroll
;     for (int ks = 0; ks < 2; ks++) {
;       bf16x8 a[4], b[4];
; #pragma unroll
;       for (int m = 0; m < 4; m++) a[m] = *(const bf16x8*)(sA + buf * 9216 + (wr * 64 + m * 16 + fr) * 72 + ks * 32 + fq * 8);
; #pragma unroll
;       for (int n = 0; n < 4; n++) b[n] = *(const bf16x8*)(sB + buf * 9216 + (wc * 64 + n * 16 + fr) * 72 + ks * 32 + fq * 8);
;       __builtin_amdgcn_s_setprio(1);
; #pragma unroll
;       for (int m = 0; m < 4; m++)
; #pragma unroll
;         for (int n = 0; n < 4; n++) acc[m][n] = mfma16(a[m], b[n], acc[m][n]);
;       __builtin_amdgcn_s_setprio(0);
;     }
;     __syncthreads();
;   }
.Lgk5_loop:
	s_waitcnt lgkmcnt(0)
	ds_read_b128 v[222:225], v161 offset:64
	ds_read_b128 v[226:229], v161 offset:2368
	ds_read_b128 v[230:233], v161 offset:4672
	ds_read_b128 v[234:237], v161 offset:6976
	ds_read_b128 v[238:241], v129 offset:36928
	ds_read_b128 v[242:245], v129 offset:39232
	ds_read_b128 v[246:249], v129 offset:41536
	ds_read_b128 v[250:253], v129 offset:43840
	v_mfma_f32_16x16x32_bf16 v[34:37], v[130:133], v[146:149], v[34:37]
	v_mfma_f32_16x16x32_bf16 v[38:41], v[130:133], v[150:153], v[38:41]
	v_mfma_f32_16x16x32_bf16 v[42:45], v[130:133], v[162:165], v[42:45]
	v_mfma_f32_16x16x32_bf16 v[46:49], v[130:133], v[166:169], v[46:49]
	s_waitcnt vmcnt(0)
	ds_write_b128 v122, v[22:25] offset:18432
	ds_write_b128 v122, v[6:9] offset:55296
	v_mfma_f32_16x16x32_bf16 v[50:53], v[134:137], v[146:149], v[50:53]
	ds_write_b128 v121, v[18:21] offset:18432
	ds_write_b128 v121, v[10:13] offset:55296
	v_mfma_f32_16x16x32_bf16 v[54:57], v[134:137], v[150:153], v[54:57]
	ds_write_b128 v120, v[14:17] offset:18432
	ds_write_b128 v120, v[2:5] offset:55296
	v_mfma_f32_16x16x32_bf16 v[58:61], v[134:137], v[162:165], v[58:61]
	ds_write_b128 v124, v[26:29] offset:18432
	ds_write_b128 v124, v[30:33] offset:55296
	v_mfma_f32_16x16x32_bf16 v[62:65], v[134:137], v[166:169], v[62:65]
	global_load_dwordx4 v[22:25], v[112:113], off
	v_mfma_f32_16x16x32_bf16 v[66:69], v[138:141], v[146:149], v[66:69]
	global_load_dwordx4 v[6:9], v[110:111], off
	v_mfma_f32_16x16x32_bf16 v[70:73], v[138:141], v[150:153], v[70:73]
	global_load_dwordx4 v[18:21], v[108:109], off
	v_mfma_f32_16x16x32_bf16 v[74:77], v[138:141], v[162:165], v[74:77]
	global_load_dwordx4 v[10:13], v[106:107], off
	v_mfma_f32_16x16x32_bf16 v[78:81], v[138:141], v[166:169], v[78:81]
	global_load_dwordx4 v[14:17], v[104:105], off
	v_mfma_f32_16x16x32_bf16 v[82:85], v[142:145], v[146:149], v[82:85]
	global_load_dwordx4 v[2:5], v[102:103], off
	v_mfma_f32_16x16x32_bf16 v[86:89], v[142:145], v[150:153], v[86:89]
	global_load_dwordx4 v[26:29], v[100:101], off
	v_mfma_f32_16x16x32_bf16 v[90:93], v[142:145], v[162:165], v[90:93]
	global_load_dwordx4 v[30:33], v[98:99], off
	v_mfma_f32_16x16x32_bf16 v[94:97], v[142:145], v[166:169], v[94:97]
	s_waitcnt lgkmcnt(0)
	s_barrier
	ds_read_b128 v[130:133], v161 offset:18432
	v_mfma_f32_16x16x32_bf16 v[34:37], v[222:225], v[238:241], v[34:37]
	ds_read_b128 v[134:137], v161 offset:20736
	v_mfma_f32_16x16x32_bf16 v[38:41], v[222:225], v[242:245], v[38:41]
	ds_read_b128 v[138:141], v161 offset:23040
	v_mfma_f32_16x16x32_bf16 v[42:45], v[222:225], v[246:249], v[42:45]
	ds_read_b128 v[142:145], v161 offset:25344
	v_mfma_f32_16x16x32_bf16 v[46:49], v[222:225], v[250:253], v[46:49]
	ds_read_b128 v[146:149], v129 offset:55296
	v_mfma_f32_16x16x32_bf16 v[50:53], v[226:229], v[238:241], v[50:53]
	ds_read_b128 v[150:153], v129 offset:57600
	v_mfma_f32_16x16x32_bf16 v[54:57], v[226:229], v[242:245], v[54:57]
	ds_read_b128 v[162:165], v129 offset:59904
	v_mfma_f32_16x16x32_bf16 v[58:61], v[226:229], v[246:249], v[58:61]
	ds_read_b128 v[166:169], v129 offset:62208
	v_mfma_f32_16x16x32_bf16 v[62:65], v[226:229], v[250:253], v[62:65]
	v_mfma_f32_16x16x32_bf16 v[66:69], v[230:233], v[238:241], v[66:69]
	v_mfma_f32_16x16x32_bf16 v[70:73], v[230:233], v[242:245], v[70:73]
	v_mfma_f32_16x16x32_bf16 v[74:77], v[230:233], v[246:249], v[74:77]
	v_mfma_f32_16x16x32_bf16 v[78:81], v[230:233], v[250:253], v[78:81]
	v_mfma_f32_16x16x32_bf16 v[82:85], v[234:237], v[238:241], v[82:85]
	v_mfma_f32_16x16x32_bf16 v[86:89], v[234:237], v[242:245], v[86:89]
	v_mfma_f32_16x16x32_bf16 v[90:93], v[234:237], v[246:249], v[90:93]
	v_mfma_f32_16x16x32_bf16 v[94:97], v[234:237], v[250:253], v[94:97]
	s_waitcnt lgkmcnt(0)
	ds_read_b128 v[222:225], v161 offset:18496
	ds_read_b128 v[226:229], v161 offset:20800
	ds_read_b128 v[230:233], v161 offset:23104
	ds_read_b128 v[234:237], v161 offset:25408
	ds_read_b128 v[238:241], v129 offset:55360
	ds_read_b128 v[242:245], v129 offset:57664
	ds_read_b128 v[246:249], v129 offset:59968
	ds_read_b128 v[250:253], v129 offset:62272
	v_mfma_f32_16x16x32_bf16 v[34:37], v[130:133], v[146:149], v[34:37]
	v_mfma_f32_16x16x32_bf16 v[38:41], v[130:133], v[150:153], v[38:41]
	v_mfma_f32_16x16x32_bf16 v[42:45], v[130:133], v[162:165], v[42:45]
	v_mfma_f32_16x16x32_bf16 v[46:49], v[130:133], v[166:169], v[46:49]
	s_waitcnt vmcnt(0)
	ds_write_b128 v122, v[22:25]
	ds_write_b128 v122, v[6:9] offset:36864
	v_mfma_f32_16x16x32_bf16 v[50:53], v[134:137], v[146:149], v[50:53]
	ds_write_b128 v121, v[18:21]
	ds_write_b128 v121, v[10:13] offset:36864
	v_mfma_f32_16x16x32_bf16 v[54:57], v[134:137], v[150:153], v[54:57]
	ds_write_b128 v120, v[14:17]
	ds_write_b128 v120, v[2:5] offset:36864
	v_mfma_f32_16x16x32_bf16 v[58:61], v[134:137], v[162:165], v[58:61]
	ds_write_b128 v124, v[26:29]
	ds_write_b128 v124, v[30:33] offset:36864
	v_mfma_f32_16x16x32_bf16 v[62:65], v[134:137], v[166:169], v[62:65]
	global_load_dwordx4 v[22:25], v[112:113], off offset:128
	v_mfma_f32_16x16x32_bf16 v[66:69], v[138:141], v[146:149], v[66:69]
	global_load_dwordx4 v[6:9], v[110:111], off offset:128
	v_mfma_f32_16x16x32_bf16 v[70:73], v[138:141], v[150:153], v[70:73]
	global_load_dwordx4 v[18:21], v[108:109], off offset:128
	v_mfma_f32_16x16x32_bf16 v[74:77], v[138:141], v[162:165], v[74:77]
	global_load_dwordx4 v[10:13], v[106:107], off offset:128
	v_mfma_f32_16x16x32_bf16 v[78:81], v[138:141], v[166:169], v[78:81]
	global_load_dwordx4 v[14:17], v[104:105], off offset:128
	v_mfma_f32_16x16x32_bf16 v[82:85], v[142:145], v[146:149], v[82:85]
	global_load_dwordx4 v[2:5], v[102:103], off offset:128
	v_mfma_f32_16x16x32_bf16 v[86:89], v[142:145], v[150:153], v[86:89]
	global_load_dwordx4 v[26:29], v[100:101], off offset:128
	v_mfma_f32_16x16x32_bf16 v[90:93], v[142:145], v[162:165], v[90:93]
	global_load_dwordx4 v[30:33], v[98:99], off offset:128
	v_mfma_f32_16x16x32_bf16 v[94:97], v[142:145], v[166:169], v[94:97]
	s_waitcnt lgkmcnt(0)
	s_barrier
; DEV f32x4 mfma16(bf16x8 a, bf16x8 b, f32x4 c) { return __builtin_amdgcn_mfma_f32_16x16x32_bf16(a, b, c, 0, 0, 0); }
; template <int EPI, bool AF32>
; DEV void gemm_tile(const void* Ap, int lda, const u16* Bt, int ldb, int K, int m0, int n0, const Epi& ea, char* smem) {
;     ...
;   for (int kt = 0; kt < nk; kt++) {
;     const int buf = kt & 1;
;     if (kt + 1 < nk) swrite(buf ^ 1);
;     if (kt + 2 < nk) gload(kt + 2);
; #pragma unroll
;     for (int ks = 0; ks < 2; ks++) {
;       bf16x8 a[4], b[4];
; #pragma unroll
;       for (int m = 0; m < 4; m++) a[m] = *(const bf16x8*)(sA + buf * 9216 + (wr * 64 + m * 16 + fr) * 72 + ks * 32 + fq * 8);
; #pragma unroll
;       for (int n = 0; n < 4; n++) b[n] = *(const bf16x8*)(sB + buf * 9216 + (wc * 64 + n * 16 + fr) * 72 + ks * 32 + fq * 8);
;       __builtin_amdgcn_s_setprio(1);
; #pragma unroll
;       for (int m = 0; m < 4; m++)
; #pragma unroll
;         for (int n = 0; n < 4; n++) acc[m][n] = mfma16(a[m], b[n], acc[m][n]);
;       __builtin_amdgcn_s_setprio(0);
;     }
;     __syncthreads();
	ds_read_b128 v[130:133], v161
	v_mfma_f32_16x16x32_bf16 v[34:37], v[222:225], v[238:241], v[34:37]
	ds_read_b128 v[134:137], v161 offset:2304
	v_mfma_f32_16x16x32_bf16 v[38:41], v[222:225], v[242:245], v[38:41]
	ds_read_b128 v[138:141], v161 offset:4608
	v_mfma_f32_16x16x32_bf16 v[42:45], v[222:225], v[246:249], v[42:45]
	ds_read_b128 v[142:145], v161 offset:6912
	v_mfma_f32_16x16x32_bf16 v[46:49], v[222:225], v[250:253], v[46:49]
	ds_read_b128 v[146:149], v129 offset:36864
	v_mfma_f32_16x16x32_bf16 v[50:53], v[226:229], v[238:241], v[50:53]
	ds_read_b128 v[150:153], v129 offset:39168
	v_mfma_f32_16x16x32_bf16 v[54:57], v[226:229], v[242:245], v[54:57]
	ds_read_b128 v[162:165], v129 offset:41472
	v_mfma_f32_16x16x32_bf16 v[58:61], v[226:229], v[246:249], v[58:61]
	ds_read_b128 v[166:169], v129 offset:43776
	v_mfma_f32_16x16x32_bf16 v[62:65], v[226:229], v[250:253], v[62:65]
	v_mfma_f32_16x16x32_bf16 v[66:69], v[230:233], v[238:241], v[66:69]
	v_lshl_add_u64 v[112:113], v[112:113], 0, s[10:11]
	v_mfma_f32_16x16x32_bf16 v[70:73], v[230:233], v[242:245], v[70:73]
	v_lshl_add_u64 v[110:111], v[110:111], 0, s[10:11]
	v_mfma_f32_16x16x32_bf16 v[74:77], v[230:233], v[246:249], v[74:77]
	v_lshl_add_u64 v[108:109], v[108:109], 0, s[10:11]
	v_mfma_f32_16x16x32_bf16 v[78:81], v[230:233], v[250:253], v[78:81]
	v_lshl_add_u64 v[106:107], v[106:107], 0, s[10:11]
	v_mfma_f32_16x16x32_bf16 v[82:85], v[234:237], v[238:241], v[82:85]
	v_lshl_add_u64 v[104:105], v[104:105], 0, s[10:11]
	v_mfma_f32_16x16x32_bf16 v[86:89], v[234:237], v[242:245], v[86:89]
	v_lshl_add_u64 v[102:103], v[102:103], 0, s[10:11]
	v_mfma_f32_16x16x32_bf16 v[90:93], v[234:237], v[246:249], v[90:93]
	v_lshl_add_u64 v[100:101], v[100:101], 0, s[10:11]
	v_mfma_f32_16x16x32_bf16 v[94:97], v[234:237], v[250:253], v[94:97]
	v_lshl_add_u64 v[98:99], v[98:99], 0, s[10:11]
	s_add_i32 s15, s15, 1
	s_cmp_lg_u32 s15, 7
	s_cbranch_scc1 .Lgk5_loop
	s_waitcnt lgkmcnt(0)
	ds_read_b128 v[222:225], v161 offset:64
	ds_read_b128 v[226:229], v161 offset:2368
	ds_read_b128 v[230:233], v161 offset:4672
	ds_read_b128 v[234:237], v161 offset:6976
	ds_read_b128 v[238:241], v129 offset:36928
	ds_read_b128 v[242:245], v129 offset:39232
	ds_read_b128 v[246:249], v129 offset:41536
	ds_read_b128 v[250:253], v129 offset:43840
	v_mfma_f32_16x16x32_bf16 v[34:37], v[130:133], v[146:149], v[34:37]
	v_mfma_f32_16x16x32_bf16 v[38:41], v[130:133], v[150:153], v[38:41]
	v_mfma_f32_16x16x32_bf16 v[42:45], v[130:133], v[162:165], v[42:45]
	v_mfma_f32_16x16x32_bf16 v[46:49], v[130:133], v[166:169], v[46:49]
	s_waitcnt vmcnt(0)
	ds_write_b128 v122, v[22:25] offset:18432
	ds_write_b128 v122, v[6:9] offset:55296
	v_mfma_f32_16x16x32_bf16 v[50:53], v[134:137], v[146:149], v[50:53]
	ds_write_b128 v121, v[18:21] offset:18432
	ds_write_b128 v121, v[10:13] offset:55296
	v_mfma_f32_16x16x32_bf16 v[54:57], v[134:137], v[150:153], v[54:57]
	ds_write_b128 v120, v[14:17] offset:18432
	ds_write_b128 v120, v[2:5] offset:55296
	v_mfma_f32_16x16x32_bf16 v[58:61], v[134:137], v[162:165], v[58:61]
	ds_write_b128 v124, v[26:29] offset:18432
	ds_write_b128 v124, v[30:33] offset:55296
	v_mfma_f32_16x16x32_bf16 v[62:65], v[134:137], v[166:169], v[62:65]
	v_mfma_f32_16x16x32_bf16 v[66:69], v[138:141], v[146:149], v[66:69]
	v_mfma_f32_16x16x32_bf16 v[70:73], v[138:141], v[150:153], v[70:73]
	v_mfma_f32_16x16x32_bf16 v[74:77], v[138:141], v[162:165], v[74:77]
	v_mfma_f32_16x16x32_bf16 v[78:81], v[138:141], v[166:169], v[78:81]
	v_mfma_f32_16x16x32_bf16 v[82:85], v[142:145], v[146:149], v[82:85]
	v_mfma_f32_16x16x32_bf16 v[86:89], v[142:145], v[150:153], v[86:89]
	v_mfma_f32_16x16x32_bf16 v[90:93], v[142:145], v[162:165], v[90:93]
	v_mfma_f32_16x16x32_bf16 v[94:97], v[142:145], v[166:169], v[94:97]
	s_waitcnt lgkmcnt(0)
	s_barrier
	ds_read_b128 v[130:133], v161 offset:18432
	v_mfma_f32_16x16x32_bf16 v[34:37], v[222:225], v[238:241], v[34:37]
	ds_read_b128 v[134:137], v161 offset:20736
	v_mfma_f32_16x16x32_bf16 v[38:41], v[222:225], v[242:245], v[38:41]
	ds_read_b128 v[138:141], v161 offset:23040
	v_mfma_f32_16x16x32_bf16 v[42:45], v[222:225], v[246:249], v[42:45]
	ds_read_b128 v[142:145], v161 offset:25344
	v_mfma_f32_16x16x32_bf16 v[46:49], v[222:225], v[250:253], v[46:49]
	ds_read_b128 v[146:149], v129 offset:55296
	v_mfma_f32_16x16x32_bf16 v[50:53], v[226:229], v[238:241], v[50:53]
	ds_read_b128 v[150:153], v129 offset:57600
	v_mfma_f32_16x16x32_bf16 v[54:57], v[226:229], v[242:245], v[54:57]
	ds_read_b128 v[162:165], v129 offset:59904
	v_mfma_f32_16x16x32_bf16 v[58:61], v[226:229], v[246:249], v[58:61]
	ds_read_b128 v[166:169], v129 offset:62208
	v_mfma_f32_16x16x32_bf16 v[62:65], v[226:229], v[250:253], v[62:65]
	v_mfma_f32_16x16x32_bf16 v[66:69], v[230:233], v[238:241], v[66:69]
	v_mfma_f32_16x16x32_bf16 v[70:73], v[230:233], v[242:245], v[70:73]
	v_mfma_f32_16x16x32_bf16 v[74:77], v[230:233], v[246:249], v[74:77]
	v_mfma_f32_16x16x32_bf16 v[78:81], v[230:233], v[250:253], v[78:81]
	v_mfma_f32_16x16x32_bf16 v[82:85], v[234:237], v[238:241], v[82:85]
	v_mfma_f32_16x16x32_bf16 v[86:89], v[234:237], v[242:245], v[86:89]
	v_mfma_f32_16x16x32_bf16 v[90:93], v[234:237], v[246:249], v[90:93]
	v_mfma_f32_16x16x32_bf16 v[94:97], v[234:237], v[250:253], v[94:97]
	s_waitcnt lgkmcnt(0)
; DEV f32x4 mfma16(bf16x8 a, bf16x8 b, f32x4 c) { return __builtin_amdgcn_mfma_f32_16x16x32_bf16(a, b, c, 0, 0, 0); }
; template <int EPI, bool AF32>
; DEV void gemm_tile(const void* Ap, int lda, const u16* Bt, int ldb, int K, int m0, int n0, const Epi& ea, char* smem) {
;     ...
;     for (int ks = 0; ks < 2; ks++) {
;       bf16x8 a[4], b[4];
; #pragma unroll
;       for (int m = 0; m < 4; m++) a[m] = *(const bf16x8*)(sA + buf * 9216 + (wr * 64 + m * 16 + fr) * 72 + ks * 32 + fq * 8);
; #pragma unroll
;       for (int n = 0; n < 4; n++) b[n] = *(const bf16x8*)(sB + buf * 9216 + (wc * 64 + n * 16 + fr) * 72 + ks * 32 + fq * 8);
;       __builtin_amdgcn_s_setprio(1);
; #pragma unroll
;       for (int m = 0; m < 4; m++)
; #pragma unroll
;         for (int n = 0; n < 4; n++) acc[m][n] = mfma16(a[m], b[n], acc[m][n]);
;       __builtin_amdgcn_s_setprio(0);
;     }
;     __syncthreads();
;     ...
;     const int rbase = m0 + wr * 64 + fq * 4, cbase = cb + fr;
;     float* C = (float*)ea.p0;
;     const u16* R = (const u16*)ea.p1;
;     u16 rv[4][4][4];
; #pragma unroll
;     for (int m = 0; m < 4; m++)
; #pragma unroll
;       for (int j = 0; j < 4; j++)
; #pragma unroll
;         for (int n = 0; n < 4; n++) rv[m][j][n] = R[(size_t)(rbase + m * 16 + j) * 1024 + cbase + n * 16];
	ds_read_b128 v[222:225], v161 offset:18496
	ds_read_b128 v[226:229], v161 offset:20800
	ds_read_b128 v[230:233], v161 offset:23104
	ds_read_b128 v[234:237], v161 offset:25408
	ds_read_b128 v[238:241], v129 offset:55360
	ds_read_b128 v[242:245], v129 offset:57664
	ds_read_b128 v[246:249], v129 offset:59968
	ds_read_b128 v[250:253], v129 offset:62272
	v_mfma_f32_16x16x32_bf16 v[34:37], v[130:133], v[146:149], v[34:37]
	v_mfma_f32_16x16x32_bf16 v[38:41], v[130:133], v[150:153], v[38:41]
	v_mfma_f32_16x16x32_bf16 v[42:45], v[130:133], v[162:165], v[42:45]
	v_mfma_f32_16x16x32_bf16 v[46:49], v[130:133], v[166:169], v[46:49]
	v_mfma_f32_16x16x32_bf16 v[50:53], v[134:137], v[146:149], v[50:53]
	v_mfma_f32_16x16x32_bf16 v[54:57], v[134:137], v[150:153], v[54:57]
	v_mfma_f32_16x16x32_bf16 v[58:61], v[134:137], v[162:165], v[58:61]
	v_mfma_f32_16x16x32_bf16 v[62:65], v[134:137], v[166:169], v[62:65]
	v_mfma_f32_16x16x32_bf16 v[66:69], v[138:141], v[146:149], v[66:69]
	v_mfma_f32_16x16x32_bf16 v[70:73], v[138:141], v[150:153], v[70:73]
	v_mfma_f32_16x16x32_bf16 v[74:77], v[138:141], v[162:165], v[74:77]
	v_mfma_f32_16x16x32_bf16 v[78:81], v[138:141], v[166:169], v[78:81]
	v_mfma_f32_16x16x32_bf16 v[82:85], v[142:145], v[146:149], v[82:85]
	v_mfma_f32_16x16x32_bf16 v[86:89], v[142:145], v[150:153], v[86:89]
	v_mfma_f32_16x16x32_bf16 v[90:93], v[142:145], v[162:165], v[90:93]
	v_mfma_f32_16x16x32_bf16 v[94:97], v[142:145], v[166:169], v[94:97]
	s_waitcnt lgkmcnt(0)
	v_mfma_f32_16x16x32_bf16 v[110:113], v[222:225], v[238:241], v[34:37]
	v_mfma_f32_16x16x32_bf16 v[118:121], v[222:225], v[242:245], v[38:41]
	v_mfma_f32_16x16x32_bf16 v[122:125], v[222:225], v[246:249], v[42:45]
	v_mfma_f32_16x16x32_bf16 v[126:129], v[222:225], v[250:253], v[46:49]
	v_mfma_f32_16x16x32_bf16 v[46:49], v[226:229], v[238:241], v[50:53]
	v_mfma_f32_16x16x32_bf16 v[42:45], v[226:229], v[242:245], v[54:57]
	v_mfma_f32_16x16x32_bf16 v[38:41], v[226:229], v[246:249], v[58:61]
	v_mfma_f32_16x16x32_bf16 v[34:37], v[226:229], v[250:253], v[62:65]
	v_mfma_f32_16x16x32_bf16 v[30:33], v[230:233], v[238:241], v[66:69]
	v_mfma_f32_16x16x32_bf16 v[26:29], v[230:233], v[242:245], v[70:73]
	v_mfma_f32_16x16x32_bf16 v[22:25], v[230:233], v[246:249], v[74:77]
	v_mfma_f32_16x16x32_bf16 v[18:21], v[230:233], v[250:253], v[78:81]
	v_mfma_f32_16x16x32_bf16 v[14:17], v[234:237], v[238:241], v[82:85]
	v_mfma_f32_16x16x32_bf16 v[10:13], v[234:237], v[242:245], v[86:89]
	v_mfma_f32_16x16x32_bf16 v[6:9], v[234:237], v[246:249], v[90:93]
	v_mfma_f32_16x16x32_bf16 v[2:5], v[234:237], v[250:253], v[94:97]
	s_nop 7
	v_and_b32_e32 v114, 64, v114
	v_add_u32_e32 v0, s14, v117
	v_lshl_or_b32 v60, v116, 2, v0
	v_or3_b32 v62, v114, s13, v115
	v_ashrrev_i32_e32 v63, 31, v62
	v_ashrrev_i32_e32 v61, 31, v60
	v_or_b32_e32 v68, 1, v60
	v_lshl_add_u64 v[64:65], v[62:63], 1, s[60:61]
	v_lshlrev_b64 v[50:51], 11, v[60:61]
	v_ashrrev_i32_e32 v69, 31, v68
	v_or_b32_e32 v72, 2, v60
	v_lshl_add_u64 v[66:67], v[64:65], 0, v[50:51]
	v_lshlrev_b64 v[50:51], 11, v[68:69]
	v_ashrrev_i32_e32 v73, 31, v72
	v_or_b32_e32 v76, 3, v60
	v_lshl_add_u64 v[70:71], v[64:65], 0, v[50:51]
	v_lshlrev_b64 v[50:51], 11, v[72:73]
	v_ashrrev_i32_e32 v77, 31, v76
	v_or_b32_e32 v80, 16, v60
	v_lshl_add_u64 v[74:75], v[64:65], 0, v[50:51]
	v_lshlrev_b64 v[50:51], 11, v[76:77]
	v_ashrrev_i32_e32 v81, 31, v80
	v_or_b32_e32 v84, 17, v60
	v_lshl_add_u64 v[78:79], v[64:65], 0, v[50:51]
	v_lshlrev_b64 v[50:51], 11, v[80:81]
	v_ashrrev_i32_e32 v85, 31, v84
	v_or_b32_e32 v88, 18, v60
	v_lshl_add_u64 v[82:83], v[64:65], 0, v[50:51]
	v_lshlrev_b64 v[50:51], 11, v[84:85]
	v_ashrrev_i32_e32 v89, 31, v88
	v_or_b32_e32 v92, 19, v60
	v_lshl_add_u64 v[86:87], v[64:65], 0, v[50:51]
	v_lshlrev_b64 v[50:51], 11, v[88:89]
	v_ashrrev_i32_e32 v93, 31, v92
	v_or_b32_e32 v96, 32, v60
	v_lshl_add_u64 v[90:91], v[64:65], 0, v[50:51]
	v_lshlrev_b64 v[50:51], 11, v[92:93]
	v_ashrrev_i32_e32 v97, 31, v96
	v_or_b32_e32 v100, 33, v60
	v_lshl_add_u64 v[94:95], v[64:65], 0, v[50:51]
	v_lshlrev_b64 v[50:51], 11, v[96:97]
	v_ashrrev_i32_e32 v101, 31, v100
	v_or_b32_e32 v104, 34, v60
	v_lshl_add_u64 v[98:99], v[64:65], 0, v[50:51]
	v_lshlrev_b64 v[50:51], 11, v[100:101]
	v_ashrrev_i32_e32 v105, 31, v104
	v_or_b32_e32 v58, 35, v60
	v_lshl_add_u64 v[102:103], v[64:65], 0, v[50:51]
	v_lshlrev_b64 v[50:51], 11, v[104:105]
	v_ashrrev_i32_e32 v59, 31, v58
	v_or_b32_e32 v56, 48, v60
	v_lshl_add_u64 v[106:107], v[64:65], 0, v[50:51]
	v_lshlrev_b64 v[50:51], 11, v[58:59]
	v_ashrrev_i32_e32 v57, 31, v56
	v_or_b32_e32 v54, 49, v60
	v_lshl_add_u64 v[108:109], v[64:65], 0, v[50:51]
	v_lshlrev_b64 v[50:51], 11, v[56:57]
	v_ashrrev_i32_e32 v55, 31, v54
	v_or_b32_e32 v52, 50, v60
	v_lshl_add_u64 v[114:115], v[64:65], 0, v[50:51]
	v_lshlrev_b64 v[50:51], 11, v[54:55]
	v_ashrrev_i32_e32 v53, 31, v52
	v_lshl_add_u64 v[116:117], v[64:65], 0, v[50:51]
	v_lshlrev_b64 v[50:51], 11, v[52:53]
	v_lshl_add_u64 v[130:131], v[64:65], 0, v[50:51]
	v_or_b32_e32 v50, 51, v60
	v_ashrrev_i32_e32 v51, 31, v50
	v_lshlrev_b64 v[132:133], 11, v[50:51]
	v_lshl_add_u64 v[64:65], v[64:65], 0, v[132:133]
	s_barrier
; DEV float bf2f(u16 h) { return __uint_as_float(((unsigned)h) << 16); }
; template <int EPI, bool AF32>
; DEV void gemm_tile(const void* Ap, int lda, const u16* Bt, int ldb, int K, int m0, int n0, const Epi& ea, char* smem) {
;     ...
;     const int rbase = m0 + wr * 64 + fq * 4, cbase = cb + fr;
;     float* C = (float*)ea.p0;
;     const u16* R = (const u16*)ea.p1;
;     u16 rv[4][4][4];
; #pragma unroll
;     for (int m = 0; m < 4; m++)
; #pragma unroll
;       for (int j = 0; j < 4; j++)
; #pragma unroll
;         for (int n = 0; n < 4; n++) rv[m][j][n] = R[(size_t)(rbase + m * 16 + j) * 1024 + cbase + n * 16];
;     __builtin_amdgcn_sched_barrier(0);
; #pragma unroll
;     for (int m = 0; m < 4; m++)
; #pragma unroll
;       for (int j = 0; j < 4; j++)
; #pragma unroll
;         for (int n = 0; n < 4; n++)
;           C[(size_t)(rbase + m * 16 + j) * 1024 + cbase + n * 16] = ALPHA_ * bf2f(rv[m][j][n]) + acc[m][n][j];
	global_load_ushort v0, v[66:67], off
	global_load_ushort v132, v[66:67], off offset:32
	global_load_ushort v133, v[66:67], off offset:64
	s_nop 0
	global_load_ushort v66, v[66:67], off offset:96
	s_nop 0
	global_load_ushort v67, v[70:71], off
	global_load_ushort v134, v[70:71], off offset:32
	global_load_ushort v135, v[70:71], off offset:64
	s_nop 0
	global_load_ushort v70, v[70:71], off offset:96
	s_nop 0
	global_load_ushort v71, v[74:75], off
	global_load_ushort v136, v[74:75], off offset:32
	global_load_ushort v137, v[74:75], off offset:64
	s_nop 0
	global_load_ushort v74, v[74:75], off offset:96
	s_nop 0
	global_load_ushort v75, v[78:79], off
	global_load_ushort v138, v[78:79], off offset:32
	global_load_ushort v139, v[78:79], off offset:64
	s_nop 0
	global_load_ushort v78, v[78:79], off offset:96
	s_nop 0
	global_load_ushort v79, v[82:83], off
	global_load_ushort v140, v[82:83], off offset:32
	global_load_ushort v141, v[82:83], off offset:64
	s_nop 0
	global_load_ushort v82, v[82:83], off offset:96
	s_nop 0
	global_load_ushort v83, v[86:87], off
	global_load_ushort v142, v[86:87], off offset:32
	global_load_ushort v143, v[86:87], off offset:64
	s_nop 0
	global_load_ushort v86, v[86:87], off offset:96
	s_nop 0
	global_load_ushort v87, v[90:91], off
	global_load_ushort v144, v[90:91], off offset:32
	global_load_ushort v145, v[90:91], off offset:64
	s_nop 0
	global_load_ushort v90, v[90:91], off offset:96
	s_nop 0
	global_load_ushort v91, v[94:95], off
	global_load_ushort v146, v[94:95], off offset:32
	global_load_ushort v147, v[94:95], off offset:64
	s_nop 0
	global_load_ushort v94, v[94:95], off offset:96
	s_nop 0
	global_load_ushort v95, v[98:99], off
	global_load_ushort v148, v[98:99], off offset:32
	global_load_ushort v149, v[98:99], off offset:64
	s_nop 0
	global_load_ushort v98, v[98:99], off offset:96
	s_nop 0
	global_load_ushort v99, v[102:103], off
	global_load_ushort v150, v[102:103], off offset:32
	global_load_ushort v151, v[102:103], off offset:64
	s_nop 0
	global_load_ushort v102, v[102:103], off offset:96
	s_nop 0
	global_load_ushort v103, v[106:107], off
	global_load_ushort v152, v[106:107], off offset:32
	global_load_ushort v153, v[106:107], off offset:64
	s_nop 0
	global_load_ushort v106, v[106:107], off offset:96
	s_nop 0
	global_load_ushort v107, v[108:109], off
	global_load_ushort v161, v[108:109], off offset:32
	global_load_ushort v162, v[108:109], off offset:64
	s_nop 0
	global_load_ushort v108, v[108:109], off offset:96
	s_nop 0
	global_load_ushort v109, v[114:115], off
	global_load_ushort v163, v[114:115], off offset:32
	global_load_ushort v164, v[114:115], off offset:64
	s_nop 0
	global_load_ushort v114, v[114:115], off offset:96
	s_nop 0
	global_load_ushort v115, v[116:117], off
	global_load_ushort v165, v[116:117], off offset:32
	global_load_ushort v166, v[116:117], off offset:64
	s_nop 0
	global_load_ushort v116, v[116:117], off offset:96
	s_nop 0
	global_load_ushort v117, v[130:131], off
	global_load_ushort v167, v[130:131], off offset:32
	global_load_ushort v168, v[130:131], off offset:64
	s_nop 0
	global_load_ushort v130, v[130:131], off offset:96
	s_nop 0
	global_load_ushort v131, v[64:65], off
	global_load_ushort v169, v[64:65], off offset:32
	global_load_ushort v170, v[64:65], off offset:64
	s_nop 0
	global_load_ushort v64, v[64:65], off offset:96
	v_lshl_add_u64 v[62:63], v[62:63], 2, s[2:3]
	v_lshlrev_b64 v[60:61], 12, v[60:61]
	s_waitcnt vmcnt(62)
	v_lshlrev_b32_e32 v0, 16, v0
	v_lshl_add_u64 v[60:61], v[62:63], 0, v[60:61]
	v_fmamk_f32 v0, v0, 0x3fb504f3, v110
	global_store_dword v[60:61], v0, off
	v_lshlrev_b32_e32 v0, 16, v132
	v_fmamk_f32 v0, v0, 0x3fb504f3, v118
	global_store_dword v[60:61], v0, off offset:64
	s_waitcnt vmcnt(62)
	v_lshlrev_b32_e32 v0, 16, v133
	v_fmamk_f32 v0, v0, 0x3fb504f3, v122
	global_store_dword v[60:61], v0, off offset:128
	v_lshlrev_b32_e32 v0, 16, v66
	v_fmamk_f32 v0, v0, 0x3fb504f3, v126
	global_store_dword v[60:61], v0, off offset:192
	v_lshlrev_b64 v[60:61], 12, v[68:69]
	s_waitcnt vmcnt(62)
	v_lshlrev_b32_e32 v0, 16, v67
	v_lshl_add_u64 v[60:61], v[62:63], 0, v[60:61]
	v_fmamk_f32 v0, v0, 0x3fb504f3, v111
	global_store_dword v[60:61], v0, off
	v_lshlrev_b32_e32 v0, 16, v134
	v_fmamk_f32 v0, v0, 0x3fb504f3, v119
	global_store_dword v[60:61], v0, off offset:64
	s_waitcnt vmcnt(62)
	v_lshlrev_b32_e32 v0, 16, v135
	v_fmamk_f32 v0, v0, 0x3fb504f3, v123
	global_store_dword v[60:61], v0, off offset:128
	v_lshlrev_b32_e32 v0, 16, v70
	v_fmamk_f32 v0, v0, 0x3fb504f3, v127
	global_store_dword v[60:61], v0, off offset:192
	v_lshlrev_b64 v[60:61], 12, v[72:73]
	s_waitcnt vmcnt(62)
	v_lshlrev_b32_e32 v0, 16, v71
	v_lshl_add_u64 v[60:61], v[62:63], 0, v[60:61]
	v_fmamk_f32 v0, v0, 0x3fb504f3, v112
	global_store_dword v[60:61], v0, off
	v_lshlrev_b32_e32 v0, 16, v136
	v_fmamk_f32 v0, v0, 0x3fb504f3, v120
	global_store_dword v[60:61], v0, off offset:64
	s_waitcnt vmcnt(62)
	v_lshlrev_b32_e32 v0, 16, v137
	v_fmamk_f32 v0, v0, 0x3fb504f3, v124
	global_store_dword v[60:61], v0, off offset:128
	v_lshlrev_b32_e32 v0, 16, v74
	v_fmamk_f32 v0, v0, 0x3fb504f3, v128
	global_store_dword v[60:61], v0, off offset:192
	s_waitcnt vmcnt(62)
	v_lshlrev_b32_e32 v0, 16, v75
	v_fmac_f32_e32 v113, 0x3fb504f3, v0
	v_lshlrev_b32_e32 v0, 16, v138
	v_fmac_f32_e32 v121, 0x3fb504f3, v0
	s_waitcnt vmcnt(61)
	v_lshlrev_b32_e32 v0, 16, v139
	v_lshlrev_b64 v[60:61], 12, v[76:77]
	v_fmac_f32_e32 v125, 0x3fb504f3, v0
	s_waitcnt vmcnt(60)
; DEV float bf2f(u16 h) { return __uint_as_float(((unsigned)h) << 16); }
; template <int EPI, bool AF32>
; DEV void gemm_tile(const void* Ap, int lda, const u16* Bt, int ldb, int K, int m0, int n0, const Epi& ea, char* smem) {
;     ...
; #pragma unroll
;     for (int m = 0; m < 4; m++)
; #pragma unroll
;       for (int j = 0; j < 4; j++)
; #pragma unroll
;         for (int n = 0; n < 4; n++)
;           C[(size_t)(rbase + m * 16 + j) * 1024 + cbase + n * 16] = ALPHA_ * bf2f(rv[m][j][n]) + acc[m][n][j];
	v_lshlrev_b32_e32 v0, 16, v78
	v_lshl_add_u64 v[60:61], v[62:63], 0, v[60:61]
	v_fmac_f32_e32 v129, 0x3fb504f3, v0
	global_store_dword v[60:61], v113, off
	global_store_dword v[60:61], v121, off offset:64
	global_store_dword v[60:61], v125, off offset:128
	global_store_dword v[60:61], v129, off offset:192
	v_lshlrev_b64 v[60:61], 12, v[80:81]
	s_waitcnt vmcnt(62)
	v_lshlrev_b32_e32 v0, 16, v79
	v_lshl_add_u64 v[60:61], v[62:63], 0, v[60:61]
	v_fmamk_f32 v0, v0, 0x3fb504f3, v46
	global_store_dword v[60:61], v0, off
	v_lshlrev_b32_e32 v0, 16, v140
	v_fmamk_f32 v0, v0, 0x3fb504f3, v42
	global_store_dword v[60:61], v0, off offset:64
	s_waitcnt vmcnt(62)
	v_lshlrev_b32_e32 v0, 16, v141
	v_fmamk_f32 v0, v0, 0x3fb504f3, v38
	global_store_dword v[60:61], v0, off offset:128
	v_lshlrev_b32_e32 v0, 16, v82
	v_fmamk_f32 v0, v0, 0x3fb504f3, v34
	global_store_dword v[60:61], v0, off offset:192
	v_lshlrev_b64 v[60:61], 12, v[84:85]
	s_waitcnt vmcnt(62)
	v_lshlrev_b32_e32 v0, 16, v83
	v_lshl_add_u64 v[60:61], v[62:63], 0, v[60:61]
	v_fmamk_f32 v0, v0, 0x3fb504f3, v47
	global_store_dword v[60:61], v0, off
	v_lshlrev_b32_e32 v0, 16, v142
	v_fmamk_f32 v0, v0, 0x3fb504f3, v43
	global_store_dword v[60:61], v0, off offset:64
	s_waitcnt vmcnt(62)
	v_lshlrev_b32_e32 v0, 16, v143
	v_fmamk_f32 v0, v0, 0x3fb504f3, v39
	global_store_dword v[60:61], v0, off offset:128
	v_lshlrev_b32_e32 v0, 16, v86
	v_fmamk_f32 v0, v0, 0x3fb504f3, v35
	global_store_dword v[60:61], v0, off offset:192
	v_lshlrev_b64 v[34:35], 12, v[88:89]
	s_waitcnt vmcnt(62)
	v_lshlrev_b32_e32 v0, 16, v87
	v_lshl_add_u64 v[34:35], v[62:63], 0, v[34:35]
	v_fmamk_f32 v0, v0, 0x3fb504f3, v48
	global_store_dword v[34:35], v0, off
	v_lshlrev_b32_e32 v0, 16, v144
	v_fmamk_f32 v0, v0, 0x3fb504f3, v44
	global_store_dword v[34:35], v0, off offset:64
	s_waitcnt vmcnt(62)
	v_lshlrev_b32_e32 v0, 16, v145
	v_fmamk_f32 v0, v0, 0x3fb504f3, v40
	global_store_dword v[34:35], v0, off offset:128
	v_lshlrev_b32_e32 v0, 16, v90
	v_fmamk_f32 v0, v0, 0x3fb504f3, v36
	global_store_dword v[34:35], v0, off offset:192
	s_waitcnt vmcnt(62)
	v_lshlrev_b32_e32 v0, 16, v91
	v_fmac_f32_e32 v49, 0x3fb504f3, v0
	v_lshlrev_b32_e32 v0, 16, v146
	v_fmac_f32_e32 v45, 0x3fb504f3, v0
	s_waitcnt vmcnt(61)
	v_lshlrev_b32_e32 v0, 16, v147
	v_lshlrev_b64 v[34:35], 12, v[92:93]
	v_fmac_f32_e32 v41, 0x3fb504f3, v0
	s_waitcnt vmcnt(60)
	v_lshlrev_b32_e32 v0, 16, v94
	v_lshl_add_u64 v[34:35], v[62:63], 0, v[34:35]
	v_fmac_f32_e32 v37, 0x3fb504f3, v0
	global_store_dword v[34:35], v49, off
	global_store_dword v[34:35], v45, off offset:64
	global_store_dword v[34:35], v41, off offset:128
	global_store_dword v[34:35], v37, off offset:192
	v_lshlrev_b64 v[34:35], 12, v[96:97]
	s_waitcnt vmcnt(62)
	v_lshlrev_b32_e32 v0, 16, v95
	v_lshl_add_u64 v[34:35], v[62:63], 0, v[34:35]
	v_fmamk_f32 v0, v0, 0x3fb504f3, v30
	global_store_dword v[34:35], v0, off
	v_lshlrev_b32_e32 v0, 16, v148
	v_fmamk_f32 v0, v0, 0x3fb504f3, v26
	global_store_dword v[34:35], v0, off offset:64
	s_waitcnt vmcnt(62)
	v_lshlrev_b32_e32 v0, 16, v149
	v_fmamk_f32 v0, v0, 0x3fb504f3, v22
	global_store_dword v[34:35], v0, off offset:128
	v_lshlrev_b32_e32 v0, 16, v98
	v_fmamk_f32 v0, v0, 0x3fb504f3, v18
	global_store_dword v[34:35], v0, off offset:192
	v_lshlrev_b64 v[34:35], 12, v[100:101]
	s_waitcnt vmcnt(62)
	v_lshlrev_b32_e32 v0, 16, v99
	v_lshl_add_u64 v[34:35], v[62:63], 0, v[34:35]
	v_fmamk_f32 v0, v0, 0x3fb504f3, v31
	global_store_dword v[34:35], v0, off
	v_lshlrev_b32_e32 v0, 16, v150
	v_fmamk_f32 v0, v0, 0x3fb504f3, v27
	global_store_dword v[34:35], v0, off offset:64
	s_waitcnt vmcnt(62)
; DEV int bidx() { int b = __builtin_amdgcn_readfirstlane(blockIdx.x); asm volatile("" : "+s"(b)); return b; }
; DEV int gdim() { int g = __builtin_amdgcn_readfirstlane(gridDim.x); asm volatile("" : "+s"(g)); return g; }
; DEV float bf2f(u16 h) { return __uint_as_float(((unsigned)h) << 16); }
; template <int EPI, bool AF32>
; DEV void gemm_tile(const void* Ap, int lda, const u16* Bt, int ldb, int K, int m0, int n0, const Epi& ea, char* smem) {
;     ...
; #pragma unroll
;     for (int m = 0; m < 4; m++)
; #pragma unroll
;       for (int j = 0; j < 4; j++)
; #pragma unroll
;         for (int n = 0; n < 4; n++)
;           C[(size_t)(rbase + m * 16 + j) * 1024 + cbase + n * 16] = ALPHA_ * bf2f(rv[m][j][n]) + acc[m][n][j];
; template <int EPI, bool AF32>
; DEV void gemm_phase(const void* A, int lda, const u16* Bt, int ldb, int M, int N, int K, const Epi& ea, char* smem) {
;     ...
;   for (int tile = bidx(); tile < ntm * ntn; tile += gdim()) {
;     int m, n;
;     tile_mn(tile, ntm, ntn, m, n);
	v_lshlrev_b32_e32 v0, 16, v151
	v_fmamk_f32 v0, v0, 0x3fb504f3, v23
	global_store_dword v[34:35], v0, off offset:128
	v_lshlrev_b32_e32 v0, 16, v102
	v_fmamk_f32 v0, v0, 0x3fb504f3, v19
	global_store_dword v[34:35], v0, off offset:192
	v_lshlrev_b64 v[18:19], 12, v[104:105]
	s_waitcnt vmcnt(62)
	v_lshlrev_b32_e32 v0, 16, v103
	v_lshl_add_u64 v[18:19], v[62:63], 0, v[18:19]
	v_fmamk_f32 v0, v0, 0x3fb504f3, v32
	global_store_dword v[18:19], v0, off
	v_lshlrev_b32_e32 v0, 16, v152
	v_fmamk_f32 v0, v0, 0x3fb504f3, v28
	global_store_dword v[18:19], v0, off offset:64
	s_waitcnt vmcnt(62)
	v_lshlrev_b32_e32 v0, 16, v153
	v_fmamk_f32 v0, v0, 0x3fb504f3, v24
	global_store_dword v[18:19], v0, off offset:128
	v_lshlrev_b32_e32 v0, 16, v106
	v_fmamk_f32 v0, v0, 0x3fb504f3, v20
	global_store_dword v[18:19], v0, off offset:192
	s_waitcnt vmcnt(62)
	v_lshlrev_b32_e32 v0, 16, v107
	v_fmac_f32_e32 v33, 0x3fb504f3, v0
	v_lshlrev_b32_e32 v0, 16, v161
	v_fmac_f32_e32 v29, 0x3fb504f3, v0
	s_waitcnt vmcnt(61)
	v_lshlrev_b32_e32 v0, 16, v162
	v_lshlrev_b64 v[18:19], 12, v[58:59]
	v_fmac_f32_e32 v25, 0x3fb504f3, v0
	s_waitcnt vmcnt(60)
	v_lshlrev_b32_e32 v0, 16, v108
	v_lshl_add_u64 v[18:19], v[62:63], 0, v[18:19]
	v_fmac_f32_e32 v21, 0x3fb504f3, v0
	global_store_dword v[18:19], v33, off
	global_store_dword v[18:19], v29, off offset:64
	global_store_dword v[18:19], v25, off offset:128
	global_store_dword v[18:19], v21, off offset:192
	v_lshlrev_b64 v[18:19], 12, v[56:57]
	s_waitcnt vmcnt(62)
	v_lshlrev_b32_e32 v0, 16, v109
	v_lshl_add_u64 v[18:19], v[62:63], 0, v[18:19]
	v_fmamk_f32 v0, v0, 0x3fb504f3, v14
	global_store_dword v[18:19], v0, off
	v_lshlrev_b32_e32 v0, 16, v163
	v_fmamk_f32 v0, v0, 0x3fb504f3, v10
	global_store_dword v[18:19], v0, off offset:64
	s_waitcnt vmcnt(62)
	v_lshlrev_b32_e32 v0, 16, v164
	v_fmamk_f32 v0, v0, 0x3fb504f3, v6
	global_store_dword v[18:19], v0, off offset:128
	v_lshlrev_b32_e32 v0, 16, v114
	v_fmamk_f32 v0, v0, 0x3fb504f3, v2
	global_store_dword v[18:19], v0, off offset:192
	v_lshlrev_b64 v[18:19], 12, v[54:55]
	s_waitcnt vmcnt(62)
	v_lshlrev_b32_e32 v0, 16, v115
	v_lshl_add_u64 v[18:19], v[62:63], 0, v[18:19]
	v_fmamk_f32 v0, v0, 0x3fb504f3, v15
	global_store_dword v[18:19], v0, off
	v_lshlrev_b32_e32 v0, 16, v165
	v_fmamk_f32 v0, v0, 0x3fb504f3, v11
	global_store_dword v[18:19], v0, off offset:64
	s_waitcnt vmcnt(62)
	v_lshlrev_b32_e32 v0, 16, v166
	v_fmamk_f32 v0, v0, 0x3fb504f3, v7
	global_store_dword v[18:19], v0, off offset:128
	v_lshlrev_b32_e32 v0, 16, v116
	v_fmamk_f32 v0, v0, 0x3fb504f3, v3
	global_store_dword v[18:19], v0, off offset:192
	v_lshlrev_b64 v[2:3], 12, v[52:53]
	s_waitcnt vmcnt(62)
	v_lshlrev_b32_e32 v0, 16, v117
	v_lshl_add_u64 v[2:3], v[62:63], 0, v[2:3]
	v_fmamk_f32 v0, v0, 0x3fb504f3, v16
	global_store_dword v[2:3], v0, off
	v_lshlrev_b32_e32 v0, 16, v167
	v_fmamk_f32 v0, v0, 0x3fb504f3, v12
	global_store_dword v[2:3], v0, off offset:64
	s_waitcnt vmcnt(62)
	v_lshlrev_b32_e32 v0, 16, v168
	v_fmamk_f32 v0, v0, 0x3fb504f3, v8
	global_store_dword v[2:3], v0, off offset:128
	v_lshlrev_b32_e32 v0, 16, v130
	v_fmamk_f32 v0, v0, 0x3fb504f3, v4
	global_store_dword v[2:3], v0, off offset:192
	s_waitcnt vmcnt(62)
	v_lshlrev_b32_e32 v0, 16, v131
	v_fmac_f32_e32 v17, 0x3fb504f3, v0
	v_lshlrev_b32_e32 v0, 16, v169
	v_fmac_f32_e32 v13, 0x3fb504f3, v0
	s_waitcnt vmcnt(61)
	v_lshlrev_b32_e32 v0, 16, v170
	v_lshlrev_b64 v[2:3], 12, v[50:51]
	v_fmac_f32_e32 v9, 0x3fb504f3, v0
	s_waitcnt vmcnt(60)
	v_lshlrev_b32_e32 v0, 16, v64
	v_lshl_add_u64 v[2:3], v[62:63], 0, v[2:3]
	v_fmac_f32_e32 v5, 0x3fb504f3, v0
	v_readfirstlane_b32 s10, v198
	global_store_dword v[2:3], v17, off
	global_store_dword v[2:3], v13, off offset:64
	global_store_dword v[2:3], v9, off offset:128
	global_store_dword v[2:3], v5, off offset:192
	s_add_i32 s12, s10, s12
	s_cmpk_lt_i32 s12, 0x820
	s_cbranch_scc1 .LBB0_1352

; DEV f32x4 mfma16(bf16x8 a, bf16x8 b, f32x4 c) { return __builtin_amdgcn_mfma_f32_16x16x32_bf16(a, b, c, 0, 0, 0); }
; template <int EPI, bool AF32>
; DEV void gemm_tile(const void* Ap, int lda, const u16* Bt, int ldb, int K, int m0, int n0, const Epi& ea, char* smem) {
;     ...
;   gload(0);
;   swrite(0);
;   if (nk > 1) gload(1);
;   __syncthreads();
;   for (int kt = 0; kt < nk; kt++) {
;     const int buf = kt & 1;
;     if (kt + 1 < nk) swrite(buf ^ 1);
;     if (kt + 2 < nk) gload(kt + 2);
; #pragma unroll
;     for (int ks = 0; ks < 2; ks++) {
;       bf16x8 a[4], b[4];
; #pragma unroll
;       for (int m = 0; m < 4; m++) a[m] = *(const bf16x8*)(sA + buf * 9216 + (wr * 64 + m * 16 + fr) * 72 + ks * 32 + fq * 8);
; #pragma unroll
;       for (int n = 0; n < 4; n++) b[n] = *(const bf16x8*)(sB + buf * 9216 + (wc * 64 + n * 16 + fr) * 72 + ks * 32 + fq * 8);
;       __builtin_amdgcn_s_setprio(1);
; #pragma unroll
;       for (int m = 0; m < 4; m++)
; #pragma unroll
;         for (int n = 0; n < 4; n++) acc[m][n] = mfma16(a[m], b[n], acc[m][n]);
;       __builtin_amdgcn_s_setprio(0);
;     }
;     __syncthreads();
;   }
.Lgk6_loop:
	s_waitcnt lgkmcnt(0)
	ds_read_b128 v[222:225], v161 offset:64
	ds_read_b128 v[226:229], v161 offset:2368
	ds_read_b128 v[230:233], v161 offset:4672
	ds_read_b128 v[234:237], v161 offset:6976
	ds_read_b128 v[238:241], v129 offset:36928
	ds_read_b128 v[242:245], v129 offset:39232
	ds_read_b128 v[246:249], v129 offset:41536
	ds_read_b128 v[250:253], v129 offset:43840
	v_mfma_f32_16x16x32_bf16 v[94:97], v[130:133], v[146:149], v[94:97]
	v_mfma_f32_16x16x32_bf16 v[90:93], v[130:133], v[150:153], v[90:93]
	v_mfma_f32_16x16x32_bf16 v[86:89], v[130:133], v[162:165], v[86:89]
	v_mfma_f32_16x16x32_bf16 v[82:85], v[130:133], v[166:169], v[82:85]
	s_waitcnt vmcnt(0)
	ds_write_b128 v122, v[22:25] offset:18432
	ds_write_b128 v122, v[6:9] offset:55296
	v_mfma_f32_16x16x32_bf16 v[78:81], v[134:137], v[146:149], v[78:81]
	ds_write_b128 v121, v[18:21] offset:18432
	ds_write_b128 v121, v[10:13] offset:55296
	v_mfma_f32_16x16x32_bf16 v[74:77], v[134:137], v[150:153], v[74:77]
	ds_write_b128 v120, v[14:17] offset:18432
	ds_write_b128 v120, v[2:5] offset:55296
	v_mfma_f32_16x16x32_bf16 v[70:73], v[134:137], v[162:165], v[70:73]
	ds_write_b128 v124, v[26:29] offset:18432
	ds_write_b128 v124, v[30:33] offset:55296
	v_mfma_f32_16x16x32_bf16 v[66:69], v[134:137], v[166:169], v[66:69]
	global_load_dwordx4 v[22:25], v[112:113], off
	v_mfma_f32_16x16x32_bf16 v[62:65], v[138:141], v[146:149], v[62:65]
	global_load_dwordx4 v[6:9], v[110:111], off
	v_mfma_f32_16x16x32_bf16 v[58:61], v[138:141], v[150:153], v[58:61]
	global_load_dwordx4 v[18:21], v[108:109], off
	v_mfma_f32_16x16x32_bf16 v[54:57], v[138:141], v[162:165], v[54:57]
	global_load_dwordx4 v[10:13], v[106:107], off
	v_mfma_f32_16x16x32_bf16 v[50:53], v[138:141], v[166:169], v[50:53]
	global_load_dwordx4 v[14:17], v[104:105], off
	v_mfma_f32_16x16x32_bf16 v[46:49], v[142:145], v[146:149], v[46:49]
	global_load_dwordx4 v[2:5], v[102:103], off
	v_mfma_f32_16x16x32_bf16 v[42:45], v[142:145], v[150:153], v[42:45]
	global_load_dwordx4 v[26:29], v[100:101], off
	v_mfma_f32_16x16x32_bf16 v[38:41], v[142:145], v[162:165], v[38:41]
	global_load_dwordx4 v[30:33], v[98:99], off
	v_mfma_f32_16x16x32_bf16 v[34:37], v[142:145], v[166:169], v[34:37]
	s_waitcnt lgkmcnt(0)
	s_barrier
	ds_read_b128 v[130:133], v161 offset:18432
	v_mfma_f32_16x16x32_bf16 v[94:97], v[222:225], v[238:241], v[94:97]
	ds_read_b128 v[134:137], v161 offset:20736
	v_mfma_f32_16x16x32_bf16 v[90:93], v[222:225], v[242:245], v[90:93]
	ds_read_b128 v[138:141], v161 offset:23040
	v_mfma_f32_16x16x32_bf16 v[86:89], v[222:225], v[246:249], v[86:89]
	ds_read_b128 v[142:145], v161 offset:25344
	v_mfma_f32_16x16x32_bf16 v[82:85], v[222:225], v[250:253], v[82:85]
	ds_read_b128 v[146:149], v129 offset:55296
	v_mfma_f32_16x16x32_bf16 v[78:81], v[226:229], v[238:241], v[78:81]
	ds_read_b128 v[150:153], v129 offset:57600
	v_mfma_f32_16x16x32_bf16 v[74:77], v[226:229], v[242:245], v[74:77]
	ds_read_b128 v[162:165], v129 offset:59904
	v_mfma_f32_16x16x32_bf16 v[70:73], v[226:229], v[246:249], v[70:73]
	ds_read_b128 v[166:169], v129 offset:62208
	v_mfma_f32_16x16x32_bf16 v[66:69], v[226:229], v[250:253], v[66:69]
	v_mfma_f32_16x16x32_bf16 v[62:65], v[230:233], v[238:241], v[62:65]
	v_mfma_f32_16x16x32_bf16 v[58:61], v[230:233], v[242:245], v[58:61]
	v_mfma_f32_16x16x32_bf16 v[54:57], v[230:233], v[246:249], v[54:57]
	v_mfma_f32_16x16x32_bf16 v[50:53], v[230:233], v[250:253], v[50:53]
	v_mfma_f32_16x16x32_bf16 v[46:49], v[234:237], v[238:241], v[46:49]
	v_mfma_f32_16x16x32_bf16 v[42:45], v[234:237], v[242:245], v[42:45]
	v_mfma_f32_16x16x32_bf16 v[38:41], v[234:237], v[246:249], v[38:41]
	v_mfma_f32_16x16x32_bf16 v[34:37], v[234:237], v[250:253], v[34:37]
	s_waitcnt lgkmcnt(0)
	ds_read_b128 v[222:225], v161 offset:18496
	ds_read_b128 v[226:229], v161 offset:20800
	ds_read_b128 v[230:233], v161 offset:23104
	ds_read_b128 v[234:237], v161 offset:25408
	ds_read_b128 v[238:241], v129 offset:55360
	ds_read_b128 v[242:245], v129 offset:57664
	ds_read_b128 v[246:249], v129 offset:59968
	ds_read_b128 v[250:253], v129 offset:62272
	v_mfma_f32_16x16x32_bf16 v[94:97], v[130:133], v[146:149], v[94:97]
	v_mfma_f32_16x16x32_bf16 v[90:93], v[130:133], v[150:153], v[90:93]
	v_mfma_f32_16x16x32_bf16 v[86:89], v[130:133], v[162:165], v[86:89]
	v_mfma_f32_16x16x32_bf16 v[82:85], v[130:133], v[166:169], v[82:85]
	s_waitcnt vmcnt(0)
	ds_write_b128 v122, v[22:25]
	ds_write_b128 v122, v[6:9] offset:36864
	v_mfma_f32_16x16x32_bf16 v[78:81], v[134:137], v[146:149], v[78:81]
	ds_write_b128 v121, v[18:21]
	ds_write_b128 v121, v[10:13] offset:36864
	v_mfma_f32_16x16x32_bf16 v[74:77], v[134:137], v[150:153], v[74:77]
	ds_write_b128 v120, v[14:17]
	ds_write_b128 v120, v[2:5] offset:36864
	v_mfma_f32_16x16x32_bf16 v[70:73], v[134:137], v[162:165], v[70:73]
	ds_write_b128 v124, v[26:29]
	ds_write_b128 v124, v[30:33] offset:36864
	v_mfma_f32_16x16x32_bf16 v[66:69], v[134:137], v[166:169], v[66:69]
	global_load_dwordx4 v[22:25], v[112:113], off offset:128
	v_mfma_f32_16x16x32_bf16 v[62:65], v[138:141], v[146:149], v[62:65]
	global_load_dwordx4 v[6:9], v[110:111], off offset:128
	v_mfma_f32_16x16x32_bf16 v[58:61], v[138:141], v[150:153], v[58:61]
	global_load_dwordx4 v[18:21], v[108:109], off offset:128
	v_mfma_f32_16x16x32_bf16 v[54:57], v[138:141], v[162:165], v[54:57]
	global_load_dwordx4 v[10:13], v[106:107], off offset:128
	v_mfma_f32_16x16x32_bf16 v[50:53], v[138:141], v[166:169], v[50:53]
	global_load_dwordx4 v[14:17], v[104:105], off offset:128
	v_mfma_f32_16x16x32_bf16 v[46:49], v[142:145], v[146:149], v[46:49]
	global_load_dwordx4 v[2:5], v[102:103], off offset:128
	v_mfma_f32_16x16x32_bf16 v[42:45], v[142:145], v[150:153], v[42:45]
	global_load_dwordx4 v[26:29], v[100:101], off offset:128
	v_mfma_f32_16x16x32_bf16 v[38:41], v[142:145], v[162:165], v[38:41]
	global_load_dwordx4 v[30:33], v[98:99], off offset:128
	v_mfma_f32_16x16x32_bf16 v[34:37], v[142:145], v[166:169], v[34:37]
	s_waitcnt lgkmcnt(0)
	s_barrier
; DEV f32x4 mfma16(bf16x8 a, bf16x8 b, f32x4 c) { return __builtin_amdgcn_mfma_f32_16x16x32_bf16(a, b, c, 0, 0, 0); }
; template <int EPI, bool AF32>
; DEV void gemm_tile(const void* Ap, int lda, const u16* Bt, int ldb, int K, int m0, int n0, const Epi& ea, char* smem) {
;     ...
;   for (int kt = 0; kt < nk; kt++) {
;     const int buf = kt & 1;
;     if (kt + 1 < nk) swrite(buf ^ 1);
;     if (kt + 2 < nk) gload(kt + 2);
; #pragma unroll
;     for (int ks = 0; ks < 2; ks++) {
;       bf16x8 a[4], b[4];
; #pragma unroll
;       for (int m = 0; m < 4; m++) a[m] = *(const bf16x8*)(sA + buf * 9216 + (wr * 64 + m * 16 + fr) * 72 + ks * 32 + fq * 8);
; #pragma unroll
;       for (int n = 0; n < 4; n++) b[n] = *(const bf16x8*)(sB + buf * 9216 + (wc * 64 + n * 16 + fr) * 72 + ks * 32 + fq * 8);
;       __builtin_amdgcn_s_setprio(1);
; #pragma unroll
;       for (int m = 0; m < 4; m++)
; #pragma unroll
;         for (int n = 0; n < 4; n++) acc[m][n] = mfma16(a[m], b[n], acc[m][n]);
;       __builtin_amdgcn_s_setprio(0);
;     }
;     __syncthreads();
	ds_read_b128 v[130:133], v161
	v_mfma_f32_16x16x32_bf16 v[94:97], v[222:225], v[238:241], v[94:97]
	ds_read_b128 v[134:137], v161 offset:2304
	v_mfma_f32_16x16x32_bf16 v[90:93], v[222:225], v[242:245], v[90:93]
	ds_read_b128 v[138:141], v161 offset:4608
	v_mfma_f32_16x16x32_bf16 v[86:89], v[222:225], v[246:249], v[86:89]
	ds_read_b128 v[142:145], v161 offset:6912
	v_mfma_f32_16x16x32_bf16 v[82:85], v[222:225], v[250:253], v[82:85]
	ds_read_b128 v[146:149], v129 offset:36864
	v_mfma_f32_16x16x32_bf16 v[78:81], v[226:229], v[238:241], v[78:81]
	ds_read_b128 v[150:153], v129 offset:39168
	v_mfma_f32_16x16x32_bf16 v[74:77], v[226:229], v[242:245], v[74:77]
	ds_read_b128 v[162:165], v129 offset:41472
	v_mfma_f32_16x16x32_bf16 v[70:73], v[226:229], v[246:249], v[70:73]
	ds_read_b128 v[166:169], v129 offset:43776
	v_mfma_f32_16x16x32_bf16 v[66:69], v[226:229], v[250:253], v[66:69]
	v_mfma_f32_16x16x32_bf16 v[62:65], v[230:233], v[238:241], v[62:65]
	v_lshl_add_u64 v[112:113], v[112:113], 0, s[0:1]
	v_mfma_f32_16x16x32_bf16 v[58:61], v[230:233], v[242:245], v[58:61]
	v_lshl_add_u64 v[110:111], v[110:111], 0, s[0:1]
	v_mfma_f32_16x16x32_bf16 v[54:57], v[230:233], v[246:249], v[54:57]
	v_lshl_add_u64 v[108:109], v[108:109], 0, s[0:1]
	v_mfma_f32_16x16x32_bf16 v[50:53], v[230:233], v[250:253], v[50:53]
	v_lshl_add_u64 v[106:107], v[106:107], 0, s[0:1]
	v_mfma_f32_16x16x32_bf16 v[46:49], v[234:237], v[238:241], v[46:49]
	v_lshl_add_u64 v[104:105], v[104:105], 0, s[0:1]
	v_mfma_f32_16x16x32_bf16 v[42:45], v[234:237], v[242:245], v[42:45]
	v_lshl_add_u64 v[102:103], v[102:103], 0, s[0:1]
	v_mfma_f32_16x16x32_bf16 v[38:41], v[234:237], v[246:249], v[38:41]
	v_lshl_add_u64 v[100:101], v[100:101], 0, s[0:1]
	v_mfma_f32_16x16x32_bf16 v[34:37], v[234:237], v[250:253], v[34:37]
	v_lshl_add_u64 v[98:99], v[98:99], 0, s[0:1]
	s_add_i32 s15, s15, 1
	s_cmp_lg_u32 s15, 7
	s_cbranch_scc1 .Lgk6_loop
	s_waitcnt lgkmcnt(0)
	ds_read_b128 v[222:225], v161 offset:64
	ds_read_b128 v[226:229], v161 offset:2368
	ds_read_b128 v[230:233], v161 offset:4672
	ds_read_b128 v[234:237], v161 offset:6976
	ds_read_b128 v[238:241], v129 offset:36928
	ds_read_b128 v[242:245], v129 offset:39232
	ds_read_b128 v[246:249], v129 offset:41536
	ds_read_b128 v[250:253], v129 offset:43840
	v_mfma_f32_16x16x32_bf16 v[94:97], v[130:133], v[146:149], v[94:97]
	v_mfma_f32_16x16x32_bf16 v[90:93], v[130:133], v[150:153], v[90:93]
	v_mfma_f32_16x16x32_bf16 v[86:89], v[130:133], v[162:165], v[86:89]
	v_mfma_f32_16x16x32_bf16 v[82:85], v[130:133], v[166:169], v[82:85]
	s_waitcnt vmcnt(0)
	ds_write_b128 v122, v[22:25] offset:18432
	ds_write_b128 v122, v[6:9] offset:55296
	v_mfma_f32_16x16x32_bf16 v[78:81], v[134:137], v[146:149], v[78:81]
	ds_write_b128 v121, v[18:21] offset:18432
	ds_write_b128 v121, v[10:13] offset:55296
	v_mfma_f32_16x16x32_bf16 v[74:77], v[134:137], v[150:153], v[74:77]
	ds_write_b128 v120, v[14:17] offset:18432
	ds_write_b128 v120, v[2:5] offset:55296
	v_mfma_f32_16x16x32_bf16 v[70:73], v[134:137], v[162:165], v[70:73]
	ds_write_b128 v124, v[26:29] offset:18432
	ds_write_b128 v124, v[30:33] offset:55296
	v_mfma_f32_16x16x32_bf16 v[66:69], v[134:137], v[166:169], v[66:69]
	v_mfma_f32_16x16x32_bf16 v[62:65], v[138:141], v[146:149], v[62:65]
	v_mfma_f32_16x16x32_bf16 v[58:61], v[138:141], v[150:153], v[58:61]
	v_mfma_f32_16x16x32_bf16 v[54:57], v[138:141], v[162:165], v[54:57]
	v_mfma_f32_16x16x32_bf16 v[50:53], v[138:141], v[166:169], v[50:53]
	v_mfma_f32_16x16x32_bf16 v[46:49], v[142:145], v[146:149], v[46:49]
	v_mfma_f32_16x16x32_bf16 v[42:45], v[142:145], v[150:153], v[42:45]
	v_mfma_f32_16x16x32_bf16 v[38:41], v[142:145], v[162:165], v[38:41]
	v_mfma_f32_16x16x32_bf16 v[34:37], v[142:145], v[166:169], v[34:37]
	s_waitcnt lgkmcnt(0)
	s_barrier
	ds_read_b128 v[130:133], v161 offset:18432
	v_mfma_f32_16x16x32_bf16 v[94:97], v[222:225], v[238:241], v[94:97]
	ds_read_b128 v[134:137], v161 offset:20736
	v_mfma_f32_16x16x32_bf16 v[90:93], v[222:225], v[242:245], v[90:93]
	ds_read_b128 v[138:141], v161 offset:23040
	v_mfma_f32_16x16x32_bf16 v[86:89], v[222:225], v[246:249], v[86:89]
	ds_read_b128 v[142:145], v161 offset:25344
	v_mfma_f32_16x16x32_bf16 v[82:85], v[222:225], v[250:253], v[82:85]
	ds_read_b128 v[146:149], v129 offset:55296
	v_mfma_f32_16x16x32_bf16 v[78:81], v[226:229], v[238:241], v[78:81]
	ds_read_b128 v[150:153], v129 offset:57600
	v_mfma_f32_16x16x32_bf16 v[74:77], v[226:229], v[242:245], v[74:77]
	ds_read_b128 v[162:165], v129 offset:59904
	v_mfma_f32_16x16x32_bf16 v[70:73], v[226:229], v[246:249], v[70:73]
	ds_read_b128 v[166:169], v129 offset:62208
	v_mfma_f32_16x16x32_bf16 v[66:69], v[226:229], v[250:253], v[66:69]
	v_mfma_f32_16x16x32_bf16 v[62:65], v[230:233], v[238:241], v[62:65]
	v_mfma_f32_16x16x32_bf16 v[58:61], v[230:233], v[242:245], v[58:61]
	v_mfma_f32_16x16x32_bf16 v[54:57], v[230:233], v[246:249], v[54:57]
	v_mfma_f32_16x16x32_bf16 v[50:53], v[230:233], v[250:253], v[50:53]
	v_mfma_f32_16x16x32_bf16 v[46:49], v[234:237], v[238:241], v[46:49]
	v_mfma_f32_16x16x32_bf16 v[42:45], v[234:237], v[242:245], v[42:45]
	v_mfma_f32_16x16x32_bf16 v[38:41], v[234:237], v[246:249], v[38:41]
	v_mfma_f32_16x16x32_bf16 v[34:37], v[234:237], v[250:253], v[34:37]
	s_waitcnt lgkmcnt(0)
; DEV float siluf(float x) { return x * __builtin_amdgcn_rcpf(1.f + __expf(-x)); }
; DEV f32x4 mfma16(bf16x8 a, bf16x8 b, f32x4 c) { return __builtin_amdgcn_mfma_f32_16x16x32_bf16(a, b, c, 0, 0, 0); }
; template <int EPI, bool AF32>
; DEV void gemm_tile(const void* Ap, int lda, const u16* Bt, int ldb, int K, int m0, int n0, const Epi& ea, char* smem) {
;     ...
;     for (int ks = 0; ks < 2; ks++) {
;       bf16x8 a[4], b[4];
; #pragma unroll
;       for (int m = 0; m < 4; m++) a[m] = *(const bf16x8*)(sA + buf * 9216 + (wr * 64 + m * 16 + fr) * 72 + ks * 32 + fq * 8);
; #pragma unroll
;       for (int n = 0; n < 4; n++) b[n] = *(const bf16x8*)(sB + buf * 9216 + (wc * 64 + n * 16 + fr) * 72 + ks * 32 + fq * 8);
;       __builtin_amdgcn_s_setprio(1);
; #pragma unroll
;       for (int m = 0; m < 4; m++)
; #pragma unroll
;         for (int n = 0; n < 4; n++) acc[m][n] = mfma16(a[m], b[n], acc[m][n]);
;       __builtin_amdgcn_s_setprio(0);
;     }
;     __syncthreads();
;     ...
;       } else if (EPI == EP_SWIGLU) {
;         u16* C = (u16*)ea.p0;
;         const int jb = (cb >> 6) * 32;
; #pragma unroll
;         for (int n = 0; n < 2; n++)
;           __builtin_nontemporal_store(f2bf(siluf(acc[m][n][j]) * acc[m][n + 2][j]), &C[(size_t)row * 2816 + jb + n * 16 + fr]);
	ds_read_b128 v[222:225], v161 offset:18496
	ds_read_b128 v[226:229], v161 offset:20800
	ds_read_b128 v[230:233], v161 offset:23104
	ds_read_b128 v[234:237], v161 offset:25408
	ds_read_b128 v[238:241], v129 offset:55360
	ds_read_b128 v[242:245], v129 offset:57664
	ds_read_b128 v[246:249], v129 offset:59968
	ds_read_b128 v[250:253], v129 offset:62272
	v_mfma_f32_16x16x32_bf16 v[94:97], v[130:133], v[146:149], v[94:97]
	v_mfma_f32_16x16x32_bf16 v[90:93], v[130:133], v[150:153], v[90:93]
	v_mfma_f32_16x16x32_bf16 v[86:89], v[130:133], v[162:165], v[86:89]
	v_mfma_f32_16x16x32_bf16 v[82:85], v[130:133], v[166:169], v[82:85]
	v_mfma_f32_16x16x32_bf16 v[78:81], v[134:137], v[146:149], v[78:81]
	v_mfma_f32_16x16x32_bf16 v[74:77], v[134:137], v[150:153], v[74:77]
	v_mfma_f32_16x16x32_bf16 v[70:73], v[134:137], v[162:165], v[70:73]
	v_mfma_f32_16x16x32_bf16 v[66:69], v[134:137], v[166:169], v[66:69]
	v_mfma_f32_16x16x32_bf16 v[62:65], v[138:141], v[146:149], v[62:65]
	v_mfma_f32_16x16x32_bf16 v[58:61], v[138:141], v[150:153], v[58:61]
	v_mfma_f32_16x16x32_bf16 v[54:57], v[138:141], v[162:165], v[54:57]
	v_mfma_f32_16x16x32_bf16 v[50:53], v[138:141], v[166:169], v[50:53]
	v_mfma_f32_16x16x32_bf16 v[46:49], v[142:145], v[146:149], v[46:49]
	v_mfma_f32_16x16x32_bf16 v[42:45], v[142:145], v[150:153], v[42:45]
	v_mfma_f32_16x16x32_bf16 v[38:41], v[142:145], v[162:165], v[38:41]
	v_mfma_f32_16x16x32_bf16 v[34:37], v[142:145], v[166:169], v[34:37]
	s_waitcnt lgkmcnt(0)
	v_mfma_f32_16x16x32_bf16 v[26:29], v[230:233], v[238:241], v[62:65]
	v_mfma_f32_16x16x32_bf16 v[18:21], v[230:233], v[242:245], v[58:61]
	v_mfma_f32_16x16x32_bf16 v[30:33], v[230:233], v[246:249], v[54:57]
	v_mfma_f32_16x16x32_bf16 v[22:25], v[230:233], v[250:253], v[50:53]
	v_mfma_f32_16x16x32_bf16 v[10:13], v[234:237], v[238:241], v[46:49]
	v_mfma_f32_16x16x32_bf16 v[2:5], v[234:237], v[242:245], v[42:45]
	v_mfma_f32_16x16x32_bf16 v[14:17], v[234:237], v[246:249], v[38:41]
	v_mfma_f32_16x16x32_bf16 v[6:9], v[234:237], v[250:253], v[34:37]
	v_mfma_f32_16x16x32_bf16 v[58:61], v[222:225], v[238:241], v[94:97]
	v_mfma_f32_16x16x32_bf16 v[50:53], v[222:225], v[242:245], v[90:93]
	v_mfma_f32_16x16x32_bf16 v[62:65], v[222:225], v[246:249], v[86:89]
	v_mfma_f32_16x16x32_bf16 v[54:57], v[222:225], v[250:253], v[82:85]
	v_mfma_f32_16x16x32_bf16 v[42:45], v[226:229], v[238:241], v[78:81]
	v_mfma_f32_16x16x32_bf16 v[34:37], v[226:229], v[242:245], v[74:77]
	v_mfma_f32_16x16x32_bf16 v[46:49], v[226:229], v[246:249], v[70:73]
	v_mfma_f32_16x16x32_bf16 v[38:41], v[226:229], v[250:253], v[66:69]
	s_nop 7
	v_and_or_b32 v0, v114, 64, s14
	v_add_u32_e32 v66, s13, v117
	v_lshl_or_b32 v68, v116, 2, v66
	v_ashrrev_i32_e32 v66, 1, v0
	v_ashrrev_i32_e32 v67, 31, v66
	v_lshl_add_u64 v[66:67], v[66:67], 1, s[2:3]
	v_lshlrev_b32_e32 v0, 1, v115
	v_lshl_add_u64 v[66:67], v[66:67], 0, v[0:1]
	v_mul_f32_e32 v0, 0xbfb8aa3b, v58
	v_exp_f32_e32 v0, v0
	v_mad_i64_i32 v[70:71], s[0:1], v68, s54, v[66:67]
	v_add_f32_e32 v0, 1.0, v0
	v_rcp_f32_e32 v0, v0
	s_barrier
	v_mul_f32_e32 v0, v58, v0
	v_mul_f32_e32 v0, v62, v0
	v_cvt_pk_bf16_f32 v0, v0, s0
	global_store_short v[70:71], v0, off nt
	v_mul_f32_e32 v0, 0xbfb8aa3b, v50
	v_exp_f32_e32 v0, v0
	s_nop 0
	v_add_f32_e32 v0, 1.0, v0
	v_rcp_f32_e32 v0, v0
	s_nop 0
	v_mul_f32_e32 v0, v50, v0
	v_mul_f32_e32 v0, v54, v0
	v_cvt_pk_bf16_f32 v0, v0, s0
	global_store_short v[70:71], v0, off offset:32 nt
	v_or_b32_e32 v0, 1, v68
	v_mad_i64_i32 v[70:71], s[0:1], v0, s54, v[66:67]
	v_mul_f32_e32 v0, 0xbfb8aa3b, v59
	v_exp_f32_e32 v0, v0
	s_nop 0
	v_add_f32_e32 v0, 1.0, v0
	v_rcp_f32_e32 v0, v0
	s_nop 0
	v_mul_f32_e32 v0, v59, v0
	v_mul_f32_e32 v0, v63, v0
	v_cvt_pk_bf16_f32 v0, v0, s0
	global_store_short v[70:71], v0, off nt
	v_mul_f32_e32 v0, 0xbfb8aa3b, v51
	v_exp_f32_e32 v0, v0
	s_nop 0
	v_add_f32_e32 v0, 1.0, v0
	v_rcp_f32_e32 v0, v0
	s_nop 0
	v_mul_f32_e32 v0, v51, v0
	v_mul_f32_e32 v0, v55, v0
	v_cvt_pk_bf16_f32 v0, v0, s0
	global_store_short v[70:71], v0, off offset:32 nt
	v_or_b32_e32 v0, 2, v68
	v_mad_i64_i32 v[50:51], s[0:1], v0, s54, v[66:67]
	v_mul_f32_e32 v0, 0xbfb8aa3b, v60
	v_exp_f32_e32 v0, v0
	s_nop 0
	v_add_f32_e32 v0, 1.0, v0
	v_rcp_f32_e32 v0, v0
	s_nop 0
	v_mul_f32_e32 v0, v60, v0
	v_mul_f32_e32 v0, v64, v0
	v_cvt_pk_bf16_f32 v0, v0, s0
	global_store_short v[50:51], v0, off nt
	v_mul_f32_e32 v0, 0xbfb8aa3b, v52
	v_exp_f32_e32 v0, v0
	s_nop 0
	v_add_f32_e32 v0, 1.0, v0
	v_rcp_f32_e32 v0, v0
	s_nop 0
	v_mul_f32_e32 v0, v52, v0
	v_mul_f32_e32 v0, v56, v0
	v_cvt_pk_bf16_f32 v0, v0, s0
	global_store_short v[50:51], v0, off offset:32 nt
	v_or_b32_e32 v0, 3, v68
	v_mad_i64_i32 v[50:51], s[0:1], v0, s54, v[66:67]
	v_mul_f32_e32 v0, 0xbfb8aa3b, v61
	v_exp_f32_e32 v0, v0
	s_nop 0
	v_add_f32_e32 v0, 1.0, v0
	v_rcp_f32_e32 v0, v0
	s_nop 0
	v_mul_f32_e32 v0, v61, v0
	v_mul_f32_e32 v0, v65, v0
	v_cvt_pk_bf16_f32 v0, v0, s0
	global_store_short v[50:51], v0, off nt
	v_mul_f32_e32 v0, 0xbfb8aa3b, v53
	v_exp_f32_e32 v0, v0
	s_nop 0
	v_add_f32_e32 v0, 1.0, v0
	v_rcp_f32_e32 v0, v0
	s_nop 0
	v_mul_f32_e32 v0, v53, v0
	v_mul_f32_e32 v0, v57, v0
	v_cvt_pk_bf16_f32 v0, v0, s0
	global_store_short v[50:51], v0, off offset:32 nt
	v_or_b32_e32 v0, 16, v68
	v_mad_i64_i32 v[50:51], s[0:1], v0, s54, v[66:67]
	v_mul_f32_e32 v0, 0xbfb8aa3b, v42
	v_exp_f32_e32 v0, v0
	s_nop 0
	v_add_f32_e32 v0, 1.0, v0
	v_rcp_f32_e32 v0, v0
	s_nop 0
	v_mul_f32_e32 v0, v42, v0
	v_mul_f32_e32 v0, v46, v0
	v_cvt_pk_bf16_f32 v0, v0, s0
	global_store_short v[50:51], v0, off nt
	v_mul_f32_e32 v0, 0xbfb8aa3b, v34
	v_exp_f32_e32 v0, v0
	s_nop 0
	v_add_f32_e32 v0, 1.0, v0
	v_rcp_f32_e32 v0, v0
	s_nop 0
	v_mul_f32_e32 v0, v34, v0
; DEV float siluf(float x) { return x * __builtin_amdgcn_rcpf(1.f + __expf(-x)); }
; template <int EPI, bool AF32>
; DEV void gemm_tile(const void* Ap, int lda, const u16* Bt, int ldb, int K, int m0, int n0, const Epi& ea, char* smem) {
;     ...
;       } else if (EPI == EP_SWIGLU) {
;         u16* C = (u16*)ea.p0;
;         const int jb = (cb >> 6) * 32;
; #pragma unroll
;         for (int n = 0; n < 2; n++)
;           __builtin_nontemporal_store(f2bf(siluf(acc[m][n][j]) * acc[m][n + 2][j]), &C[(size_t)row * 2816 + jb + n * 16 + fr]);
	v_mul_f32_e32 v0, v38, v0
	v_cvt_pk_bf16_f32 v0, v0, s0
	global_store_short v[50:51], v0, off offset:32 nt
	v_or_b32_e32 v0, 17, v68
	v_mad_i64_i32 v[50:51], s[0:1], v0, s54, v[66:67]
	v_mul_f32_e32 v0, 0xbfb8aa3b, v43
	v_exp_f32_e32 v0, v0
	s_nop 0
	v_add_f32_e32 v0, 1.0, v0
	v_rcp_f32_e32 v0, v0
	s_nop 0
	v_mul_f32_e32 v0, v43, v0
	v_mul_f32_e32 v0, v47, v0
	v_cvt_pk_bf16_f32 v0, v0, s0
	global_store_short v[50:51], v0, off nt
	v_mul_f32_e32 v0, 0xbfb8aa3b, v35
	v_exp_f32_e32 v0, v0
	s_nop 0
	v_add_f32_e32 v0, 1.0, v0
	v_rcp_f32_e32 v0, v0
	s_nop 0
	v_mul_f32_e32 v0, v35, v0
	v_mul_f32_e32 v0, v39, v0
	v_cvt_pk_bf16_f32 v0, v0, s0
	global_store_short v[50:51], v0, off offset:32 nt
	v_or_b32_e32 v0, 18, v68
	v_mad_i64_i32 v[34:35], s[0:1], v0, s54, v[66:67]
	v_mul_f32_e32 v0, 0xbfb8aa3b, v44
	v_exp_f32_e32 v0, v0
	s_nop 0
	v_add_f32_e32 v0, 1.0, v0
	v_rcp_f32_e32 v0, v0
	s_nop 0
	v_mul_f32_e32 v0, v44, v0
	v_mul_f32_e32 v0, v48, v0
	v_cvt_pk_bf16_f32 v0, v0, s0
	global_store_short v[34:35], v0, off nt
	v_mul_f32_e32 v0, 0xbfb8aa3b, v36
	v_exp_f32_e32 v0, v0
	s_nop 0
	v_add_f32_e32 v0, 1.0, v0
	v_rcp_f32_e32 v0, v0
	s_nop 0
	v_mul_f32_e32 v0, v36, v0
	v_mul_f32_e32 v0, v40, v0
	v_cvt_pk_bf16_f32 v0, v0, s0
	global_store_short v[34:35], v0, off offset:32 nt
	v_or_b32_e32 v0, 19, v68
	v_mad_i64_i32 v[34:35], s[0:1], v0, s54, v[66:67]
	v_mul_f32_e32 v0, 0xbfb8aa3b, v45
	v_exp_f32_e32 v0, v0
	s_nop 0
	v_add_f32_e32 v0, 1.0, v0
	v_rcp_f32_e32 v0, v0
	s_nop 0
	v_mul_f32_e32 v0, v45, v0
	v_mul_f32_e32 v0, v49, v0
	v_cvt_pk_bf16_f32 v0, v0, s0
	global_store_short v[34:35], v0, off nt
	v_mul_f32_e32 v0, 0xbfb8aa3b, v37
	v_exp_f32_e32 v0, v0
	s_nop 0
	v_add_f32_e32 v0, 1.0, v0
	v_rcp_f32_e32 v0, v0
	s_nop 0
	v_mul_f32_e32 v0, v37, v0
	v_mul_f32_e32 v0, v41, v0
	v_cvt_pk_bf16_f32 v0, v0, s0
	global_store_short v[34:35], v0, off offset:32 nt
	v_or_b32_e32 v0, 32, v68
	v_mad_i64_i32 v[34:35], s[0:1], v0, s54, v[66:67]
	v_mul_f32_e32 v0, 0xbfb8aa3b, v26
	v_exp_f32_e32 v0, v0
	s_nop 0
	v_add_f32_e32 v0, 1.0, v0
	v_rcp_f32_e32 v0, v0
	s_nop 0
	v_mul_f32_e32 v0, v26, v0
	v_mul_f32_e32 v0, v30, v0
	v_cvt_pk_bf16_f32 v0, v0, s0
	global_store_short v[34:35], v0, off nt
	v_mul_f32_e32 v0, 0xbfb8aa3b, v18
	v_exp_f32_e32 v0, v0
	s_nop 0
	v_add_f32_e32 v0, 1.0, v0
	v_rcp_f32_e32 v0, v0
	s_nop 0
	v_mul_f32_e32 v0, v18, v0
	v_mul_f32_e32 v0, v22, v0
	v_cvt_pk_bf16_f32 v0, v0, s0
	global_store_short v[34:35], v0, off offset:32 nt
	v_or_b32_e32 v0, 33, v68
	v_mad_i64_i32 v[34:35], s[0:1], v0, s54, v[66:67]
	v_mul_f32_e32 v0, 0xbfb8aa3b, v27
	v_exp_f32_e32 v0, v0
	s_nop 0
	v_add_f32_e32 v0, 1.0, v0
	v_rcp_f32_e32 v0, v0
	s_nop 0
	v_mul_f32_e32 v0, v27, v0
	v_mul_f32_e32 v0, v31, v0
	v_cvt_pk_bf16_f32 v0, v0, s0
	global_store_short v[34:35], v0, off nt
	v_mul_f32_e32 v0, 0xbfb8aa3b, v19
	v_exp_f32_e32 v0, v0
	s_nop 0
	v_add_f32_e32 v0, 1.0, v0
	v_rcp_f32_e32 v0, v0
	s_nop 0
	v_mul_f32_e32 v0, v19, v0
	v_mul_f32_e32 v0, v23, v0
	v_cvt_pk_bf16_f32 v0, v0, s0
	global_store_short v[34:35], v0, off offset:32 nt
	v_or_b32_e32 v0, 34, v68
	v_mad_i64_i32 v[18:19], s[0:1], v0, s54, v[66:67]
	v_mul_f32_e32 v0, 0xbfb8aa3b, v28
	v_exp_f32_e32 v0, v0
	s_nop 0
	v_add_f32_e32 v0, 1.0, v0
	v_rcp_f32_e32 v0, v0
	s_nop 0
	v_mul_f32_e32 v0, v28, v0
	v_mul_f32_e32 v0, v32, v0
	v_cvt_pk_bf16_f32 v0, v0, s0
	global_store_short v[18:19], v0, off nt
	v_mul_f32_e32 v0, 0xbfb8aa3b, v20
	v_exp_f32_e32 v0, v0
	s_nop 0
	v_add_f32_e32 v0, 1.0, v0
	v_rcp_f32_e32 v0, v0
	s_nop 0
	v_mul_f32_e32 v0, v20, v0
	v_mul_f32_e32 v0, v24, v0
	v_cvt_pk_bf16_f32 v0, v0, s0
	global_store_short v[18:19], v0, off offset:32 nt
	v_or_b32_e32 v0, 35, v68
	v_mad_i64_i32 v[18:19], s[0:1], v0, s54, v[66:67]
	v_mul_f32_e32 v0, 0xbfb8aa3b, v29
	v_exp_f32_e32 v0, v0
	s_nop 0
	v_add_f32_e32 v0, 1.0, v0
	v_rcp_f32_e32 v0, v0
	s_nop 0
	v_mul_f32_e32 v0, v29, v0
	v_mul_f32_e32 v0, v33, v0
	v_cvt_pk_bf16_f32 v0, v0, s0
	global_store_short v[18:19], v0, off nt
	v_mul_f32_e32 v0, 0xbfb8aa3b, v21
	v_exp_f32_e32 v0, v0
	s_nop 0
	v_add_f32_e32 v0, 1.0, v0
	v_rcp_f32_e32 v0, v0
	s_nop 0
	v_mul_f32_e32 v0, v21, v0
	v_mul_f32_e32 v0, v25, v0
	v_cvt_pk_bf16_f32 v0, v0, s0
	global_store_short v[18:19], v0, off offset:32 nt
	v_or_b32_e32 v0, 48, v68
	v_mad_i64_i32 v[18:19], s[0:1], v0, s54, v[66:67]
	v_mul_f32_e32 v0, 0xbfb8aa3b, v10
	v_exp_f32_e32 v0, v0
	s_nop 0
	v_add_f32_e32 v0, 1.0, v0
	v_rcp_f32_e32 v0, v0
	s_nop 0
	v_mul_f32_e32 v0, v10, v0
	v_mul_f32_e32 v0, v14, v0
	v_cvt_pk_bf16_f32 v0, v0, s0
	global_store_short v[18:19], v0, off nt
	v_mul_f32_e32 v0, 0xbfb8aa3b, v2
	v_exp_f32_e32 v0, v0
	s_nop 0
	v_add_f32_e32 v0, 1.0, v0
	v_rcp_f32_e32 v0, v0
	s_nop 0
	v_mul_f32_e32 v0, v2, v0
	v_mul_f32_e32 v0, v6, v0
	v_cvt_pk_bf16_f32 v0, v0, s0
	global_store_short v[18:19], v0, off offset:32 nt
	v_or_b32_e32 v0, 49, v68
	v_mad_i64_i32 v[18:19], s[0:1], v0, s54, v[66:67]
	v_mul_f32_e32 v0, 0xbfb8aa3b, v11
	v_exp_f32_e32 v0, v0
	s_nop 0
	v_add_f32_e32 v0, 1.0, v0
	v_rcp_f32_e32 v0, v0
	s_nop 0
	v_mul_f32_e32 v0, v11, v0
	v_mul_f32_e32 v0, v15, v0
	v_cvt_pk_bf16_f32 v0, v0, s0
	global_store_short v[18:19], v0, off nt
	v_mul_f32_e32 v0, 0xbfb8aa3b, v3
	v_exp_f32_e32 v0, v0
	s_nop 0
	v_add_f32_e32 v0, 1.0, v0
	v_rcp_f32_e32 v0, v0
	s_nop 0
	v_mul_f32_e32 v0, v3, v0
	v_mul_f32_e32 v0, v7, v0
	v_cvt_pk_bf16_f32 v0, v0, s0
	global_store_short v[18:19], v0, off offset:32 nt
	v_or_b32_e32 v0, 50, v68
	v_mad_i64_i32 v[2:3], s[0:1], v0, s54, v[66:67]
	v_mul_f32_e32 v0, 0xbfb8aa3b, v12
	v_exp_f32_e32 v0, v0
	s_nop 0
	v_add_f32_e32 v0, 1.0, v0
	v_rcp_f32_e32 v0, v0
	s_nop 0
	v_mul_f32_e32 v0, v12, v0
	v_mul_f32_e32 v0, v16, v0
	v_cvt_pk_bf16_f32 v0, v0, s0
	global_store_short v[2:3], v0, off nt
	v_mul_f32_e32 v0, 0xbfb8aa3b, v4
	v_exp_f32_e32 v0, v0
	s_nop 0
	v_add_f32_e32 v0, 1.0, v0
	v_rcp_f32_e32 v0, v0
	s_nop 0
	v_mul_f32_e32 v0, v4, v0
	v_mul_f32_e32 v0, v8, v0
	v_cvt_pk_bf16_f32 v0, v0, s0
	global_store_short v[2:3], v0, off offset:32 nt
	v_or_b32_e32 v0, 51, v68
	v_mad_i64_i32 v[2:3], s[0:1], v0, s54, v[66:67]
	v_mul_f32_e32 v0, 0xbfb8aa3b, v13
	v_exp_f32_e32 v0, v0
	s_nop 0
	v_add_f32_e32 v0, 1.0, v0
	v_rcp_f32_e32 v0, v0
	s_nop 0
	v_mul_f32_e32 v0, v13, v0
	v_mul_f32_e32 v0, v17, v0
	v_cvt_pk_bf16_f32 v0, v0, s0
	global_store_short v[2:3], v0, off nt
	v_mul_f32_e32 v0, 0xbfb8aa3b, v5
	v_exp_f32_e32 v0, v0
	s_nop 0
	v_add_f32_e32 v0, 1.0, v0
	v_rcp_f32_e32 v0, v0
	s_nop 0
	v_mul_f32_e32 v0, v5, v0
	v_mul_f32_e32 v0, v9, v0
	v_cvt_pk_bf16_f32 v0, v0, s0
	v_readfirstlane_b32 s0, v198
	global_store_short v[2:3], v0, off offset:32 nt
	s_add_i32 s12, s0, s12
	s_cmpk_lt_i32 s12, 0x2cb0
	s_cbranch_scc1 .LBB0_1436

; DEV f32x4 mfma16(bf16x8 a, bf16x8 b, f32x4 c) { return __builtin_amdgcn_mfma_f32_16x16x32_bf16(a, b, c, 0, 0, 0); }
; template <int EPI, bool AF32>
; DEV void gemm_tile(const void* Ap, int lda, const u16* Bt, int ldb, int K, int m0, int n0, const Epi& ea, char* smem) {
;     ...
;   for (int kt = 0; kt < nk; kt++) {
;     const int buf = kt & 1;
;     if (kt + 1 < nk) swrite(buf ^ 1);
;     if (kt + 2 < nk) gload(kt + 2);
; #pragma unroll
;     for (int ks = 0; ks < 2; ks++) {
;       bf16x8 a[4], b[4];
; #pragma unroll
;       for (int m = 0; m < 4; m++) a[m] = *(const bf16x8*)(sA + buf * 9216 + (wr * 64 + m * 16 + fr) * 72 + ks * 32 + fq * 8);
; #pragma unroll
;       for (int n = 0; n < 4; n++) b[n] = *(const bf16x8*)(sB + buf * 9216 + (wc * 64 + n * 16 + fr) * 72 + ks * 32 + fq * 8);
;       __builtin_amdgcn_s_setprio(1);
; #pragma unroll
;       for (int m = 0; m < 4; m++)
; #pragma unroll
;         for (int n = 0; n < 4; n++) acc[m][n] = mfma16(a[m], b[n], acc[m][n]);
;       __builtin_amdgcn_s_setprio(0);
;     }
;     __syncthreads();
.Lgk7_loop:
	s_waitcnt lgkmcnt(0)
	ds_read_b128 v[222:225], v161 offset:64
	ds_read_b128 v[226:229], v161 offset:2368
	ds_read_b128 v[230:233], v161 offset:4672
	ds_read_b128 v[234:237], v161 offset:6976
	ds_read_b128 v[238:241], v129 offset:36928
	ds_read_b128 v[242:245], v129 offset:39232
	ds_read_b128 v[246:249], v129 offset:41536
	ds_read_b128 v[250:253], v129 offset:43840
	v_mfma_f32_16x16x32_bf16 v[34:37], v[130:133], v[146:149], v[34:37]
	v_mfma_f32_16x16x32_bf16 v[38:41], v[130:133], v[150:153], v[38:41]
	v_mfma_f32_16x16x32_bf16 v[42:45], v[130:133], v[162:165], v[42:45]
	v_mfma_f32_16x16x32_bf16 v[46:49], v[130:133], v[166:169], v[46:49]
	s_waitcnt vmcnt(0)
	ds_write_b128 v118, v[6:9] offset:18432
	ds_write_b128 v118, v[2:5] offset:55296
	v_mfma_f32_16x16x32_bf16 v[50:53], v[134:137], v[146:149], v[50:53]
	ds_write_b128 v120, v[10:13] offset:18432
	ds_write_b128 v120, v[14:17] offset:55296
	v_mfma_f32_16x16x32_bf16 v[54:57], v[134:137], v[150:153], v[54:57]
	ds_write_b128 v122, v[18:21] offset:18432
	ds_write_b128 v122, v[22:25] offset:55296
	v_mfma_f32_16x16x32_bf16 v[58:61], v[134:137], v[162:165], v[58:61]
	ds_write_b128 v123, v[26:29] offset:18432
	ds_write_b128 v123, v[30:33] offset:55296
	v_mfma_f32_16x16x32_bf16 v[62:65], v[134:137], v[166:169], v[62:65]
	global_load_dwordx4 v[6:9], v[112:113], off
	v_mfma_f32_16x16x32_bf16 v[66:69], v[138:141], v[146:149], v[66:69]
	global_load_dwordx4 v[2:5], v[110:111], off
	v_mfma_f32_16x16x32_bf16 v[70:73], v[138:141], v[150:153], v[70:73]
	global_load_dwordx4 v[10:13], v[108:109], off
	v_mfma_f32_16x16x32_bf16 v[74:77], v[138:141], v[162:165], v[74:77]
	global_load_dwordx4 v[14:17], v[106:107], off
	v_mfma_f32_16x16x32_bf16 v[78:81], v[138:141], v[166:169], v[78:81]
	global_load_dwordx4 v[18:21], v[104:105], off
	v_mfma_f32_16x16x32_bf16 v[82:85], v[142:145], v[146:149], v[82:85]
	global_load_dwordx4 v[22:25], v[102:103], off
	v_mfma_f32_16x16x32_bf16 v[86:89], v[142:145], v[150:153], v[86:89]
	global_load_dwordx4 v[26:29], v[100:101], off
	v_mfma_f32_16x16x32_bf16 v[90:93], v[142:145], v[162:165], v[90:93]
	global_load_dwordx4 v[30:33], v[98:99], off
	v_mfma_f32_16x16x32_bf16 v[94:97], v[142:145], v[166:169], v[94:97]
	s_waitcnt lgkmcnt(0)
	s_barrier
	ds_read_b128 v[130:133], v161 offset:18432
	v_mfma_f32_16x16x32_bf16 v[34:37], v[222:225], v[238:241], v[34:37]
	ds_read_b128 v[134:137], v161 offset:20736
	v_mfma_f32_16x16x32_bf16 v[38:41], v[222:225], v[242:245], v[38:41]
	ds_read_b128 v[138:141], v161 offset:23040
	v_mfma_f32_16x16x32_bf16 v[42:45], v[222:225], v[246:249], v[42:45]
	ds_read_b128 v[142:145], v161 offset:25344
	v_mfma_f32_16x16x32_bf16 v[46:49], v[222:225], v[250:253], v[46:49]
	ds_read_b128 v[146:149], v129 offset:55296
	v_mfma_f32_16x16x32_bf16 v[50:53], v[226:229], v[238:241], v[50:53]
	ds_read_b128 v[150:153], v129 offset:57600
	v_mfma_f32_16x16x32_bf16 v[54:57], v[226:229], v[242:245], v[54:57]
	ds_read_b128 v[162:165], v129 offset:59904
	v_mfma_f32_16x16x32_bf16 v[58:61], v[226:229], v[246:249], v[58:61]
	ds_read_b128 v[166:169], v129 offset:62208
	v_mfma_f32_16x16x32_bf16 v[62:65], v[226:229], v[250:253], v[62:65]
	v_mfma_f32_16x16x32_bf16 v[66:69], v[230:233], v[238:241], v[66:69]
	v_mfma_f32_16x16x32_bf16 v[70:73], v[230:233], v[242:245], v[70:73]
	v_mfma_f32_16x16x32_bf16 v[74:77], v[230:233], v[246:249], v[74:77]
	v_mfma_f32_16x16x32_bf16 v[78:81], v[230:233], v[250:253], v[78:81]
	v_mfma_f32_16x16x32_bf16 v[82:85], v[234:237], v[238:241], v[82:85]
	v_mfma_f32_16x16x32_bf16 v[86:89], v[234:237], v[242:245], v[86:89]
	v_mfma_f32_16x16x32_bf16 v[90:93], v[234:237], v[246:249], v[90:93]
	v_mfma_f32_16x16x32_bf16 v[94:97], v[234:237], v[250:253], v[94:97]
	s_waitcnt lgkmcnt(0)
	ds_read_b128 v[222:225], v161 offset:18496
	ds_read_b128 v[226:229], v161 offset:20800
	ds_read_b128 v[230:233], v161 offset:23104
	ds_read_b128 v[234:237], v161 offset:25408
	ds_read_b128 v[238:241], v129 offset:55360
	ds_read_b128 v[242:245], v129 offset:57664
	ds_read_b128 v[246:249], v129 offset:59968
	ds_read_b128 v[250:253], v129 offset:62272
	v_mfma_f32_16x16x32_bf16 v[34:37], v[130:133], v[146:149], v[34:37]
	v_mfma_f32_16x16x32_bf16 v[38:41], v[130:133], v[150:153], v[38:41]
	v_mfma_f32_16x16x32_bf16 v[42:45], v[130:133], v[162:165], v[42:45]
	v_mfma_f32_16x16x32_bf16 v[46:49], v[130:133], v[166:169], v[46:49]
	s_waitcnt vmcnt(0)
	ds_write_b128 v118, v[6:9]
	ds_write_b128 v118, v[2:5] offset:36864
	v_mfma_f32_16x16x32_bf16 v[50:53], v[134:137], v[146:149], v[50:53]
	ds_write_b128 v120, v[10:13]
	ds_write_b128 v120, v[14:17] offset:36864
	v_mfma_f32_16x16x32_bf16 v[54:57], v[134:137], v[150:153], v[54:57]
	ds_write_b128 v122, v[18:21]
	ds_write_b128 v122, v[22:25] offset:36864
	v_mfma_f32_16x16x32_bf16 v[58:61], v[134:137], v[162:165], v[58:61]
	ds_write_b128 v123, v[26:29]
	ds_write_b128 v123, v[30:33] offset:36864
	v_mfma_f32_16x16x32_bf16 v[62:65], v[134:137], v[166:169], v[62:65]
	global_load_dwordx4 v[6:9], v[112:113], off offset:128
	v_mfma_f32_16x16x32_bf16 v[66:69], v[138:141], v[146:149], v[66:69]
	global_load_dwordx4 v[2:5], v[110:111], off offset:128
	v_mfma_f32_16x16x32_bf16 v[70:73], v[138:141], v[150:153], v[70:73]
	global_load_dwordx4 v[10:13], v[108:109], off offset:128
	v_mfma_f32_16x16x32_bf16 v[74:77], v[138:141], v[162:165], v[74:77]
	global_load_dwordx4 v[14:17], v[106:107], off offset:128
	v_mfma_f32_16x16x32_bf16 v[78:81], v[138:141], v[166:169], v[78:81]
	global_load_dwordx4 v[18:21], v[104:105], off offset:128
	v_mfma_f32_16x16x32_bf16 v[82:85], v[142:145], v[146:149], v[82:85]
	global_load_dwordx4 v[22:25], v[102:103], off offset:128
	v_mfma_f32_16x16x32_bf16 v[86:89], v[142:145], v[150:153], v[86:89]
	global_load_dwordx4 v[26:29], v[100:101], off offset:128
	v_mfma_f32_16x16x32_bf16 v[90:93], v[142:145], v[162:165], v[90:93]
	global_load_dwordx4 v[30:33], v[98:99], off offset:128
	v_mfma_f32_16x16x32_bf16 v[94:97], v[142:145], v[166:169], v[94:97]
	s_waitcnt lgkmcnt(0)
	s_barrier
; DEV f32x4 mfma16(bf16x8 a, bf16x8 b, f32x4 c) { return __builtin_amdgcn_mfma_f32_16x16x32_bf16(a, b, c, 0, 0, 0); }
; template <int EPI, bool AF32>
; DEV void gemm_tile(const void* Ap, int lda, const u16* Bt, int ldb, int K, int m0, int n0, const Epi& ea, char* smem) {
;     ...
;   for (int kt = 0; kt < nk; kt++) {
;     const int buf = kt & 1;
;     if (kt + 1 < nk) swrite(buf ^ 1);
;     if (kt + 2 < nk) gload(kt + 2);
; #pragma unroll
;     for (int ks = 0; ks < 2; ks++) {
;       bf16x8 a[4], b[4];
; #pragma unroll
;       for (int m = 0; m < 4; m++) a[m] = *(const bf16x8*)(sA + buf * 9216 + (wr * 64 + m * 16 + fr) * 72 + ks * 32 + fq * 8);
; #pragma unroll
;       for (int n = 0; n < 4; n++) b[n] = *(const bf16x8*)(sB + buf * 9216 + (wc * 64 + n * 16 + fr) * 72 + ks * 32 + fq * 8);
;       __builtin_amdgcn_s_setprio(1);
; #pragma unroll
;       for (int m = 0; m < 4; m++)
; #pragma unroll
;         for (int n = 0; n < 4; n++) acc[m][n] = mfma16(a[m], b[n], acc[m][n]);
;       __builtin_amdgcn_s_setprio(0);
;     }
;     __syncthreads();
	ds_read_b128 v[130:133], v161
	v_mfma_f32_16x16x32_bf16 v[34:37], v[222:225], v[238:241], v[34:37]
	ds_read_b128 v[134:137], v161 offset:2304
	v_mfma_f32_16x16x32_bf16 v[38:41], v[222:225], v[242:245], v[38:41]
	ds_read_b128 v[138:141], v161 offset:4608
	v_mfma_f32_16x16x32_bf16 v[42:45], v[222:225], v[246:249], v[42:45]
	ds_read_b128 v[142:145], v161 offset:6912
	v_mfma_f32_16x16x32_bf16 v[46:49], v[222:225], v[250:253], v[46:49]
	ds_read_b128 v[146:149], v129 offset:36864
	v_mfma_f32_16x16x32_bf16 v[50:53], v[226:229], v[238:241], v[50:53]
	ds_read_b128 v[150:153], v129 offset:39168
	v_mfma_f32_16x16x32_bf16 v[54:57], v[226:229], v[242:245], v[54:57]
	ds_read_b128 v[162:165], v129 offset:41472
	v_mfma_f32_16x16x32_bf16 v[58:61], v[226:229], v[246:249], v[58:61]
	ds_read_b128 v[166:169], v129 offset:43776
	v_mfma_f32_16x16x32_bf16 v[62:65], v[226:229], v[250:253], v[62:65]
	v_mfma_f32_16x16x32_bf16 v[66:69], v[230:233], v[238:241], v[66:69]
	v_lshl_add_u64 v[112:113], v[112:113], 0, s[0:1]
	v_mfma_f32_16x16x32_bf16 v[70:73], v[230:233], v[242:245], v[70:73]
	v_lshl_add_u64 v[110:111], v[110:111], 0, s[0:1]
	v_mfma_f32_16x16x32_bf16 v[74:77], v[230:233], v[246:249], v[74:77]
	v_lshl_add_u64 v[108:109], v[108:109], 0, s[0:1]
	v_mfma_f32_16x16x32_bf16 v[78:81], v[230:233], v[250:253], v[78:81]
	v_lshl_add_u64 v[106:107], v[106:107], 0, s[0:1]
	v_mfma_f32_16x16x32_bf16 v[82:85], v[234:237], v[238:241], v[82:85]
	v_lshl_add_u64 v[104:105], v[104:105], 0, s[0:1]
	v_mfma_f32_16x16x32_bf16 v[86:89], v[234:237], v[242:245], v[86:89]
	v_lshl_add_u64 v[102:103], v[102:103], 0, s[0:1]
	v_mfma_f32_16x16x32_bf16 v[90:93], v[234:237], v[246:249], v[90:93]
	v_lshl_add_u64 v[100:101], v[100:101], 0, s[0:1]
	v_mfma_f32_16x16x32_bf16 v[94:97], v[234:237], v[250:253], v[94:97]
	v_lshl_add_u64 v[98:99], v[98:99], 0, s[0:1]
	s_add_i32 s17, s17, 1
	s_cmp_lg_u32 s17, 21
	s_cbranch_scc1 .Lgk7_loop
	s_waitcnt lgkmcnt(0)
	ds_read_b128 v[222:225], v161 offset:64
	ds_read_b128 v[226:229], v161 offset:2368
	ds_read_b128 v[230:233], v161 offset:4672
	ds_read_b128 v[234:237], v161 offset:6976
	ds_read_b128 v[238:241], v129 offset:36928
	ds_read_b128 v[242:245], v129 offset:39232
	ds_read_b128 v[246:249], v129 offset:41536
	ds_read_b128 v[250:253], v129 offset:43840
	v_mfma_f32_16x16x32_bf16 v[34:37], v[130:133], v[146:149], v[34:37]
	v_mfma_f32_16x16x32_bf16 v[38:41], v[130:133], v[150:153], v[38:41]
	v_mfma_f32_16x16x32_bf16 v[42:45], v[130:133], v[162:165], v[42:45]
	v_mfma_f32_16x16x32_bf16 v[46:49], v[130:133], v[166:169], v[46:49]
	s_waitcnt vmcnt(0)
	ds_write_b128 v118, v[6:9] offset:18432
	ds_write_b128 v118, v[2:5] offset:55296
	v_mfma_f32_16x16x32_bf16 v[50:53], v[134:137], v[146:149], v[50:53]
	ds_write_b128 v120, v[10:13] offset:18432
	ds_write_b128 v120, v[14:17] offset:55296
	v_mfma_f32_16x16x32_bf16 v[54:57], v[134:137], v[150:153], v[54:57]
	ds_write_b128 v122, v[18:21] offset:18432
	ds_write_b128 v122, v[22:25] offset:55296
	v_mfma_f32_16x16x32_bf16 v[58:61], v[134:137], v[162:165], v[58:61]
	ds_write_b128 v123, v[26:29] offset:18432
	ds_write_b128 v123, v[30:33] offset:55296
	v_mfma_f32_16x16x32_bf16 v[62:65], v[134:137], v[166:169], v[62:65]
	v_mfma_f32_16x16x32_bf16 v[66:69], v[138:141], v[146:149], v[66:69]
	v_mfma_f32_16x16x32_bf16 v[70:73], v[138:141], v[150:153], v[70:73]
	v_mfma_f32_16x16x32_bf16 v[74:77], v[138:141], v[162:165], v[74:77]
	v_mfma_f32_16x16x32_bf16 v[78:81], v[138:141], v[166:169], v[78:81]
	v_mfma_f32_16x16x32_bf16 v[82:85], v[142:145], v[146:149], v[82:85]
	v_mfma_f32_16x16x32_bf16 v[86:89], v[142:145], v[150:153], v[86:89]
	v_mfma_f32_16x16x32_bf16 v[90:93], v[142:145], v[162:165], v[90:93]
	v_mfma_f32_16x16x32_bf16 v[94:97], v[142:145], v[166:169], v[94:97]
	s_waitcnt lgkmcnt(0)
	s_barrier
	ds_read_b128 v[130:133], v161 offset:18432
	v_mfma_f32_16x16x32_bf16 v[34:37], v[222:225], v[238:241], v[34:37]
	ds_read_b128 v[134:137], v161 offset:20736
	v_mfma_f32_16x16x32_bf16 v[38:41], v[222:225], v[242:245], v[38:41]
	ds_read_b128 v[138:141], v161 offset:23040
	v_mfma_f32_16x16x32_bf16 v[42:45], v[222:225], v[246:249], v[42:45]
	ds_read_b128 v[142:145], v161 offset:25344
	v_mfma_f32_16x16x32_bf16 v[46:49], v[222:225], v[250:253], v[46:49]
	ds_read_b128 v[146:149], v129 offset:55296
	v_mfma_f32_16x16x32_bf16 v[50:53], v[226:229], v[238:241], v[50:53]
	ds_read_b128 v[150:153], v129 offset:57600
	v_mfma_f32_16x16x32_bf16 v[54:57], v[226:229], v[242:245], v[54:57]
	ds_read_b128 v[162:165], v129 offset:59904
	v_mfma_f32_16x16x32_bf16 v[58:61], v[226:229], v[246:249], v[58:61]
	ds_read_b128 v[166:169], v129 offset:62208
	v_mfma_f32_16x16x32_bf16 v[62:65], v[226:229], v[250:253], v[62:65]
	v_mfma_f32_16x16x32_bf16 v[66:69], v[230:233], v[238:241], v[66:69]
	v_mfma_f32_16x16x32_bf16 v[70:73], v[230:233], v[242:245], v[70:73]
	v_mfma_f32_16x16x32_bf16 v[74:77], v[230:233], v[246:249], v[74:77]
	v_mfma_f32_16x16x32_bf16 v[78:81], v[230:233], v[250:253], v[78:81]
	v_mfma_f32_16x16x32_bf16 v[82:85], v[234:237], v[238:241], v[82:85]
	v_mfma_f32_16x16x32_bf16 v[86:89], v[234:237], v[242:245], v[86:89]
	v_mfma_f32_16x16x32_bf16 v[90:93], v[234:237], v[246:249], v[90:93]
	v_mfma_f32_16x16x32_bf16 v[94:97], v[234:237], v[250:253], v[94:97]
	s_waitcnt lgkmcnt(0)
; DEV f32x4 mfma16(bf16x8 a, bf16x8 b, f32x4 c) { return __builtin_amdgcn_mfma_f32_16x16x32_bf16(a, b, c, 0, 0, 0); }
; template <int EPI, bool AF32>
; DEV void gemm_tile(const void* Ap, int lda, const u16* Bt, int ldb, int K, int m0, int n0, const Epi& ea, char* smem) {
;     ...
;   for (int kt = 0; kt < nk; kt++) {
;     const int buf = kt & 1;
;     if (kt + 1 < nk) swrite(buf ^ 1);
;     if (kt + 2 < nk) gload(kt + 2);
; #pragma unroll
;     for (int ks = 0; ks < 2; ks++) {
;       bf16x8 a[4], b[4];
; #pragma unroll
;       for (int m = 0; m < 4; m++) a[m] = *(const bf16x8*)(sA + buf * 9216 + (wr * 64 + m * 16 + fr) * 72 + ks * 32 + fq * 8);
; #pragma unroll
;       for (int n = 0; n < 4; n++) b[n] = *(const bf16x8*)(sB + buf * 9216 + (wc * 64 + n * 16 + fr) * 72 + ks * 32 + fq * 8);
;       __builtin_amdgcn_s_setprio(1);
; #pragma unroll
;       for (int m = 0; m < 4; m++)
; #pragma unroll
;         for (int n = 0; n < 4; n++) acc[m][n] = mfma16(a[m], b[n], acc[m][n]);
;       __builtin_amdgcn_s_setprio(0);
;     }
;     __syncthreads();
;     ...
;   if (EPI == EP_RES || EPI == EP_MERGE1 || EPI == EP_MERGE2) {
;     const int rbase = m0 + wr * 64 + fq * 4, cbase = cb + fr;
;     if (EPI == EP_RES) {
;       float* C = (float*)ea.p0;
;       const float* R = (const float*)ea.p1;
;       float rv[4][4][4];
; #pragma unroll
;       for (int m = 0; m < 4; m++)
; #pragma unroll
;         for (int j = 0; j < 4; j++)
; #pragma unroll
;           for (int n = 0; n < 4; n++) rv[m][j][n] = R[(size_t)(rbase + m * 16 + j) * 1024 + cbase + n * 16];
;       __builtin_amdgcn_sched_barrier(0);
	ds_read_b128 v[222:225], v161 offset:18496
	ds_read_b128 v[226:229], v161 offset:20800
	ds_read_b128 v[230:233], v161 offset:23104
	ds_read_b128 v[234:237], v161 offset:25408
	ds_read_b128 v[238:241], v129 offset:55360
	ds_read_b128 v[242:245], v129 offset:57664
	ds_read_b128 v[246:249], v129 offset:59968
	ds_read_b128 v[250:253], v129 offset:62272
	v_mfma_f32_16x16x32_bf16 v[98:101], v[130:133], v[146:149], v[34:37]
	v_mfma_f32_16x16x32_bf16 v[102:105], v[130:133], v[150:153], v[38:41]
	v_mfma_f32_16x16x32_bf16 v[106:109], v[130:133], v[162:165], v[42:45]
	v_mfma_f32_16x16x32_bf16 v[110:113], v[130:133], v[166:169], v[46:49]
	v_mfma_f32_16x16x32_bf16 v[50:53], v[134:137], v[146:149], v[50:53]
	v_mfma_f32_16x16x32_bf16 v[54:57], v[134:137], v[150:153], v[54:57]
	v_mfma_f32_16x16x32_bf16 v[58:61], v[134:137], v[162:165], v[58:61]
	v_mfma_f32_16x16x32_bf16 v[62:65], v[134:137], v[166:169], v[62:65]
	v_mfma_f32_16x16x32_bf16 v[66:69], v[138:141], v[146:149], v[66:69]
	v_mfma_f32_16x16x32_bf16 v[70:73], v[138:141], v[150:153], v[70:73]
	v_mfma_f32_16x16x32_bf16 v[74:77], v[138:141], v[162:165], v[74:77]
	v_mfma_f32_16x16x32_bf16 v[78:81], v[138:141], v[166:169], v[78:81]
	v_mfma_f32_16x16x32_bf16 v[82:85], v[142:145], v[146:149], v[82:85]
	v_mfma_f32_16x16x32_bf16 v[86:89], v[142:145], v[150:153], v[86:89]
	v_mfma_f32_16x16x32_bf16 v[90:93], v[142:145], v[162:165], v[90:93]
	v_mfma_f32_16x16x32_bf16 v[94:97], v[142:145], v[166:169], v[94:97]
	s_waitcnt lgkmcnt(0)
	v_mfma_f32_16x16x32_bf16 v[30:33], v[230:233], v[238:241], v[66:69]
	v_mfma_f32_16x16x32_bf16 v[26:29], v[230:233], v[242:245], v[70:73]
	v_mfma_f32_16x16x32_bf16 v[22:25], v[230:233], v[246:249], v[74:77]
	v_mfma_f32_16x16x32_bf16 v[18:21], v[230:233], v[250:253], v[78:81]
	v_mfma_f32_16x16x32_bf16 v[14:17], v[234:237], v[238:241], v[82:85]
	v_mfma_f32_16x16x32_bf16 v[10:13], v[234:237], v[242:245], v[86:89]
	v_mfma_f32_16x16x32_bf16 v[6:9], v[234:237], v[246:249], v[90:93]
	v_mfma_f32_16x16x32_bf16 v[2:5], v[234:237], v[250:253], v[94:97]
	v_mfma_f32_16x16x32_bf16 v[34:37], v[226:229], v[250:253], v[62:65]
	v_mfma_f32_16x16x32_bf16 v[62:65], v[222:225], v[238:241], v[98:101]
	v_mfma_f32_16x16x32_bf16 v[38:41], v[226:229], v[246:249], v[58:61]
	v_mfma_f32_16x16x32_bf16 v[58:61], v[222:225], v[242:245], v[102:105]
	v_mfma_f32_16x16x32_bf16 v[42:45], v[226:229], v[242:245], v[54:57]
	v_mfma_f32_16x16x32_bf16 v[54:57], v[222:225], v[246:249], v[106:109]
	v_mfma_f32_16x16x32_bf16 v[46:49], v[226:229], v[238:241], v[50:53]
	v_mfma_f32_16x16x32_bf16 v[50:53], v[222:225], v[250:253], v[110:113]
	s_nop 7
	v_and_b32_e32 v116, 64, v116
	v_add_u32_e32 v0, s16, v117
	v_or3_b32 v66, v116, s15, v114
	v_lshl_or_b32 v72, v115, 2, v0
	v_ashrrev_i32_e32 v67, 31, v66
	v_lshlrev_b64 v[66:67], 2, v[66:67]
	v_ashrrev_i32_e32 v73, 31, v72
	v_lshl_add_u64 v[74:75], s[4:5], 0, v[66:67]
	v_lshlrev_b64 v[68:69], 12, v[72:73]
	v_lshl_add_u64 v[70:71], v[74:75], 0, v[68:69]
	s_barrier
	global_load_dword v0, v[70:71], off
	global_load_dword v104, v[70:71], off offset:64
	global_load_dword v105, v[70:71], off offset:128
	global_load_dword v106, v[70:71], off offset:192
	v_or_b32_e32 v70, 1, v72
	v_ashrrev_i32_e32 v71, 31, v70
	v_lshlrev_b64 v[70:71], 12, v[70:71]
	v_lshl_add_u64 v[76:77], v[74:75], 0, v[70:71]
	global_load_dword v107, v[76:77], off
	global_load_dword v108, v[76:77], off offset:64
	global_load_dword v109, v[76:77], off offset:128
	global_load_dword v110, v[76:77], off offset:192
	v_or_b32_e32 v76, 2, v72
	v_ashrrev_i32_e32 v77, 31, v76
	v_lshlrev_b64 v[76:77], 12, v[76:77]
	v_lshl_add_u64 v[78:79], v[74:75], 0, v[76:77]
	global_load_dword v111, v[78:79], off
	global_load_dword v112, v[78:79], off offset:64
	global_load_dword v113, v[78:79], off offset:128
	global_load_dword v114, v[78:79], off offset:192
	v_or_b32_e32 v78, 3, v72
	v_ashrrev_i32_e32 v79, 31, v78
	v_lshlrev_b64 v[78:79], 12, v[78:79]
	v_lshl_add_u64 v[80:81], v[74:75], 0, v[78:79]
	global_load_dword v115, v[80:81], off
	global_load_dword v116, v[80:81], off offset:64
	global_load_dword v117, v[80:81], off offset:128
	global_load_dword v118, v[80:81], off offset:192
	v_or_b32_e32 v80, 16, v72
	v_ashrrev_i32_e32 v81, 31, v80
	v_lshlrev_b64 v[80:81], 12, v[80:81]
	v_lshl_add_u64 v[82:83], v[74:75], 0, v[80:81]
	global_load_dword v119, v[82:83], off
	global_load_dword v120, v[82:83], off offset:64
	global_load_dword v121, v[82:83], off offset:128
	global_load_dword v122, v[82:83], off offset:192
	v_or_b32_e32 v82, 17, v72
	v_ashrrev_i32_e32 v83, 31, v82
	v_lshlrev_b64 v[82:83], 12, v[82:83]
	v_lshl_add_u64 v[84:85], v[74:75], 0, v[82:83]
	global_load_dword v123, v[84:85], off
	global_load_dword v124, v[84:85], off offset:64
	global_load_dword v125, v[84:85], off offset:128
	global_load_dword v126, v[84:85], off offset:192
	v_or_b32_e32 v84, 18, v72
	v_ashrrev_i32_e32 v85, 31, v84
	v_lshlrev_b64 v[84:85], 12, v[84:85]
	v_lshl_add_u64 v[86:87], v[74:75], 0, v[84:85]
	global_load_dword v127, v[86:87], off
	global_load_dword v128, v[86:87], off offset:64
	global_load_dword v129, v[86:87], off offset:128
	global_load_dword v130, v[86:87], off offset:192
	v_or_b32_e32 v86, 19, v72
	v_ashrrev_i32_e32 v87, 31, v86
	v_lshlrev_b64 v[86:87], 12, v[86:87]
	v_lshl_add_u64 v[88:89], v[74:75], 0, v[86:87]
	global_load_dword v131, v[88:89], off
	global_load_dword v132, v[88:89], off offset:64
	global_load_dword v133, v[88:89], off offset:128
	global_load_dword v134, v[88:89], off offset:192
	v_or_b32_e32 v88, 32, v72
	v_ashrrev_i32_e32 v89, 31, v88
	v_lshlrev_b64 v[88:89], 12, v[88:89]
	v_lshl_add_u64 v[90:91], v[74:75], 0, v[88:89]
; template <int EPI, bool AF32>
; DEV void gemm_tile(const void* Ap, int lda, const u16* Bt, int ldb, int K, int m0, int n0, const Epi& ea, char* smem) {
;     ...
; #pragma unroll
;       for (int m = 0; m < 4; m++)
; #pragma unroll
;         for (int j = 0; j < 4; j++)
; #pragma unroll
;           for (int n = 0; n < 4; n++) rv[m][j][n] = R[(size_t)(rbase + m * 16 + j) * 1024 + cbase + n * 16];
;       __builtin_amdgcn_sched_barrier(0);
; #pragma unroll
;       for (int m = 0; m < 4; m++)
; #pragma unroll
;         for (int j = 0; j < 4; j++)
; #pragma unroll
;           for (int n = 0; n < 4; n++)
;             C[(size_t)(rbase + m * 16 + j) * 1024 + cbase + n * 16] = ALPHA_ * rv[m][j][n] + acc[m][n][j];
	global_load_dword v135, v[90:91], off
	global_load_dword v136, v[90:91], off offset:64
	global_load_dword v137, v[90:91], off offset:128
	global_load_dword v138, v[90:91], off offset:192
	v_or_b32_e32 v90, 33, v72
	v_ashrrev_i32_e32 v91, 31, v90
	v_lshlrev_b64 v[90:91], 12, v[90:91]
	v_lshl_add_u64 v[92:93], v[74:75], 0, v[90:91]
	global_load_dword v139, v[92:93], off
	global_load_dword v140, v[92:93], off offset:64
	global_load_dword v141, v[92:93], off offset:128
	global_load_dword v142, v[92:93], off offset:192
	v_or_b32_e32 v92, 34, v72
	v_ashrrev_i32_e32 v93, 31, v92
	v_lshlrev_b64 v[92:93], 12, v[92:93]
	v_lshl_add_u64 v[94:95], v[74:75], 0, v[92:93]
	global_load_dword v143, v[94:95], off
	global_load_dword v144, v[94:95], off offset:64
	global_load_dword v145, v[94:95], off offset:128
	global_load_dword v146, v[94:95], off offset:192
	v_or_b32_e32 v94, 35, v72
	v_ashrrev_i32_e32 v95, 31, v94
	v_lshlrev_b64 v[94:95], 12, v[94:95]
	v_lshl_add_u64 v[96:97], v[74:75], 0, v[94:95]
	global_load_dword v147, v[96:97], off
	global_load_dword v148, v[96:97], off offset:64
	global_load_dword v149, v[96:97], off offset:128
	global_load_dword v150, v[96:97], off offset:192
	v_or_b32_e32 v96, 48, v72
	v_ashrrev_i32_e32 v97, 31, v96
	v_lshlrev_b64 v[96:97], 12, v[96:97]
	v_lshl_add_u64 v[98:99], v[74:75], 0, v[96:97]
	global_load_dword v151, v[98:99], off
	global_load_dword v152, v[98:99], off offset:64
	global_load_dword v153, v[98:99], off offset:128
	global_load_dword v161, v[98:99], off offset:192
	v_or_b32_e32 v98, 49, v72
	v_ashrrev_i32_e32 v99, 31, v98
	v_lshlrev_b64 v[98:99], 12, v[98:99]
	v_lshl_add_u64 v[100:101], v[74:75], 0, v[98:99]
	global_load_dword v162, v[100:101], off
	global_load_dword v163, v[100:101], off offset:64
	global_load_dword v164, v[100:101], off offset:128
	global_load_dword v165, v[100:101], off offset:192
	v_or_b32_e32 v100, 50, v72
	v_or_b32_e32 v72, 51, v72
	v_ashrrev_i32_e32 v101, 31, v100
	v_ashrrev_i32_e32 v73, 31, v72
	v_lshlrev_b64 v[100:101], 12, v[100:101]
	v_lshlrev_b64 v[72:73], 12, v[72:73]
	v_lshl_add_u64 v[102:103], v[74:75], 0, v[100:101]
	v_lshl_add_u64 v[74:75], v[74:75], 0, v[72:73]
	global_load_dword v166, v[102:103], off
	global_load_dword v167, v[102:103], off offset:64
	global_load_dword v168, v[102:103], off offset:128
	s_nop 0
	global_load_dword v102, v[102:103], off offset:192
	s_nop 0
	global_load_dword v103, v[74:75], off
	global_load_dword v169, v[74:75], off offset:64
	global_load_dword v170, v[74:75], off offset:128
	s_nop 0
	global_load_dword v74, v[74:75], off offset:192
	v_lshl_add_u64 v[66:67], s[2:3], 0, v[66:67]
	v_lshl_add_u64 v[68:69], v[66:67], 0, v[68:69]
	s_waitcnt vmcnt(62)
	v_fmamk_f32 v0, v0, 0x3fb504f3, v62
	global_store_dword v[68:69], v0, off
	v_fmamk_f32 v0, v104, 0x3fb504f3, v58
	global_store_dword v[68:69], v0, off offset:64
	s_waitcnt vmcnt(62)
	v_fmamk_f32 v0, v105, 0x3fb504f3, v54
	global_store_dword v[68:69], v0, off offset:128
	v_fmamk_f32 v0, v106, 0x3fb504f3, v50
	global_store_dword v[68:69], v0, off offset:192
	v_lshl_add_u64 v[68:69], v[66:67], 0, v[70:71]
	s_waitcnt vmcnt(62)
	v_fmamk_f32 v0, v107, 0x3fb504f3, v63
	global_store_dword v[68:69], v0, off
	v_fmamk_f32 v0, v108, 0x3fb504f3, v59
	global_store_dword v[68:69], v0, off offset:64
	s_waitcnt vmcnt(62)
	v_fmamk_f32 v0, v109, 0x3fb504f3, v55
	global_store_dword v[68:69], v0, off offset:128
	v_fmamk_f32 v0, v110, 0x3fb504f3, v51
	global_store_dword v[68:69], v0, off offset:192
	v_lshl_add_u64 v[50:51], v[66:67], 0, v[76:77]
	s_waitcnt vmcnt(62)
	v_fmamk_f32 v0, v111, 0x3fb504f3, v64
	global_store_dword v[50:51], v0, off
	v_fmamk_f32 v0, v112, 0x3fb504f3, v60
	global_store_dword v[50:51], v0, off offset:64
	s_waitcnt vmcnt(62)
	v_fmamk_f32 v0, v113, 0x3fb504f3, v56
	global_store_dword v[50:51], v0, off offset:128
	v_fmamk_f32 v0, v114, 0x3fb504f3, v52
	global_store_dword v[50:51], v0, off offset:192
	v_lshl_add_u64 v[50:51], v[66:67], 0, v[78:79]
	s_waitcnt vmcnt(62)
	v_fmac_f32_e32 v65, 0x3fb504f3, v115
	v_fmac_f32_e32 v61, 0x3fb504f3, v116
	s_waitcnt vmcnt(61)
	v_fmac_f32_e32 v57, 0x3fb504f3, v117
	s_waitcnt vmcnt(60)
	v_fmac_f32_e32 v53, 0x3fb504f3, v118
	global_store_dword v[50:51], v65, off
	global_store_dword v[50:51], v61, off offset:64
	global_store_dword v[50:51], v57, off offset:128
	global_store_dword v[50:51], v53, off offset:192
	v_lshl_add_u64 v[50:51], v[66:67], 0, v[80:81]
	s_waitcnt vmcnt(62)
	v_fmamk_f32 v0, v119, 0x3fb504f3, v46
	global_store_dword v[50:51], v0, off
	v_fmamk_f32 v0, v120, 0x3fb504f3, v42
	global_store_dword v[50:51], v0, off offset:64
	s_waitcnt vmcnt(62)
	v_fmamk_f32 v0, v121, 0x3fb504f3, v38
	global_store_dword v[50:51], v0, off offset:128
	v_fmamk_f32 v0, v122, 0x3fb504f3, v34
	global_store_dword v[50:51], v0, off offset:192
	v_lshl_add_u64 v[50:51], v[66:67], 0, v[82:83]
	s_waitcnt vmcnt(62)
; template <int EPI, bool AF32>
; DEV void gemm_tile(const void* Ap, int lda, const u16* Bt, int ldb, int K, int m0, int n0, const Epi& ea, char* smem) {
;     ...
; #pragma unroll
;       for (int m = 0; m < 4; m++)
; #pragma unroll
;         for (int j = 0; j < 4; j++)
; #pragma unroll
;           for (int n = 0; n < 4; n++)
;             C[(size_t)(rbase + m * 16 + j) * 1024 + cbase + n * 16] = ALPHA_ * rv[m][j][n] + acc[m][n][j];
	v_fmamk_f32 v0, v123, 0x3fb504f3, v47
	global_store_dword v[50:51], v0, off
	v_fmamk_f32 v0, v124, 0x3fb504f3, v43
	global_store_dword v[50:51], v0, off offset:64
	s_waitcnt vmcnt(62)
	v_fmamk_f32 v0, v125, 0x3fb504f3, v39
	global_store_dword v[50:51], v0, off offset:128
	v_fmamk_f32 v0, v126, 0x3fb504f3, v35
	global_store_dword v[50:51], v0, off offset:192
	v_lshl_add_u64 v[34:35], v[66:67], 0, v[84:85]
	s_waitcnt vmcnt(62)
	v_fmamk_f32 v0, v127, 0x3fb504f3, v48
	global_store_dword v[34:35], v0, off
	v_fmamk_f32 v0, v128, 0x3fb504f3, v44
	global_store_dword v[34:35], v0, off offset:64
	s_waitcnt vmcnt(62)
	v_fmamk_f32 v0, v129, 0x3fb504f3, v40
	global_store_dword v[34:35], v0, off offset:128
	v_fmamk_f32 v0, v130, 0x3fb504f3, v36
	global_store_dword v[34:35], v0, off offset:192
	v_lshl_add_u64 v[34:35], v[66:67], 0, v[86:87]
	s_waitcnt vmcnt(62)
	v_fmac_f32_e32 v49, 0x3fb504f3, v131
	v_fmac_f32_e32 v45, 0x3fb504f3, v132
	s_waitcnt vmcnt(61)
	v_fmac_f32_e32 v41, 0x3fb504f3, v133
	s_waitcnt vmcnt(60)
	v_fmac_f32_e32 v37, 0x3fb504f3, v134
	global_store_dword v[34:35], v49, off
	global_store_dword v[34:35], v45, off offset:64
	global_store_dword v[34:35], v41, off offset:128
	global_store_dword v[34:35], v37, off offset:192
	v_lshl_add_u64 v[34:35], v[66:67], 0, v[88:89]
	s_waitcnt vmcnt(62)
	v_fmamk_f32 v0, v135, 0x3fb504f3, v30
	global_store_dword v[34:35], v0, off
	v_fmamk_f32 v0, v136, 0x3fb504f3, v26
	global_store_dword v[34:35], v0, off offset:64
	s_waitcnt vmcnt(62)
	v_fmamk_f32 v0, v137, 0x3fb504f3, v22
	global_store_dword v[34:35], v0, off offset:128
	v_fmamk_f32 v0, v138, 0x3fb504f3, v18
	global_store_dword v[34:35], v0, off offset:192
	v_lshl_add_u64 v[34:35], v[66:67], 0, v[90:91]
	s_waitcnt vmcnt(62)
	v_fmamk_f32 v0, v139, 0x3fb504f3, v31
	global_store_dword v[34:35], v0, off
	v_fmamk_f32 v0, v140, 0x3fb504f3, v27
	global_store_dword v[34:35], v0, off offset:64
	s_waitcnt vmcnt(62)
	v_fmamk_f32 v0, v141, 0x3fb504f3, v23
	global_store_dword v[34:35], v0, off offset:128
	v_fmamk_f32 v0, v142, 0x3fb504f3, v19
	global_store_dword v[34:35], v0, off offset:192
	v_lshl_add_u64 v[18:19], v[66:67], 0, v[92:93]
	s_waitcnt vmcnt(62)
	v_fmamk_f32 v0, v143, 0x3fb504f3, v32
	global_store_dword v[18:19], v0, off
	v_fmamk_f32 v0, v144, 0x3fb504f3, v28
	global_store_dword v[18:19], v0, off offset:64
	s_waitcnt vmcnt(62)
	v_fmamk_f32 v0, v145, 0x3fb504f3, v24
	global_store_dword v[18:19], v0, off offset:128
	v_fmamk_f32 v0, v146, 0x3fb504f3, v20
	global_store_dword v[18:19], v0, off offset:192
	v_lshl_add_u64 v[18:19], v[66:67], 0, v[94:95]
	s_waitcnt vmcnt(62)
	v_fmac_f32_e32 v33, 0x3fb504f3, v147
	v_fmac_f32_e32 v29, 0x3fb504f3, v148
	s_waitcnt vmcnt(61)
	v_fmac_f32_e32 v25, 0x3fb504f3, v149
	s_waitcnt vmcnt(60)
	v_fmac_f32_e32 v21, 0x3fb504f3, v150
	global_store_dword v[18:19], v33, off
	global_store_dword v[18:19], v29, off offset:64
	global_store_dword v[18:19], v25, off offset:128
	global_store_dword v[18:19], v21, off offset:192
	v_lshl_add_u64 v[18:19], v[66:67], 0, v[96:97]
	s_waitcnt vmcnt(62)
	v_fmamk_f32 v0, v151, 0x3fb504f3, v14
	global_store_dword v[18:19], v0, off
	v_fmamk_f32 v0, v152, 0x3fb504f3, v10
	global_store_dword v[18:19], v0, off offset:64
	s_waitcnt vmcnt(62)
	v_fmamk_f32 v0, v153, 0x3fb504f3, v6
	global_store_dword v[18:19], v0, off offset:128
	v_fmamk_f32 v0, v161, 0x3fb504f3, v2
	global_store_dword v[18:19], v0, off offset:192
	v_lshl_add_u64 v[18:19], v[66:67], 0, v[98:99]
	s_waitcnt vmcnt(62)
	v_fmamk_f32 v0, v162, 0x3fb504f3, v15
	global_store_dword v[18:19], v0, off
	v_fmamk_f32 v0, v163, 0x3fb504f3, v11
	global_store_dword v[18:19], v0, off offset:64
	s_waitcnt vmcnt(62)
	v_fmamk_f32 v0, v164, 0x3fb504f3, v7
	global_store_dword v[18:19], v0, off offset:128
	v_fmamk_f32 v0, v165, 0x3fb504f3, v3
	global_store_dword v[18:19], v0, off offset:192
	v_lshl_add_u64 v[2:3], v[66:67], 0, v[100:101]
	s_waitcnt vmcnt(62)
	v_fmamk_f32 v0, v166, 0x3fb504f3, v16
	global_store_dword v[2:3], v0, off
	v_fmamk_f32 v0, v167, 0x3fb504f3, v12
	global_store_dword v[2:3], v0, off offset:64
	s_waitcnt vmcnt(62)
	v_fmamk_f32 v0, v168, 0x3fb504f3, v8
	global_store_dword v[2:3], v0, off offset:128
	v_fmamk_f32 v0, v102, 0x3fb504f3, v4
	global_store_dword v[2:3], v0, off offset:192
	v_lshl_add_u64 v[2:3], v[66:67], 0, v[72:73]
	s_waitcnt vmcnt(62)
	v_fmac_f32_e32 v17, 0x3fb504f3, v103
	v_fmac_f32_e32 v13, 0x3fb504f3, v169
	s_waitcnt vmcnt(61)
	v_fmac_f32_e32 v9, 0x3fb504f3, v170
	s_waitcnt vmcnt(60)
	v_fmac_f32_e32 v5, 0x3fb504f3, v74
	v_readfirstlane_b32 s0, v198
	global_store_dword v[2:3], v17, off
	global_store_dword v[2:3], v13, off offset:64
	global_store_dword v[2:3], v9, off offset:128
	global_store_dword v[2:3], v5, off offset:192
	s_add_i32 s14, s0, s14
	s_cmpk_lt_i32 s14, 0x820
	s_cbranch_scc1 .LBB0_1478
